# W_in log-forget epilogue: per-wave run-time choice of a copy without the denormal pre-scale of the second logf (exact when no la is a positive denormal)
# speedup vs baseline: 1.0099x; 1.0025x over previous
;     __device__ __forceinline__ void operator()(const f32x4 (&acc)[2][2][4][2], const pg8::Unit& u, int wr, int wc, int fr, int fq) const {
;     ...
;             for (int bj = 0; bj < 2; ++bj) { l0[bj] = *(const f32x4*)(lb + cb + bj * 128); l1[bj] = *(const f32x4*)(lb + cb + bj * 128 + 4); }
;             WIN_LOOP( _Pragma("unroll") for (int i = 0; i < 4; ++i) { const float s0 = fminf(a[i], 0.f) - __logf(1.f + __expf(-fabsf(a[i]))), s1 = fminf(b[i], 0.f) - __logf(1.f + __expf(-fabsf(b[i]))); const float la = l0[bj][i], lbv = l1[bj][i];
;                     a[i] = la > 0.f ? __logf(la + (1.f - la) * __expf(s0)) : s0; b[i] = lbv > 0.f ? __logf(lbv + (1.f - lbv) * __expf(s1)) : s1; }
.LBB0_414:
	s_andn2_b64 vcc, exec, s[8:9]
	s_cbranch_vccnz .LBB0_416
	v_readlane_b32 s8, v255, 35
	v_readlane_b32 s9, v255, 36
	v_lshlrev_b32_e32 v144, 2, v176
	s_nop 4
	global_load_dwordx4 v[128:131], v144, s[8:9]
	global_load_dwordx4 v[132:135], v144, s[8:9] offset:16
	global_load_dwordx4 v[136:139], v144, s[8:9] offset:512
	global_load_dwordx4 v[140:143], v144, s[8:9] offset:528
	s_waitcnt vmcnt(0)
	v_add_u32_e32 v128, -1, v128
	v_add_u32_e32 v129, -1, v129
	v_add_u32_e32 v130, -1, v130
	v_add_u32_e32 v131, -1, v131
	v_add_u32_e32 v132, -1, v132
	v_add_u32_e32 v133, -1, v133
	v_add_u32_e32 v134, -1, v134
	v_add_u32_e32 v135, -1, v135
	v_add_u32_e32 v136, -1, v136
	v_add_u32_e32 v137, -1, v137
	v_add_u32_e32 v138, -1, v138
	v_add_u32_e32 v139, -1, v139
	v_add_u32_e32 v140, -1, v140
	v_add_u32_e32 v141, -1, v141
	v_add_u32_e32 v142, -1, v142
	v_add_u32_e32 v143, -1, v143
	v_min_u32_e32 v128, v128, v129
	v_min_u32_e32 v130, v130, v131
	v_min_u32_e32 v132, v132, v133
	v_min_u32_e32 v134, v134, v135
	v_min_u32_e32 v136, v136, v137
	v_min_u32_e32 v138, v138, v139
	v_min_u32_e32 v140, v140, v141
	v_min_u32_e32 v142, v142, v143
	v_min_u32_e32 v128, v128, v130
	v_min_u32_e32 v132, v132, v134
	v_min_u32_e32 v136, v136, v138
	v_min_u32_e32 v140, v140, v142
	v_min_u32_e32 v128, v128, v132
	v_min_u32_e32 v136, v136, v140
	v_min_u32_e32 v128, v128, v136
	v_mov_b32_e32 v129, 0x7fffff
	v_cmp_lt_u32_e32 vcc, v128, v129
	s_nop 1
	s_cmp_eq_u64 vcc, 0
	s_cbranch_scc1 .Llf_fast
	v_ashrrev_i32_e32 v167, 31, v166
	v_lshlrev_b64 v[128:129], 6, v[166:167]
	v_lshl_add_u64 v[128:129], v[160:161], 0, v[128:129]
	s_nop 0
	v_readlane_b32 s8, v255, 35
	v_lshlrev_b32_e32 v192, 2, v176
	v_readlane_b32 s9, v255, 36
	v_and_b32_e32 v133, 64, v215
	v_xor_b32_e32 v132, 16, v215
	v_lshl_add_u64 v[144:145], s[8:9], 0, v[192:193]
	flat_load_dwordx4 v[140:143], v[144:145]
	flat_load_dwordx4 v[136:139], v[144:145] offset:16
	v_add_u32_e32 v134, 64, v133
	v_cmp_lt_i32_e32 vcc, v132, v134
	v_lshlrev_b64 v[146:147], 11, v[166:167]
	v_readlane_b32 s50, v255, 45
	v_cndmask_b32_e32 v132, v215, v132, vcc
	v_lshlrev_b32_e32 v169, 2, v132
	v_readlane_b32 s51, v255, 46
	s_mov_b32 s95, s28
	s_mov_b32 s91, s29
	v_lshl_add_u64 v[170:171], s[50:51], 0, v[146:147]
	v_lshl_add_u64 v[170:171], v[170:171], 0, v[192:193]
	s_waitcnt vmcnt(0) lgkmcnt(0)
	s_nop 3
	v_xor_b32_e32 v130, 32, v215
	s_nop 1
	v_cmp_lt_i32_e32 vcc, v130, v134
	v_sub_f32_e32 v190, 1.0, v140
	v_sub_f32_e32 v191, 1.0, v136
	v_cndmask_b32_e32 v130, v215, v130, vcc
	v_lshlrev_b32_e32 v202, 2, v130
	s_waitcnt lgkmcnt(0)
	s_nop 1
	flat_load_dwordx4 v[132:135], v[144:145] offset:512
	flat_load_dwordx4 v[128:131], v[144:145] offset:528
	v_sub_f32_e32 v188, 1.0, v141
	v_cmp_lt_f32_e64 s[38:39], 0, v140
	v_cmp_lt_f32_e64 s[36:37], 0, v136
	s_waitcnt lgkmcnt(0)
	s_nop 1
	v_mov_b32_e32 v168, v250
	v_sub_f32_e32 v189, 1.0, v137
	v_cmp_lt_f32_e64 s[34:35], 0, v141
	v_cmp_lt_f32_e64 s[30:31], 0, v137
	v_pk_mul_f32 v[144:145], v[60:61], v[168:169] op_sel_hi:[1,0]
	v_pk_mul_f32 v[148:149], v[56:57], v[168:169] op_sel_hi:[1,0]
	v_min_f32_e32 v167, 0, v144
	v_mul_f32_e64 v144, |v144|, s57
	v_min_f32_e32 v177, 0, v148
	v_mul_f32_e64 v148, |v148|, s57
	v_exp_f32_e32 v144, v144
	v_exp_f32_e32 v148, v148
	v_min_f32_e32 v179, 0, v149
	v_mul_f32_e64 v149, |v149|, s57
	v_add_f32_e32 v144, 1.0, v144
	v_exp_f32_e32 v149, v149
	v_add_f32_e32 v148, 1.0, v148
	v_min_f32_e32 v178, 0, v145
	v_mul_f32_e64 v145, |v145|, s57
	v_exp_f32_e32 v145, v145
	v_log_f32_e32 v144, v144
	v_add_f32_e32 v149, 1.0, v149
	v_log_f32_e32 v148, v148
	v_add_f32_e32 v145, 1.0, v145
	v_mul_f32_e32 v183, 0x3f317217, v144
	v_mul_f32_e32 v184, 0x3f317217, v148
	v_fma_f32 v183, v144, s52, -v183
	v_fma_f32 v184, v148, s52, -v184
	v_fmac_f32_e32 v183, 0x3377d1cf, v144
	v_fmac_f32_e32 v184, 0x3377d1cf, v148
	v_fmac_f32_e32 v183, 0x3f317217, v144
	v_log_f32_e32 v145, v145
	v_fmac_f32_e32 v184, 0x3f317217, v148
	v_mov_b32_e32 v144, v183
	v_log_f32_e32 v149, v149
	v_mov_b32_e32 v148, v184
	v_sub_f32_e32 v144, v167, v144
	v_sub_f32_e32 v167, v177, v148
	v_mul_f32_e32 v148, 0x3fb8aa3b, v144
	v_mul_f32_e32 v185, 0x3f317217, v145
	v_mul_f32_e32 v177, 0x3fb8aa3b, v167
	v_exp_f32_e32 v148, v148
	v_mul_f32_e32 v186, 0x3f317217, v149
	v_fma_f32 v185, v145, s52, -v185
	v_exp_f32_e32 v177, v177
	v_fma_f32 v186, v149, s52, -v186
	v_fmac_f32_e32 v185, 0x3377d1cf, v145
	v_fmac_f32_e32 v186, 0x3377d1cf, v149
	v_fmac_f32_e32 v185, 0x3f317217, v145
	v_fmac_f32_e32 v186, 0x3f317217, v149
	v_fma_f32 v148, v190, v148, v140
	v_mov_b32_e32 v145, v185
	v_fma_f32 v177, v191, v177, v136
	v_cmp_gt_f32_e64 s[10:11], s97, v177
	v_mov_b32_e32 v149, v186
	v_cmp_gt_f32_e64 s[8:9], s97, v148
	v_cndmask_b32_e64 v181, 0, 32, s[10:11]
	v_ldexp_f32 v177, v177, v181
	v_cndmask_b32_e64 v180, 0, 32, s[8:9]
	v_ldexp_f32 v148, v148, v180
	v_log_f32_e32 v148, v148
	v_log_f32_e32 v177, v177
	v_sub_f32_e32 v145, v178, v145
	v_mul_f32_e32 v178, 0x3fb8aa3b, v145
	v_mul_f32_e32 v182, 0x3f317217, v148
	v_exp_f32_e32 v178, v178
	v_mul_f32_e32 v183, 0x3f317217, v177
	v_fma_f32 v182, v148, s52, -v182
	v_fma_f32 v183, v177, s52, -v183
	v_fmac_f32_e32 v182, 0x3377d1cf, v148
	v_cndmask_b32_e64 v180, 0, v216, s[8:9]
	v_fmac_f32_e32 v183, 0x3377d1cf, v177
	v_fmac_f32_e32 v182, 0x3f317217, v148
	v_fmac_f32_e32 v183, 0x3f317217, v177
	v_fma_f32 v178, v188, v178, v141
	v_mov_b32_e32 v148, v182
	v_cndmask_b32_e64 v181, 0, v216, s[10:11]
	v_sub_f32_e32 v148, v148, v180
	v_mov_b32_e32 v177, v183
	v_sub_f32_e32 v177, v177, v181
	v_cmp_gt_f32_e64 s[8:9], s97, v178
	v_cndmask_b32_e64 v148, v144, v148, s[38:39]
	v_cndmask_b32_e64 v144, v167, v177, s[36:37]
; __device__ __forceinline__ float silu_f(float x) { return x * __builtin_amdgcn_rcpf(1.f + __expf(-x)); }
; __device__ __forceinline__ v4u pack8(const f32x4 a, const f32x4 b) { v4u w; w.x = cvt_pk_bf16(a[0], a[1]); w.y = cvt_pk_bf16(a[2], a[3]); w.z = cvt_pk_bf16(b[0], b[1]); w.w = cvt_pk_bf16(b[2], b[3]); return w; }
;     __device__ __forceinline__ void operator()(const f32x4 (&acc)[2][2][4][2], const pg8::Unit& u, int wr, int wc, int fr, int fq) const {
;     ...
;         if (grp == 0) { WIN_LOOP( _Pragma("unroll") for (int i = 0; i < 4; ++i) { a[i] = silu_f(a[i]); b[i] = silu_f(b[i]); } *(v4u*)(QO + (size_t)row * DM + c) = pack8(a, b); ) }
;         else if (grp == 3) { WIN_LOOP( _Pragma("unroll") for (int i = 0; i < 4; ++i) { a[i] = silu_f(a[i]); b[i] = silu_f(b[i]); } *(v4u*)(GH + (size_t)row * 512 + c) = pack8(a, b); ) }
;         else if (grp == 1) {
;             f32x4 l0[2], l1[2];
; #pragma unroll
;             for (int bj = 0; bj < 2; ++bj) { l0[bj] = *(const f32x4*)(lb + cb + bj * 128); l1[bj] = *(const f32x4*)(lb + cb + bj * 128 + 4); }
;             WIN_LOOP( _Pragma("unroll") for (int i = 0; i < 4; ++i) { const float s0 = fminf(a[i], 0.f) - __logf(1.f + __expf(-fabsf(a[i]))), s1 = fminf(b[i], 0.f) - __logf(1.f + __expf(-fabsf(b[i]))); const float la = l0[bj][i], lbv = l1[bj][i];
;                     a[i] = la > 0.f ? __logf(la + (1.f - la) * __expf(s0)) : s0; b[i] = lbv > 0.f ? __logf(lbv + (1.f - lbv) * __expf(s1)) : s1; }
;                 *(f32x4*)(LF + (size_t)row * 512 + c) = a; *(f32x4*)(LF + (size_t)row * 512 + c + 4) = b; __builtin_amdgcn_sched_barrier(0); ) }
	v_cndmask_b32_e64 v167, 0, 32, s[8:9]
	v_ldexp_f32 v167, v178, v167
	v_log_f32_e32 v167, v167
	v_sub_f32_e32 v177, v179, v149
	v_mul_f32_e32 v178, 0x3fb8aa3b, v177
	v_exp_f32_e32 v178, v178
	v_mul_f32_e32 v149, 0x3f317217, v167
	v_fma_f32 v149, v167, s52, -v149
	v_fmac_f32_e32 v149, 0x3377d1cf, v167
	v_fmac_f32_e32 v149, 0x3f317217, v167
	v_fma_f32 v178, v189, v178, v137
	v_pk_mul_f32 v[150:151], v[62:63], v[168:169] op_sel_hi:[1,0]
	v_cmp_gt_f32_e32 vcc, s97, v178
	v_cndmask_b32_e64 v167, 0, v216, s[8:9]
	v_sub_f32_e32 v149, v149, v167
	v_cndmask_b32_e64 v179, 0, 32, vcc
	v_ldexp_f32 v178, v178, v179
	v_log_f32_e32 v178, v178
	v_mul_f32_e64 v167, |v150|, s57
	v_exp_f32_e32 v167, v167
	v_cndmask_b32_e64 v149, v145, v149, s[34:35]
	v_mul_f32_e32 v145, 0x3f317217, v178
	v_fma_f32 v145, v178, s52, -v145
	v_fmac_f32_e32 v145, 0x3377d1cf, v178
	v_fmac_f32_e32 v145, 0x3f317217, v178
	v_add_f32_e32 v167, 1.0, v167
	v_pk_mul_f32 v[146:147], v[58:59], v[168:169] op_sel_hi:[1,0]
	v_cndmask_b32_e32 v178, 0, v216, vcc
	v_sub_f32_e32 v145, v145, v178
	v_cndmask_b32_e64 v145, v177, v145, s[30:31]
	v_log_f32_e32 v167, v167
	v_mul_f32_e64 v178, |v146|, s57
	v_exp_f32_e32 v178, v178
	v_min_f32_e32 v150, 0, v150
	v_mul_f32_e32 v177, 0x3f317217, v167
	v_fma_f32 v177, v167, s52, -v177
	v_fmac_f32_e32 v177, 0x3377d1cf, v167
	v_fmac_f32_e32 v177, 0x3f317217, v167
	v_add_f32_e32 v178, 1.0, v178
	v_sub_f32_e32 v187, 1.0, v142
	v_mov_b32_e32 v167, v177
	v_sub_f32_e32 v150, v150, v167
	v_log_f32_e32 v178, v178
	v_mul_f32_e32 v177, 0x3fb8aa3b, v150
	v_exp_f32_e32 v177, v177
	v_min_f32_e32 v146, 0, v146
	v_mul_f32_e32 v167, 0x3f317217, v178
	v_fma_f32 v167, v178, s52, -v167
	v_fmac_f32_e32 v167, 0x3377d1cf, v178
	v_fmac_f32_e32 v167, 0x3f317217, v178
	v_fma_f32 v177, v187, v177, v142
	v_sub_f32_e32 v186, 1.0, v138
	v_mov_b32_e32 v167, v167
	v_cmp_gt_f32_e64 s[8:9], s97, v177
	v_cmp_lt_f32_e64 s[28:29], 0, v142
	v_cmp_lt_f32_e64 s[26:27], 0, v138
	v_cndmask_b32_e64 v178, 0, 32, s[8:9]
	v_ldexp_f32 v177, v177, v178
	v_log_f32_e32 v177, v177
	v_sub_f32_e32 v146, v146, v167
	v_mul_f32_e32 v178, 0x3fb8aa3b, v146
	v_exp_f32_e32 v178, v178
	v_mul_f32_e32 v167, 0x3f317217, v177
	v_fma_f32 v167, v177, s52, -v167
	v_fmac_f32_e32 v167, 0x3377d1cf, v177
	v_fmac_f32_e32 v167, 0x3f317217, v177
	v_fma_f32 v178, v186, v178, v138
	v_sub_f32_e32 v185, 1.0, v143
	v_cmp_gt_f32_e32 vcc, s97, v178
	v_cndmask_b32_e64 v177, 0, v216, s[8:9]
	v_sub_f32_e32 v167, v167, v177
	v_cndmask_b32_e64 v179, 0, 32, vcc
	v_ldexp_f32 v178, v178, v179
	v_log_f32_e32 v178, v178
	v_mul_f32_e64 v177, |v151|, s57
	v_exp_f32_e32 v177, v177
	v_cndmask_b32_e64 v150, v150, v167, s[28:29]
	v_mul_f32_e32 v167, 0x3f317217, v178
	v_fma_f32 v167, v178, s52, -v167
	v_fmac_f32_e32 v167, 0x3377d1cf, v178
	v_fmac_f32_e32 v167, 0x3f317217, v178
	v_add_f32_e32 v177, 1.0, v177
	v_min_f32_e32 v151, 0, v151
	v_cndmask_b32_e32 v178, 0, v216, vcc
	v_sub_f32_e32 v167, v167, v178
	v_cndmask_b32_e64 v146, v146, v167, s[26:27]
	v_log_f32_e32 v177, v177
	v_mul_f32_e64 v178, |v147|, s57
	v_exp_f32_e32 v178, v178
	v_min_f32_e32 v147, 0, v147
	v_mul_f32_e32 v167, 0x3f317217, v177
	v_fma_f32 v167, v177, s52, -v167
	v_fmac_f32_e32 v167, 0x3377d1cf, v177
	v_fmac_f32_e32 v167, 0x3f317217, v177
	v_add_f32_e32 v178, 1.0, v178
	v_sub_f32_e32 v184, 1.0, v139
	v_mov_b32_e32 v167, v167
	v_sub_f32_e32 v151, v151, v167
	v_log_f32_e32 v178, v178
	v_mul_f32_e32 v177, 0x3fb8aa3b, v151
	v_exp_f32_e32 v177, v177
	v_cmp_lt_f32_e64 s[24:25], 0, v143
	v_mul_f32_e32 v167, 0x3f317217, v178
	v_fma_f32 v167, v178, s52, -v167
	v_fmac_f32_e32 v167, 0x3377d1cf, v178
	v_fmac_f32_e32 v167, 0x3f317217, v178
	v_fma_f32 v177, v185, v177, v143
	v_cmp_lt_f32_e64 s[22:23], 0, v139
	v_mov_b32_e32 v167, v167
	v_cmp_gt_f32_e64 s[8:9], s97, v177
	s_nop 1
	v_cndmask_b32_e64 v178, 0, 32, s[8:9]
	v_ldexp_f32 v177, v177, v178
	v_log_f32_e32 v177, v177
	v_sub_f32_e32 v147, v147, v167
	v_mul_f32_e32 v178, 0x3fb8aa3b, v147
	v_exp_f32_e32 v178, v178
	v_mul_f32_e32 v167, 0x3f317217, v177
	v_fma_f32 v167, v177, s52, -v167
	v_fmac_f32_e32 v167, 0x3377d1cf, v177
	v_fmac_f32_e32 v167, 0x3f317217, v177
	v_fma_f32 v178, v184, v178, v139
	s_nop 0
	v_cmp_gt_f32_e32 vcc, s97, v178
	v_cndmask_b32_e64 v177, 0, v216, s[8:9]
	v_sub_f32_e32 v167, v167, v177
	v_cndmask_b32_e64 v179, 0, 32, vcc
	v_ldexp_f32 v178, v178, v179
	v_log_f32_e32 v178, v178
	v_cndmask_b32_e64 v151, v151, v167, s[24:25]
	v_cndmask_b32_e32 v177, 0, v216, vcc
	v_mul_f32_e32 v167, 0x3f317217, v178
	v_fma_f32 v167, v178, s52, -v167
	v_fmac_f32_e32 v167, 0x3377d1cf, v178
	v_fmac_f32_e32 v167, 0x3f317217, v178
	v_sub_f32_e32 v167, v167, v177
	v_cndmask_b32_e64 v147, v147, v167, s[22:23]
	global_store_dwordx4 v[170:171], v[148:151], off
	global_store_dwordx4 v[170:171], v[144:147], off offset:16
	s_nop 1
	v_pk_mul_f32 v[144:145], v[124:125], v[168:169] op_sel_hi:[1,0]
	v_pk_mul_f32 v[150:151], v[126:127], v[168:169] op_sel_hi:[1,0]
	v_mul_f32_e64 v146, |v144|, s57
	v_exp_f32_e32 v148, v146
	v_pk_mul_f32 v[146:147], v[122:123], v[168:169] op_sel_hi:[1,0]
	v_min_f32_e32 v144, 0, v144
	s_waitcnt vmcnt(0)
; __device__ __forceinline__ float silu_f(float x) { return x * __builtin_amdgcn_rcpf(1.f + __expf(-x)); }
; __device__ __forceinline__ v4u pack8(const f32x4 a, const f32x4 b) { v4u w; w.x = cvt_pk_bf16(a[0], a[1]); w.y = cvt_pk_bf16(a[2], a[3]); w.z = cvt_pk_bf16(b[0], b[1]); w.w = cvt_pk_bf16(b[2], b[3]); return w; }
;     __device__ __forceinline__ void operator()(const f32x4 (&acc)[2][2][4][2], const pg8::Unit& u, int wr, int wc, int fr, int fq) const {
;     ...
;         if (grp == 0) { WIN_LOOP( _Pragma("unroll") for (int i = 0; i < 4; ++i) { a[i] = silu_f(a[i]); b[i] = silu_f(b[i]); } *(v4u*)(QO + (size_t)row * DM + c) = pack8(a, b); ) }
;         else if (grp == 3) { WIN_LOOP( _Pragma("unroll") for (int i = 0; i < 4; ++i) { a[i] = silu_f(a[i]); b[i] = silu_f(b[i]); } *(v4u*)(GH + (size_t)row * 512 + c) = pack8(a, b); ) }
;         else if (grp == 1) {
;             f32x4 l0[2], l1[2];
; #pragma unroll
;             for (int bj = 0; bj < 2; ++bj) { l0[bj] = *(const f32x4*)(lb + cb + bj * 128); l1[bj] = *(const f32x4*)(lb + cb + bj * 128 + 4); }
;             WIN_LOOP( _Pragma("unroll") for (int i = 0; i < 4; ++i) { const float s0 = fminf(a[i], 0.f) - __logf(1.f + __expf(-fabsf(a[i]))), s1 = fminf(b[i], 0.f) - __logf(1.f + __expf(-fabsf(b[i]))); const float la = l0[bj][i], lbv = l1[bj][i];
;                     a[i] = la > 0.f ? __logf(la + (1.f - la) * __expf(s0)) : s0; b[i] = lbv > 0.f ? __logf(lbv + (1.f - lbv) * __expf(s1)) : s1; }
;                 *(f32x4*)(LF + (size_t)row * 512 + c) = a; *(f32x4*)(LF + (size_t)row * 512 + c + 4) = b; __builtin_amdgcn_sched_barrier(0); ) }
	v_sub_f32_e32 v183, 1.0, v132
	v_add_f32_e32 v148, 1.0, v148
	v_sub_f32_e32 v182, 1.0, v128
	v_cmp_lt_f32_e64 s[20:21], 0, v132
	v_log_f32_e32 v167, v148
	v_pk_mul_f32 v[148:149], v[120:121], v[168:169] op_sel_hi:[1,0]
	v_cmp_lt_f32_e64 s[18:19], 0, v128
	v_mul_f32_e64 v168, |v148|, s57
	v_exp_f32_e32 v168, v168
	v_mul_f32_e32 v177, 0x3f317217, v167
	v_fma_f32 v177, v167, s52, -v177
	v_fmac_f32_e32 v177, 0x3377d1cf, v167
	v_fmac_f32_e32 v177, 0x3f317217, v167
	v_add_f32_e32 v168, 1.0, v168
	v_min_f32_e32 v148, 0, v148
	v_mov_b32_e32 v167, v177
	v_sub_f32_e32 v144, v144, v167
	v_log_f32_e32 v168, v168
	v_mul_f32_e32 v177, 0x3fb8aa3b, v144
	v_exp_f32_e32 v177, v177
	v_sub_f32_e32 v181, 1.0, v133
	v_mul_f32_e32 v167, 0x3f317217, v168
	v_fma_f32 v167, v168, s52, -v167
	v_fmac_f32_e32 v167, 0x3377d1cf, v168
	v_fmac_f32_e32 v167, 0x3f317217, v168
	v_sub_f32_e32 v180, 1.0, v129
	v_cmp_lt_f32_e64 s[16:17], 0, v133
	v_mov_b32_e32 v167, v167
	v_fma_f32 v168, v183, v177, v132
	v_cmp_gt_f32_e64 s[8:9], s97, v168
	v_cmp_lt_f32_e64 s[14:15], 0, v129
	v_sub_f32_e32 v179, 1.0, v134
	v_cndmask_b32_e64 v177, 0, 32, s[8:9]
	v_ldexp_f32 v168, v168, v177
	v_log_f32_e32 v168, v168
	v_sub_f32_e32 v148, v148, v167
	v_mul_f32_e32 v177, 0x3fb8aa3b, v148
	v_exp_f32_e32 v177, v177
	v_mul_f32_e32 v167, 0x3f317217, v168
	v_fma_f32 v167, v168, s52, -v167
	v_fmac_f32_e32 v167, 0x3377d1cf, v168
	v_fmac_f32_e32 v167, 0x3f317217, v168
	v_fma_f32 v177, v182, v177, v128
	v_cmp_lt_f32_e64 s[12:13], 0, v134
	v_cmp_gt_f32_e32 vcc, s97, v177
	v_cndmask_b32_e64 v168, 0, v216, s[8:9]
	v_sub_f32_e32 v167, v167, v168
	v_cndmask_b32_e64 v178, 0, 32, vcc
	v_ldexp_f32 v177, v177, v178
	v_log_f32_e32 v177, v177
	v_mul_f32_e64 v168, |v145|, s57
	v_exp_f32_e32 v168, v168
	v_cndmask_b32_e64 v144, v144, v167, s[20:21]
	v_mul_f32_e32 v167, 0x3f317217, v177
	v_fma_f32 v167, v177, s52, -v167
	v_fmac_f32_e32 v167, 0x3377d1cf, v177
	v_fmac_f32_e32 v167, 0x3f317217, v177
	v_add_f32_e32 v168, 1.0, v168
	v_min_f32_e32 v145, 0, v145
	v_cndmask_b32_e32 v177, 0, v216, vcc
	v_sub_f32_e32 v167, v167, v177
	v_cndmask_b32_e64 v148, v148, v167, s[18:19]
	v_log_f32_e32 v168, v168
	v_mul_f32_e64 v177, |v149|, s57
	v_exp_f32_e32 v177, v177
	v_min_f32_e32 v149, 0, v149
	v_mul_f32_e32 v167, 0x3f317217, v168
	v_fma_f32 v167, v168, s52, -v167
	v_fmac_f32_e32 v167, 0x3377d1cf, v168
	v_fmac_f32_e32 v167, 0x3f317217, v168
	v_add_f32_e32 v177, 1.0, v177
	v_cmp_lt_f32_e64 s[10:11], 0, v130
	v_mov_b32_e32 v167, v167
	v_sub_f32_e32 v145, v145, v167
	v_log_f32_e32 v177, v177
	v_mul_f32_e32 v168, 0x3fb8aa3b, v145
	v_exp_f32_e32 v168, v168
	s_mov_b32 s2, s40
	v_mul_f32_e32 v167, 0x3f317217, v177
	v_fma_f32 v167, v177, s52, -v167
	v_fmac_f32_e32 v167, 0x3377d1cf, v177
	v_fmac_f32_e32 v167, 0x3f317217, v177
	v_fma_f32 v168, v181, v168, v133
	s_nop 0
	v_mov_b32_e32 v167, v167
	v_cmp_gt_f32_e64 s[8:9], s97, v168
	s_nop 1
	v_cndmask_b32_e64 v177, 0, 32, s[8:9]
	v_ldexp_f32 v168, v168, v177
	v_log_f32_e32 v168, v168
	v_sub_f32_e32 v149, v149, v167
	v_mul_f32_e32 v177, 0x3fb8aa3b, v149
	v_exp_f32_e32 v177, v177
	v_mul_f32_e32 v167, 0x3f317217, v168
	v_fma_f32 v167, v168, s52, -v167
	v_fmac_f32_e32 v167, 0x3377d1cf, v168
	v_fmac_f32_e32 v167, 0x3f317217, v168
	v_fma_f32 v177, v180, v177, v129
	s_nop 0
	v_cmp_gt_f32_e32 vcc, s97, v177
	v_cndmask_b32_e64 v168, 0, v216, s[8:9]
	v_sub_f32_e32 v167, v167, v168
	v_cndmask_b32_e64 v178, 0, 32, vcc
	v_ldexp_f32 v177, v177, v178
	v_log_f32_e32 v177, v177
	v_mul_f32_e64 v168, |v150|, s57
	v_exp_f32_e32 v168, v168
	v_cndmask_b32_e64 v145, v145, v167, s[16:17]
	v_mul_f32_e32 v167, 0x3f317217, v177
	v_fma_f32 v167, v177, s52, -v167
	v_fmac_f32_e32 v167, 0x3377d1cf, v177
	v_fmac_f32_e32 v167, 0x3f317217, v177
	v_add_f32_e32 v168, 1.0, v168
	v_min_f32_e32 v150, 0, v150
	v_cndmask_b32_e32 v177, 0, v216, vcc
	v_sub_f32_e32 v167, v167, v177
	v_cndmask_b32_e64 v149, v149, v167, s[14:15]
	v_log_f32_e32 v168, v168
	v_mul_f32_e64 v177, |v146|, s57
	v_exp_f32_e32 v177, v177
	v_min_f32_e32 v146, 0, v146
	v_mul_f32_e32 v167, 0x3f317217, v168
	v_fma_f32 v167, v168, s52, -v167
	v_fmac_f32_e32 v167, 0x3377d1cf, v168
	v_fmac_f32_e32 v167, 0x3f317217, v168
	v_add_f32_e32 v177, 1.0, v177
	s_nop 0
	v_mov_b32_e32 v167, v167
	v_sub_f32_e32 v150, v150, v167
	v_log_f32_e32 v177, v177
	v_mul_f32_e32 v168, 0x3fb8aa3b, v150
	v_exp_f32_e32 v168, v168
	v_sub_f32_e32 v178, 1.0, v130
	v_mul_f32_e32 v167, 0x3f317217, v177
	v_fma_f32 v167, v177, s52, -v167
	v_fmac_f32_e32 v167, 0x3377d1cf, v177
	v_fmac_f32_e32 v167, 0x3f317217, v177
	v_fma_f32 v168, v179, v168, v134
	s_nop 0
	v_mov_b32_e32 v167, v167
	v_cmp_gt_f32_e64 s[8:9], s97, v168
	s_nop 1
	v_cndmask_b32_e64 v177, 0, 32, s[8:9]
	v_ldexp_f32 v168, v168, v177
	v_log_f32_e32 v168, v168
	v_sub_f32_e32 v167, v146, v167
	v_mul_f32_e32 v177, 0x3fb8aa3b, v167
	v_exp_f32_e32 v177, v177
	v_mul_f32_e32 v146, 0x3f317217, v168
	v_fma_f32 v146, v168, s52, -v146
	v_fmac_f32_e32 v146, 0x3377d1cf, v168
	v_fmac_f32_e32 v146, 0x3f317217, v168
	v_fma_f32 v177, v178, v177, v130
	s_nop 0
	v_cmp_gt_f32_e32 vcc, s97, v177
	v_cndmask_b32_e64 v168, 0, v216, s[8:9]
	v_sub_f32_e32 v146, v146, v168
	v_cndmask_b32_e64 v194, 0, 32, vcc
	v_ldexp_f32 v177, v177, v194
	v_log_f32_e32 v177, v177
	v_mul_f32_e64 v168, |v151|, s57
	v_exp_f32_e32 v168, v168
	v_cndmask_b32_e64 v146, v150, v146, s[12:13]
	v_mul_f32_e32 v150, 0x3f317217, v177
	v_fma_f32 v150, v177, s52, -v150
	v_fmac_f32_e32 v150, 0x3377d1cf, v177
	v_fmac_f32_e32 v150, 0x3f317217, v177
	v_add_f32_e32 v168, 1.0, v168
	v_min_f32_e32 v151, 0, v151
	v_cndmask_b32_e32 v177, 0, v216, vcc
	v_sub_f32_e32 v150, v150, v177
	v_cndmask_b32_e64 v150, v167, v150, s[10:11]
; __device__ __forceinline__ float silu_f(float x) { return x * __builtin_amdgcn_rcpf(1.f + __expf(-x)); }
; __device__ __forceinline__ v4u pack8(const f32x4 a, const f32x4 b) { v4u w; w.x = cvt_pk_bf16(a[0], a[1]); w.y = cvt_pk_bf16(a[2], a[3]); w.z = cvt_pk_bf16(b[0], b[1]); w.w = cvt_pk_bf16(b[2], b[3]); return w; }
;     __device__ __forceinline__ void operator()(const f32x4 (&acc)[2][2][4][2], const pg8::Unit& u, int wr, int wc, int fr, int fq) const {
;     ...
;         if (grp == 0) { WIN_LOOP( _Pragma("unroll") for (int i = 0; i < 4; ++i) { a[i] = silu_f(a[i]); b[i] = silu_f(b[i]); } *(v4u*)(QO + (size_t)row * DM + c) = pack8(a, b); ) }
;         else if (grp == 3) { WIN_LOOP( _Pragma("unroll") for (int i = 0; i < 4; ++i) { a[i] = silu_f(a[i]); b[i] = silu_f(b[i]); } *(v4u*)(GH + (size_t)row * 512 + c) = pack8(a, b); ) }
;         else if (grp == 1) {
;             f32x4 l0[2], l1[2];
; #pragma unroll
;             for (int bj = 0; bj < 2; ++bj) { l0[bj] = *(const f32x4*)(lb + cb + bj * 128); l1[bj] = *(const f32x4*)(lb + cb + bj * 128 + 4); }
;             WIN_LOOP( _Pragma("unroll") for (int i = 0; i < 4; ++i) { const float s0 = fminf(a[i], 0.f) - __logf(1.f + __expf(-fabsf(a[i]))), s1 = fminf(b[i], 0.f) - __logf(1.f + __expf(-fabsf(b[i]))); const float la = l0[bj][i], lbv = l1[bj][i];
;                     a[i] = la > 0.f ? __logf(la + (1.f - la) * __expf(s0)) : s0; b[i] = lbv > 0.f ? __logf(lbv + (1.f - lbv) * __expf(s1)) : s1; }
;                 *(f32x4*)(LF + (size_t)row * 512 + c) = a; *(f32x4*)(LF + (size_t)row * 512 + c + 4) = b; __builtin_amdgcn_sched_barrier(0); ) }
	v_log_f32_e32 v168, v168
	v_mul_f32_e64 v177, |v147|, s57
	v_exp_f32_e32 v177, v177
	v_min_f32_e32 v147, 0, v147
	v_mul_f32_e32 v167, 0x3f317217, v168
	v_fma_f32 v167, v168, s52, -v167
	v_fmac_f32_e32 v167, 0x3377d1cf, v168
	v_fmac_f32_e32 v167, 0x3f317217, v168
	v_add_f32_e32 v177, 1.0, v177
	s_nop 0
	v_mov_b32_e32 v167, v167
	v_sub_f32_e32 v151, v151, v167
	v_log_f32_e32 v177, v177
	v_mul_f32_e32 v168, 0x3fb8aa3b, v151
	v_exp_f32_e32 v168, v168
	v_mul_f32_e32 v167, 0x3f317217, v177
	v_fma_f32 v167, v177, s52, -v167
	v_fmac_f32_e32 v167, 0x3377d1cf, v177
	v_fmac_f32_e32 v167, 0x3f317217, v177
	v_mov_b32_e32 v167, v167
	v_sub_f32_e32 v177, 1.0, v135
	v_fma_f32 v168, v177, v168, v135
	v_cmp_gt_f32_e64 s[8:9], s97, v168
	s_nop 1
	v_cndmask_b32_e64 v194, 0, 32, s[8:9]
	v_ldexp_f32 v168, v168, v194
	v_log_f32_e32 v168, v168
	v_sub_f32_e32 v194, v147, v167
	v_mul_f32_e32 v167, 0x3fb8aa3b, v194
	v_exp_f32_e32 v195, v167
	v_mul_f32_e32 v147, 0x3f317217, v168
	v_fma_f32 v147, v168, s52, -v147
	v_fmac_f32_e32 v147, 0x3377d1cf, v168
	v_sub_f32_e32 v167, 1.0, v131
	v_fmac_f32_e32 v147, 0x3f317217, v168
	v_fma_f32 v195, v167, v195, v131
	s_nop 0
	v_cmp_gt_f32_e32 vcc, s97, v195
	v_cndmask_b32_e64 v168, 0, v216, s[8:9]
	v_sub_f32_e32 v147, v147, v168
	v_cndmask_b32_e64 v204, 0, 32, vcc
	v_ldexp_f32 v195, v195, v204
	v_log_f32_e32 v195, v195
	v_cmp_lt_f32_e64 s[8:9], 0, v135
	v_cndmask_b32_e32 v168, 0, v216, vcc
	v_cmp_lt_f32_e32 vcc, 0, v131
	v_cndmask_b32_e64 v147, v151, v147, s[8:9]
	v_mul_f32_e32 v151, 0x3f317217, v195
	v_fma_f32 v151, v195, s52, -v151
	v_fmac_f32_e32 v151, 0x3377d1cf, v195
	v_fmac_f32_e32 v151, 0x3f317217, v195
	v_sub_f32_e32 v151, v151, v168
	v_cndmask_b32_e32 v151, v194, v151, vcc
	global_store_dwordx4 v[170:171], v[144:147], off offset:512
	global_store_dwordx4 v[170:171], v[148:151], off offset:528
	s_nop 1
	v_or_b32_e32 v148, 16, v166
	v_ashrrev_i32_e32 v149, 31, v148
	v_lshlrev_b64 v[144:145], 6, v[148:149]
	v_lshl_add_u64 v[144:145], v[160:161], 0, v[144:145]
	s_nop 0
	s_waitcnt lgkmcnt(0)
	s_nop 3
	s_nop 0
	s_nop 1
	s_waitcnt lgkmcnt(0)
	s_nop 1
	s_waitcnt lgkmcnt(0)
	s_nop 1
	v_mov_b32_e32 v168, v251
	v_lshlrev_b64 v[144:145], 11, v[148:149]
	v_lshl_add_u64 v[170:171], s[50:51], 0, v[144:145]
	v_lshl_add_u64 v[170:171], v[170:171], 0, v[192:193]
	v_pk_mul_f32 v[148:149], v[52:53], v[168:169] op_sel_hi:[1,0]
	v_pk_mul_f32 v[144:145], v[48:49], v[168:169] op_sel_hi:[1,0]
	v_min_f32_e32 v194, 0, v148
	v_mul_f32_e64 v148, |v148|, s57
	v_exp_f32_e32 v148, v148
	v_pk_mul_f32 v[150:151], v[54:55], v[168:169] op_sel_hi:[1,0]
	v_pk_mul_f32 v[146:147], v[50:51], v[168:169] op_sel_hi:[1,0]
	v_add_f32_e32 v148, 1.0, v148
	v_log_f32_e32 v148, v148
	s_nop 0
	v_mul_f32_e32 v195, 0x3f317217, v148
	v_fma_f32 v195, v148, s52, -v195
	v_fmac_f32_e32 v195, 0x3377d1cf, v148
	v_fmac_f32_e32 v195, 0x3f317217, v148
	v_mov_b32_e32 v148, v195
	v_sub_f32_e32 v148, v194, v148
	v_min_f32_e32 v194, 0, v144
	v_mul_f32_e64 v144, |v144|, s57
	v_exp_f32_e32 v144, v144
	s_nop 0
	v_add_f32_e32 v144, 1.0, v144
	v_log_f32_e32 v144, v144
	s_nop 0
	v_mul_f32_e32 v195, 0x3f317217, v144
	v_fma_f32 v195, v144, s52, -v195
	v_fmac_f32_e32 v195, 0x3377d1cf, v144
	v_fmac_f32_e32 v195, 0x3f317217, v144
	v_mov_b32_e32 v144, v195
	v_sub_f32_e32 v194, v194, v144
	v_mul_f32_e32 v144, 0x3fb8aa3b, v148
	v_exp_f32_e32 v144, v144
	s_nop 0
	v_fma_f32 v144, v190, v144, v140
	v_cmp_gt_f32_e64 s[40:41], s97, v144
	s_nop 1
	v_cndmask_b32_e64 v195, 0, 32, s[40:41]
	v_ldexp_f32 v144, v144, v195
	v_log_f32_e32 v144, v144
	s_nop 0
	v_mul_f32_e32 v195, 0x3f317217, v144
	v_fma_f32 v195, v144, s52, -v195
	v_fmac_f32_e32 v195, 0x3377d1cf, v144
	v_fmac_f32_e32 v195, 0x3f317217, v144
	v_mov_b32_e32 v144, v195
	v_cndmask_b32_e64 v195, 0, v216, s[40:41]
	v_sub_f32_e32 v144, v144, v195
	v_cndmask_b32_e64 v144, v148, v144, s[38:39]
	v_mul_f32_e32 v148, 0x3fb8aa3b, v194
	v_exp_f32_e32 v148, v148
	s_nop 0
	v_fma_f32 v148, v191, v148, v136
	v_cmp_gt_f32_e64 s[40:41], s97, v148
	s_nop 1
	v_cndmask_b32_e64 v195, 0, 32, s[40:41]
	v_ldexp_f32 v148, v148, v195
	v_log_f32_e32 v148, v148
	s_nop 0
	v_mul_f32_e32 v195, 0x3f317217, v148
	v_fma_f32 v195, v148, s52, -v195
	v_fmac_f32_e32 v195, 0x3377d1cf, v148
	v_fmac_f32_e32 v195, 0x3f317217, v148
	v_mov_b32_e32 v148, v195
	v_cndmask_b32_e64 v195, 0, v216, s[40:41]
	v_sub_f32_e32 v148, v148, v195
	v_cndmask_b32_e64 v148, v194, v148, s[36:37]
	v_min_f32_e32 v194, 0, v149
	v_mul_f32_e64 v149, |v149|, s57
	v_exp_f32_e32 v149, v149
	s_nop 0
	v_add_f32_e32 v149, 1.0, v149
	v_log_f32_e32 v149, v149
	s_nop 0
	v_mul_f32_e32 v195, 0x3f317217, v149
	v_fma_f32 v195, v149, s52, -v195
	v_fmac_f32_e32 v195, 0x3377d1cf, v149
	v_fmac_f32_e32 v195, 0x3f317217, v149
	v_mov_b32_e32 v149, v195
	v_sub_f32_e32 v149, v194, v149
	v_min_f32_e32 v194, 0, v145
	v_mul_f32_e64 v145, |v145|, s57
	v_exp_f32_e32 v145, v145
	s_nop 0
	v_add_f32_e32 v145, 1.0, v145
	v_log_f32_e32 v145, v145
	s_nop 0
	v_mul_f32_e32 v195, 0x3f317217, v145
	v_fma_f32 v195, v145, s52, -v195
	v_fmac_f32_e32 v195, 0x3377d1cf, v145
	v_fmac_f32_e32 v195, 0x3f317217, v145
	v_mov_b32_e32 v145, v195
	v_sub_f32_e32 v194, v194, v145
	v_mul_f32_e32 v145, 0x3fb8aa3b, v149
	v_exp_f32_e32 v145, v145
	s_nop 0
	v_fma_f32 v145, v188, v145, v141
	v_cmp_gt_f32_e64 s[40:41], s97, v145
	s_nop 1
	v_cndmask_b32_e64 v195, 0, 32, s[40:41]
	v_ldexp_f32 v145, v145, v195
	v_log_f32_e32 v145, v145
	s_nop 0
	v_mul_f32_e32 v195, 0x3f317217, v145
	v_fma_f32 v195, v145, s52, -v195
	v_fmac_f32_e32 v195, 0x3377d1cf, v145
	v_fmac_f32_e32 v195, 0x3f317217, v145
	v_mov_b32_e32 v145, v195
	v_cndmask_b32_e64 v195, 0, v216, s[40:41]
; __device__ __forceinline__ float silu_f(float x) { return x * __builtin_amdgcn_rcpf(1.f + __expf(-x)); }
; __device__ __forceinline__ v4u pack8(const f32x4 a, const f32x4 b) { v4u w; w.x = cvt_pk_bf16(a[0], a[1]); w.y = cvt_pk_bf16(a[2], a[3]); w.z = cvt_pk_bf16(b[0], b[1]); w.w = cvt_pk_bf16(b[2], b[3]); return w; }
;     __device__ __forceinline__ void operator()(const f32x4 (&acc)[2][2][4][2], const pg8::Unit& u, int wr, int wc, int fr, int fq) const {
;     ...
;         if (grp == 0) { WIN_LOOP( _Pragma("unroll") for (int i = 0; i < 4; ++i) { a[i] = silu_f(a[i]); b[i] = silu_f(b[i]); } *(v4u*)(QO + (size_t)row * DM + c) = pack8(a, b); ) }
;         else if (grp == 3) { WIN_LOOP( _Pragma("unroll") for (int i = 0; i < 4; ++i) { a[i] = silu_f(a[i]); b[i] = silu_f(b[i]); } *(v4u*)(GH + (size_t)row * 512 + c) = pack8(a, b); ) }
;         else if (grp == 1) {
;             f32x4 l0[2], l1[2];
; #pragma unroll
;             for (int bj = 0; bj < 2; ++bj) { l0[bj] = *(const f32x4*)(lb + cb + bj * 128); l1[bj] = *(const f32x4*)(lb + cb + bj * 128 + 4); }
;             WIN_LOOP( _Pragma("unroll") for (int i = 0; i < 4; ++i) { const float s0 = fminf(a[i], 0.f) - __logf(1.f + __expf(-fabsf(a[i]))), s1 = fminf(b[i], 0.f) - __logf(1.f + __expf(-fabsf(b[i]))); const float la = l0[bj][i], lbv = l1[bj][i];
;                     a[i] = la > 0.f ? __logf(la + (1.f - la) * __expf(s0)) : s0; b[i] = lbv > 0.f ? __logf(lbv + (1.f - lbv) * __expf(s1)) : s1; }
;                 *(f32x4*)(LF + (size_t)row * 512 + c) = a; *(f32x4*)(LF + (size_t)row * 512 + c + 4) = b; __builtin_amdgcn_sched_barrier(0); ) }
	v_sub_f32_e32 v145, v145, v195
	v_cndmask_b32_e64 v145, v149, v145, s[34:35]
	v_mul_f32_e32 v149, 0x3fb8aa3b, v194
	v_exp_f32_e32 v149, v149
	s_nop 0
	v_fma_f32 v149, v189, v149, v137
	v_cmp_gt_f32_e64 s[40:41], s97, v149
	s_nop 1
	v_cndmask_b32_e64 v195, 0, 32, s[40:41]
	v_ldexp_f32 v149, v149, v195
	v_log_f32_e32 v149, v149
	s_nop 0
	v_mul_f32_e32 v195, 0x3f317217, v149
	v_fma_f32 v195, v149, s52, -v195
	v_fmac_f32_e32 v195, 0x3377d1cf, v149
	v_fmac_f32_e32 v195, 0x3f317217, v149
	v_mov_b32_e32 v149, v195
	v_cndmask_b32_e64 v195, 0, v216, s[40:41]
	v_sub_f32_e32 v149, v149, v195
	v_cndmask_b32_e64 v149, v194, v149, s[30:31]
	v_min_f32_e32 v194, 0, v150
	v_mul_f32_e64 v150, |v150|, s57
	v_exp_f32_e32 v150, v150
	s_nop 0
	v_add_f32_e32 v150, 1.0, v150
	v_log_f32_e32 v150, v150
	s_nop 0
	v_mul_f32_e32 v195, 0x3f317217, v150
	v_fma_f32 v195, v150, s52, -v195
	v_fmac_f32_e32 v195, 0x3377d1cf, v150
	v_fmac_f32_e32 v195, 0x3f317217, v150
	v_mov_b32_e32 v150, v195
	v_sub_f32_e32 v150, v194, v150
	v_min_f32_e32 v194, 0, v146
	v_mul_f32_e64 v146, |v146|, s57
	v_exp_f32_e32 v146, v146
	s_nop 0
	v_add_f32_e32 v146, 1.0, v146
	v_log_f32_e32 v146, v146
	s_nop 0
	v_mul_f32_e32 v195, 0x3f317217, v146
	v_fma_f32 v195, v146, s52, -v195
	v_fmac_f32_e32 v195, 0x3377d1cf, v146
	v_fmac_f32_e32 v195, 0x3f317217, v146
	v_mov_b32_e32 v146, v195
	v_sub_f32_e32 v194, v194, v146
	v_mul_f32_e32 v146, 0x3fb8aa3b, v150
	v_exp_f32_e32 v146, v146
	s_nop 0
	v_fma_f32 v146, v187, v146, v142
	v_cmp_gt_f32_e64 s[40:41], s97, v146
	s_nop 1
	v_cndmask_b32_e64 v195, 0, 32, s[40:41]
	v_ldexp_f32 v146, v146, v195
	v_log_f32_e32 v146, v146
	s_nop 0
	v_mul_f32_e32 v195, 0x3f317217, v146
	v_fma_f32 v195, v146, s52, -v195
	v_fmac_f32_e32 v195, 0x3377d1cf, v146
	v_fmac_f32_e32 v195, 0x3f317217, v146
	v_mov_b32_e32 v146, v195
	v_cndmask_b32_e64 v195, 0, v216, s[40:41]
	v_sub_f32_e32 v146, v146, v195
	v_cndmask_b32_e64 v146, v150, v146, s[28:29]
	v_mul_f32_e32 v150, 0x3fb8aa3b, v194
	v_exp_f32_e32 v150, v150
	s_nop 0
	v_fma_f32 v150, v186, v150, v138
	v_cmp_gt_f32_e64 s[40:41], s97, v150
	s_nop 1
	v_cndmask_b32_e64 v195, 0, 32, s[40:41]
	v_ldexp_f32 v150, v150, v195
	v_log_f32_e32 v150, v150
	s_nop 0
	v_mul_f32_e32 v195, 0x3f317217, v150
	v_fma_f32 v195, v150, s52, -v195
	v_fmac_f32_e32 v195, 0x3377d1cf, v150
	v_fmac_f32_e32 v195, 0x3f317217, v150
	v_mov_b32_e32 v150, v195
	v_cndmask_b32_e64 v195, 0, v216, s[40:41]
	v_sub_f32_e32 v150, v150, v195
	v_cndmask_b32_e64 v150, v194, v150, s[26:27]
	v_min_f32_e32 v194, 0, v151
	v_mul_f32_e64 v151, |v151|, s57
	v_exp_f32_e32 v151, v151
	s_nop 0
	v_add_f32_e32 v151, 1.0, v151
	v_log_f32_e32 v151, v151
	s_nop 0
	v_mul_f32_e32 v195, 0x3f317217, v151
	v_fma_f32 v195, v151, s52, -v195
	v_fmac_f32_e32 v195, 0x3377d1cf, v151
	v_fmac_f32_e32 v195, 0x3f317217, v151
	v_mov_b32_e32 v151, v195
	v_sub_f32_e32 v151, v194, v151
	v_min_f32_e32 v194, 0, v147
	v_mul_f32_e64 v147, |v147|, s57
	v_exp_f32_e32 v147, v147
	s_nop 0
	v_add_f32_e32 v147, 1.0, v147
	v_log_f32_e32 v147, v147
	s_nop 0
	v_mul_f32_e32 v195, 0x3f317217, v147
	v_fma_f32 v195, v147, s52, -v195
	v_fmac_f32_e32 v195, 0x3377d1cf, v147
	v_fmac_f32_e32 v195, 0x3f317217, v147
	v_mov_b32_e32 v147, v195
	v_sub_f32_e32 v194, v194, v147
	v_mul_f32_e32 v147, 0x3fb8aa3b, v151
	v_exp_f32_e32 v147, v147
	s_nop 0
	v_fma_f32 v147, v185, v147, v143
	v_cmp_gt_f32_e64 s[40:41], s97, v147
	s_nop 1
	v_cndmask_b32_e64 v195, 0, 32, s[40:41]
	v_ldexp_f32 v147, v147, v195
	v_log_f32_e32 v147, v147
	s_nop 0
	v_mul_f32_e32 v195, 0x3f317217, v147
	v_fma_f32 v195, v147, s52, -v195
	v_fmac_f32_e32 v195, 0x3377d1cf, v147
	v_fmac_f32_e32 v195, 0x3f317217, v147
	v_mov_b32_e32 v147, v195
	v_cndmask_b32_e64 v195, 0, v216, s[40:41]
	v_sub_f32_e32 v147, v147, v195
	v_cndmask_b32_e64 v147, v151, v147, s[24:25]
	v_mul_f32_e32 v151, 0x3fb8aa3b, v194
	v_exp_f32_e32 v151, v151
	s_nop 0
	v_fma_f32 v151, v184, v151, v139
	v_cmp_gt_f32_e64 s[40:41], s97, v151
	s_nop 1
	v_cndmask_b32_e64 v195, 0, 32, s[40:41]
	v_ldexp_f32 v151, v151, v195
	v_log_f32_e32 v151, v151
	s_nop 0
	v_mul_f32_e32 v195, 0x3f317217, v151
	v_fma_f32 v195, v151, s52, -v195
	v_fmac_f32_e32 v195, 0x3377d1cf, v151
	v_fmac_f32_e32 v195, 0x3f317217, v151
	v_mov_b32_e32 v151, v195
	v_cndmask_b32_e64 v195, 0, v216, s[40:41]
	v_sub_f32_e32 v151, v151, v195
	v_cndmask_b32_e64 v151, v194, v151, s[22:23]
	global_store_dwordx4 v[170:171], v[144:147], off
	global_store_dwordx4 v[170:171], v[148:151], off offset:16
	s_nop 1
	v_pk_mul_f32 v[148:149], v[116:117], v[168:169] op_sel_hi:[1,0]
	v_pk_mul_f32 v[150:151], v[118:119], v[168:169] op_sel_hi:[1,0]
	v_pk_mul_f32 v[146:147], v[114:115], v[168:169] op_sel_hi:[1,0]
	v_pk_mul_f32 v[144:145], v[112:113], v[168:169] op_sel_hi:[1,0]
	v_min_f32_e32 v168, 0, v148
	v_mul_f32_e64 v148, |v148|, s57
	v_exp_f32_e32 v148, v148
	s_nop 0
	v_add_f32_e32 v148, 1.0, v148
	v_log_f32_e32 v148, v148
	s_nop 0
	v_mul_f32_e32 v194, 0x3f317217, v148
	v_fma_f32 v194, v148, s52, -v194
	v_fmac_f32_e32 v194, 0x3377d1cf, v148
	v_fmac_f32_e32 v194, 0x3f317217, v148
	v_mov_b32_e32 v148, v194
	v_sub_f32_e32 v148, v168, v148
	v_min_f32_e32 v168, 0, v144
	v_mul_f32_e64 v144, |v144|, s57
	v_exp_f32_e32 v144, v144
	s_nop 0
	v_add_f32_e32 v144, 1.0, v144
	v_log_f32_e32 v144, v144
	s_nop 0
	v_mul_f32_e32 v194, 0x3f317217, v144
	v_fma_f32 v194, v144, s52, -v194
	v_fmac_f32_e32 v194, 0x3377d1cf, v144
	v_fmac_f32_e32 v194, 0x3f317217, v144
	v_mov_b32_e32 v144, v194
	v_sub_f32_e32 v168, v168, v144
	v_mul_f32_e32 v144, 0x3fb8aa3b, v148
	v_exp_f32_e32 v144, v144
	s_nop 0
	v_fma_f32 v144, v183, v144, v132
	v_cmp_gt_f32_e64 s[40:41], s97, v144
	s_nop 1
; __device__ __forceinline__ float silu_f(float x) { return x * __builtin_amdgcn_rcpf(1.f + __expf(-x)); }
; __device__ __forceinline__ v4u pack8(const f32x4 a, const f32x4 b) { v4u w; w.x = cvt_pk_bf16(a[0], a[1]); w.y = cvt_pk_bf16(a[2], a[3]); w.z = cvt_pk_bf16(b[0], b[1]); w.w = cvt_pk_bf16(b[2], b[3]); return w; }
;     __device__ __forceinline__ void operator()(const f32x4 (&acc)[2][2][4][2], const pg8::Unit& u, int wr, int wc, int fr, int fq) const {
;     ...
;         if (grp == 0) { WIN_LOOP( _Pragma("unroll") for (int i = 0; i < 4; ++i) { a[i] = silu_f(a[i]); b[i] = silu_f(b[i]); } *(v4u*)(QO + (size_t)row * DM + c) = pack8(a, b); ) }
;         else if (grp == 3) { WIN_LOOP( _Pragma("unroll") for (int i = 0; i < 4; ++i) { a[i] = silu_f(a[i]); b[i] = silu_f(b[i]); } *(v4u*)(GH + (size_t)row * 512 + c) = pack8(a, b); ) }
;         else if (grp == 1) {
;             f32x4 l0[2], l1[2];
; #pragma unroll
;             for (int bj = 0; bj < 2; ++bj) { l0[bj] = *(const f32x4*)(lb + cb + bj * 128); l1[bj] = *(const f32x4*)(lb + cb + bj * 128 + 4); }
;             WIN_LOOP( _Pragma("unroll") for (int i = 0; i < 4; ++i) { const float s0 = fminf(a[i], 0.f) - __logf(1.f + __expf(-fabsf(a[i]))), s1 = fminf(b[i], 0.f) - __logf(1.f + __expf(-fabsf(b[i]))); const float la = l0[bj][i], lbv = l1[bj][i];
;                     a[i] = la > 0.f ? __logf(la + (1.f - la) * __expf(s0)) : s0; b[i] = lbv > 0.f ? __logf(lbv + (1.f - lbv) * __expf(s1)) : s1; }
;                 *(f32x4*)(LF + (size_t)row * 512 + c) = a; *(f32x4*)(LF + (size_t)row * 512 + c + 4) = b; __builtin_amdgcn_sched_barrier(0); ) }
	v_cndmask_b32_e64 v194, 0, 32, s[40:41]
	v_ldexp_f32 v144, v144, v194
	v_log_f32_e32 v144, v144
	s_nop 0
	v_mul_f32_e32 v194, 0x3f317217, v144
	v_fma_f32 v194, v144, s52, -v194
	v_fmac_f32_e32 v194, 0x3377d1cf, v144
	v_fmac_f32_e32 v194, 0x3f317217, v144
	v_mov_b32_e32 v144, v194
	v_cndmask_b32_e64 v194, 0, v216, s[40:41]
	v_sub_f32_e32 v144, v144, v194
	v_cndmask_b32_e64 v144, v148, v144, s[20:21]
	v_mul_f32_e32 v148, 0x3fb8aa3b, v168
	v_exp_f32_e32 v148, v148
	s_nop 0
	v_fma_f32 v148, v182, v148, v128
	v_cmp_gt_f32_e64 s[40:41], s97, v148
	s_nop 1
	v_cndmask_b32_e64 v194, 0, 32, s[40:41]
	v_ldexp_f32 v148, v148, v194
	v_log_f32_e32 v148, v148
	s_nop 0
	v_mul_f32_e32 v194, 0x3f317217, v148
	v_fma_f32 v194, v148, s52, -v194
	v_fmac_f32_e32 v194, 0x3377d1cf, v148
	v_fmac_f32_e32 v194, 0x3f317217, v148
	v_mov_b32_e32 v148, v194
	v_cndmask_b32_e64 v194, 0, v216, s[40:41]
	v_sub_f32_e32 v148, v148, v194
	v_cndmask_b32_e64 v148, v168, v148, s[18:19]
	v_min_f32_e32 v168, 0, v149
	v_mul_f32_e64 v149, |v149|, s57
	v_exp_f32_e32 v149, v149
	s_nop 0
	v_add_f32_e32 v149, 1.0, v149
	v_log_f32_e32 v149, v149
	s_nop 0
	v_mul_f32_e32 v194, 0x3f317217, v149
	v_fma_f32 v194, v149, s52, -v194
	v_fmac_f32_e32 v194, 0x3377d1cf, v149
	v_fmac_f32_e32 v194, 0x3f317217, v149
	v_mov_b32_e32 v149, v194
	v_sub_f32_e32 v149, v168, v149
	v_min_f32_e32 v168, 0, v145
	v_mul_f32_e64 v145, |v145|, s57
	v_exp_f32_e32 v145, v145
	s_nop 0
	v_add_f32_e32 v145, 1.0, v145
	v_log_f32_e32 v145, v145
	s_nop 0
	v_mul_f32_e32 v194, 0x3f317217, v145
	v_fma_f32 v194, v145, s52, -v194
	v_fmac_f32_e32 v194, 0x3377d1cf, v145
	v_fmac_f32_e32 v194, 0x3f317217, v145
	v_mov_b32_e32 v145, v194
	v_sub_f32_e32 v168, v168, v145
	v_mul_f32_e32 v145, 0x3fb8aa3b, v149
	v_exp_f32_e32 v145, v145
	s_nop 0
	v_fma_f32 v145, v181, v145, v133
	v_cmp_gt_f32_e64 s[40:41], s97, v145
	s_nop 1
	v_cndmask_b32_e64 v194, 0, 32, s[40:41]
	v_ldexp_f32 v145, v145, v194
	v_log_f32_e32 v145, v145
	s_nop 0
	v_mul_f32_e32 v194, 0x3f317217, v145
	v_fma_f32 v194, v145, s52, -v194
	v_fmac_f32_e32 v194, 0x3377d1cf, v145
	v_fmac_f32_e32 v194, 0x3f317217, v145
	v_mov_b32_e32 v145, v194
	v_cndmask_b32_e64 v194, 0, v216, s[40:41]
	v_sub_f32_e32 v145, v145, v194
	v_cndmask_b32_e64 v145, v149, v145, s[16:17]
	v_mul_f32_e32 v149, 0x3fb8aa3b, v168
	v_exp_f32_e32 v149, v149
	s_nop 0
	v_fma_f32 v149, v180, v149, v129
	v_cmp_gt_f32_e64 s[40:41], s97, v149
	s_nop 1
	v_cndmask_b32_e64 v194, 0, 32, s[40:41]
	v_ldexp_f32 v149, v149, v194
	v_log_f32_e32 v149, v149
	s_nop 0
	v_mul_f32_e32 v194, 0x3f317217, v149
	v_fma_f32 v194, v149, s52, -v194
	v_fmac_f32_e32 v194, 0x3377d1cf, v149
	v_fmac_f32_e32 v194, 0x3f317217, v149
	v_mov_b32_e32 v149, v194
	v_cndmask_b32_e64 v194, 0, v216, s[40:41]
	v_sub_f32_e32 v149, v149, v194
	v_cndmask_b32_e64 v149, v168, v149, s[14:15]
	v_min_f32_e32 v168, 0, v150
	v_mul_f32_e64 v150, |v150|, s57
	v_exp_f32_e32 v150, v150
	s_nop 0
	v_add_f32_e32 v150, 1.0, v150
	v_log_f32_e32 v150, v150
	s_nop 0
	v_mul_f32_e32 v194, 0x3f317217, v150
	v_fma_f32 v194, v150, s52, -v194
	v_fmac_f32_e32 v194, 0x3377d1cf, v150
	v_fmac_f32_e32 v194, 0x3f317217, v150
	v_mov_b32_e32 v150, v194
	v_sub_f32_e32 v150, v168, v150
	v_min_f32_e32 v168, 0, v146
	v_mul_f32_e64 v146, |v146|, s57
	v_exp_f32_e32 v146, v146
	s_nop 0
	v_add_f32_e32 v146, 1.0, v146
	v_log_f32_e32 v146, v146
	s_nop 0
	v_mul_f32_e32 v194, 0x3f317217, v146
	v_fma_f32 v194, v146, s52, -v194
	v_fmac_f32_e32 v194, 0x3377d1cf, v146
	v_fmac_f32_e32 v194, 0x3f317217, v146
	v_mov_b32_e32 v146, v194
	v_sub_f32_e32 v168, v168, v146
	v_mul_f32_e32 v146, 0x3fb8aa3b, v150
	v_exp_f32_e32 v146, v146
	s_nop 0
	v_fma_f32 v146, v179, v146, v134
	v_cmp_gt_f32_e64 s[40:41], s97, v146
	s_nop 1
	v_cndmask_b32_e64 v194, 0, 32, s[40:41]
	v_ldexp_f32 v146, v146, v194
	v_log_f32_e32 v146, v146
	s_nop 0
	v_mul_f32_e32 v194, 0x3f317217, v146
	v_fma_f32 v194, v146, s52, -v194
	v_fmac_f32_e32 v194, 0x3377d1cf, v146
	v_fmac_f32_e32 v194, 0x3f317217, v146
	v_mov_b32_e32 v146, v194
	v_cndmask_b32_e64 v194, 0, v216, s[40:41]
	v_sub_f32_e32 v146, v146, v194
	v_cndmask_b32_e64 v146, v150, v146, s[12:13]
	v_mul_f32_e32 v150, 0x3fb8aa3b, v168
	v_exp_f32_e32 v150, v150
	s_nop 0
	v_fma_f32 v150, v178, v150, v130
	v_cmp_gt_f32_e64 s[40:41], s97, v150
	s_nop 1
	v_cndmask_b32_e64 v194, 0, 32, s[40:41]
	v_ldexp_f32 v150, v150, v194
	v_log_f32_e32 v150, v150
	s_nop 0
	v_mul_f32_e32 v194, 0x3f317217, v150
	v_fma_f32 v194, v150, s52, -v194
	v_fmac_f32_e32 v194, 0x3377d1cf, v150
	v_fmac_f32_e32 v194, 0x3f317217, v150
	v_mov_b32_e32 v150, v194
	v_cndmask_b32_e64 v194, 0, v216, s[40:41]
	v_sub_f32_e32 v150, v150, v194
	v_cndmask_b32_e64 v150, v168, v150, s[10:11]
	v_min_f32_e32 v168, 0, v151
	v_mul_f32_e64 v151, |v151|, s57
	v_exp_f32_e32 v151, v151
	s_nop 0
	v_add_f32_e32 v151, 1.0, v151
	v_log_f32_e32 v151, v151
	s_nop 0
	v_mul_f32_e32 v194, 0x3f317217, v151
	v_fma_f32 v194, v151, s52, -v194
	v_fmac_f32_e32 v194, 0x3377d1cf, v151
	v_fmac_f32_e32 v194, 0x3f317217, v151
	v_mov_b32_e32 v151, v194
	v_sub_f32_e32 v151, v168, v151
	v_min_f32_e32 v168, 0, v147
	v_mul_f32_e64 v147, |v147|, s57
	v_exp_f32_e32 v147, v147
	s_nop 0
	v_add_f32_e32 v147, 1.0, v147
	v_log_f32_e32 v147, v147
	s_nop 0
	v_mul_f32_e32 v194, 0x3f317217, v147
	v_fma_f32 v194, v147, s52, -v194
	v_fmac_f32_e32 v194, 0x3377d1cf, v147
	v_fmac_f32_e32 v194, 0x3f317217, v147
	v_mov_b32_e32 v147, v194
	v_sub_f32_e32 v168, v168, v147
	v_mul_f32_e32 v147, 0x3fb8aa3b, v151
	v_exp_f32_e32 v147, v147
	s_nop 0
	v_fma_f32 v147, v177, v147, v135
	v_cmp_gt_f32_e64 s[40:41], s97, v147
	s_nop 1
	v_cndmask_b32_e64 v194, 0, 32, s[40:41]
	v_ldexp_f32 v147, v147, v194
	v_log_f32_e32 v147, v147
	s_nop 0
	v_mul_f32_e32 v194, 0x3f317217, v147
	v_fma_f32 v194, v147, s52, -v194
	v_fmac_f32_e32 v194, 0x3377d1cf, v147
	v_fmac_f32_e32 v194, 0x3f317217, v147
	v_mov_b32_e32 v147, v194
	v_cndmask_b32_e64 v194, 0, v216, s[40:41]
	v_sub_f32_e32 v147, v147, v194
	v_cndmask_b32_e64 v147, v151, v147, s[8:9]
	v_mul_f32_e32 v151, 0x3fb8aa3b, v168
	v_exp_f32_e32 v151, v151
	s_nop 0
	v_fma_f32 v151, v167, v151, v131
	v_cmp_gt_f32_e64 s[40:41], s97, v151
	s_nop 1
	v_cndmask_b32_e64 v194, 0, 32, s[40:41]
	v_ldexp_f32 v151, v151, v194
	v_log_f32_e32 v151, v151
	s_nop 0
	v_mul_f32_e32 v194, 0x3f317217, v151
	v_fma_f32 v194, v151, s52, -v194
	v_fmac_f32_e32 v194, 0x3377d1cf, v151
	v_fmac_f32_e32 v194, 0x3f317217, v151
	v_mov_b32_e32 v151, v194
	v_cndmask_b32_e64 v194, 0, v216, s[40:41]
	v_sub_f32_e32 v151, v151, v194
	v_cndmask_b32_e32 v151, v168, v151, vcc
	global_store_dwordx4 v[170:171], v[144:147], off offset:512
	global_store_dwordx4 v[170:171], v[148:151], off offset:528
	s_nop 1
	v_or_b32_e32 v148, 32, v166
	v_ashrrev_i32_e32 v149, 31, v148
	v_lshlrev_b64 v[144:145], 6, v[148:149]
	v_lshl_add_u64 v[144:145], v[160:161], 0, v[144:145]
	s_nop 0
	s_waitcnt lgkmcnt(0)
; __device__ __forceinline__ float silu_f(float x) { return x * __builtin_amdgcn_rcpf(1.f + __expf(-x)); }
; __device__ __forceinline__ v4u pack8(const f32x4 a, const f32x4 b) { v4u w; w.x = cvt_pk_bf16(a[0], a[1]); w.y = cvt_pk_bf16(a[2], a[3]); w.z = cvt_pk_bf16(b[0], b[1]); w.w = cvt_pk_bf16(b[2], b[3]); return w; }
;     __device__ __forceinline__ void operator()(const f32x4 (&acc)[2][2][4][2], const pg8::Unit& u, int wr, int wc, int fr, int fq) const {
;     ...
;         if (grp == 0) { WIN_LOOP( _Pragma("unroll") for (int i = 0; i < 4; ++i) { a[i] = silu_f(a[i]); b[i] = silu_f(b[i]); } *(v4u*)(QO + (size_t)row * DM + c) = pack8(a, b); ) }
;         else if (grp == 3) { WIN_LOOP( _Pragma("unroll") for (int i = 0; i < 4; ++i) { a[i] = silu_f(a[i]); b[i] = silu_f(b[i]); } *(v4u*)(GH + (size_t)row * 512 + c) = pack8(a, b); ) }
;         else if (grp == 1) {
;             f32x4 l0[2], l1[2];
; #pragma unroll
;             for (int bj = 0; bj < 2; ++bj) { l0[bj] = *(const f32x4*)(lb + cb + bj * 128); l1[bj] = *(const f32x4*)(lb + cb + bj * 128 + 4); }
;             WIN_LOOP( _Pragma("unroll") for (int i = 0; i < 4; ++i) { const float s0 = fminf(a[i], 0.f) - __logf(1.f + __expf(-fabsf(a[i]))), s1 = fminf(b[i], 0.f) - __logf(1.f + __expf(-fabsf(b[i]))); const float la = l0[bj][i], lbv = l1[bj][i];
;                     a[i] = la > 0.f ? __logf(la + (1.f - la) * __expf(s0)) : s0; b[i] = lbv > 0.f ? __logf(lbv + (1.f - lbv) * __expf(s1)) : s1; }
;                 *(f32x4*)(LF + (size_t)row * 512 + c) = a; *(f32x4*)(LF + (size_t)row * 512 + c + 4) = b; __builtin_amdgcn_sched_barrier(0); ) }
	s_nop 3
	s_nop 0
	s_nop 1
	s_waitcnt lgkmcnt(0)
	s_nop 1
	s_waitcnt lgkmcnt(0)
	s_nop 1
	v_mov_b32_e32 v168, v252
	v_lshlrev_b64 v[144:145], 11, v[148:149]
	v_lshl_add_u64 v[170:171], s[50:51], 0, v[144:145]
	v_lshl_add_u64 v[170:171], v[170:171], 0, v[192:193]
	v_pk_mul_f32 v[148:149], v[44:45], v[168:169] op_sel_hi:[1,0]
	v_pk_mul_f32 v[144:145], v[40:41], v[168:169] op_sel_hi:[1,0]
	v_min_f32_e32 v194, 0, v148
	v_mul_f32_e64 v148, |v148|, s57
	v_exp_f32_e32 v148, v148
	v_pk_mul_f32 v[150:151], v[46:47], v[168:169] op_sel_hi:[1,0]
	v_pk_mul_f32 v[146:147], v[42:43], v[168:169] op_sel_hi:[1,0]
	v_add_f32_e32 v148, 1.0, v148
	v_log_f32_e32 v148, v148
	s_nop 0
	v_mul_f32_e32 v195, 0x3f317217, v148
	v_fma_f32 v195, v148, s52, -v195
	v_fmac_f32_e32 v195, 0x3377d1cf, v148
	v_fmac_f32_e32 v195, 0x3f317217, v148
	v_mov_b32_e32 v148, v195
	v_sub_f32_e32 v148, v194, v148
	v_min_f32_e32 v194, 0, v144
	v_mul_f32_e64 v144, |v144|, s57
	v_exp_f32_e32 v144, v144
	s_nop 0
	v_add_f32_e32 v144, 1.0, v144
	v_log_f32_e32 v144, v144
	s_nop 0
	v_mul_f32_e32 v195, 0x3f317217, v144
	v_fma_f32 v195, v144, s52, -v195
	v_fmac_f32_e32 v195, 0x3377d1cf, v144
	v_fmac_f32_e32 v195, 0x3f317217, v144
	v_mov_b32_e32 v144, v195
	v_sub_f32_e32 v194, v194, v144
	v_mul_f32_e32 v144, 0x3fb8aa3b, v148
	v_exp_f32_e32 v144, v144
	s_nop 0
	v_fma_f32 v144, v190, v144, v140
	v_cmp_gt_f32_e64 s[40:41], s97, v144
	s_nop 1
	v_cndmask_b32_e64 v195, 0, 32, s[40:41]
	v_ldexp_f32 v144, v144, v195
	v_log_f32_e32 v144, v144
	s_nop 0
	v_mul_f32_e32 v195, 0x3f317217, v144
	v_fma_f32 v195, v144, s52, -v195
	v_fmac_f32_e32 v195, 0x3377d1cf, v144
	v_fmac_f32_e32 v195, 0x3f317217, v144
	v_mov_b32_e32 v144, v195
	v_cndmask_b32_e64 v195, 0, v216, s[40:41]
	v_sub_f32_e32 v144, v144, v195
	v_cndmask_b32_e64 v144, v148, v144, s[38:39]
	v_mul_f32_e32 v148, 0x3fb8aa3b, v194
	v_exp_f32_e32 v148, v148
	s_nop 0
	v_fma_f32 v148, v191, v148, v136
	v_cmp_gt_f32_e64 s[40:41], s97, v148
	s_nop 1
	v_cndmask_b32_e64 v195, 0, 32, s[40:41]
	v_ldexp_f32 v148, v148, v195
	v_log_f32_e32 v148, v148
	s_nop 0
	v_mul_f32_e32 v195, 0x3f317217, v148
	v_fma_f32 v195, v148, s52, -v195
	v_fmac_f32_e32 v195, 0x3377d1cf, v148
	v_fmac_f32_e32 v195, 0x3f317217, v148
	v_mov_b32_e32 v148, v195
	v_cndmask_b32_e64 v195, 0, v216, s[40:41]
	v_sub_f32_e32 v148, v148, v195
	v_cndmask_b32_e64 v148, v194, v148, s[36:37]
	v_min_f32_e32 v194, 0, v149
	v_mul_f32_e64 v149, |v149|, s57
	v_exp_f32_e32 v149, v149
	s_nop 0
	v_add_f32_e32 v149, 1.0, v149
	v_log_f32_e32 v149, v149
	s_nop 0
	v_mul_f32_e32 v195, 0x3f317217, v149
	v_fma_f32 v195, v149, s52, -v195
	v_fmac_f32_e32 v195, 0x3377d1cf, v149
	v_fmac_f32_e32 v195, 0x3f317217, v149
	v_mov_b32_e32 v149, v195
	v_sub_f32_e32 v149, v194, v149
	v_min_f32_e32 v194, 0, v145
	v_mul_f32_e64 v145, |v145|, s57
	v_exp_f32_e32 v145, v145
	s_nop 0
	v_add_f32_e32 v145, 1.0, v145
	v_log_f32_e32 v145, v145
	s_nop 0
	v_mul_f32_e32 v195, 0x3f317217, v145
	v_fma_f32 v195, v145, s52, -v195
	v_fmac_f32_e32 v195, 0x3377d1cf, v145
	v_fmac_f32_e32 v195, 0x3f317217, v145
	v_mov_b32_e32 v145, v195
	v_sub_f32_e32 v194, v194, v145
	v_mul_f32_e32 v145, 0x3fb8aa3b, v149
	v_exp_f32_e32 v145, v145
	s_nop 0
	v_fma_f32 v145, v188, v145, v141
	v_cmp_gt_f32_e64 s[40:41], s97, v145
	s_nop 1
	v_cndmask_b32_e64 v195, 0, 32, s[40:41]
	v_ldexp_f32 v145, v145, v195
	v_log_f32_e32 v145, v145
	s_nop 0
	v_mul_f32_e32 v195, 0x3f317217, v145
	v_fma_f32 v195, v145, s52, -v195
	v_fmac_f32_e32 v195, 0x3377d1cf, v145
	v_fmac_f32_e32 v195, 0x3f317217, v145
	v_mov_b32_e32 v145, v195
	v_cndmask_b32_e64 v195, 0, v216, s[40:41]
	v_sub_f32_e32 v145, v145, v195
	v_cndmask_b32_e64 v145, v149, v145, s[34:35]
	v_mul_f32_e32 v149, 0x3fb8aa3b, v194
	v_exp_f32_e32 v149, v149
	s_nop 0
	v_fma_f32 v149, v189, v149, v137
	v_cmp_gt_f32_e64 s[40:41], s97, v149
	s_nop 1
	v_cndmask_b32_e64 v195, 0, 32, s[40:41]
	v_ldexp_f32 v149, v149, v195
	v_log_f32_e32 v149, v149
	s_nop 0
	v_mul_f32_e32 v195, 0x3f317217, v149
	v_fma_f32 v195, v149, s52, -v195
	v_fmac_f32_e32 v195, 0x3377d1cf, v149
	v_fmac_f32_e32 v195, 0x3f317217, v149
	v_mov_b32_e32 v149, v195
	v_cndmask_b32_e64 v195, 0, v216, s[40:41]
	v_sub_f32_e32 v149, v149, v195
	v_cndmask_b32_e64 v149, v194, v149, s[30:31]
	v_min_f32_e32 v194, 0, v150
	v_mul_f32_e64 v150, |v150|, s57
	v_exp_f32_e32 v150, v150
	s_nop 0
	v_add_f32_e32 v150, 1.0, v150
	v_log_f32_e32 v150, v150
	s_nop 0
	v_mul_f32_e32 v195, 0x3f317217, v150
	v_fma_f32 v195, v150, s52, -v195
	v_fmac_f32_e32 v195, 0x3377d1cf, v150
	v_fmac_f32_e32 v195, 0x3f317217, v150
	v_mov_b32_e32 v150, v195
	v_sub_f32_e32 v150, v194, v150
	v_min_f32_e32 v194, 0, v146
	v_mul_f32_e64 v146, |v146|, s57
	v_exp_f32_e32 v146, v146
	s_nop 0
	v_add_f32_e32 v146, 1.0, v146
	v_log_f32_e32 v146, v146
	s_nop 0
	v_mul_f32_e32 v195, 0x3f317217, v146
	v_fma_f32 v195, v146, s52, -v195
	v_fmac_f32_e32 v195, 0x3377d1cf, v146
	v_fmac_f32_e32 v195, 0x3f317217, v146
	v_mov_b32_e32 v146, v195
	v_sub_f32_e32 v194, v194, v146
	v_mul_f32_e32 v146, 0x3fb8aa3b, v150
	v_exp_f32_e32 v146, v146
	s_nop 0
	v_fma_f32 v146, v187, v146, v142
	v_cmp_gt_f32_e64 s[40:41], s97, v146
	s_nop 1
	v_cndmask_b32_e64 v195, 0, 32, s[40:41]
	v_ldexp_f32 v146, v146, v195
	v_log_f32_e32 v146, v146
	s_nop 0
	v_mul_f32_e32 v195, 0x3f317217, v146
	v_fma_f32 v195, v146, s52, -v195
	v_fmac_f32_e32 v195, 0x3377d1cf, v146
	v_fmac_f32_e32 v195, 0x3f317217, v146
	v_mov_b32_e32 v146, v195
	v_cndmask_b32_e64 v195, 0, v216, s[40:41]
	v_sub_f32_e32 v146, v146, v195
	v_cndmask_b32_e64 v146, v150, v146, s[28:29]
	v_mul_f32_e32 v150, 0x3fb8aa3b, v194
	v_exp_f32_e32 v150, v150
	s_nop 0
	v_fma_f32 v150, v186, v150, v138
; __device__ __forceinline__ float silu_f(float x) { return x * __builtin_amdgcn_rcpf(1.f + __expf(-x)); }
; __device__ __forceinline__ v4u pack8(const f32x4 a, const f32x4 b) { v4u w; w.x = cvt_pk_bf16(a[0], a[1]); w.y = cvt_pk_bf16(a[2], a[3]); w.z = cvt_pk_bf16(b[0], b[1]); w.w = cvt_pk_bf16(b[2], b[3]); return w; }
;     __device__ __forceinline__ void operator()(const f32x4 (&acc)[2][2][4][2], const pg8::Unit& u, int wr, int wc, int fr, int fq) const {
;     ...
;         if (grp == 0) { WIN_LOOP( _Pragma("unroll") for (int i = 0; i < 4; ++i) { a[i] = silu_f(a[i]); b[i] = silu_f(b[i]); } *(v4u*)(QO + (size_t)row * DM + c) = pack8(a, b); ) }
;         else if (grp == 3) { WIN_LOOP( _Pragma("unroll") for (int i = 0; i < 4; ++i) { a[i] = silu_f(a[i]); b[i] = silu_f(b[i]); } *(v4u*)(GH + (size_t)row * 512 + c) = pack8(a, b); ) }
;         else if (grp == 1) {
;             f32x4 l0[2], l1[2];
; #pragma unroll
;             for (int bj = 0; bj < 2; ++bj) { l0[bj] = *(const f32x4*)(lb + cb + bj * 128); l1[bj] = *(const f32x4*)(lb + cb + bj * 128 + 4); }
;             WIN_LOOP( _Pragma("unroll") for (int i = 0; i < 4; ++i) { const float s0 = fminf(a[i], 0.f) - __logf(1.f + __expf(-fabsf(a[i]))), s1 = fminf(b[i], 0.f) - __logf(1.f + __expf(-fabsf(b[i]))); const float la = l0[bj][i], lbv = l1[bj][i];
;                     a[i] = la > 0.f ? __logf(la + (1.f - la) * __expf(s0)) : s0; b[i] = lbv > 0.f ? __logf(lbv + (1.f - lbv) * __expf(s1)) : s1; }
;                 *(f32x4*)(LF + (size_t)row * 512 + c) = a; *(f32x4*)(LF + (size_t)row * 512 + c + 4) = b; __builtin_amdgcn_sched_barrier(0); ) }
	v_cmp_gt_f32_e64 s[40:41], s97, v150
	s_nop 1
	v_cndmask_b32_e64 v195, 0, 32, s[40:41]
	v_ldexp_f32 v150, v150, v195
	v_log_f32_e32 v150, v150
	s_nop 0
	v_mul_f32_e32 v195, 0x3f317217, v150
	v_fma_f32 v195, v150, s52, -v195
	v_fmac_f32_e32 v195, 0x3377d1cf, v150
	v_fmac_f32_e32 v195, 0x3f317217, v150
	v_mov_b32_e32 v150, v195
	v_cndmask_b32_e64 v195, 0, v216, s[40:41]
	v_sub_f32_e32 v150, v150, v195
	v_cndmask_b32_e64 v150, v194, v150, s[26:27]
	v_min_f32_e32 v194, 0, v151
	v_mul_f32_e64 v151, |v151|, s57
	v_exp_f32_e32 v151, v151
	s_nop 0
	v_add_f32_e32 v151, 1.0, v151
	v_log_f32_e32 v151, v151
	s_nop 0
	v_mul_f32_e32 v195, 0x3f317217, v151
	v_fma_f32 v195, v151, s52, -v195
	v_fmac_f32_e32 v195, 0x3377d1cf, v151
	v_fmac_f32_e32 v195, 0x3f317217, v151
	v_mov_b32_e32 v151, v195
	v_sub_f32_e32 v151, v194, v151
	v_min_f32_e32 v194, 0, v147
	v_mul_f32_e64 v147, |v147|, s57
	v_exp_f32_e32 v147, v147
	s_nop 0
	v_add_f32_e32 v147, 1.0, v147
	v_log_f32_e32 v147, v147
	s_nop 0
	v_mul_f32_e32 v195, 0x3f317217, v147
	v_fma_f32 v195, v147, s52, -v195
	v_fmac_f32_e32 v195, 0x3377d1cf, v147
	v_fmac_f32_e32 v195, 0x3f317217, v147
	v_mov_b32_e32 v147, v195
	v_sub_f32_e32 v194, v194, v147
	v_mul_f32_e32 v147, 0x3fb8aa3b, v151
	v_exp_f32_e32 v147, v147
	s_nop 0
	v_fma_f32 v147, v185, v147, v143
	v_cmp_gt_f32_e64 s[40:41], s97, v147
	s_nop 1
	v_cndmask_b32_e64 v195, 0, 32, s[40:41]
	v_ldexp_f32 v147, v147, v195
	v_log_f32_e32 v147, v147
	s_nop 0
	v_mul_f32_e32 v195, 0x3f317217, v147
	v_fma_f32 v195, v147, s52, -v195
	v_fmac_f32_e32 v195, 0x3377d1cf, v147
	v_fmac_f32_e32 v195, 0x3f317217, v147
	v_mov_b32_e32 v147, v195
	v_cndmask_b32_e64 v195, 0, v216, s[40:41]
	v_sub_f32_e32 v147, v147, v195
	v_cndmask_b32_e64 v147, v151, v147, s[24:25]
	v_mul_f32_e32 v151, 0x3fb8aa3b, v194
	v_exp_f32_e32 v151, v151
	s_nop 0
	v_fma_f32 v151, v184, v151, v139
	v_cmp_gt_f32_e64 s[40:41], s97, v151
	s_nop 1
	v_cndmask_b32_e64 v195, 0, 32, s[40:41]
	v_ldexp_f32 v151, v151, v195
	v_log_f32_e32 v151, v151
	s_nop 0
	v_mul_f32_e32 v195, 0x3f317217, v151
	v_fma_f32 v195, v151, s52, -v195
	v_fmac_f32_e32 v195, 0x3377d1cf, v151
	v_fmac_f32_e32 v195, 0x3f317217, v151
	v_mov_b32_e32 v151, v195
	v_cndmask_b32_e64 v195, 0, v216, s[40:41]
	v_sub_f32_e32 v151, v151, v195
	v_cndmask_b32_e64 v151, v194, v151, s[22:23]
	global_store_dwordx4 v[170:171], v[144:147], off
	global_store_dwordx4 v[170:171], v[148:151], off offset:16
	s_nop 1
	v_pk_mul_f32 v[148:149], v[108:109], v[168:169] op_sel_hi:[1,0]
	v_pk_mul_f32 v[150:151], v[110:111], v[168:169] op_sel_hi:[1,0]
	v_pk_mul_f32 v[146:147], v[106:107], v[168:169] op_sel_hi:[1,0]
	v_pk_mul_f32 v[144:145], v[104:105], v[168:169] op_sel_hi:[1,0]
	v_min_f32_e32 v168, 0, v148
	v_mul_f32_e64 v148, |v148|, s57
	v_exp_f32_e32 v148, v148
	s_nop 0
	v_add_f32_e32 v148, 1.0, v148
	v_log_f32_e32 v148, v148
	s_nop 0
	v_mul_f32_e32 v194, 0x3f317217, v148
	v_fma_f32 v194, v148, s52, -v194
	v_fmac_f32_e32 v194, 0x3377d1cf, v148
	v_fmac_f32_e32 v194, 0x3f317217, v148
	v_mov_b32_e32 v148, v194
	v_sub_f32_e32 v148, v168, v148
	v_min_f32_e32 v168, 0, v144
	v_mul_f32_e64 v144, |v144|, s57
	v_exp_f32_e32 v144, v144
	s_nop 0
	v_add_f32_e32 v144, 1.0, v144
	v_log_f32_e32 v144, v144
	s_nop 0
	v_mul_f32_e32 v194, 0x3f317217, v144
	v_fma_f32 v194, v144, s52, -v194
	v_fmac_f32_e32 v194, 0x3377d1cf, v144
	v_fmac_f32_e32 v194, 0x3f317217, v144
	v_mov_b32_e32 v144, v194
	v_sub_f32_e32 v168, v168, v144
	v_mul_f32_e32 v144, 0x3fb8aa3b, v148
	v_exp_f32_e32 v144, v144
	s_nop 0
	v_fma_f32 v144, v183, v144, v132
	v_cmp_gt_f32_e64 s[40:41], s97, v144
	s_nop 1
	v_cndmask_b32_e64 v194, 0, 32, s[40:41]
	v_ldexp_f32 v144, v144, v194
	v_log_f32_e32 v144, v144
	s_nop 0
	v_mul_f32_e32 v194, 0x3f317217, v144
	v_fma_f32 v194, v144, s52, -v194
	v_fmac_f32_e32 v194, 0x3377d1cf, v144
	v_fmac_f32_e32 v194, 0x3f317217, v144
	v_mov_b32_e32 v144, v194
	v_cndmask_b32_e64 v194, 0, v216, s[40:41]
	v_sub_f32_e32 v144, v144, v194
	v_cndmask_b32_e64 v144, v148, v144, s[20:21]
	v_mul_f32_e32 v148, 0x3fb8aa3b, v168
	v_exp_f32_e32 v148, v148
	s_nop 0
	v_fma_f32 v148, v182, v148, v128
	v_cmp_gt_f32_e64 s[40:41], s97, v148
	s_nop 1
	v_cndmask_b32_e64 v194, 0, 32, s[40:41]
	v_ldexp_f32 v148, v148, v194
	v_log_f32_e32 v148, v148
	s_nop 0
	v_mul_f32_e32 v194, 0x3f317217, v148
	v_fma_f32 v194, v148, s52, -v194
	v_fmac_f32_e32 v194, 0x3377d1cf, v148
	v_fmac_f32_e32 v194, 0x3f317217, v148
	v_mov_b32_e32 v148, v194
	v_cndmask_b32_e64 v194, 0, v216, s[40:41]
	v_sub_f32_e32 v148, v148, v194
	v_cndmask_b32_e64 v148, v168, v148, s[18:19]
	v_min_f32_e32 v168, 0, v149
	v_mul_f32_e64 v149, |v149|, s57
	v_exp_f32_e32 v149, v149
	s_nop 0
	v_add_f32_e32 v149, 1.0, v149
	v_log_f32_e32 v149, v149
	s_nop 0
	v_mul_f32_e32 v194, 0x3f317217, v149
	v_fma_f32 v194, v149, s52, -v194
	v_fmac_f32_e32 v194, 0x3377d1cf, v149
	v_fmac_f32_e32 v194, 0x3f317217, v149
	v_mov_b32_e32 v149, v194
	v_sub_f32_e32 v149, v168, v149
	v_min_f32_e32 v168, 0, v145
	v_mul_f32_e64 v145, |v145|, s57
	v_exp_f32_e32 v145, v145
	s_nop 0
	v_add_f32_e32 v145, 1.0, v145
	v_log_f32_e32 v145, v145
	s_nop 0
	v_mul_f32_e32 v194, 0x3f317217, v145
	v_fma_f32 v194, v145, s52, -v194
	v_fmac_f32_e32 v194, 0x3377d1cf, v145
	v_fmac_f32_e32 v194, 0x3f317217, v145
	v_mov_b32_e32 v145, v194
	v_sub_f32_e32 v168, v168, v145
	v_mul_f32_e32 v145, 0x3fb8aa3b, v149
	v_exp_f32_e32 v145, v145
	s_nop 0
	v_fma_f32 v145, v181, v145, v133
	v_cmp_gt_f32_e64 s[40:41], s97, v145
	s_nop 1
	v_cndmask_b32_e64 v194, 0, 32, s[40:41]
	v_ldexp_f32 v145, v145, v194
	v_log_f32_e32 v145, v145
	s_nop 0
	v_mul_f32_e32 v194, 0x3f317217, v145
	v_fma_f32 v194, v145, s52, -v194
	v_fmac_f32_e32 v194, 0x3377d1cf, v145
; __device__ __forceinline__ float silu_f(float x) { return x * __builtin_amdgcn_rcpf(1.f + __expf(-x)); }
; __device__ __forceinline__ v4u pack8(const f32x4 a, const f32x4 b) { v4u w; w.x = cvt_pk_bf16(a[0], a[1]); w.y = cvt_pk_bf16(a[2], a[3]); w.z = cvt_pk_bf16(b[0], b[1]); w.w = cvt_pk_bf16(b[2], b[3]); return w; }
;     __device__ __forceinline__ void operator()(const f32x4 (&acc)[2][2][4][2], const pg8::Unit& u, int wr, int wc, int fr, int fq) const {
;     ...
;         if (grp == 0) { WIN_LOOP( _Pragma("unroll") for (int i = 0; i < 4; ++i) { a[i] = silu_f(a[i]); b[i] = silu_f(b[i]); } *(v4u*)(QO + (size_t)row * DM + c) = pack8(a, b); ) }
;         else if (grp == 3) { WIN_LOOP( _Pragma("unroll") for (int i = 0; i < 4; ++i) { a[i] = silu_f(a[i]); b[i] = silu_f(b[i]); } *(v4u*)(GH + (size_t)row * 512 + c) = pack8(a, b); ) }
;         else if (grp == 1) {
;             f32x4 l0[2], l1[2];
; #pragma unroll
;             for (int bj = 0; bj < 2; ++bj) { l0[bj] = *(const f32x4*)(lb + cb + bj * 128); l1[bj] = *(const f32x4*)(lb + cb + bj * 128 + 4); }
;             WIN_LOOP( _Pragma("unroll") for (int i = 0; i < 4; ++i) { const float s0 = fminf(a[i], 0.f) - __logf(1.f + __expf(-fabsf(a[i]))), s1 = fminf(b[i], 0.f) - __logf(1.f + __expf(-fabsf(b[i]))); const float la = l0[bj][i], lbv = l1[bj][i];
;                     a[i] = la > 0.f ? __logf(la + (1.f - la) * __expf(s0)) : s0; b[i] = lbv > 0.f ? __logf(lbv + (1.f - lbv) * __expf(s1)) : s1; }
;                 *(f32x4*)(LF + (size_t)row * 512 + c) = a; *(f32x4*)(LF + (size_t)row * 512 + c + 4) = b; __builtin_amdgcn_sched_barrier(0); ) }
	v_fmac_f32_e32 v194, 0x3f317217, v145
	v_mov_b32_e32 v145, v194
	v_cndmask_b32_e64 v194, 0, v216, s[40:41]
	v_sub_f32_e32 v145, v145, v194
	v_cndmask_b32_e64 v145, v149, v145, s[16:17]
	v_mul_f32_e32 v149, 0x3fb8aa3b, v168
	v_exp_f32_e32 v149, v149
	s_nop 0
	v_fma_f32 v149, v180, v149, v129
	v_cmp_gt_f32_e64 s[40:41], s97, v149
	s_nop 1
	v_cndmask_b32_e64 v194, 0, 32, s[40:41]
	v_ldexp_f32 v149, v149, v194
	v_log_f32_e32 v149, v149
	s_nop 0
	v_mul_f32_e32 v194, 0x3f317217, v149
	v_fma_f32 v194, v149, s52, -v194
	v_fmac_f32_e32 v194, 0x3377d1cf, v149
	v_fmac_f32_e32 v194, 0x3f317217, v149
	v_mov_b32_e32 v149, v194
	v_cndmask_b32_e64 v194, 0, v216, s[40:41]
	v_sub_f32_e32 v149, v149, v194
	v_cndmask_b32_e64 v149, v168, v149, s[14:15]
	v_min_f32_e32 v168, 0, v150
	v_mul_f32_e64 v150, |v150|, s57
	v_exp_f32_e32 v150, v150
	s_nop 0
	v_add_f32_e32 v150, 1.0, v150
	v_log_f32_e32 v150, v150
	s_nop 0
	v_mul_f32_e32 v194, 0x3f317217, v150
	v_fma_f32 v194, v150, s52, -v194
	v_fmac_f32_e32 v194, 0x3377d1cf, v150
	v_fmac_f32_e32 v194, 0x3f317217, v150
	v_mov_b32_e32 v150, v194
	v_sub_f32_e32 v150, v168, v150
	v_min_f32_e32 v168, 0, v146
	v_mul_f32_e64 v146, |v146|, s57
	v_exp_f32_e32 v146, v146
	s_nop 0
	v_add_f32_e32 v146, 1.0, v146
	v_log_f32_e32 v146, v146
	s_nop 0
	v_mul_f32_e32 v194, 0x3f317217, v146
	v_fma_f32 v194, v146, s52, -v194
	v_fmac_f32_e32 v194, 0x3377d1cf, v146
	v_fmac_f32_e32 v194, 0x3f317217, v146
	v_mov_b32_e32 v146, v194
	v_sub_f32_e32 v168, v168, v146
	v_mul_f32_e32 v146, 0x3fb8aa3b, v150
	v_exp_f32_e32 v146, v146
	s_nop 0
	v_fma_f32 v146, v179, v146, v134
	v_cmp_gt_f32_e64 s[40:41], s97, v146
	s_nop 1
	v_cndmask_b32_e64 v194, 0, 32, s[40:41]
	v_ldexp_f32 v146, v146, v194
	v_log_f32_e32 v146, v146
	s_nop 0
	v_mul_f32_e32 v194, 0x3f317217, v146
	v_fma_f32 v194, v146, s52, -v194
	v_fmac_f32_e32 v194, 0x3377d1cf, v146
	v_fmac_f32_e32 v194, 0x3f317217, v146
	v_mov_b32_e32 v146, v194
	v_cndmask_b32_e64 v194, 0, v216, s[40:41]
	v_sub_f32_e32 v146, v146, v194
	v_cndmask_b32_e64 v146, v150, v146, s[12:13]
	v_mul_f32_e32 v150, 0x3fb8aa3b, v168
	v_exp_f32_e32 v150, v150
	s_nop 0
	v_fma_f32 v150, v178, v150, v130
	v_cmp_gt_f32_e64 s[40:41], s97, v150
	s_nop 1
	v_cndmask_b32_e64 v194, 0, 32, s[40:41]
	v_ldexp_f32 v150, v150, v194
	v_log_f32_e32 v150, v150
	s_nop 0
	v_mul_f32_e32 v194, 0x3f317217, v150
	v_fma_f32 v194, v150, s52, -v194
	v_fmac_f32_e32 v194, 0x3377d1cf, v150
	v_fmac_f32_e32 v194, 0x3f317217, v150
	v_mov_b32_e32 v150, v194
	v_cndmask_b32_e64 v194, 0, v216, s[40:41]
	v_sub_f32_e32 v150, v150, v194
	v_cndmask_b32_e64 v150, v168, v150, s[10:11]
	v_min_f32_e32 v168, 0, v151
	v_mul_f32_e64 v151, |v151|, s57
	v_exp_f32_e32 v151, v151
	s_nop 0
	v_add_f32_e32 v151, 1.0, v151
	v_log_f32_e32 v151, v151
	s_nop 0
	v_mul_f32_e32 v194, 0x3f317217, v151
	v_fma_f32 v194, v151, s52, -v194
	v_fmac_f32_e32 v194, 0x3377d1cf, v151
	v_fmac_f32_e32 v194, 0x3f317217, v151
	v_mov_b32_e32 v151, v194
	v_sub_f32_e32 v151, v168, v151
	v_min_f32_e32 v168, 0, v147
	v_mul_f32_e64 v147, |v147|, s57
	v_exp_f32_e32 v147, v147
	s_nop 0
	v_add_f32_e32 v147, 1.0, v147
	v_log_f32_e32 v147, v147
	s_nop 0
	v_mul_f32_e32 v194, 0x3f317217, v147
	v_fma_f32 v194, v147, s52, -v194
	v_fmac_f32_e32 v194, 0x3377d1cf, v147
	v_fmac_f32_e32 v194, 0x3f317217, v147
	v_mov_b32_e32 v147, v194
	v_sub_f32_e32 v168, v168, v147
	v_mul_f32_e32 v147, 0x3fb8aa3b, v151
	v_exp_f32_e32 v147, v147
	s_nop 0
	v_fma_f32 v147, v177, v147, v135
	v_cmp_gt_f32_e64 s[40:41], s97, v147
	s_nop 1
	v_cndmask_b32_e64 v194, 0, 32, s[40:41]
	v_ldexp_f32 v147, v147, v194
	v_log_f32_e32 v147, v147
	s_nop 0
	v_mul_f32_e32 v194, 0x3f317217, v147
	v_fma_f32 v194, v147, s52, -v194
	v_fmac_f32_e32 v194, 0x3377d1cf, v147
	v_fmac_f32_e32 v194, 0x3f317217, v147
	v_mov_b32_e32 v147, v194
	v_cndmask_b32_e64 v194, 0, v216, s[40:41]
	v_sub_f32_e32 v147, v147, v194
	v_cndmask_b32_e64 v147, v151, v147, s[8:9]
	v_mul_f32_e32 v151, 0x3fb8aa3b, v168
	v_exp_f32_e32 v151, v151
	s_nop 0
	v_fma_f32 v151, v167, v151, v131
	v_cmp_gt_f32_e64 s[40:41], s97, v151
	s_nop 1
	v_cndmask_b32_e64 v194, 0, 32, s[40:41]
	v_ldexp_f32 v151, v151, v194
	v_log_f32_e32 v151, v151
	s_nop 0
	v_mul_f32_e32 v194, 0x3f317217, v151
	v_fma_f32 v194, v151, s52, -v194
	v_fmac_f32_e32 v194, 0x3377d1cf, v151
	v_fmac_f32_e32 v194, 0x3f317217, v151
	v_mov_b32_e32 v151, v194
	v_cndmask_b32_e64 v194, 0, v216, s[40:41]
	v_sub_f32_e32 v151, v151, v194
	v_cndmask_b32_e32 v151, v168, v151, vcc
	global_store_dwordx4 v[170:171], v[144:147], off offset:512
	global_store_dwordx4 v[170:171], v[148:151], off offset:528
	s_nop 1
	v_or_b32_e32 v148, 48, v166
	v_ashrrev_i32_e32 v149, 31, v148
	v_lshlrev_b64 v[144:145], 6, v[148:149]
	v_lshl_add_u64 v[144:145], v[160:161], 0, v[144:145]
	s_nop 0
	s_waitcnt lgkmcnt(0)
	s_nop 3
	s_nop 0
	s_nop 1
	s_waitcnt lgkmcnt(0)
	s_nop 1
	s_waitcnt lgkmcnt(0)
; __device__ __forceinline__ float silu_f(float x) { return x * __builtin_amdgcn_rcpf(1.f + __expf(-x)); }
; __device__ __forceinline__ v4u pack8(const f32x4 a, const f32x4 b) { v4u w; w.x = cvt_pk_bf16(a[0], a[1]); w.y = cvt_pk_bf16(a[2], a[3]); w.z = cvt_pk_bf16(b[0], b[1]); w.w = cvt_pk_bf16(b[2], b[3]); return w; }
;     __device__ __forceinline__ void operator()(const f32x4 (&acc)[2][2][4][2], const pg8::Unit& u, int wr, int wc, int fr, int fq) const {
;     ...
;         if (grp == 0) { WIN_LOOP( _Pragma("unroll") for (int i = 0; i < 4; ++i) { a[i] = silu_f(a[i]); b[i] = silu_f(b[i]); } *(v4u*)(QO + (size_t)row * DM + c) = pack8(a, b); ) }
;         else if (grp == 3) { WIN_LOOP( _Pragma("unroll") for (int i = 0; i < 4; ++i) { a[i] = silu_f(a[i]); b[i] = silu_f(b[i]); } *(v4u*)(GH + (size_t)row * 512 + c) = pack8(a, b); ) }
;         else if (grp == 1) {
;             f32x4 l0[2], l1[2];
; #pragma unroll
;             for (int bj = 0; bj < 2; ++bj) { l0[bj] = *(const f32x4*)(lb + cb + bj * 128); l1[bj] = *(const f32x4*)(lb + cb + bj * 128 + 4); }
;             WIN_LOOP( _Pragma("unroll") for (int i = 0; i < 4; ++i) { const float s0 = fminf(a[i], 0.f) - __logf(1.f + __expf(-fabsf(a[i]))), s1 = fminf(b[i], 0.f) - __logf(1.f + __expf(-fabsf(b[i]))); const float la = l0[bj][i], lbv = l1[bj][i];
;                     a[i] = la > 0.f ? __logf(la + (1.f - la) * __expf(s0)) : s0; b[i] = lbv > 0.f ? __logf(lbv + (1.f - lbv) * __expf(s1)) : s1; }
;                 *(f32x4*)(LF + (size_t)row * 512 + c) = a; *(f32x4*)(LF + (size_t)row * 512 + c + 4) = b; __builtin_amdgcn_sched_barrier(0); ) }
	s_nop 1
	v_mov_b32_e32 v168, v253
	v_lshlrev_b64 v[144:145], 11, v[148:149]
	v_lshl_add_u64 v[170:171], s[50:51], 0, v[144:145]
	v_lshl_add_u64 v[170:171], v[170:171], 0, v[192:193]
	v_pk_mul_f32 v[148:149], v[36:37], v[168:169] op_sel_hi:[1,0]
	v_pk_mul_f32 v[144:145], v[32:33], v[168:169] op_sel_hi:[1,0]
	v_min_f32_e32 v194, 0, v148
	v_mul_f32_e64 v148, |v148|, s57
	v_exp_f32_e32 v148, v148
	v_pk_mul_f32 v[150:151], v[38:39], v[168:169] op_sel_hi:[1,0]
	v_pk_mul_f32 v[146:147], v[34:35], v[168:169] op_sel_hi:[1,0]
	v_add_f32_e32 v148, 1.0, v148
	v_log_f32_e32 v148, v148
	s_nop 0
	v_mul_f32_e32 v195, 0x3f317217, v148
	v_fma_f32 v195, v148, s52, -v195
	v_fmac_f32_e32 v195, 0x3377d1cf, v148
	v_fmac_f32_e32 v195, 0x3f317217, v148
	v_mov_b32_e32 v148, v195
	v_sub_f32_e32 v148, v194, v148
	v_min_f32_e32 v194, 0, v144
	v_mul_f32_e64 v144, |v144|, s57
	v_exp_f32_e32 v144, v144
	s_nop 0
	v_add_f32_e32 v144, 1.0, v144
	v_log_f32_e32 v144, v144
	s_nop 0
	v_mul_f32_e32 v195, 0x3f317217, v144
	v_fma_f32 v195, v144, s52, -v195
	v_fmac_f32_e32 v195, 0x3377d1cf, v144
	v_fmac_f32_e32 v195, 0x3f317217, v144
	v_mov_b32_e32 v144, v195
	v_sub_f32_e32 v194, v194, v144
	v_mul_f32_e32 v144, 0x3fb8aa3b, v148
	v_exp_f32_e32 v144, v144
	s_nop 0
	v_fma_f32 v144, v190, v144, v140
	v_cmp_gt_f32_e64 s[40:41], s97, v144
	s_nop 1
	v_cndmask_b32_e64 v195, 0, 32, s[40:41]
	v_ldexp_f32 v144, v144, v195
	v_log_f32_e32 v144, v144
	s_nop 0
	v_mul_f32_e32 v195, 0x3f317217, v144
	v_fma_f32 v195, v144, s52, -v195
	v_fmac_f32_e32 v195, 0x3377d1cf, v144
	v_fmac_f32_e32 v195, 0x3f317217, v144
	v_mov_b32_e32 v144, v195
	v_cndmask_b32_e64 v195, 0, v216, s[40:41]
	v_sub_f32_e32 v144, v144, v195
	v_cndmask_b32_e64 v144, v148, v144, s[38:39]
	v_mul_f32_e32 v148, 0x3fb8aa3b, v194
	v_exp_f32_e32 v148, v148
	s_nop 0
	v_fma_f32 v148, v191, v148, v136
	v_cmp_gt_f32_e64 s[40:41], s97, v148
	s_nop 1
	v_cndmask_b32_e64 v195, 0, 32, s[40:41]
	v_ldexp_f32 v148, v148, v195
	v_log_f32_e32 v148, v148
	s_nop 0
	v_mul_f32_e32 v195, 0x3f317217, v148
	v_fma_f32 v195, v148, s52, -v195
	v_fmac_f32_e32 v195, 0x3377d1cf, v148
	v_fmac_f32_e32 v195, 0x3f317217, v148
	v_mov_b32_e32 v148, v195
	v_cndmask_b32_e64 v195, 0, v216, s[40:41]
	v_sub_f32_e32 v148, v148, v195
	v_cndmask_b32_e64 v148, v194, v148, s[36:37]
	v_min_f32_e32 v194, 0, v149
	v_mul_f32_e64 v149, |v149|, s57
	v_exp_f32_e32 v149, v149
	s_nop 0
	v_add_f32_e32 v149, 1.0, v149
	v_log_f32_e32 v149, v149
	s_nop 0
	v_mul_f32_e32 v195, 0x3f317217, v149
	v_fma_f32 v195, v149, s52, -v195
	v_fmac_f32_e32 v195, 0x3377d1cf, v149
	v_fmac_f32_e32 v195, 0x3f317217, v149
	v_mov_b32_e32 v149, v195
	v_sub_f32_e32 v149, v194, v149
	v_min_f32_e32 v194, 0, v145
	v_mul_f32_e64 v145, |v145|, s57
	v_exp_f32_e32 v145, v145
	s_nop 0
	v_add_f32_e32 v145, 1.0, v145
	v_log_f32_e32 v145, v145
	s_nop 0
	v_mul_f32_e32 v195, 0x3f317217, v145
	v_fma_f32 v195, v145, s52, -v195
	v_fmac_f32_e32 v195, 0x3377d1cf, v145
	v_fmac_f32_e32 v195, 0x3f317217, v145
	v_mov_b32_e32 v145, v195
	v_sub_f32_e32 v194, v194, v145
	v_mul_f32_e32 v145, 0x3fb8aa3b, v149
	v_exp_f32_e32 v145, v145
	s_nop 0
	v_fma_f32 v145, v188, v145, v141
	v_cmp_gt_f32_e64 s[40:41], s97, v145
	s_nop 1
	v_cndmask_b32_e64 v195, 0, 32, s[40:41]
	v_ldexp_f32 v145, v145, v195
	v_log_f32_e32 v145, v145
	s_nop 0
	v_mul_f32_e32 v195, 0x3f317217, v145
	v_fma_f32 v195, v145, s52, -v195
	v_fmac_f32_e32 v195, 0x3377d1cf, v145
	v_fmac_f32_e32 v195, 0x3f317217, v145
	v_mov_b32_e32 v145, v195
	v_cndmask_b32_e64 v195, 0, v216, s[40:41]
	v_sub_f32_e32 v145, v145, v195
	v_cndmask_b32_e64 v145, v149, v145, s[34:35]
	v_mul_f32_e32 v149, 0x3fb8aa3b, v194
	v_exp_f32_e32 v149, v149
	s_nop 0
	v_fma_f32 v149, v189, v149, v137
	v_cmp_gt_f32_e64 s[40:41], s97, v149
	s_nop 1
	v_cndmask_b32_e64 v195, 0, 32, s[40:41]
	v_ldexp_f32 v149, v149, v195
	v_log_f32_e32 v149, v149
	s_nop 0
	v_mul_f32_e32 v195, 0x3f317217, v149
	v_fma_f32 v195, v149, s52, -v195
	v_fmac_f32_e32 v195, 0x3377d1cf, v149
	v_fmac_f32_e32 v195, 0x3f317217, v149
	v_mov_b32_e32 v149, v195
	v_cndmask_b32_e64 v195, 0, v216, s[40:41]
	v_sub_f32_e32 v149, v149, v195
	v_cndmask_b32_e64 v149, v194, v149, s[30:31]
	v_min_f32_e32 v194, 0, v150
	v_mul_f32_e64 v150, |v150|, s57
	v_exp_f32_e32 v150, v150
	s_nop 0
	v_add_f32_e32 v150, 1.0, v150
	v_log_f32_e32 v150, v150
	s_nop 0
	v_mul_f32_e32 v195, 0x3f317217, v150
	v_fma_f32 v195, v150, s52, -v195
	v_fmac_f32_e32 v195, 0x3377d1cf, v150
	v_fmac_f32_e32 v195, 0x3f317217, v150
	v_mov_b32_e32 v150, v195
	v_sub_f32_e32 v150, v194, v150
	v_min_f32_e32 v194, 0, v146
	v_mul_f32_e64 v146, |v146|, s57
	v_exp_f32_e32 v146, v146
	s_nop 0
	v_add_f32_e32 v146, 1.0, v146
	v_log_f32_e32 v146, v146
	s_nop 0
	v_mul_f32_e32 v195, 0x3f317217, v146
	v_fma_f32 v195, v146, s52, -v195
	v_fmac_f32_e32 v195, 0x3377d1cf, v146
	v_fmac_f32_e32 v195, 0x3f317217, v146
	v_mov_b32_e32 v146, v195
	v_sub_f32_e32 v194, v194, v146
	v_mul_f32_e32 v146, 0x3fb8aa3b, v150
	v_exp_f32_e32 v146, v146
	s_nop 0
	v_fma_f32 v146, v187, v146, v142
	v_cmp_gt_f32_e64 s[40:41], s97, v146
	s_nop 1
	v_cndmask_b32_e64 v195, 0, 32, s[40:41]
	v_ldexp_f32 v146, v146, v195
	v_log_f32_e32 v146, v146
	s_nop 0
	v_mul_f32_e32 v195, 0x3f317217, v146
	v_fma_f32 v195, v146, s52, -v195
	v_fmac_f32_e32 v195, 0x3377d1cf, v146
	v_fmac_f32_e32 v195, 0x3f317217, v146
	v_mov_b32_e32 v146, v195
	v_cndmask_b32_e64 v195, 0, v216, s[40:41]
	v_sub_f32_e32 v146, v146, v195
	v_cndmask_b32_e64 v146, v150, v146, s[28:29]
	v_mul_f32_e32 v150, 0x3fb8aa3b, v194
	v_exp_f32_e32 v150, v150
	s_nop 0
	v_fma_f32 v150, v186, v150, v138
	v_cmp_gt_f32_e64 s[40:41], s97, v150
	s_nop 1
	v_cndmask_b32_e64 v195, 0, 32, s[40:41]
; __device__ __forceinline__ float silu_f(float x) { return x * __builtin_amdgcn_rcpf(1.f + __expf(-x)); }
; __device__ __forceinline__ v4u pack8(const f32x4 a, const f32x4 b) { v4u w; w.x = cvt_pk_bf16(a[0], a[1]); w.y = cvt_pk_bf16(a[2], a[3]); w.z = cvt_pk_bf16(b[0], b[1]); w.w = cvt_pk_bf16(b[2], b[3]); return w; }
;     __device__ __forceinline__ void operator()(const f32x4 (&acc)[2][2][4][2], const pg8::Unit& u, int wr, int wc, int fr, int fq) const {
;     ...
;         if (grp == 0) { WIN_LOOP( _Pragma("unroll") for (int i = 0; i < 4; ++i) { a[i] = silu_f(a[i]); b[i] = silu_f(b[i]); } *(v4u*)(QO + (size_t)row * DM + c) = pack8(a, b); ) }
;         else if (grp == 3) { WIN_LOOP( _Pragma("unroll") for (int i = 0; i < 4; ++i) { a[i] = silu_f(a[i]); b[i] = silu_f(b[i]); } *(v4u*)(GH + (size_t)row * 512 + c) = pack8(a, b); ) }
;         else if (grp == 1) {
;             f32x4 l0[2], l1[2];
; #pragma unroll
;             for (int bj = 0; bj < 2; ++bj) { l0[bj] = *(const f32x4*)(lb + cb + bj * 128); l1[bj] = *(const f32x4*)(lb + cb + bj * 128 + 4); }
;             WIN_LOOP( _Pragma("unroll") for (int i = 0; i < 4; ++i) { const float s0 = fminf(a[i], 0.f) - __logf(1.f + __expf(-fabsf(a[i]))), s1 = fminf(b[i], 0.f) - __logf(1.f + __expf(-fabsf(b[i]))); const float la = l0[bj][i], lbv = l1[bj][i];
;                     a[i] = la > 0.f ? __logf(la + (1.f - la) * __expf(s0)) : s0; b[i] = lbv > 0.f ? __logf(lbv + (1.f - lbv) * __expf(s1)) : s1; }
;                 *(f32x4*)(LF + (size_t)row * 512 + c) = a; *(f32x4*)(LF + (size_t)row * 512 + c + 4) = b; __builtin_amdgcn_sched_barrier(0); ) }
	v_ldexp_f32 v150, v150, v195
	v_log_f32_e32 v150, v150
	s_nop 0
	v_mul_f32_e32 v195, 0x3f317217, v150
	v_fma_f32 v195, v150, s52, -v195
	v_fmac_f32_e32 v195, 0x3377d1cf, v150
	v_fmac_f32_e32 v195, 0x3f317217, v150
	v_mov_b32_e32 v150, v195
	v_cndmask_b32_e64 v195, 0, v216, s[40:41]
	v_sub_f32_e32 v150, v150, v195
	v_cndmask_b32_e64 v150, v194, v150, s[26:27]
	v_min_f32_e32 v194, 0, v151
	v_mul_f32_e64 v151, |v151|, s57
	v_exp_f32_e32 v151, v151
	s_nop 0
	v_add_f32_e32 v151, 1.0, v151
	v_log_f32_e32 v151, v151
	s_nop 0
	v_mul_f32_e32 v195, 0x3f317217, v151
	v_fma_f32 v195, v151, s52, -v195
	v_fmac_f32_e32 v195, 0x3377d1cf, v151
	v_fmac_f32_e32 v195, 0x3f317217, v151
	v_mov_b32_e32 v151, v195
	v_sub_f32_e32 v151, v194, v151
	v_min_f32_e32 v194, 0, v147
	v_mul_f32_e64 v147, |v147|, s57
	v_exp_f32_e32 v147, v147
	s_nop 0
	v_add_f32_e32 v147, 1.0, v147
	v_log_f32_e32 v147, v147
	s_nop 0
	v_mul_f32_e32 v195, 0x3f317217, v147
	v_fma_f32 v195, v147, s52, -v195
	v_fmac_f32_e32 v195, 0x3377d1cf, v147
	v_fmac_f32_e32 v195, 0x3f317217, v147
	v_mov_b32_e32 v147, v195
	v_sub_f32_e32 v194, v194, v147
	v_mul_f32_e32 v147, 0x3fb8aa3b, v151
	v_exp_f32_e32 v147, v147
	s_nop 0
	v_fma_f32 v147, v185, v147, v143
	v_cmp_gt_f32_e64 s[40:41], s97, v147
	s_nop 1
	v_cndmask_b32_e64 v195, 0, 32, s[40:41]
	v_ldexp_f32 v147, v147, v195
	v_log_f32_e32 v147, v147
	s_nop 0
	v_mul_f32_e32 v195, 0x3f317217, v147
	v_fma_f32 v195, v147, s52, -v195
	v_fmac_f32_e32 v195, 0x3377d1cf, v147
	v_fmac_f32_e32 v195, 0x3f317217, v147
	v_mov_b32_e32 v147, v195
	v_cndmask_b32_e64 v195, 0, v216, s[40:41]
	v_sub_f32_e32 v147, v147, v195
	v_cndmask_b32_e64 v147, v151, v147, s[24:25]
	v_mul_f32_e32 v151, 0x3fb8aa3b, v194
	v_exp_f32_e32 v151, v151
	s_nop 0
	v_fma_f32 v151, v184, v151, v139
	v_cmp_gt_f32_e64 s[40:41], s97, v151
	s_nop 1
	v_cndmask_b32_e64 v195, 0, 32, s[40:41]
	v_ldexp_f32 v151, v151, v195
	v_log_f32_e32 v151, v151
	s_nop 0
	v_mul_f32_e32 v195, 0x3f317217, v151
	v_fma_f32 v195, v151, s52, -v195
	v_fmac_f32_e32 v195, 0x3377d1cf, v151
	v_fmac_f32_e32 v195, 0x3f317217, v151
	v_mov_b32_e32 v151, v195
	v_cndmask_b32_e64 v195, 0, v216, s[40:41]
	v_sub_f32_e32 v151, v151, v195
	v_cndmask_b32_e64 v151, v194, v151, s[22:23]
	global_store_dwordx4 v[170:171], v[144:147], off
	global_store_dwordx4 v[170:171], v[148:151], off offset:16
	s_nop 1
	v_pk_mul_f32 v[148:149], v[100:101], v[168:169] op_sel_hi:[1,0]
	v_pk_mul_f32 v[150:151], v[102:103], v[168:169] op_sel_hi:[1,0]
	v_pk_mul_f32 v[146:147], v[98:99], v[168:169] op_sel_hi:[1,0]
	v_pk_mul_f32 v[144:145], v[96:97], v[168:169] op_sel_hi:[1,0]
	v_min_f32_e32 v168, 0, v148
	v_mul_f32_e64 v148, |v148|, s57
	v_exp_f32_e32 v148, v148
	s_nop 0
	v_add_f32_e32 v148, 1.0, v148
	v_log_f32_e32 v148, v148
	s_nop 0
	v_mul_f32_e32 v194, 0x3f317217, v148
	v_fma_f32 v194, v148, s52, -v194
	v_fmac_f32_e32 v194, 0x3377d1cf, v148
	v_fmac_f32_e32 v194, 0x3f317217, v148
	v_mov_b32_e32 v148, v194
	v_sub_f32_e32 v148, v168, v148
	v_min_f32_e32 v168, 0, v144
	v_mul_f32_e64 v144, |v144|, s57
	v_exp_f32_e32 v144, v144
	s_nop 0
	v_add_f32_e32 v144, 1.0, v144
	v_log_f32_e32 v144, v144
	s_nop 0
	v_mul_f32_e32 v194, 0x3f317217, v144
	v_fma_f32 v194, v144, s52, -v194
	v_fmac_f32_e32 v194, 0x3377d1cf, v144
	v_fmac_f32_e32 v194, 0x3f317217, v144
	v_mov_b32_e32 v144, v194
	v_sub_f32_e32 v168, v168, v144
	v_mul_f32_e32 v144, 0x3fb8aa3b, v148
	v_exp_f32_e32 v144, v144
	s_nop 0
	v_fma_f32 v144, v183, v144, v132
	v_cmp_gt_f32_e64 s[40:41], s97, v144
	s_nop 1
	v_cndmask_b32_e64 v194, 0, 32, s[40:41]
	v_ldexp_f32 v144, v144, v194
	v_log_f32_e32 v144, v144
	s_nop 0
	v_mul_f32_e32 v194, 0x3f317217, v144
	v_fma_f32 v194, v144, s52, -v194
	v_fmac_f32_e32 v194, 0x3377d1cf, v144
	v_fmac_f32_e32 v194, 0x3f317217, v144
	v_mov_b32_e32 v144, v194
	v_cndmask_b32_e64 v194, 0, v216, s[40:41]
	v_sub_f32_e32 v144, v144, v194
	v_cndmask_b32_e64 v144, v148, v144, s[20:21]
	v_mul_f32_e32 v148, 0x3fb8aa3b, v168
	v_exp_f32_e32 v148, v148
	s_nop 0
	v_fma_f32 v148, v182, v148, v128
	v_cmp_gt_f32_e64 s[40:41], s97, v148
	s_nop 1
	v_cndmask_b32_e64 v194, 0, 32, s[40:41]
	v_ldexp_f32 v148, v148, v194
	v_log_f32_e32 v148, v148
	s_nop 0
	v_mul_f32_e32 v194, 0x3f317217, v148
	v_fma_f32 v194, v148, s52, -v194
	v_fmac_f32_e32 v194, 0x3377d1cf, v148
	v_fmac_f32_e32 v194, 0x3f317217, v148
	v_mov_b32_e32 v148, v194
	v_cndmask_b32_e64 v194, 0, v216, s[40:41]
	v_sub_f32_e32 v148, v148, v194
	v_cndmask_b32_e64 v148, v168, v148, s[18:19]
	v_min_f32_e32 v168, 0, v149
	v_mul_f32_e64 v149, |v149|, s57
	v_exp_f32_e32 v149, v149
	s_nop 0
	v_add_f32_e32 v149, 1.0, v149
	v_log_f32_e32 v149, v149
	s_nop 0
	v_mul_f32_e32 v194, 0x3f317217, v149
	v_fma_f32 v194, v149, s52, -v194
	v_fmac_f32_e32 v194, 0x3377d1cf, v149
	v_fmac_f32_e32 v194, 0x3f317217, v149
	v_mov_b32_e32 v149, v194
	v_sub_f32_e32 v149, v168, v149
	v_min_f32_e32 v168, 0, v145
	v_mul_f32_e64 v145, |v145|, s57
	v_exp_f32_e32 v145, v145
	s_nop 0
	v_add_f32_e32 v145, 1.0, v145
	v_log_f32_e32 v145, v145
	s_nop 0
	v_mul_f32_e32 v194, 0x3f317217, v145
	v_fma_f32 v194, v145, s52, -v194
	v_fmac_f32_e32 v194, 0x3377d1cf, v145
	v_fmac_f32_e32 v194, 0x3f317217, v145
	v_mov_b32_e32 v145, v194
	v_sub_f32_e32 v168, v168, v145
	v_mul_f32_e32 v145, 0x3fb8aa3b, v149
	v_exp_f32_e32 v145, v145
	s_nop 0
	v_fma_f32 v145, v181, v145, v133
	v_cmp_gt_f32_e64 s[40:41], s97, v145
	s_nop 1
	v_cndmask_b32_e64 v194, 0, 32, s[40:41]
	v_ldexp_f32 v145, v145, v194
	v_log_f32_e32 v145, v145
	s_nop 0
	v_mul_f32_e32 v194, 0x3f317217, v145
	v_fma_f32 v194, v145, s52, -v194
	v_fmac_f32_e32 v194, 0x3377d1cf, v145
	v_fmac_f32_e32 v194, 0x3f317217, v145
	v_mov_b32_e32 v145, v194
; __device__ __forceinline__ float silu_f(float x) { return x * __builtin_amdgcn_rcpf(1.f + __expf(-x)); }
; __device__ __forceinline__ v4u pack8(const f32x4 a, const f32x4 b) { v4u w; w.x = cvt_pk_bf16(a[0], a[1]); w.y = cvt_pk_bf16(a[2], a[3]); w.z = cvt_pk_bf16(b[0], b[1]); w.w = cvt_pk_bf16(b[2], b[3]); return w; }
;     __device__ __forceinline__ void operator()(const f32x4 (&acc)[2][2][4][2], const pg8::Unit& u, int wr, int wc, int fr, int fq) const {
;     ...
;         if (grp == 0) { WIN_LOOP( _Pragma("unroll") for (int i = 0; i < 4; ++i) { a[i] = silu_f(a[i]); b[i] = silu_f(b[i]); } *(v4u*)(QO + (size_t)row * DM + c) = pack8(a, b); ) }
;         else if (grp == 3) { WIN_LOOP( _Pragma("unroll") for (int i = 0; i < 4; ++i) { a[i] = silu_f(a[i]); b[i] = silu_f(b[i]); } *(v4u*)(GH + (size_t)row * 512 + c) = pack8(a, b); ) }
;         else if (grp == 1) {
;             f32x4 l0[2], l1[2];
; #pragma unroll
;             for (int bj = 0; bj < 2; ++bj) { l0[bj] = *(const f32x4*)(lb + cb + bj * 128); l1[bj] = *(const f32x4*)(lb + cb + bj * 128 + 4); }
;             WIN_LOOP( _Pragma("unroll") for (int i = 0; i < 4; ++i) { const float s0 = fminf(a[i], 0.f) - __logf(1.f + __expf(-fabsf(a[i]))), s1 = fminf(b[i], 0.f) - __logf(1.f + __expf(-fabsf(b[i]))); const float la = l0[bj][i], lbv = l1[bj][i];
;                     a[i] = la > 0.f ? __logf(la + (1.f - la) * __expf(s0)) : s0; b[i] = lbv > 0.f ? __logf(lbv + (1.f - lbv) * __expf(s1)) : s1; }
;                 *(f32x4*)(LF + (size_t)row * 512 + c) = a; *(f32x4*)(LF + (size_t)row * 512 + c + 4) = b; __builtin_amdgcn_sched_barrier(0); ) }
	v_cndmask_b32_e64 v194, 0, v216, s[40:41]
	v_sub_f32_e32 v145, v145, v194
	v_cndmask_b32_e64 v145, v149, v145, s[16:17]
	v_mul_f32_e32 v149, 0x3fb8aa3b, v168
	v_exp_f32_e32 v149, v149
	s_nop 0
	v_fma_f32 v149, v180, v149, v129
	v_cmp_gt_f32_e64 s[40:41], s97, v149
	s_nop 1
	v_cndmask_b32_e64 v194, 0, 32, s[40:41]
	v_ldexp_f32 v149, v149, v194
	v_log_f32_e32 v149, v149
	s_nop 0
	v_mul_f32_e32 v194, 0x3f317217, v149
	v_fma_f32 v194, v149, s52, -v194
	v_fmac_f32_e32 v194, 0x3377d1cf, v149
	v_fmac_f32_e32 v194, 0x3f317217, v149
	v_mov_b32_e32 v149, v194
	v_cndmask_b32_e64 v194, 0, v216, s[40:41]
	v_sub_f32_e32 v149, v149, v194
	v_cndmask_b32_e64 v149, v168, v149, s[14:15]
	v_min_f32_e32 v168, 0, v150
	v_mul_f32_e64 v150, |v150|, s57
	v_exp_f32_e32 v150, v150
	s_nop 0
	v_add_f32_e32 v150, 1.0, v150
	v_log_f32_e32 v150, v150
	s_nop 0
	v_mul_f32_e32 v194, 0x3f317217, v150
	v_fma_f32 v194, v150, s52, -v194
	v_fmac_f32_e32 v194, 0x3377d1cf, v150
	v_fmac_f32_e32 v194, 0x3f317217, v150
	v_mov_b32_e32 v150, v194
	v_sub_f32_e32 v150, v168, v150
	v_min_f32_e32 v168, 0, v146
	v_mul_f32_e64 v146, |v146|, s57
	v_exp_f32_e32 v146, v146
	s_nop 0
	v_add_f32_e32 v146, 1.0, v146
	v_log_f32_e32 v146, v146
	s_nop 0
	v_mul_f32_e32 v194, 0x3f317217, v146
	v_fma_f32 v194, v146, s52, -v194
	v_fmac_f32_e32 v194, 0x3377d1cf, v146
	v_fmac_f32_e32 v194, 0x3f317217, v146
	v_mov_b32_e32 v146, v194
	v_sub_f32_e32 v168, v168, v146
	v_mul_f32_e32 v146, 0x3fb8aa3b, v150
	v_exp_f32_e32 v146, v146
	s_nop 0
	v_fma_f32 v146, v179, v146, v134
	v_cmp_gt_f32_e64 s[40:41], s97, v146
	s_nop 1
	v_cndmask_b32_e64 v194, 0, 32, s[40:41]
	v_ldexp_f32 v146, v146, v194
	v_log_f32_e32 v146, v146
	s_nop 0
	v_mul_f32_e32 v194, 0x3f317217, v146
	v_fma_f32 v194, v146, s52, -v194
	v_fmac_f32_e32 v194, 0x3377d1cf, v146
	v_fmac_f32_e32 v194, 0x3f317217, v146
	v_mov_b32_e32 v146, v194
	v_cndmask_b32_e64 v194, 0, v216, s[40:41]
	v_sub_f32_e32 v146, v146, v194
	v_cndmask_b32_e64 v146, v150, v146, s[12:13]
	v_mul_f32_e32 v150, 0x3fb8aa3b, v168
	v_exp_f32_e32 v150, v150
	s_nop 0
	v_fma_f32 v150, v178, v150, v130
	v_cmp_gt_f32_e64 s[40:41], s97, v150
	s_nop 1
	v_cndmask_b32_e64 v194, 0, 32, s[40:41]
	v_ldexp_f32 v150, v150, v194
	v_log_f32_e32 v150, v150
	s_nop 0
	v_mul_f32_e32 v194, 0x3f317217, v150
	v_fma_f32 v194, v150, s52, -v194
	v_fmac_f32_e32 v194, 0x3377d1cf, v150
	v_fmac_f32_e32 v194, 0x3f317217, v150
	v_mov_b32_e32 v150, v194
	v_cndmask_b32_e64 v194, 0, v216, s[40:41]
	v_sub_f32_e32 v150, v150, v194
	v_cndmask_b32_e64 v150, v168, v150, s[10:11]
	v_min_f32_e32 v168, 0, v151
	v_mul_f32_e64 v151, |v151|, s57
	v_exp_f32_e32 v151, v151
	s_nop 0
	v_add_f32_e32 v151, 1.0, v151
	v_log_f32_e32 v151, v151
	s_nop 0
	v_mul_f32_e32 v194, 0x3f317217, v151
	v_fma_f32 v194, v151, s52, -v194
	v_fmac_f32_e32 v194, 0x3377d1cf, v151
	v_fmac_f32_e32 v194, 0x3f317217, v151
	v_mov_b32_e32 v151, v194
	v_sub_f32_e32 v151, v168, v151
	v_min_f32_e32 v168, 0, v147
	v_mul_f32_e64 v147, |v147|, s57
	v_exp_f32_e32 v147, v147
	s_nop 0
	v_add_f32_e32 v147, 1.0, v147
	v_log_f32_e32 v147, v147
	s_nop 0
	v_mul_f32_e32 v194, 0x3f317217, v147
	v_fma_f32 v194, v147, s52, -v194
	v_fmac_f32_e32 v194, 0x3377d1cf, v147
	v_fmac_f32_e32 v194, 0x3f317217, v147
	v_mov_b32_e32 v147, v194
	v_sub_f32_e32 v168, v168, v147
	v_mul_f32_e32 v147, 0x3fb8aa3b, v151
	v_exp_f32_e32 v147, v147
	s_nop 0
	v_fma_f32 v147, v177, v147, v135
	v_cmp_gt_f32_e64 s[40:41], s97, v147
	s_nop 1
	v_cndmask_b32_e64 v194, 0, 32, s[40:41]
	v_ldexp_f32 v147, v147, v194
	v_log_f32_e32 v147, v147
	s_nop 0
	v_mul_f32_e32 v194, 0x3f317217, v147
	v_fma_f32 v194, v147, s52, -v194
	v_fmac_f32_e32 v194, 0x3377d1cf, v147
	v_fmac_f32_e32 v194, 0x3f317217, v147
	v_mov_b32_e32 v147, v194
	v_cndmask_b32_e64 v194, 0, v216, s[40:41]
	v_sub_f32_e32 v147, v147, v194
	v_cndmask_b32_e64 v147, v151, v147, s[8:9]
	v_mul_f32_e32 v151, 0x3fb8aa3b, v168
	v_exp_f32_e32 v151, v151
	s_nop 0
	v_fma_f32 v151, v167, v151, v131
	v_cmp_gt_f32_e64 s[40:41], s97, v151
	s_nop 1
	v_cndmask_b32_e64 v194, 0, 32, s[40:41]
	v_ldexp_f32 v151, v151, v194
	v_log_f32_e32 v151, v151
	s_nop 0
	v_mul_f32_e32 v194, 0x3f317217, v151
	v_fma_f32 v194, v151, s52, -v194
	v_fmac_f32_e32 v194, 0x3377d1cf, v151
	v_fmac_f32_e32 v194, 0x3f317217, v151
	v_mov_b32_e32 v151, v194
	v_cndmask_b32_e64 v194, 0, v216, s[40:41]
	v_sub_f32_e32 v151, v151, v194
	v_cndmask_b32_e32 v151, v168, v151, vcc
	global_store_dwordx4 v[170:171], v[144:147], off offset:512
	global_store_dwordx4 v[170:171], v[148:151], off offset:528
	s_nop 1
	v_add_u32_e32 v148, 0x80, v166
	v_ashrrev_i32_e32 v149, 31, v148
	v_lshlrev_b64 v[144:145], 6, v[148:149]
	v_lshl_add_u64 v[144:145], v[160:161], 0, v[144:145]
	s_nop 0
	s_waitcnt lgkmcnt(0)
	s_nop 3
	s_nop 0
	s_nop 1
	s_waitcnt lgkmcnt(0)
	s_nop 1
	s_waitcnt lgkmcnt(0)
; __device__ __forceinline__ float silu_f(float x) { return x * __builtin_amdgcn_rcpf(1.f + __expf(-x)); }
; __device__ __forceinline__ v4u pack8(const f32x4 a, const f32x4 b) { v4u w; w.x = cvt_pk_bf16(a[0], a[1]); w.y = cvt_pk_bf16(a[2], a[3]); w.z = cvt_pk_bf16(b[0], b[1]); w.w = cvt_pk_bf16(b[2], b[3]); return w; }
;     __device__ __forceinline__ void operator()(const f32x4 (&acc)[2][2][4][2], const pg8::Unit& u, int wr, int wc, int fr, int fq) const {
;     ...
;         if (grp == 0) { WIN_LOOP( _Pragma("unroll") for (int i = 0; i < 4; ++i) { a[i] = silu_f(a[i]); b[i] = silu_f(b[i]); } *(v4u*)(QO + (size_t)row * DM + c) = pack8(a, b); ) }
;         else if (grp == 3) { WIN_LOOP( _Pragma("unroll") for (int i = 0; i < 4; ++i) { a[i] = silu_f(a[i]); b[i] = silu_f(b[i]); } *(v4u*)(GH + (size_t)row * 512 + c) = pack8(a, b); ) }
;         else if (grp == 1) {
;             f32x4 l0[2], l1[2];
; #pragma unroll
;             for (int bj = 0; bj < 2; ++bj) { l0[bj] = *(const f32x4*)(lb + cb + bj * 128); l1[bj] = *(const f32x4*)(lb + cb + bj * 128 + 4); }
;             WIN_LOOP( _Pragma("unroll") for (int i = 0; i < 4; ++i) { const float s0 = fminf(a[i], 0.f) - __logf(1.f + __expf(-fabsf(a[i]))), s1 = fminf(b[i], 0.f) - __logf(1.f + __expf(-fabsf(b[i]))); const float la = l0[bj][i], lbv = l1[bj][i];
;                     a[i] = la > 0.f ? __logf(la + (1.f - la) * __expf(s0)) : s0; b[i] = lbv > 0.f ? __logf(lbv + (1.f - lbv) * __expf(s1)) : s1; }
;                 *(f32x4*)(LF + (size_t)row * 512 + c) = a; *(f32x4*)(LF + (size_t)row * 512 + c + 4) = b; __builtin_amdgcn_sched_barrier(0); ) }
	s_nop 1
	v_mov_b32_e32 v168, v254
	v_lshlrev_b64 v[144:145], 11, v[148:149]
	v_lshl_add_u64 v[170:171], s[50:51], 0, v[144:145]
	v_lshl_add_u64 v[170:171], v[170:171], 0, v[192:193]
	v_pk_mul_f32 v[148:149], v[28:29], v[168:169] op_sel_hi:[1,0]
	v_pk_mul_f32 v[144:145], v[24:25], v[168:169] op_sel_hi:[1,0]
	v_min_f32_e32 v194, 0, v148
	v_mul_f32_e64 v148, |v148|, s57
	v_exp_f32_e32 v148, v148
	v_pk_mul_f32 v[150:151], v[30:31], v[168:169] op_sel_hi:[1,0]
	v_pk_mul_f32 v[146:147], v[26:27], v[168:169] op_sel_hi:[1,0]
	v_add_f32_e32 v148, 1.0, v148
	v_log_f32_e32 v148, v148
	s_nop 0
	v_mul_f32_e32 v195, 0x3f317217, v148
	v_fma_f32 v195, v148, s52, -v195
	v_fmac_f32_e32 v195, 0x3377d1cf, v148
	v_fmac_f32_e32 v195, 0x3f317217, v148
	v_mov_b32_e32 v148, v195
	v_sub_f32_e32 v148, v194, v148
	v_min_f32_e32 v194, 0, v144
	v_mul_f32_e64 v144, |v144|, s57
	v_exp_f32_e32 v144, v144
	s_nop 0
	v_add_f32_e32 v144, 1.0, v144
	v_log_f32_e32 v144, v144
	s_nop 0
	v_mul_f32_e32 v195, 0x3f317217, v144
	v_fma_f32 v195, v144, s52, -v195
	v_fmac_f32_e32 v195, 0x3377d1cf, v144
	v_fmac_f32_e32 v195, 0x3f317217, v144
	v_mov_b32_e32 v144, v195
	v_sub_f32_e32 v194, v194, v144
	v_mul_f32_e32 v144, 0x3fb8aa3b, v148
	v_exp_f32_e32 v144, v144
	s_nop 0
	v_fma_f32 v144, v190, v144, v140
	v_cmp_gt_f32_e64 s[40:41], s97, v144
	s_nop 1
	v_cndmask_b32_e64 v195, 0, 32, s[40:41]
	v_ldexp_f32 v144, v144, v195
	v_log_f32_e32 v144, v144
	s_nop 0
	v_mul_f32_e32 v195, 0x3f317217, v144
	v_fma_f32 v195, v144, s52, -v195
	v_fmac_f32_e32 v195, 0x3377d1cf, v144
	v_fmac_f32_e32 v195, 0x3f317217, v144
	v_mov_b32_e32 v144, v195
	v_cndmask_b32_e64 v195, 0, v216, s[40:41]
	v_sub_f32_e32 v144, v144, v195
	v_cndmask_b32_e64 v144, v148, v144, s[38:39]
	v_mul_f32_e32 v148, 0x3fb8aa3b, v194
	v_exp_f32_e32 v148, v148
	s_nop 0
	v_fma_f32 v148, v191, v148, v136
	v_cmp_gt_f32_e64 s[40:41], s97, v148
	s_nop 1
	v_cndmask_b32_e64 v195, 0, 32, s[40:41]
	v_ldexp_f32 v148, v148, v195
	v_log_f32_e32 v148, v148
	s_nop 0
	v_mul_f32_e32 v195, 0x3f317217, v148
	v_fma_f32 v195, v148, s52, -v195
	v_fmac_f32_e32 v195, 0x3377d1cf, v148
	v_fmac_f32_e32 v195, 0x3f317217, v148
	v_mov_b32_e32 v148, v195
	v_cndmask_b32_e64 v195, 0, v216, s[40:41]
	v_sub_f32_e32 v148, v148, v195
	v_cndmask_b32_e64 v148, v194, v148, s[36:37]
	v_min_f32_e32 v194, 0, v149
	v_mul_f32_e64 v149, |v149|, s57
	v_exp_f32_e32 v149, v149
	s_nop 0
	v_add_f32_e32 v149, 1.0, v149
	v_log_f32_e32 v149, v149
	s_nop 0
	v_mul_f32_e32 v195, 0x3f317217, v149
	v_fma_f32 v195, v149, s52, -v195
	v_fmac_f32_e32 v195, 0x3377d1cf, v149
	v_fmac_f32_e32 v195, 0x3f317217, v149
	v_mov_b32_e32 v149, v195
	v_sub_f32_e32 v149, v194, v149
	v_min_f32_e32 v194, 0, v145
	v_mul_f32_e64 v145, |v145|, s57
	v_exp_f32_e32 v145, v145
	s_nop 0
	v_add_f32_e32 v145, 1.0, v145
	v_log_f32_e32 v145, v145
	s_nop 0
	v_mul_f32_e32 v195, 0x3f317217, v145
	v_fma_f32 v195, v145, s52, -v195
	v_fmac_f32_e32 v195, 0x3377d1cf, v145
	v_fmac_f32_e32 v195, 0x3f317217, v145
	v_mov_b32_e32 v145, v195
	v_sub_f32_e32 v194, v194, v145
	v_mul_f32_e32 v145, 0x3fb8aa3b, v149
	v_exp_f32_e32 v145, v145
	s_nop 0
	v_fma_f32 v145, v188, v145, v141
	v_cmp_gt_f32_e64 s[40:41], s97, v145
	s_nop 1
	v_cndmask_b32_e64 v195, 0, 32, s[40:41]
	v_ldexp_f32 v145, v145, v195
	v_log_f32_e32 v145, v145
	s_nop 0
	v_mul_f32_e32 v195, 0x3f317217, v145
	v_fma_f32 v195, v145, s52, -v195
	v_fmac_f32_e32 v195, 0x3377d1cf, v145
	v_fmac_f32_e32 v195, 0x3f317217, v145
	v_mov_b32_e32 v145, v195
	v_cndmask_b32_e64 v195, 0, v216, s[40:41]
	v_sub_f32_e32 v145, v145, v195
	v_cndmask_b32_e64 v145, v149, v145, s[34:35]
	v_mul_f32_e32 v149, 0x3fb8aa3b, v194
	v_exp_f32_e32 v149, v149
	s_nop 0
	v_fma_f32 v149, v189, v149, v137
	v_cmp_gt_f32_e64 s[40:41], s97, v149
	s_nop 1
	v_cndmask_b32_e64 v195, 0, 32, s[40:41]
	v_ldexp_f32 v149, v149, v195
	v_log_f32_e32 v149, v149
	s_nop 0
	v_mul_f32_e32 v195, 0x3f317217, v149
	v_fma_f32 v195, v149, s52, -v195
	v_fmac_f32_e32 v195, 0x3377d1cf, v149
	v_fmac_f32_e32 v195, 0x3f317217, v149
	v_mov_b32_e32 v149, v195
	v_cndmask_b32_e64 v195, 0, v216, s[40:41]
	v_sub_f32_e32 v149, v149, v195
	v_cndmask_b32_e64 v149, v194, v149, s[30:31]
	v_min_f32_e32 v194, 0, v150
	v_mul_f32_e64 v150, |v150|, s57
	v_exp_f32_e32 v150, v150
	s_nop 0
	v_add_f32_e32 v150, 1.0, v150
	v_log_f32_e32 v150, v150
	s_nop 0
	v_mul_f32_e32 v195, 0x3f317217, v150
	v_fma_f32 v195, v150, s52, -v195
	v_fmac_f32_e32 v195, 0x3377d1cf, v150
	v_fmac_f32_e32 v195, 0x3f317217, v150
	v_mov_b32_e32 v150, v195
	v_sub_f32_e32 v150, v194, v150
	v_min_f32_e32 v194, 0, v146
	v_mul_f32_e64 v146, |v146|, s57
	v_exp_f32_e32 v146, v146
	s_nop 0
	v_add_f32_e32 v146, 1.0, v146
	v_log_f32_e32 v146, v146
	s_nop 0
	v_mul_f32_e32 v195, 0x3f317217, v146
	v_fma_f32 v195, v146, s52, -v195
	v_fmac_f32_e32 v195, 0x3377d1cf, v146
	v_fmac_f32_e32 v195, 0x3f317217, v146
	v_mov_b32_e32 v146, v195
	v_sub_f32_e32 v194, v194, v146
	v_mul_f32_e32 v146, 0x3fb8aa3b, v150
	v_exp_f32_e32 v146, v146
	s_nop 0
	v_fma_f32 v146, v187, v146, v142
	v_cmp_gt_f32_e64 s[40:41], s97, v146
	s_nop 1
	v_cndmask_b32_e64 v195, 0, 32, s[40:41]
	v_ldexp_f32 v146, v146, v195
	v_log_f32_e32 v146, v146
	s_nop 0
	v_mul_f32_e32 v195, 0x3f317217, v146
	v_fma_f32 v195, v146, s52, -v195
	v_fmac_f32_e32 v195, 0x3377d1cf, v146
	v_fmac_f32_e32 v195, 0x3f317217, v146
	v_mov_b32_e32 v146, v195
	v_cndmask_b32_e64 v195, 0, v216, s[40:41]
	v_sub_f32_e32 v146, v146, v195
	v_cndmask_b32_e64 v146, v150, v146, s[28:29]
	v_mul_f32_e32 v150, 0x3fb8aa3b, v194
	v_exp_f32_e32 v150, v150
	s_nop 0
	v_fma_f32 v150, v186, v150, v138
	v_cmp_gt_f32_e64 s[40:41], s97, v150
	s_nop 1
	v_cndmask_b32_e64 v195, 0, 32, s[40:41]
; __device__ __forceinline__ float silu_f(float x) { return x * __builtin_amdgcn_rcpf(1.f + __expf(-x)); }
; __device__ __forceinline__ v4u pack8(const f32x4 a, const f32x4 b) { v4u w; w.x = cvt_pk_bf16(a[0], a[1]); w.y = cvt_pk_bf16(a[2], a[3]); w.z = cvt_pk_bf16(b[0], b[1]); w.w = cvt_pk_bf16(b[2], b[3]); return w; }
;     __device__ __forceinline__ void operator()(const f32x4 (&acc)[2][2][4][2], const pg8::Unit& u, int wr, int wc, int fr, int fq) const {
;     ...
;         if (grp == 0) { WIN_LOOP( _Pragma("unroll") for (int i = 0; i < 4; ++i) { a[i] = silu_f(a[i]); b[i] = silu_f(b[i]); } *(v4u*)(QO + (size_t)row * DM + c) = pack8(a, b); ) }
;         else if (grp == 3) { WIN_LOOP( _Pragma("unroll") for (int i = 0; i < 4; ++i) { a[i] = silu_f(a[i]); b[i] = silu_f(b[i]); } *(v4u*)(GH + (size_t)row * 512 + c) = pack8(a, b); ) }
;         else if (grp == 1) {
;             f32x4 l0[2], l1[2];
; #pragma unroll
;             for (int bj = 0; bj < 2; ++bj) { l0[bj] = *(const f32x4*)(lb + cb + bj * 128); l1[bj] = *(const f32x4*)(lb + cb + bj * 128 + 4); }
;             WIN_LOOP( _Pragma("unroll") for (int i = 0; i < 4; ++i) { const float s0 = fminf(a[i], 0.f) - __logf(1.f + __expf(-fabsf(a[i]))), s1 = fminf(b[i], 0.f) - __logf(1.f + __expf(-fabsf(b[i]))); const float la = l0[bj][i], lbv = l1[bj][i];
;                     a[i] = la > 0.f ? __logf(la + (1.f - la) * __expf(s0)) : s0; b[i] = lbv > 0.f ? __logf(lbv + (1.f - lbv) * __expf(s1)) : s1; }
;                 *(f32x4*)(LF + (size_t)row * 512 + c) = a; *(f32x4*)(LF + (size_t)row * 512 + c + 4) = b; __builtin_amdgcn_sched_barrier(0); ) }
	v_ldexp_f32 v150, v150, v195
	v_log_f32_e32 v150, v150
	s_nop 0
	v_mul_f32_e32 v195, 0x3f317217, v150
	v_fma_f32 v195, v150, s52, -v195
	v_fmac_f32_e32 v195, 0x3377d1cf, v150
	v_fmac_f32_e32 v195, 0x3f317217, v150
	v_mov_b32_e32 v150, v195
	v_cndmask_b32_e64 v195, 0, v216, s[40:41]
	v_sub_f32_e32 v150, v150, v195
	v_cndmask_b32_e64 v150, v194, v150, s[26:27]
	v_min_f32_e32 v194, 0, v151
	v_mul_f32_e64 v151, |v151|, s57
	v_exp_f32_e32 v151, v151
	s_nop 0
	v_add_f32_e32 v151, 1.0, v151
	v_log_f32_e32 v151, v151
	s_nop 0
	v_mul_f32_e32 v195, 0x3f317217, v151
	v_fma_f32 v195, v151, s52, -v195
	v_fmac_f32_e32 v195, 0x3377d1cf, v151
	v_fmac_f32_e32 v195, 0x3f317217, v151
	v_mov_b32_e32 v151, v195
	v_sub_f32_e32 v151, v194, v151
	v_min_f32_e32 v194, 0, v147
	v_mul_f32_e64 v147, |v147|, s57
	v_exp_f32_e32 v147, v147
	s_nop 0
	v_add_f32_e32 v147, 1.0, v147
	v_log_f32_e32 v147, v147
	s_nop 0
	v_mul_f32_e32 v195, 0x3f317217, v147
	v_fma_f32 v195, v147, s52, -v195
	v_fmac_f32_e32 v195, 0x3377d1cf, v147
	v_fmac_f32_e32 v195, 0x3f317217, v147
	v_mov_b32_e32 v147, v195
	v_sub_f32_e32 v194, v194, v147
	v_mul_f32_e32 v147, 0x3fb8aa3b, v151
	v_exp_f32_e32 v147, v147
	s_nop 0
	v_fma_f32 v147, v185, v147, v143
	v_cmp_gt_f32_e64 s[40:41], s97, v147
	s_nop 1
	v_cndmask_b32_e64 v195, 0, 32, s[40:41]
	v_ldexp_f32 v147, v147, v195
	v_log_f32_e32 v147, v147
	s_nop 0
	v_mul_f32_e32 v195, 0x3f317217, v147
	v_fma_f32 v195, v147, s52, -v195
	v_fmac_f32_e32 v195, 0x3377d1cf, v147
	v_fmac_f32_e32 v195, 0x3f317217, v147
	v_mov_b32_e32 v147, v195
	v_cndmask_b32_e64 v195, 0, v216, s[40:41]
	v_sub_f32_e32 v147, v147, v195
	v_cndmask_b32_e64 v147, v151, v147, s[24:25]
	v_mul_f32_e32 v151, 0x3fb8aa3b, v194
	v_exp_f32_e32 v151, v151
	s_nop 0
	v_fma_f32 v151, v184, v151, v139
	v_cmp_gt_f32_e64 s[40:41], s97, v151
	s_nop 1
	v_cndmask_b32_e64 v195, 0, 32, s[40:41]
	v_ldexp_f32 v151, v151, v195
	v_log_f32_e32 v151, v151
	s_nop 0
	v_mul_f32_e32 v195, 0x3f317217, v151
	v_fma_f32 v195, v151, s52, -v195
	v_fmac_f32_e32 v195, 0x3377d1cf, v151
	v_fmac_f32_e32 v195, 0x3f317217, v151
	v_mov_b32_e32 v151, v195
	v_cndmask_b32_e64 v195, 0, v216, s[40:41]
	v_sub_f32_e32 v151, v151, v195
	v_cndmask_b32_e64 v151, v194, v151, s[22:23]
	global_store_dwordx4 v[170:171], v[144:147], off
	global_store_dwordx4 v[170:171], v[148:151], off offset:16
	s_nop 1
	v_pk_mul_f32 v[148:149], v[92:93], v[168:169] op_sel_hi:[1,0]
	v_pk_mul_f32 v[150:151], v[94:95], v[168:169] op_sel_hi:[1,0]
	v_pk_mul_f32 v[146:147], v[90:91], v[168:169] op_sel_hi:[1,0]
	v_pk_mul_f32 v[144:145], v[88:89], v[168:169] op_sel_hi:[1,0]
	v_min_f32_e32 v168, 0, v148
	v_mul_f32_e64 v148, |v148|, s57
	v_exp_f32_e32 v148, v148
	s_nop 0
	v_add_f32_e32 v148, 1.0, v148
	v_log_f32_e32 v148, v148
	s_nop 0
	v_mul_f32_e32 v194, 0x3f317217, v148
	v_fma_f32 v194, v148, s52, -v194
	v_fmac_f32_e32 v194, 0x3377d1cf, v148
	v_fmac_f32_e32 v194, 0x3f317217, v148
	v_mov_b32_e32 v148, v194
	v_sub_f32_e32 v148, v168, v148
	v_min_f32_e32 v168, 0, v144
	v_mul_f32_e64 v144, |v144|, s57
	v_exp_f32_e32 v144, v144
	s_nop 0
	v_add_f32_e32 v144, 1.0, v144
	v_log_f32_e32 v144, v144
	s_nop 0
	v_mul_f32_e32 v194, 0x3f317217, v144
	v_fma_f32 v194, v144, s52, -v194
	v_fmac_f32_e32 v194, 0x3377d1cf, v144
	v_fmac_f32_e32 v194, 0x3f317217, v144
	v_mov_b32_e32 v144, v194
	v_sub_f32_e32 v168, v168, v144
	v_mul_f32_e32 v144, 0x3fb8aa3b, v148
	v_exp_f32_e32 v144, v144
	s_nop 0
	v_fma_f32 v144, v183, v144, v132
	v_cmp_gt_f32_e64 s[40:41], s97, v144
	s_nop 1
	v_cndmask_b32_e64 v194, 0, 32, s[40:41]
	v_ldexp_f32 v144, v144, v194
	v_log_f32_e32 v144, v144
	s_nop 0
	v_mul_f32_e32 v194, 0x3f317217, v144
	v_fma_f32 v194, v144, s52, -v194
	v_fmac_f32_e32 v194, 0x3377d1cf, v144
	v_fmac_f32_e32 v194, 0x3f317217, v144
	v_mov_b32_e32 v144, v194
	v_cndmask_b32_e64 v194, 0, v216, s[40:41]
	v_sub_f32_e32 v144, v144, v194
	v_cndmask_b32_e64 v144, v148, v144, s[20:21]
	v_mul_f32_e32 v148, 0x3fb8aa3b, v168
	v_exp_f32_e32 v148, v148
	s_nop 0
	v_fma_f32 v148, v182, v148, v128
	v_cmp_gt_f32_e64 s[40:41], s97, v148
	s_nop 1
	v_cndmask_b32_e64 v194, 0, 32, s[40:41]
	v_ldexp_f32 v148, v148, v194
	v_log_f32_e32 v148, v148
	s_nop 0
	v_mul_f32_e32 v194, 0x3f317217, v148
	v_fma_f32 v194, v148, s52, -v194
	v_fmac_f32_e32 v194, 0x3377d1cf, v148
	v_fmac_f32_e32 v194, 0x3f317217, v148
	v_mov_b32_e32 v148, v194
	v_cndmask_b32_e64 v194, 0, v216, s[40:41]
	v_sub_f32_e32 v148, v148, v194
	v_cndmask_b32_e64 v148, v168, v148, s[18:19]
	v_min_f32_e32 v168, 0, v149
	v_mul_f32_e64 v149, |v149|, s57
	v_exp_f32_e32 v149, v149
	s_nop 0
	v_add_f32_e32 v149, 1.0, v149
	v_log_f32_e32 v149, v149
	s_nop 0
	v_mul_f32_e32 v194, 0x3f317217, v149
	v_fma_f32 v194, v149, s52, -v194
	v_fmac_f32_e32 v194, 0x3377d1cf, v149
	v_fmac_f32_e32 v194, 0x3f317217, v149
	v_mov_b32_e32 v149, v194
	v_sub_f32_e32 v149, v168, v149
	v_min_f32_e32 v168, 0, v145
	v_mul_f32_e64 v145, |v145|, s57
	v_exp_f32_e32 v145, v145
	s_nop 0
	v_add_f32_e32 v145, 1.0, v145
	v_log_f32_e32 v145, v145
	s_nop 0
	v_mul_f32_e32 v194, 0x3f317217, v145
	v_fma_f32 v194, v145, s52, -v194
	v_fmac_f32_e32 v194, 0x3377d1cf, v145
	v_fmac_f32_e32 v194, 0x3f317217, v145
	v_mov_b32_e32 v145, v194
	v_sub_f32_e32 v168, v168, v145
	v_mul_f32_e32 v145, 0x3fb8aa3b, v149
	v_exp_f32_e32 v145, v145
	s_nop 0
	v_fma_f32 v145, v181, v145, v133
	v_cmp_gt_f32_e64 s[40:41], s97, v145
	s_nop 1
	v_cndmask_b32_e64 v194, 0, 32, s[40:41]
	v_ldexp_f32 v145, v145, v194
	v_log_f32_e32 v145, v145
	s_nop 0
	v_mul_f32_e32 v194, 0x3f317217, v145
	v_fma_f32 v194, v145, s52, -v194
	v_fmac_f32_e32 v194, 0x3377d1cf, v145
	v_fmac_f32_e32 v194, 0x3f317217, v145
	v_mov_b32_e32 v145, v194
; __device__ __forceinline__ float silu_f(float x) { return x * __builtin_amdgcn_rcpf(1.f + __expf(-x)); }
; __device__ __forceinline__ v4u pack8(const f32x4 a, const f32x4 b) { v4u w; w.x = cvt_pk_bf16(a[0], a[1]); w.y = cvt_pk_bf16(a[2], a[3]); w.z = cvt_pk_bf16(b[0], b[1]); w.w = cvt_pk_bf16(b[2], b[3]); return w; }
;     __device__ __forceinline__ void operator()(const f32x4 (&acc)[2][2][4][2], const pg8::Unit& u, int wr, int wc, int fr, int fq) const {
;     ...
;         if (grp == 0) { WIN_LOOP( _Pragma("unroll") for (int i = 0; i < 4; ++i) { a[i] = silu_f(a[i]); b[i] = silu_f(b[i]); } *(v4u*)(QO + (size_t)row * DM + c) = pack8(a, b); ) }
;         else if (grp == 3) { WIN_LOOP( _Pragma("unroll") for (int i = 0; i < 4; ++i) { a[i] = silu_f(a[i]); b[i] = silu_f(b[i]); } *(v4u*)(GH + (size_t)row * 512 + c) = pack8(a, b); ) }
;         else if (grp == 1) {
;             f32x4 l0[2], l1[2];
; #pragma unroll
;             for (int bj = 0; bj < 2; ++bj) { l0[bj] = *(const f32x4*)(lb + cb + bj * 128); l1[bj] = *(const f32x4*)(lb + cb + bj * 128 + 4); }
;             WIN_LOOP( _Pragma("unroll") for (int i = 0; i < 4; ++i) { const float s0 = fminf(a[i], 0.f) - __logf(1.f + __expf(-fabsf(a[i]))), s1 = fminf(b[i], 0.f) - __logf(1.f + __expf(-fabsf(b[i]))); const float la = l0[bj][i], lbv = l1[bj][i];
;                     a[i] = la > 0.f ? __logf(la + (1.f - la) * __expf(s0)) : s0; b[i] = lbv > 0.f ? __logf(lbv + (1.f - lbv) * __expf(s1)) : s1; }
;                 *(f32x4*)(LF + (size_t)row * 512 + c) = a; *(f32x4*)(LF + (size_t)row * 512 + c + 4) = b; __builtin_amdgcn_sched_barrier(0); ) }
	v_cndmask_b32_e64 v194, 0, v216, s[40:41]
	v_sub_f32_e32 v145, v145, v194
	v_cndmask_b32_e64 v145, v149, v145, s[16:17]
	v_mul_f32_e32 v149, 0x3fb8aa3b, v168
	v_exp_f32_e32 v149, v149
	s_nop 0
	v_fma_f32 v149, v180, v149, v129
	v_cmp_gt_f32_e64 s[40:41], s97, v149
	s_nop 1
	v_cndmask_b32_e64 v194, 0, 32, s[40:41]
	v_ldexp_f32 v149, v149, v194
	v_log_f32_e32 v149, v149
	s_nop 0
	v_mul_f32_e32 v194, 0x3f317217, v149
	v_fma_f32 v194, v149, s52, -v194
	v_fmac_f32_e32 v194, 0x3377d1cf, v149
	v_fmac_f32_e32 v194, 0x3f317217, v149
	v_mov_b32_e32 v149, v194
	v_cndmask_b32_e64 v194, 0, v216, s[40:41]
	v_sub_f32_e32 v149, v149, v194
	v_cndmask_b32_e64 v149, v168, v149, s[14:15]
	v_min_f32_e32 v168, 0, v150
	v_mul_f32_e64 v150, |v150|, s57
	v_exp_f32_e32 v150, v150
	s_nop 0
	v_add_f32_e32 v150, 1.0, v150
	v_log_f32_e32 v150, v150
	s_nop 0
	v_mul_f32_e32 v194, 0x3f317217, v150
	v_fma_f32 v194, v150, s52, -v194
	v_fmac_f32_e32 v194, 0x3377d1cf, v150
	v_fmac_f32_e32 v194, 0x3f317217, v150
	v_mov_b32_e32 v150, v194
	v_sub_f32_e32 v150, v168, v150
	v_min_f32_e32 v168, 0, v146
	v_mul_f32_e64 v146, |v146|, s57
	v_exp_f32_e32 v146, v146
	s_nop 0
	v_add_f32_e32 v146, 1.0, v146
	v_log_f32_e32 v146, v146
	s_nop 0
	v_mul_f32_e32 v194, 0x3f317217, v146
	v_fma_f32 v194, v146, s52, -v194
	v_fmac_f32_e32 v194, 0x3377d1cf, v146
	v_fmac_f32_e32 v194, 0x3f317217, v146
	v_mov_b32_e32 v146, v194
	v_sub_f32_e32 v168, v168, v146
	v_mul_f32_e32 v146, 0x3fb8aa3b, v150
	v_exp_f32_e32 v146, v146
	s_nop 0
	v_fma_f32 v146, v179, v146, v134
	v_cmp_gt_f32_e64 s[40:41], s97, v146
	s_nop 1
	v_cndmask_b32_e64 v194, 0, 32, s[40:41]
	v_ldexp_f32 v146, v146, v194
	v_log_f32_e32 v146, v146
	s_nop 0
	v_mul_f32_e32 v194, 0x3f317217, v146
	v_fma_f32 v194, v146, s52, -v194
	v_fmac_f32_e32 v194, 0x3377d1cf, v146
	v_fmac_f32_e32 v194, 0x3f317217, v146
	v_mov_b32_e32 v146, v194
	v_cndmask_b32_e64 v194, 0, v216, s[40:41]
	v_sub_f32_e32 v146, v146, v194
	v_cndmask_b32_e64 v146, v150, v146, s[12:13]
	v_mul_f32_e32 v150, 0x3fb8aa3b, v168
	v_exp_f32_e32 v150, v150
	s_nop 0
	v_fma_f32 v150, v178, v150, v130
	v_cmp_gt_f32_e64 s[40:41], s97, v150
	s_nop 1
	v_cndmask_b32_e64 v194, 0, 32, s[40:41]
	v_ldexp_f32 v150, v150, v194
	v_log_f32_e32 v150, v150
	s_nop 0
	v_mul_f32_e32 v194, 0x3f317217, v150
	v_fma_f32 v194, v150, s52, -v194
	v_fmac_f32_e32 v194, 0x3377d1cf, v150
	v_fmac_f32_e32 v194, 0x3f317217, v150
	v_mov_b32_e32 v150, v194
	v_cndmask_b32_e64 v194, 0, v216, s[40:41]
	v_sub_f32_e32 v150, v150, v194
	v_cndmask_b32_e64 v150, v168, v150, s[10:11]
	v_min_f32_e32 v168, 0, v151
	v_mul_f32_e64 v151, |v151|, s57
	v_exp_f32_e32 v151, v151
	s_nop 0
	v_add_f32_e32 v151, 1.0, v151
	v_log_f32_e32 v151, v151
	s_nop 0
	v_mul_f32_e32 v194, 0x3f317217, v151
	v_fma_f32 v194, v151, s52, -v194
	v_fmac_f32_e32 v194, 0x3377d1cf, v151
	v_fmac_f32_e32 v194, 0x3f317217, v151
	v_mov_b32_e32 v151, v194
	v_sub_f32_e32 v151, v168, v151
	v_min_f32_e32 v168, 0, v147
	v_mul_f32_e64 v147, |v147|, s57
	v_exp_f32_e32 v147, v147
	s_nop 0
	v_add_f32_e32 v147, 1.0, v147
	v_log_f32_e32 v147, v147
	s_nop 0
	v_mul_f32_e32 v194, 0x3f317217, v147
	v_fma_f32 v194, v147, s52, -v194
	v_fmac_f32_e32 v194, 0x3377d1cf, v147
	v_fmac_f32_e32 v194, 0x3f317217, v147
	v_mov_b32_e32 v147, v194
	v_sub_f32_e32 v168, v168, v147
	v_mul_f32_e32 v147, 0x3fb8aa3b, v151
	v_exp_f32_e32 v147, v147
	s_nop 0
	v_fma_f32 v147, v177, v147, v135
	v_cmp_gt_f32_e64 s[40:41], s97, v147
	s_nop 1
	v_cndmask_b32_e64 v194, 0, 32, s[40:41]
	v_ldexp_f32 v147, v147, v194
	v_log_f32_e32 v147, v147
	s_nop 0
	v_mul_f32_e32 v194, 0x3f317217, v147
	v_fma_f32 v194, v147, s52, -v194
	v_fmac_f32_e32 v194, 0x3377d1cf, v147
	v_fmac_f32_e32 v194, 0x3f317217, v147
	v_mov_b32_e32 v147, v194
	v_cndmask_b32_e64 v194, 0, v216, s[40:41]
	v_sub_f32_e32 v147, v147, v194
	v_cndmask_b32_e64 v147, v151, v147, s[8:9]
	v_mul_f32_e32 v151, 0x3fb8aa3b, v168
	v_exp_f32_e32 v151, v151
	s_nop 0
	v_fma_f32 v151, v167, v151, v131
	v_cmp_gt_f32_e64 s[40:41], s97, v151
	s_nop 1
	v_cndmask_b32_e64 v194, 0, 32, s[40:41]
	v_ldexp_f32 v151, v151, v194
	v_log_f32_e32 v151, v151
	s_nop 0
	v_mul_f32_e32 v194, 0x3f317217, v151
	v_fma_f32 v194, v151, s52, -v194
	v_fmac_f32_e32 v194, 0x3377d1cf, v151
	v_fmac_f32_e32 v194, 0x3f317217, v151
	v_mov_b32_e32 v151, v194
	v_cndmask_b32_e64 v194, 0, v216, s[40:41]
	v_sub_f32_e32 v151, v151, v194
	v_cndmask_b32_e32 v151, v168, v151, vcc
	global_store_dwordx4 v[170:171], v[144:147], off offset:512
	global_store_dwordx4 v[170:171], v[148:151], off offset:528
	s_nop 1
	v_add_u32_e32 v148, 0x90, v166
	v_ashrrev_i32_e32 v149, 31, v148
	v_lshlrev_b64 v[144:145], 6, v[148:149]
	v_lshl_add_u64 v[144:145], v[160:161], 0, v[144:145]
	s_nop 0
	s_waitcnt lgkmcnt(0)
	s_nop 3
	s_nop 0
	s_nop 1
	s_waitcnt lgkmcnt(0)
	s_nop 1
	s_waitcnt lgkmcnt(0)
; __device__ __forceinline__ float silu_f(float x) { return x * __builtin_amdgcn_rcpf(1.f + __expf(-x)); }
; __device__ __forceinline__ v4u pack8(const f32x4 a, const f32x4 b) { v4u w; w.x = cvt_pk_bf16(a[0], a[1]); w.y = cvt_pk_bf16(a[2], a[3]); w.z = cvt_pk_bf16(b[0], b[1]); w.w = cvt_pk_bf16(b[2], b[3]); return w; }
;     __device__ __forceinline__ void operator()(const f32x4 (&acc)[2][2][4][2], const pg8::Unit& u, int wr, int wc, int fr, int fq) const {
;     ...
;         if (grp == 0) { WIN_LOOP( _Pragma("unroll") for (int i = 0; i < 4; ++i) { a[i] = silu_f(a[i]); b[i] = silu_f(b[i]); } *(v4u*)(QO + (size_t)row * DM + c) = pack8(a, b); ) }
;         else if (grp == 3) { WIN_LOOP( _Pragma("unroll") for (int i = 0; i < 4; ++i) { a[i] = silu_f(a[i]); b[i] = silu_f(b[i]); } *(v4u*)(GH + (size_t)row * 512 + c) = pack8(a, b); ) }
;         else if (grp == 1) {
;             f32x4 l0[2], l1[2];
; #pragma unroll
;             for (int bj = 0; bj < 2; ++bj) { l0[bj] = *(const f32x4*)(lb + cb + bj * 128); l1[bj] = *(const f32x4*)(lb + cb + bj * 128 + 4); }
;             WIN_LOOP( _Pragma("unroll") for (int i = 0; i < 4; ++i) { const float s0 = fminf(a[i], 0.f) - __logf(1.f + __expf(-fabsf(a[i]))), s1 = fminf(b[i], 0.f) - __logf(1.f + __expf(-fabsf(b[i]))); const float la = l0[bj][i], lbv = l1[bj][i];
;                     a[i] = la > 0.f ? __logf(la + (1.f - la) * __expf(s0)) : s0; b[i] = lbv > 0.f ? __logf(lbv + (1.f - lbv) * __expf(s1)) : s1; }
;                 *(f32x4*)(LF + (size_t)row * 512 + c) = a; *(f32x4*)(LF + (size_t)row * 512 + c + 4) = b; __builtin_amdgcn_sched_barrier(0); ) }
	s_nop 1
	v_mov_b32_e32 v168, v240
	v_lshlrev_b64 v[144:145], 11, v[148:149]
	v_lshl_add_u64 v[170:171], s[50:51], 0, v[144:145]
	v_lshl_add_u64 v[170:171], v[170:171], 0, v[192:193]
	v_pk_mul_f32 v[148:149], v[20:21], v[168:169] op_sel_hi:[1,0]
	v_pk_mul_f32 v[144:145], v[16:17], v[168:169] op_sel_hi:[1,0]
	v_min_f32_e32 v194, 0, v148
	v_mul_f32_e64 v148, |v148|, s57
	v_exp_f32_e32 v148, v148
	v_pk_mul_f32 v[150:151], v[22:23], v[168:169] op_sel_hi:[1,0]
	v_pk_mul_f32 v[146:147], v[18:19], v[168:169] op_sel_hi:[1,0]
	v_add_f32_e32 v148, 1.0, v148
	v_log_f32_e32 v148, v148
	s_nop 0
	v_mul_f32_e32 v195, 0x3f317217, v148
	v_fma_f32 v195, v148, s52, -v195
	v_fmac_f32_e32 v195, 0x3377d1cf, v148
	v_fmac_f32_e32 v195, 0x3f317217, v148
	v_mov_b32_e32 v148, v195
	v_sub_f32_e32 v148, v194, v148
	v_min_f32_e32 v194, 0, v144
	v_mul_f32_e64 v144, |v144|, s57
	v_exp_f32_e32 v144, v144
	s_nop 0
	v_add_f32_e32 v144, 1.0, v144
	v_log_f32_e32 v144, v144
	s_nop 0
	v_mul_f32_e32 v195, 0x3f317217, v144
	v_fma_f32 v195, v144, s52, -v195
	v_fmac_f32_e32 v195, 0x3377d1cf, v144
	v_fmac_f32_e32 v195, 0x3f317217, v144
	v_mov_b32_e32 v144, v195
	v_sub_f32_e32 v194, v194, v144
	v_mul_f32_e32 v144, 0x3fb8aa3b, v148
	v_exp_f32_e32 v144, v144
	s_nop 0
	v_fma_f32 v144, v190, v144, v140
	v_cmp_gt_f32_e64 s[40:41], s97, v144
	s_nop 1
	v_cndmask_b32_e64 v195, 0, 32, s[40:41]
	v_ldexp_f32 v144, v144, v195
	v_log_f32_e32 v144, v144
	s_nop 0
	v_mul_f32_e32 v195, 0x3f317217, v144
	v_fma_f32 v195, v144, s52, -v195
	v_fmac_f32_e32 v195, 0x3377d1cf, v144
	v_fmac_f32_e32 v195, 0x3f317217, v144
	v_mov_b32_e32 v144, v195
	v_cndmask_b32_e64 v195, 0, v216, s[40:41]
	v_sub_f32_e32 v144, v144, v195
	v_cndmask_b32_e64 v144, v148, v144, s[38:39]
	v_mul_f32_e32 v148, 0x3fb8aa3b, v194
	v_exp_f32_e32 v148, v148
	s_nop 0
	v_fma_f32 v148, v191, v148, v136
	v_cmp_gt_f32_e64 s[40:41], s97, v148
	s_nop 1
	v_cndmask_b32_e64 v195, 0, 32, s[40:41]
	v_ldexp_f32 v148, v148, v195
	v_log_f32_e32 v148, v148
	s_nop 0
	v_mul_f32_e32 v195, 0x3f317217, v148
	v_fma_f32 v195, v148, s52, -v195
	v_fmac_f32_e32 v195, 0x3377d1cf, v148
	v_fmac_f32_e32 v195, 0x3f317217, v148
	v_mov_b32_e32 v148, v195
	v_cndmask_b32_e64 v195, 0, v216, s[40:41]
	v_sub_f32_e32 v148, v148, v195
	v_cndmask_b32_e64 v148, v194, v148, s[36:37]
	v_min_f32_e32 v194, 0, v149
	v_mul_f32_e64 v149, |v149|, s57
	v_exp_f32_e32 v149, v149
	s_nop 0
	v_add_f32_e32 v149, 1.0, v149
	v_log_f32_e32 v149, v149
	s_nop 0
	v_mul_f32_e32 v195, 0x3f317217, v149
	v_fma_f32 v195, v149, s52, -v195
	v_fmac_f32_e32 v195, 0x3377d1cf, v149
	v_fmac_f32_e32 v195, 0x3f317217, v149
	v_mov_b32_e32 v149, v195
	v_sub_f32_e32 v149, v194, v149
	v_min_f32_e32 v194, 0, v145
	v_mul_f32_e64 v145, |v145|, s57
	v_exp_f32_e32 v145, v145
	s_nop 0
	v_add_f32_e32 v145, 1.0, v145
	v_log_f32_e32 v145, v145
	s_nop 0
	v_mul_f32_e32 v195, 0x3f317217, v145
	v_fma_f32 v195, v145, s52, -v195
	v_fmac_f32_e32 v195, 0x3377d1cf, v145
	v_fmac_f32_e32 v195, 0x3f317217, v145
	v_mov_b32_e32 v145, v195
	v_sub_f32_e32 v194, v194, v145
	v_mul_f32_e32 v145, 0x3fb8aa3b, v149
	v_exp_f32_e32 v145, v145
	s_nop 0
	v_fma_f32 v145, v188, v145, v141
	v_cmp_gt_f32_e64 s[40:41], s97, v145
	s_nop 1
	v_cndmask_b32_e64 v195, 0, 32, s[40:41]
	v_ldexp_f32 v145, v145, v195
	v_log_f32_e32 v145, v145
	s_nop 0
	v_mul_f32_e32 v195, 0x3f317217, v145
	v_fma_f32 v195, v145, s52, -v195
	v_fmac_f32_e32 v195, 0x3377d1cf, v145
	v_fmac_f32_e32 v195, 0x3f317217, v145
	v_mov_b32_e32 v145, v195
	v_cndmask_b32_e64 v195, 0, v216, s[40:41]
	v_sub_f32_e32 v145, v145, v195
	v_cndmask_b32_e64 v145, v149, v145, s[34:35]
	v_mul_f32_e32 v149, 0x3fb8aa3b, v194
	v_exp_f32_e32 v149, v149
	s_nop 0
	v_fma_f32 v149, v189, v149, v137
	v_cmp_gt_f32_e64 s[40:41], s97, v149
	s_nop 1
	v_cndmask_b32_e64 v195, 0, 32, s[40:41]
	v_ldexp_f32 v149, v149, v195
	v_log_f32_e32 v149, v149
	s_nop 0
	v_mul_f32_e32 v195, 0x3f317217, v149
	v_fma_f32 v195, v149, s52, -v195
	v_fmac_f32_e32 v195, 0x3377d1cf, v149
	v_fmac_f32_e32 v195, 0x3f317217, v149
	v_mov_b32_e32 v149, v195
	v_cndmask_b32_e64 v195, 0, v216, s[40:41]
	v_sub_f32_e32 v149, v149, v195
	v_cndmask_b32_e64 v149, v194, v149, s[30:31]
	v_min_f32_e32 v194, 0, v150
	v_mul_f32_e64 v150, |v150|, s57
	v_exp_f32_e32 v150, v150
	s_nop 0
	v_add_f32_e32 v150, 1.0, v150
	v_log_f32_e32 v150, v150
	s_nop 0
	v_mul_f32_e32 v195, 0x3f317217, v150
	v_fma_f32 v195, v150, s52, -v195
	v_fmac_f32_e32 v195, 0x3377d1cf, v150
	v_fmac_f32_e32 v195, 0x3f317217, v150
	v_mov_b32_e32 v150, v195
	v_sub_f32_e32 v150, v194, v150
	v_min_f32_e32 v194, 0, v146
	v_mul_f32_e64 v146, |v146|, s57
	v_exp_f32_e32 v146, v146
	s_nop 0
	v_add_f32_e32 v146, 1.0, v146
	v_log_f32_e32 v146, v146
	s_nop 0
	v_mul_f32_e32 v195, 0x3f317217, v146
	v_fma_f32 v195, v146, s52, -v195
	v_fmac_f32_e32 v195, 0x3377d1cf, v146
	v_fmac_f32_e32 v195, 0x3f317217, v146
	v_mov_b32_e32 v146, v195
	v_sub_f32_e32 v194, v194, v146
	v_mul_f32_e32 v146, 0x3fb8aa3b, v150
	v_exp_f32_e32 v146, v146
	s_nop 0
	v_fma_f32 v146, v187, v146, v142
	v_cmp_gt_f32_e64 s[40:41], s97, v146
	s_nop 1
	v_cndmask_b32_e64 v195, 0, 32, s[40:41]
	v_ldexp_f32 v146, v146, v195
	v_log_f32_e32 v146, v146
	s_nop 0
	v_mul_f32_e32 v195, 0x3f317217, v146
	v_fma_f32 v195, v146, s52, -v195
	v_fmac_f32_e32 v195, 0x3377d1cf, v146
	v_fmac_f32_e32 v195, 0x3f317217, v146
	v_mov_b32_e32 v146, v195
	v_cndmask_b32_e64 v195, 0, v216, s[40:41]
	v_sub_f32_e32 v146, v146, v195
	v_cndmask_b32_e64 v146, v150, v146, s[28:29]
	v_mul_f32_e32 v150, 0x3fb8aa3b, v194
	v_exp_f32_e32 v150, v150
	s_nop 0
	v_fma_f32 v150, v186, v150, v138
	v_cmp_gt_f32_e64 s[40:41], s97, v150
	s_nop 1
	v_cndmask_b32_e64 v195, 0, 32, s[40:41]
; __device__ __forceinline__ float silu_f(float x) { return x * __builtin_amdgcn_rcpf(1.f + __expf(-x)); }
; __device__ __forceinline__ v4u pack8(const f32x4 a, const f32x4 b) { v4u w; w.x = cvt_pk_bf16(a[0], a[1]); w.y = cvt_pk_bf16(a[2], a[3]); w.z = cvt_pk_bf16(b[0], b[1]); w.w = cvt_pk_bf16(b[2], b[3]); return w; }
;     __device__ __forceinline__ void operator()(const f32x4 (&acc)[2][2][4][2], const pg8::Unit& u, int wr, int wc, int fr, int fq) const {
;     ...
;         if (grp == 0) { WIN_LOOP( _Pragma("unroll") for (int i = 0; i < 4; ++i) { a[i] = silu_f(a[i]); b[i] = silu_f(b[i]); } *(v4u*)(QO + (size_t)row * DM + c) = pack8(a, b); ) }
;         else if (grp == 3) { WIN_LOOP( _Pragma("unroll") for (int i = 0; i < 4; ++i) { a[i] = silu_f(a[i]); b[i] = silu_f(b[i]); } *(v4u*)(GH + (size_t)row * 512 + c) = pack8(a, b); ) }
;         else if (grp == 1) {
;             f32x4 l0[2], l1[2];
; #pragma unroll
;             for (int bj = 0; bj < 2; ++bj) { l0[bj] = *(const f32x4*)(lb + cb + bj * 128); l1[bj] = *(const f32x4*)(lb + cb + bj * 128 + 4); }
;             WIN_LOOP( _Pragma("unroll") for (int i = 0; i < 4; ++i) { const float s0 = fminf(a[i], 0.f) - __logf(1.f + __expf(-fabsf(a[i]))), s1 = fminf(b[i], 0.f) - __logf(1.f + __expf(-fabsf(b[i]))); const float la = l0[bj][i], lbv = l1[bj][i];
;                     a[i] = la > 0.f ? __logf(la + (1.f - la) * __expf(s0)) : s0; b[i] = lbv > 0.f ? __logf(lbv + (1.f - lbv) * __expf(s1)) : s1; }
;                 *(f32x4*)(LF + (size_t)row * 512 + c) = a; *(f32x4*)(LF + (size_t)row * 512 + c + 4) = b; __builtin_amdgcn_sched_barrier(0); ) }
	v_ldexp_f32 v150, v150, v195
	v_log_f32_e32 v150, v150
	s_nop 0
	v_mul_f32_e32 v195, 0x3f317217, v150
	v_fma_f32 v195, v150, s52, -v195
	v_fmac_f32_e32 v195, 0x3377d1cf, v150
	v_fmac_f32_e32 v195, 0x3f317217, v150
	v_mov_b32_e32 v150, v195
	v_cndmask_b32_e64 v195, 0, v216, s[40:41]
	v_sub_f32_e32 v150, v150, v195
	v_cndmask_b32_e64 v150, v194, v150, s[26:27]
	v_min_f32_e32 v194, 0, v151
	v_mul_f32_e64 v151, |v151|, s57
	v_exp_f32_e32 v151, v151
	s_nop 0
	v_add_f32_e32 v151, 1.0, v151
	v_log_f32_e32 v151, v151
	s_nop 0
	v_mul_f32_e32 v195, 0x3f317217, v151
	v_fma_f32 v195, v151, s52, -v195
	v_fmac_f32_e32 v195, 0x3377d1cf, v151
	v_fmac_f32_e32 v195, 0x3f317217, v151
	v_mov_b32_e32 v151, v195
	v_sub_f32_e32 v151, v194, v151
	v_min_f32_e32 v194, 0, v147
	v_mul_f32_e64 v147, |v147|, s57
	v_exp_f32_e32 v147, v147
	s_nop 0
	v_add_f32_e32 v147, 1.0, v147
	v_log_f32_e32 v147, v147
	s_nop 0
	v_mul_f32_e32 v195, 0x3f317217, v147
	v_fma_f32 v195, v147, s52, -v195
	v_fmac_f32_e32 v195, 0x3377d1cf, v147
	v_fmac_f32_e32 v195, 0x3f317217, v147
	v_mov_b32_e32 v147, v195
	v_sub_f32_e32 v194, v194, v147
	v_mul_f32_e32 v147, 0x3fb8aa3b, v151
	v_exp_f32_e32 v147, v147
	s_nop 0
	v_fma_f32 v147, v185, v147, v143
	v_cmp_gt_f32_e64 s[40:41], s97, v147
	s_nop 1
	v_cndmask_b32_e64 v195, 0, 32, s[40:41]
	v_ldexp_f32 v147, v147, v195
	v_log_f32_e32 v147, v147
	s_nop 0
	v_mul_f32_e32 v195, 0x3f317217, v147
	v_fma_f32 v195, v147, s52, -v195
	v_fmac_f32_e32 v195, 0x3377d1cf, v147
	v_fmac_f32_e32 v195, 0x3f317217, v147
	v_mov_b32_e32 v147, v195
	v_cndmask_b32_e64 v195, 0, v216, s[40:41]
	v_sub_f32_e32 v147, v147, v195
	v_cndmask_b32_e64 v147, v151, v147, s[24:25]
	v_mul_f32_e32 v151, 0x3fb8aa3b, v194
	v_exp_f32_e32 v151, v151
	s_nop 0
	v_fma_f32 v151, v184, v151, v139
	v_cmp_gt_f32_e64 s[40:41], s97, v151
	s_nop 1
	v_cndmask_b32_e64 v195, 0, 32, s[40:41]
	v_ldexp_f32 v151, v151, v195
	v_log_f32_e32 v151, v151
	s_nop 0
	v_mul_f32_e32 v195, 0x3f317217, v151
	v_fma_f32 v195, v151, s52, -v195
	v_fmac_f32_e32 v195, 0x3377d1cf, v151
	v_fmac_f32_e32 v195, 0x3f317217, v151
	v_mov_b32_e32 v151, v195
	v_cndmask_b32_e64 v195, 0, v216, s[40:41]
	v_sub_f32_e32 v151, v151, v195
	v_cndmask_b32_e64 v151, v194, v151, s[22:23]
	global_store_dwordx4 v[170:171], v[144:147], off
	global_store_dwordx4 v[170:171], v[148:151], off offset:16
	s_nop 1
	v_pk_mul_f32 v[148:149], v[84:85], v[168:169] op_sel_hi:[1,0]
	v_pk_mul_f32 v[150:151], v[86:87], v[168:169] op_sel_hi:[1,0]
	v_pk_mul_f32 v[146:147], v[82:83], v[168:169] op_sel_hi:[1,0]
	v_pk_mul_f32 v[144:145], v[80:81], v[168:169] op_sel_hi:[1,0]
	v_min_f32_e32 v168, 0, v148
	v_mul_f32_e64 v148, |v148|, s57
	v_exp_f32_e32 v148, v148
	s_nop 0
	v_add_f32_e32 v148, 1.0, v148
	v_log_f32_e32 v148, v148
	s_nop 0
	v_mul_f32_e32 v194, 0x3f317217, v148
	v_fma_f32 v194, v148, s52, -v194
	v_fmac_f32_e32 v194, 0x3377d1cf, v148
	v_fmac_f32_e32 v194, 0x3f317217, v148
	v_mov_b32_e32 v148, v194
	v_sub_f32_e32 v148, v168, v148
	v_min_f32_e32 v168, 0, v144
	v_mul_f32_e64 v144, |v144|, s57
	v_exp_f32_e32 v144, v144
	s_nop 0
	v_add_f32_e32 v144, 1.0, v144
	v_log_f32_e32 v144, v144
	s_nop 0
	v_mul_f32_e32 v194, 0x3f317217, v144
	v_fma_f32 v194, v144, s52, -v194
	v_fmac_f32_e32 v194, 0x3377d1cf, v144
	v_fmac_f32_e32 v194, 0x3f317217, v144
	v_mov_b32_e32 v144, v194
	v_sub_f32_e32 v168, v168, v144
	v_mul_f32_e32 v144, 0x3fb8aa3b, v148
	v_exp_f32_e32 v144, v144
	s_nop 0
	v_fma_f32 v144, v183, v144, v132
	v_cmp_gt_f32_e64 s[40:41], s97, v144
	s_nop 1
	v_cndmask_b32_e64 v194, 0, 32, s[40:41]
	v_ldexp_f32 v144, v144, v194
	v_log_f32_e32 v144, v144
	s_nop 0
	v_mul_f32_e32 v194, 0x3f317217, v144
	v_fma_f32 v194, v144, s52, -v194
	v_fmac_f32_e32 v194, 0x3377d1cf, v144
	v_fmac_f32_e32 v194, 0x3f317217, v144
	v_mov_b32_e32 v144, v194
	v_cndmask_b32_e64 v194, 0, v216, s[40:41]
	v_sub_f32_e32 v144, v144, v194
	v_cndmask_b32_e64 v144, v148, v144, s[20:21]
	v_mul_f32_e32 v148, 0x3fb8aa3b, v168
	v_exp_f32_e32 v148, v148
	s_nop 0
	v_fma_f32 v148, v182, v148, v128
	v_cmp_gt_f32_e64 s[40:41], s97, v148
	s_nop 1
	v_cndmask_b32_e64 v194, 0, 32, s[40:41]
	v_ldexp_f32 v148, v148, v194
	v_log_f32_e32 v148, v148
	s_nop 0
	v_mul_f32_e32 v194, 0x3f317217, v148
	v_fma_f32 v194, v148, s52, -v194
	v_fmac_f32_e32 v194, 0x3377d1cf, v148
	v_fmac_f32_e32 v194, 0x3f317217, v148
	v_mov_b32_e32 v148, v194
	v_cndmask_b32_e64 v194, 0, v216, s[40:41]
	v_sub_f32_e32 v148, v148, v194
	v_cndmask_b32_e64 v148, v168, v148, s[18:19]
	v_min_f32_e32 v168, 0, v149
	v_mul_f32_e64 v149, |v149|, s57
	v_exp_f32_e32 v149, v149
	s_nop 0
	v_add_f32_e32 v149, 1.0, v149
	v_log_f32_e32 v149, v149
	s_nop 0
	v_mul_f32_e32 v194, 0x3f317217, v149
	v_fma_f32 v194, v149, s52, -v194
	v_fmac_f32_e32 v194, 0x3377d1cf, v149
	v_fmac_f32_e32 v194, 0x3f317217, v149
	v_mov_b32_e32 v149, v194
	v_sub_f32_e32 v149, v168, v149
	v_min_f32_e32 v168, 0, v145
	v_mul_f32_e64 v145, |v145|, s57
	v_exp_f32_e32 v145, v145
	s_nop 0
	v_add_f32_e32 v145, 1.0, v145
	v_log_f32_e32 v145, v145
	s_nop 0
	v_mul_f32_e32 v194, 0x3f317217, v145
	v_fma_f32 v194, v145, s52, -v194
	v_fmac_f32_e32 v194, 0x3377d1cf, v145
	v_fmac_f32_e32 v194, 0x3f317217, v145
	v_mov_b32_e32 v145, v194
	v_sub_f32_e32 v168, v168, v145
	v_mul_f32_e32 v145, 0x3fb8aa3b, v149
	v_exp_f32_e32 v145, v145
	s_nop 0
	v_fma_f32 v145, v181, v145, v133
	v_cmp_gt_f32_e64 s[40:41], s97, v145
	s_nop 1
	v_cndmask_b32_e64 v194, 0, 32, s[40:41]
	v_ldexp_f32 v145, v145, v194
	v_log_f32_e32 v145, v145
	s_nop 0
	v_mul_f32_e32 v194, 0x3f317217, v145
	v_fma_f32 v194, v145, s52, -v194
	v_fmac_f32_e32 v194, 0x3377d1cf, v145
	v_fmac_f32_e32 v194, 0x3f317217, v145
	v_mov_b32_e32 v145, v194
; __device__ __forceinline__ float silu_f(float x) { return x * __builtin_amdgcn_rcpf(1.f + __expf(-x)); }
; __device__ __forceinline__ v4u pack8(const f32x4 a, const f32x4 b) { v4u w; w.x = cvt_pk_bf16(a[0], a[1]); w.y = cvt_pk_bf16(a[2], a[3]); w.z = cvt_pk_bf16(b[0], b[1]); w.w = cvt_pk_bf16(b[2], b[3]); return w; }
;     __device__ __forceinline__ void operator()(const f32x4 (&acc)[2][2][4][2], const pg8::Unit& u, int wr, int wc, int fr, int fq) const {
;     ...
;         if (grp == 0) { WIN_LOOP( _Pragma("unroll") for (int i = 0; i < 4; ++i) { a[i] = silu_f(a[i]); b[i] = silu_f(b[i]); } *(v4u*)(QO + (size_t)row * DM + c) = pack8(a, b); ) }
;         else if (grp == 3) { WIN_LOOP( _Pragma("unroll") for (int i = 0; i < 4; ++i) { a[i] = silu_f(a[i]); b[i] = silu_f(b[i]); } *(v4u*)(GH + (size_t)row * 512 + c) = pack8(a, b); ) }
;         else if (grp == 1) {
;             f32x4 l0[2], l1[2];
; #pragma unroll
;             for (int bj = 0; bj < 2; ++bj) { l0[bj] = *(const f32x4*)(lb + cb + bj * 128); l1[bj] = *(const f32x4*)(lb + cb + bj * 128 + 4); }
;             WIN_LOOP( _Pragma("unroll") for (int i = 0; i < 4; ++i) { const float s0 = fminf(a[i], 0.f) - __logf(1.f + __expf(-fabsf(a[i]))), s1 = fminf(b[i], 0.f) - __logf(1.f + __expf(-fabsf(b[i]))); const float la = l0[bj][i], lbv = l1[bj][i];
;                     a[i] = la > 0.f ? __logf(la + (1.f - la) * __expf(s0)) : s0; b[i] = lbv > 0.f ? __logf(lbv + (1.f - lbv) * __expf(s1)) : s1; }
;                 *(f32x4*)(LF + (size_t)row * 512 + c) = a; *(f32x4*)(LF + (size_t)row * 512 + c + 4) = b; __builtin_amdgcn_sched_barrier(0); ) }
	v_cndmask_b32_e64 v194, 0, v216, s[40:41]
	v_sub_f32_e32 v145, v145, v194
	v_cndmask_b32_e64 v145, v149, v145, s[16:17]
	v_mul_f32_e32 v149, 0x3fb8aa3b, v168
	v_exp_f32_e32 v149, v149
	s_nop 0
	v_fma_f32 v149, v180, v149, v129
	v_cmp_gt_f32_e64 s[40:41], s97, v149
	s_nop 1
	v_cndmask_b32_e64 v194, 0, 32, s[40:41]
	v_ldexp_f32 v149, v149, v194
	v_log_f32_e32 v149, v149
	s_nop 0
	v_mul_f32_e32 v194, 0x3f317217, v149
	v_fma_f32 v194, v149, s52, -v194
	v_fmac_f32_e32 v194, 0x3377d1cf, v149
	v_fmac_f32_e32 v194, 0x3f317217, v149
	v_mov_b32_e32 v149, v194
	v_cndmask_b32_e64 v194, 0, v216, s[40:41]
	v_sub_f32_e32 v149, v149, v194
	v_cndmask_b32_e64 v149, v168, v149, s[14:15]
	v_min_f32_e32 v168, 0, v150
	v_mul_f32_e64 v150, |v150|, s57
	v_exp_f32_e32 v150, v150
	s_nop 0
	v_add_f32_e32 v150, 1.0, v150
	v_log_f32_e32 v150, v150
	s_nop 0
	v_mul_f32_e32 v194, 0x3f317217, v150
	v_fma_f32 v194, v150, s52, -v194
	v_fmac_f32_e32 v194, 0x3377d1cf, v150
	v_fmac_f32_e32 v194, 0x3f317217, v150
	v_mov_b32_e32 v150, v194
	v_sub_f32_e32 v150, v168, v150
	v_min_f32_e32 v168, 0, v146
	v_mul_f32_e64 v146, |v146|, s57
	v_exp_f32_e32 v146, v146
	s_nop 0
	v_add_f32_e32 v146, 1.0, v146
	v_log_f32_e32 v146, v146
	s_nop 0
	v_mul_f32_e32 v194, 0x3f317217, v146
	v_fma_f32 v194, v146, s52, -v194
	v_fmac_f32_e32 v194, 0x3377d1cf, v146
	v_fmac_f32_e32 v194, 0x3f317217, v146
	v_mov_b32_e32 v146, v194
	v_sub_f32_e32 v168, v168, v146
	v_mul_f32_e32 v146, 0x3fb8aa3b, v150
	v_exp_f32_e32 v146, v146
	s_nop 0
	v_fma_f32 v146, v179, v146, v134
	v_cmp_gt_f32_e64 s[40:41], s97, v146
	s_nop 1
	v_cndmask_b32_e64 v194, 0, 32, s[40:41]
	v_ldexp_f32 v146, v146, v194
	v_log_f32_e32 v146, v146
	s_nop 0
	v_mul_f32_e32 v194, 0x3f317217, v146
	v_fma_f32 v194, v146, s52, -v194
	v_fmac_f32_e32 v194, 0x3377d1cf, v146
	v_fmac_f32_e32 v194, 0x3f317217, v146
	v_mov_b32_e32 v146, v194
	v_cndmask_b32_e64 v194, 0, v216, s[40:41]
	v_sub_f32_e32 v146, v146, v194
	v_cndmask_b32_e64 v146, v150, v146, s[12:13]
	v_mul_f32_e32 v150, 0x3fb8aa3b, v168
	v_exp_f32_e32 v150, v150
	s_nop 0
	v_fma_f32 v150, v178, v150, v130
	v_cmp_gt_f32_e64 s[40:41], s97, v150
	s_nop 1
	v_cndmask_b32_e64 v194, 0, 32, s[40:41]
	v_ldexp_f32 v150, v150, v194
	v_log_f32_e32 v150, v150
	s_nop 0
	v_mul_f32_e32 v194, 0x3f317217, v150
	v_fma_f32 v194, v150, s52, -v194
	v_fmac_f32_e32 v194, 0x3377d1cf, v150
	v_fmac_f32_e32 v194, 0x3f317217, v150
	v_mov_b32_e32 v150, v194
	v_cndmask_b32_e64 v194, 0, v216, s[40:41]
	v_sub_f32_e32 v150, v150, v194
	v_cndmask_b32_e64 v150, v168, v150, s[10:11]
	v_min_f32_e32 v168, 0, v151
	v_mul_f32_e64 v151, |v151|, s57
	v_exp_f32_e32 v151, v151
	s_nop 0
	v_add_f32_e32 v151, 1.0, v151
	v_log_f32_e32 v151, v151
	s_nop 0
	v_mul_f32_e32 v194, 0x3f317217, v151
	v_fma_f32 v194, v151, s52, -v194
	v_fmac_f32_e32 v194, 0x3377d1cf, v151
	v_fmac_f32_e32 v194, 0x3f317217, v151
	v_mov_b32_e32 v151, v194
	v_sub_f32_e32 v151, v168, v151
	v_min_f32_e32 v168, 0, v147
	v_mul_f32_e64 v147, |v147|, s57
	v_exp_f32_e32 v147, v147
	s_nop 0
	v_add_f32_e32 v147, 1.0, v147
	v_log_f32_e32 v147, v147
	s_nop 0
	v_mul_f32_e32 v194, 0x3f317217, v147
	v_fma_f32 v194, v147, s52, -v194
	v_fmac_f32_e32 v194, 0x3377d1cf, v147
	v_fmac_f32_e32 v194, 0x3f317217, v147
	v_mov_b32_e32 v147, v194
	v_sub_f32_e32 v168, v168, v147
	v_mul_f32_e32 v147, 0x3fb8aa3b, v151
	v_exp_f32_e32 v147, v147
	s_nop 0
	v_fma_f32 v147, v177, v147, v135
	v_cmp_gt_f32_e64 s[40:41], s97, v147
	s_nop 1
	v_cndmask_b32_e64 v194, 0, 32, s[40:41]
	v_ldexp_f32 v147, v147, v194
	v_log_f32_e32 v147, v147
	s_nop 0
	v_mul_f32_e32 v194, 0x3f317217, v147
	v_fma_f32 v194, v147, s52, -v194
	v_fmac_f32_e32 v194, 0x3377d1cf, v147
	v_fmac_f32_e32 v194, 0x3f317217, v147
	v_mov_b32_e32 v147, v194
	v_cndmask_b32_e64 v194, 0, v216, s[40:41]
	v_sub_f32_e32 v147, v147, v194
	v_cndmask_b32_e64 v147, v151, v147, s[8:9]
	v_mul_f32_e32 v151, 0x3fb8aa3b, v168
	v_exp_f32_e32 v151, v151
	s_nop 0
	v_fma_f32 v151, v167, v151, v131
	v_cmp_gt_f32_e64 s[40:41], s97, v151
	s_nop 1
	v_cndmask_b32_e64 v194, 0, 32, s[40:41]
	v_ldexp_f32 v151, v151, v194
	v_log_f32_e32 v151, v151
	s_nop 0
	v_mul_f32_e32 v194, 0x3f317217, v151
	v_fma_f32 v194, v151, s52, -v194
	v_fmac_f32_e32 v194, 0x3377d1cf, v151
	v_fmac_f32_e32 v194, 0x3f317217, v151
	v_mov_b32_e32 v151, v194
	v_cndmask_b32_e64 v194, 0, v216, s[40:41]
	v_sub_f32_e32 v151, v151, v194
	v_cndmask_b32_e32 v151, v168, v151, vcc
	global_store_dwordx4 v[170:171], v[144:147], off offset:512
	global_store_dwordx4 v[170:171], v[148:151], off offset:528
	s_nop 1
	v_add_u32_e32 v148, 0xa0, v166
	v_ashrrev_i32_e32 v149, 31, v148
	v_lshlrev_b64 v[144:145], 6, v[148:149]
	v_lshl_add_u64 v[144:145], v[160:161], 0, v[144:145]
	s_nop 0
	s_waitcnt lgkmcnt(0)
	s_nop 3
	s_nop 0
	s_nop 1
	s_waitcnt lgkmcnt(0)
	s_nop 1
	s_waitcnt lgkmcnt(0)
; __device__ __forceinline__ float silu_f(float x) { return x * __builtin_amdgcn_rcpf(1.f + __expf(-x)); }
; __device__ __forceinline__ v4u pack8(const f32x4 a, const f32x4 b) { v4u w; w.x = cvt_pk_bf16(a[0], a[1]); w.y = cvt_pk_bf16(a[2], a[3]); w.z = cvt_pk_bf16(b[0], b[1]); w.w = cvt_pk_bf16(b[2], b[3]); return w; }
;     __device__ __forceinline__ void operator()(const f32x4 (&acc)[2][2][4][2], const pg8::Unit& u, int wr, int wc, int fr, int fq) const {
;     ...
;         if (grp == 0) { WIN_LOOP( _Pragma("unroll") for (int i = 0; i < 4; ++i) { a[i] = silu_f(a[i]); b[i] = silu_f(b[i]); } *(v4u*)(QO + (size_t)row * DM + c) = pack8(a, b); ) }
;         else if (grp == 3) { WIN_LOOP( _Pragma("unroll") for (int i = 0; i < 4; ++i) { a[i] = silu_f(a[i]); b[i] = silu_f(b[i]); } *(v4u*)(GH + (size_t)row * 512 + c) = pack8(a, b); ) }
;         else if (grp == 1) {
;             f32x4 l0[2], l1[2];
; #pragma unroll
;             for (int bj = 0; bj < 2; ++bj) { l0[bj] = *(const f32x4*)(lb + cb + bj * 128); l1[bj] = *(const f32x4*)(lb + cb + bj * 128 + 4); }
;             WIN_LOOP( _Pragma("unroll") for (int i = 0; i < 4; ++i) { const float s0 = fminf(a[i], 0.f) - __logf(1.f + __expf(-fabsf(a[i]))), s1 = fminf(b[i], 0.f) - __logf(1.f + __expf(-fabsf(b[i]))); const float la = l0[bj][i], lbv = l1[bj][i];
;                     a[i] = la > 0.f ? __logf(la + (1.f - la) * __expf(s0)) : s0; b[i] = lbv > 0.f ? __logf(lbv + (1.f - lbv) * __expf(s1)) : s1; }
;                 *(f32x4*)(LF + (size_t)row * 512 + c) = a; *(f32x4*)(LF + (size_t)row * 512 + c + 4) = b; __builtin_amdgcn_sched_barrier(0); ) }
	s_nop 1
	v_mov_b32_e32 v168, v241
	v_lshlrev_b64 v[144:145], 11, v[148:149]
	v_lshl_add_u64 v[170:171], s[50:51], 0, v[144:145]
	v_lshl_add_u64 v[170:171], v[170:171], 0, v[192:193]
	v_pk_mul_f32 v[148:149], v[12:13], v[168:169] op_sel_hi:[1,0]
	v_pk_mul_f32 v[144:145], v[8:9], v[168:169] op_sel_hi:[1,0]
	v_min_f32_e32 v194, 0, v148
	v_mul_f32_e64 v148, |v148|, s57
	v_exp_f32_e32 v148, v148
	v_pk_mul_f32 v[150:151], v[14:15], v[168:169] op_sel_hi:[1,0]
	v_pk_mul_f32 v[146:147], v[10:11], v[168:169] op_sel_hi:[1,0]
	v_add_f32_e32 v148, 1.0, v148
	v_log_f32_e32 v148, v148
	s_nop 0
	v_mul_f32_e32 v195, 0x3f317217, v148
	v_fma_f32 v195, v148, s52, -v195
	v_fmac_f32_e32 v195, 0x3377d1cf, v148
	v_fmac_f32_e32 v195, 0x3f317217, v148
	v_mov_b32_e32 v148, v195
	v_sub_f32_e32 v148, v194, v148
	v_min_f32_e32 v194, 0, v144
	v_mul_f32_e64 v144, |v144|, s57
	v_exp_f32_e32 v144, v144
	s_nop 0
	v_add_f32_e32 v144, 1.0, v144
	v_log_f32_e32 v144, v144
	s_nop 0
	v_mul_f32_e32 v195, 0x3f317217, v144
	v_fma_f32 v195, v144, s52, -v195
	v_fmac_f32_e32 v195, 0x3377d1cf, v144
	v_fmac_f32_e32 v195, 0x3f317217, v144
	v_mov_b32_e32 v144, v195
	v_sub_f32_e32 v194, v194, v144
	v_mul_f32_e32 v144, 0x3fb8aa3b, v148
	v_exp_f32_e32 v144, v144
	s_nop 0
	v_fma_f32 v144, v190, v144, v140
	v_cmp_gt_f32_e64 s[40:41], s97, v144
	s_nop 1
	v_cndmask_b32_e64 v195, 0, 32, s[40:41]
	v_ldexp_f32 v144, v144, v195
	v_log_f32_e32 v144, v144
	s_nop 0
	v_mul_f32_e32 v195, 0x3f317217, v144
	v_fma_f32 v195, v144, s52, -v195
	v_fmac_f32_e32 v195, 0x3377d1cf, v144
	v_fmac_f32_e32 v195, 0x3f317217, v144
	v_mov_b32_e32 v144, v195
	v_cndmask_b32_e64 v195, 0, v216, s[40:41]
	v_sub_f32_e32 v144, v144, v195
	v_cndmask_b32_e64 v144, v148, v144, s[38:39]
	v_mul_f32_e32 v148, 0x3fb8aa3b, v194
	v_exp_f32_e32 v148, v148
	s_nop 0
	v_fma_f32 v148, v191, v148, v136
	v_cmp_gt_f32_e64 s[40:41], s97, v148
	s_nop 1
	v_cndmask_b32_e64 v195, 0, 32, s[40:41]
	v_ldexp_f32 v148, v148, v195
	v_log_f32_e32 v148, v148
	s_nop 0
	v_mul_f32_e32 v195, 0x3f317217, v148
	v_fma_f32 v195, v148, s52, -v195
	v_fmac_f32_e32 v195, 0x3377d1cf, v148
	v_fmac_f32_e32 v195, 0x3f317217, v148
	v_mov_b32_e32 v148, v195
	v_cndmask_b32_e64 v195, 0, v216, s[40:41]
	v_sub_f32_e32 v148, v148, v195
	v_cndmask_b32_e64 v148, v194, v148, s[36:37]
	v_min_f32_e32 v194, 0, v149
	v_mul_f32_e64 v149, |v149|, s57
	v_exp_f32_e32 v149, v149
	s_nop 0
	v_add_f32_e32 v149, 1.0, v149
	v_log_f32_e32 v149, v149
	s_nop 0
	v_mul_f32_e32 v195, 0x3f317217, v149
	v_fma_f32 v195, v149, s52, -v195
	v_fmac_f32_e32 v195, 0x3377d1cf, v149
	v_fmac_f32_e32 v195, 0x3f317217, v149
	v_mov_b32_e32 v149, v195
	v_sub_f32_e32 v149, v194, v149
	v_min_f32_e32 v194, 0, v145
	v_mul_f32_e64 v145, |v145|, s57
	v_exp_f32_e32 v145, v145
	s_nop 0
	v_add_f32_e32 v145, 1.0, v145
	v_log_f32_e32 v145, v145
	s_nop 0
	v_mul_f32_e32 v195, 0x3f317217, v145
	v_fma_f32 v195, v145, s52, -v195
	v_fmac_f32_e32 v195, 0x3377d1cf, v145
	v_fmac_f32_e32 v195, 0x3f317217, v145
	v_mov_b32_e32 v145, v195
	v_sub_f32_e32 v194, v194, v145
	v_mul_f32_e32 v145, 0x3fb8aa3b, v149
	v_exp_f32_e32 v145, v145
	s_nop 0
	v_fma_f32 v145, v188, v145, v141
	v_cmp_gt_f32_e64 s[40:41], s97, v145
	s_nop 1
	v_cndmask_b32_e64 v195, 0, 32, s[40:41]
	v_ldexp_f32 v145, v145, v195
	v_log_f32_e32 v145, v145
	s_nop 0
	v_mul_f32_e32 v195, 0x3f317217, v145
	v_fma_f32 v195, v145, s52, -v195
	v_fmac_f32_e32 v195, 0x3377d1cf, v145
	v_fmac_f32_e32 v195, 0x3f317217, v145
	v_mov_b32_e32 v145, v195
	v_cndmask_b32_e64 v195, 0, v216, s[40:41]
	v_sub_f32_e32 v145, v145, v195
	v_cndmask_b32_e64 v145, v149, v145, s[34:35]
	v_mul_f32_e32 v149, 0x3fb8aa3b, v194
	v_exp_f32_e32 v149, v149
	s_nop 0
	v_fma_f32 v149, v189, v149, v137
	v_cmp_gt_f32_e64 s[40:41], s97, v149
	s_nop 1
	v_cndmask_b32_e64 v195, 0, 32, s[40:41]
	v_ldexp_f32 v149, v149, v195
	v_log_f32_e32 v149, v149
	s_nop 0
	v_mul_f32_e32 v195, 0x3f317217, v149
	v_fma_f32 v195, v149, s52, -v195
	v_fmac_f32_e32 v195, 0x3377d1cf, v149
	v_fmac_f32_e32 v195, 0x3f317217, v149
	v_mov_b32_e32 v149, v195
	v_cndmask_b32_e64 v195, 0, v216, s[40:41]
	v_sub_f32_e32 v149, v149, v195
	v_cndmask_b32_e64 v149, v194, v149, s[30:31]
	v_min_f32_e32 v194, 0, v150
	v_mul_f32_e64 v150, |v150|, s57
	v_exp_f32_e32 v150, v150
	s_nop 0
	v_add_f32_e32 v150, 1.0, v150
	v_log_f32_e32 v150, v150
	s_nop 0
	v_mul_f32_e32 v195, 0x3f317217, v150
	v_fma_f32 v195, v150, s52, -v195
	v_fmac_f32_e32 v195, 0x3377d1cf, v150
	v_fmac_f32_e32 v195, 0x3f317217, v150
	v_mov_b32_e32 v150, v195
	v_sub_f32_e32 v150, v194, v150
	v_min_f32_e32 v194, 0, v146
	v_mul_f32_e64 v146, |v146|, s57
	v_exp_f32_e32 v146, v146
	s_nop 0
	v_add_f32_e32 v146, 1.0, v146
	v_log_f32_e32 v146, v146
	s_nop 0
	v_mul_f32_e32 v195, 0x3f317217, v146
	v_fma_f32 v195, v146, s52, -v195
	v_fmac_f32_e32 v195, 0x3377d1cf, v146
	v_fmac_f32_e32 v195, 0x3f317217, v146
	v_mov_b32_e32 v146, v195
	v_sub_f32_e32 v194, v194, v146
	v_mul_f32_e32 v146, 0x3fb8aa3b, v150
	v_exp_f32_e32 v146, v146
	s_nop 0
	v_fma_f32 v146, v187, v146, v142
	v_cmp_gt_f32_e64 s[40:41], s97, v146
	s_nop 1
	v_cndmask_b32_e64 v195, 0, 32, s[40:41]
	v_ldexp_f32 v146, v146, v195
	v_log_f32_e32 v146, v146
	s_nop 0
	v_mul_f32_e32 v195, 0x3f317217, v146
	v_fma_f32 v195, v146, s52, -v195
	v_fmac_f32_e32 v195, 0x3377d1cf, v146
	v_fmac_f32_e32 v195, 0x3f317217, v146
	v_mov_b32_e32 v146, v195
	v_cndmask_b32_e64 v195, 0, v216, s[40:41]
	v_sub_f32_e32 v146, v146, v195
	v_cndmask_b32_e64 v146, v150, v146, s[28:29]
	v_mul_f32_e32 v150, 0x3fb8aa3b, v194
	v_exp_f32_e32 v150, v150
	s_nop 0
	v_fma_f32 v150, v186, v150, v138
	v_cmp_gt_f32_e64 s[40:41], s97, v150
	s_nop 1
	v_cndmask_b32_e64 v195, 0, 32, s[40:41]
; __device__ __forceinline__ float silu_f(float x) { return x * __builtin_amdgcn_rcpf(1.f + __expf(-x)); }
; __device__ __forceinline__ v4u pack8(const f32x4 a, const f32x4 b) { v4u w; w.x = cvt_pk_bf16(a[0], a[1]); w.y = cvt_pk_bf16(a[2], a[3]); w.z = cvt_pk_bf16(b[0], b[1]); w.w = cvt_pk_bf16(b[2], b[3]); return w; }
;     __device__ __forceinline__ void operator()(const f32x4 (&acc)[2][2][4][2], const pg8::Unit& u, int wr, int wc, int fr, int fq) const {
;     ...
;         if (grp == 0) { WIN_LOOP( _Pragma("unroll") for (int i = 0; i < 4; ++i) { a[i] = silu_f(a[i]); b[i] = silu_f(b[i]); } *(v4u*)(QO + (size_t)row * DM + c) = pack8(a, b); ) }
;         else if (grp == 3) { WIN_LOOP( _Pragma("unroll") for (int i = 0; i < 4; ++i) { a[i] = silu_f(a[i]); b[i] = silu_f(b[i]); } *(v4u*)(GH + (size_t)row * 512 + c) = pack8(a, b); ) }
;         else if (grp == 1) {
;             f32x4 l0[2], l1[2];
; #pragma unroll
;             for (int bj = 0; bj < 2; ++bj) { l0[bj] = *(const f32x4*)(lb + cb + bj * 128); l1[bj] = *(const f32x4*)(lb + cb + bj * 128 + 4); }
;             WIN_LOOP( _Pragma("unroll") for (int i = 0; i < 4; ++i) { const float s0 = fminf(a[i], 0.f) - __logf(1.f + __expf(-fabsf(a[i]))), s1 = fminf(b[i], 0.f) - __logf(1.f + __expf(-fabsf(b[i]))); const float la = l0[bj][i], lbv = l1[bj][i];
;                     a[i] = la > 0.f ? __logf(la + (1.f - la) * __expf(s0)) : s0; b[i] = lbv > 0.f ? __logf(lbv + (1.f - lbv) * __expf(s1)) : s1; }
;                 *(f32x4*)(LF + (size_t)row * 512 + c) = a; *(f32x4*)(LF + (size_t)row * 512 + c + 4) = b; __builtin_amdgcn_sched_barrier(0); ) }
	v_ldexp_f32 v150, v150, v195
	v_log_f32_e32 v150, v150
	s_nop 0
	v_mul_f32_e32 v195, 0x3f317217, v150
	v_fma_f32 v195, v150, s52, -v195
	v_fmac_f32_e32 v195, 0x3377d1cf, v150
	v_fmac_f32_e32 v195, 0x3f317217, v150
	v_mov_b32_e32 v150, v195
	v_cndmask_b32_e64 v195, 0, v216, s[40:41]
	v_sub_f32_e32 v150, v150, v195
	v_cndmask_b32_e64 v150, v194, v150, s[26:27]
	v_min_f32_e32 v194, 0, v151
	v_mul_f32_e64 v151, |v151|, s57
	v_exp_f32_e32 v151, v151
	s_nop 0
	v_add_f32_e32 v151, 1.0, v151
	v_log_f32_e32 v151, v151
	s_nop 0
	v_mul_f32_e32 v195, 0x3f317217, v151
	v_fma_f32 v195, v151, s52, -v195
	v_fmac_f32_e32 v195, 0x3377d1cf, v151
	v_fmac_f32_e32 v195, 0x3f317217, v151
	v_mov_b32_e32 v151, v195
	v_sub_f32_e32 v151, v194, v151
	v_min_f32_e32 v194, 0, v147
	v_mul_f32_e64 v147, |v147|, s57
	v_exp_f32_e32 v147, v147
	s_nop 0
	v_add_f32_e32 v147, 1.0, v147
	v_log_f32_e32 v147, v147
	s_nop 0
	v_mul_f32_e32 v195, 0x3f317217, v147
	v_fma_f32 v195, v147, s52, -v195
	v_fmac_f32_e32 v195, 0x3377d1cf, v147
	v_fmac_f32_e32 v195, 0x3f317217, v147
	v_mov_b32_e32 v147, v195
	v_sub_f32_e32 v194, v194, v147
	v_mul_f32_e32 v147, 0x3fb8aa3b, v151
	v_exp_f32_e32 v147, v147
	s_nop 0
	v_fma_f32 v147, v185, v147, v143
	v_cmp_gt_f32_e64 s[40:41], s97, v147
	s_nop 1
	v_cndmask_b32_e64 v195, 0, 32, s[40:41]
	v_ldexp_f32 v147, v147, v195
	v_log_f32_e32 v147, v147
	s_nop 0
	v_mul_f32_e32 v195, 0x3f317217, v147
	v_fma_f32 v195, v147, s52, -v195
	v_fmac_f32_e32 v195, 0x3377d1cf, v147
	v_fmac_f32_e32 v195, 0x3f317217, v147
	v_mov_b32_e32 v147, v195
	v_cndmask_b32_e64 v195, 0, v216, s[40:41]
	v_sub_f32_e32 v147, v147, v195
	v_cndmask_b32_e64 v147, v151, v147, s[24:25]
	v_mul_f32_e32 v151, 0x3fb8aa3b, v194
	v_exp_f32_e32 v151, v151
	s_nop 0
	v_fma_f32 v151, v184, v151, v139
	v_cmp_gt_f32_e64 s[40:41], s97, v151
	s_nop 1
	v_cndmask_b32_e64 v195, 0, 32, s[40:41]
	v_ldexp_f32 v151, v151, v195
	v_log_f32_e32 v151, v151
	s_nop 0
	v_mul_f32_e32 v195, 0x3f317217, v151
	v_fma_f32 v195, v151, s52, -v195
	v_fmac_f32_e32 v195, 0x3377d1cf, v151
	v_fmac_f32_e32 v195, 0x3f317217, v151
	v_mov_b32_e32 v151, v195
	v_cndmask_b32_e64 v195, 0, v216, s[40:41]
	v_sub_f32_e32 v151, v151, v195
	v_cndmask_b32_e64 v151, v194, v151, s[22:23]
	global_store_dwordx4 v[170:171], v[144:147], off
	global_store_dwordx4 v[170:171], v[148:151], off offset:16
	s_nop 1
	v_pk_mul_f32 v[148:149], v[76:77], v[168:169] op_sel_hi:[1,0]
	v_pk_mul_f32 v[150:151], v[78:79], v[168:169] op_sel_hi:[1,0]
	v_pk_mul_f32 v[146:147], v[74:75], v[168:169] op_sel_hi:[1,0]
	v_pk_mul_f32 v[144:145], v[72:73], v[168:169] op_sel_hi:[1,0]
	v_min_f32_e32 v168, 0, v148
	v_mul_f32_e64 v148, |v148|, s57
	v_exp_f32_e32 v148, v148
	s_nop 0
	v_add_f32_e32 v148, 1.0, v148
	v_log_f32_e32 v148, v148
	s_nop 0
	v_mul_f32_e32 v194, 0x3f317217, v148
	v_fma_f32 v194, v148, s52, -v194
	v_fmac_f32_e32 v194, 0x3377d1cf, v148
	v_fmac_f32_e32 v194, 0x3f317217, v148
	v_mov_b32_e32 v148, v194
	v_sub_f32_e32 v148, v168, v148
	v_min_f32_e32 v168, 0, v144
	v_mul_f32_e64 v144, |v144|, s57
	v_exp_f32_e32 v144, v144
	s_nop 0
	v_add_f32_e32 v144, 1.0, v144
	v_log_f32_e32 v144, v144
	s_nop 0
	v_mul_f32_e32 v194, 0x3f317217, v144
	v_fma_f32 v194, v144, s52, -v194
	v_fmac_f32_e32 v194, 0x3377d1cf, v144
	v_fmac_f32_e32 v194, 0x3f317217, v144
	v_mov_b32_e32 v144, v194
	v_sub_f32_e32 v168, v168, v144
	v_mul_f32_e32 v144, 0x3fb8aa3b, v148
	v_exp_f32_e32 v144, v144
	s_nop 0
	v_fma_f32 v144, v183, v144, v132
	v_cmp_gt_f32_e64 s[40:41], s97, v144
	s_nop 1
	v_cndmask_b32_e64 v194, 0, 32, s[40:41]
	v_ldexp_f32 v144, v144, v194
	v_log_f32_e32 v144, v144
	s_nop 0
	v_mul_f32_e32 v194, 0x3f317217, v144
	v_fma_f32 v194, v144, s52, -v194
	v_fmac_f32_e32 v194, 0x3377d1cf, v144
	v_fmac_f32_e32 v194, 0x3f317217, v144
	v_mov_b32_e32 v144, v194
	v_cndmask_b32_e64 v194, 0, v216, s[40:41]
	v_sub_f32_e32 v144, v144, v194
	v_cndmask_b32_e64 v144, v148, v144, s[20:21]
	v_mul_f32_e32 v148, 0x3fb8aa3b, v168
	v_exp_f32_e32 v148, v148
	s_nop 0
	v_fma_f32 v148, v182, v148, v128
	v_cmp_gt_f32_e64 s[40:41], s97, v148
	s_nop 1
	v_cndmask_b32_e64 v194, 0, 32, s[40:41]
	v_ldexp_f32 v148, v148, v194
	v_log_f32_e32 v148, v148
	s_nop 0
	v_mul_f32_e32 v194, 0x3f317217, v148
	v_fma_f32 v194, v148, s52, -v194
	v_fmac_f32_e32 v194, 0x3377d1cf, v148
	v_fmac_f32_e32 v194, 0x3f317217, v148
	v_mov_b32_e32 v148, v194
	v_cndmask_b32_e64 v194, 0, v216, s[40:41]
	v_sub_f32_e32 v148, v148, v194
	v_cndmask_b32_e64 v148, v168, v148, s[18:19]
	v_min_f32_e32 v168, 0, v149
	v_mul_f32_e64 v149, |v149|, s57
	v_exp_f32_e32 v149, v149
	s_nop 0
	v_add_f32_e32 v149, 1.0, v149
	v_log_f32_e32 v149, v149
	s_nop 0
	v_mul_f32_e32 v194, 0x3f317217, v149
	v_fma_f32 v194, v149, s52, -v194
	v_fmac_f32_e32 v194, 0x3377d1cf, v149
	v_fmac_f32_e32 v194, 0x3f317217, v149
	v_mov_b32_e32 v149, v194
	v_sub_f32_e32 v149, v168, v149
	v_min_f32_e32 v168, 0, v145
	v_mul_f32_e64 v145, |v145|, s57
	v_exp_f32_e32 v145, v145
	s_nop 0
	v_add_f32_e32 v145, 1.0, v145
	v_log_f32_e32 v145, v145
	s_nop 0
	v_mul_f32_e32 v194, 0x3f317217, v145
	v_fma_f32 v194, v145, s52, -v194
	v_fmac_f32_e32 v194, 0x3377d1cf, v145
	v_fmac_f32_e32 v194, 0x3f317217, v145
	v_mov_b32_e32 v145, v194
	v_sub_f32_e32 v168, v168, v145
	v_mul_f32_e32 v145, 0x3fb8aa3b, v149
	v_exp_f32_e32 v145, v145
	s_nop 0
	v_fma_f32 v145, v181, v145, v133
	v_cmp_gt_f32_e64 s[40:41], s97, v145
	s_nop 1
	v_cndmask_b32_e64 v194, 0, 32, s[40:41]
	v_ldexp_f32 v145, v145, v194
	v_log_f32_e32 v145, v145
	s_nop 0
	v_mul_f32_e32 v194, 0x3f317217, v145
	v_fma_f32 v194, v145, s52, -v194
	v_fmac_f32_e32 v194, 0x3377d1cf, v145
	v_fmac_f32_e32 v194, 0x3f317217, v145
	v_mov_b32_e32 v145, v194
; __device__ __forceinline__ float silu_f(float x) { return x * __builtin_amdgcn_rcpf(1.f + __expf(-x)); }
; __device__ __forceinline__ v4u pack8(const f32x4 a, const f32x4 b) { v4u w; w.x = cvt_pk_bf16(a[0], a[1]); w.y = cvt_pk_bf16(a[2], a[3]); w.z = cvt_pk_bf16(b[0], b[1]); w.w = cvt_pk_bf16(b[2], b[3]); return w; }
;     __device__ __forceinline__ void operator()(const f32x4 (&acc)[2][2][4][2], const pg8::Unit& u, int wr, int wc, int fr, int fq) const {
;     ...
;         if (grp == 0) { WIN_LOOP( _Pragma("unroll") for (int i = 0; i < 4; ++i) { a[i] = silu_f(a[i]); b[i] = silu_f(b[i]); } *(v4u*)(QO + (size_t)row * DM + c) = pack8(a, b); ) }
;         else if (grp == 3) { WIN_LOOP( _Pragma("unroll") for (int i = 0; i < 4; ++i) { a[i] = silu_f(a[i]); b[i] = silu_f(b[i]); } *(v4u*)(GH + (size_t)row * 512 + c) = pack8(a, b); ) }
;         else if (grp == 1) {
;             f32x4 l0[2], l1[2];
; #pragma unroll
;             for (int bj = 0; bj < 2; ++bj) { l0[bj] = *(const f32x4*)(lb + cb + bj * 128); l1[bj] = *(const f32x4*)(lb + cb + bj * 128 + 4); }
;             WIN_LOOP( _Pragma("unroll") for (int i = 0; i < 4; ++i) { const float s0 = fminf(a[i], 0.f) - __logf(1.f + __expf(-fabsf(a[i]))), s1 = fminf(b[i], 0.f) - __logf(1.f + __expf(-fabsf(b[i]))); const float la = l0[bj][i], lbv = l1[bj][i];
;                     a[i] = la > 0.f ? __logf(la + (1.f - la) * __expf(s0)) : s0; b[i] = lbv > 0.f ? __logf(lbv + (1.f - lbv) * __expf(s1)) : s1; }
;                 *(f32x4*)(LF + (size_t)row * 512 + c) = a; *(f32x4*)(LF + (size_t)row * 512 + c + 4) = b; __builtin_amdgcn_sched_barrier(0); ) }
	v_cndmask_b32_e64 v194, 0, v216, s[40:41]
	v_sub_f32_e32 v145, v145, v194
	v_cndmask_b32_e64 v145, v149, v145, s[16:17]
	v_mul_f32_e32 v149, 0x3fb8aa3b, v168
	v_exp_f32_e32 v149, v149
	s_nop 0
	v_fma_f32 v149, v180, v149, v129
	v_cmp_gt_f32_e64 s[40:41], s97, v149
	s_nop 1
	v_cndmask_b32_e64 v194, 0, 32, s[40:41]
	v_ldexp_f32 v149, v149, v194
	v_log_f32_e32 v149, v149
	s_nop 0
	v_mul_f32_e32 v194, 0x3f317217, v149
	v_fma_f32 v194, v149, s52, -v194
	v_fmac_f32_e32 v194, 0x3377d1cf, v149
	v_fmac_f32_e32 v194, 0x3f317217, v149
	v_mov_b32_e32 v149, v194
	v_cndmask_b32_e64 v194, 0, v216, s[40:41]
	v_sub_f32_e32 v149, v149, v194
	v_cndmask_b32_e64 v149, v168, v149, s[14:15]
	v_min_f32_e32 v168, 0, v150
	v_mul_f32_e64 v150, |v150|, s57
	v_exp_f32_e32 v150, v150
	s_nop 0
	v_add_f32_e32 v150, 1.0, v150
	v_log_f32_e32 v150, v150
	s_nop 0
	v_mul_f32_e32 v194, 0x3f317217, v150
	v_fma_f32 v194, v150, s52, -v194
	v_fmac_f32_e32 v194, 0x3377d1cf, v150
	v_fmac_f32_e32 v194, 0x3f317217, v150
	v_mov_b32_e32 v150, v194
	v_sub_f32_e32 v150, v168, v150
	v_min_f32_e32 v168, 0, v146
	v_mul_f32_e64 v146, |v146|, s57
	v_exp_f32_e32 v146, v146
	s_nop 0
	v_add_f32_e32 v146, 1.0, v146
	v_log_f32_e32 v146, v146
	s_nop 0
	v_mul_f32_e32 v194, 0x3f317217, v146
	v_fma_f32 v194, v146, s52, -v194
	v_fmac_f32_e32 v194, 0x3377d1cf, v146
	v_fmac_f32_e32 v194, 0x3f317217, v146
	v_mov_b32_e32 v146, v194
	v_sub_f32_e32 v168, v168, v146
	v_mul_f32_e32 v146, 0x3fb8aa3b, v150
	v_exp_f32_e32 v146, v146
	s_nop 0
	v_fma_f32 v146, v179, v146, v134
	v_cmp_gt_f32_e64 s[40:41], s97, v146
	s_nop 1
	v_cndmask_b32_e64 v194, 0, 32, s[40:41]
	v_ldexp_f32 v146, v146, v194
	v_log_f32_e32 v146, v146
	s_nop 0
	v_mul_f32_e32 v194, 0x3f317217, v146
	v_fma_f32 v194, v146, s52, -v194
	v_fmac_f32_e32 v194, 0x3377d1cf, v146
	v_fmac_f32_e32 v194, 0x3f317217, v146
	v_mov_b32_e32 v146, v194
	v_cndmask_b32_e64 v194, 0, v216, s[40:41]
	v_sub_f32_e32 v146, v146, v194
	v_cndmask_b32_e64 v146, v150, v146, s[12:13]
	v_mul_f32_e32 v150, 0x3fb8aa3b, v168
	v_exp_f32_e32 v150, v150
	s_nop 0
	v_fma_f32 v150, v178, v150, v130
	v_cmp_gt_f32_e64 s[40:41], s97, v150
	s_nop 1
	v_cndmask_b32_e64 v194, 0, 32, s[40:41]
	v_ldexp_f32 v150, v150, v194
	v_log_f32_e32 v150, v150
	s_nop 0
	v_mul_f32_e32 v194, 0x3f317217, v150
	v_fma_f32 v194, v150, s52, -v194
	v_fmac_f32_e32 v194, 0x3377d1cf, v150
	v_fmac_f32_e32 v194, 0x3f317217, v150
	v_mov_b32_e32 v150, v194
	v_cndmask_b32_e64 v194, 0, v216, s[40:41]
	v_sub_f32_e32 v150, v150, v194
	v_cndmask_b32_e64 v150, v168, v150, s[10:11]
	v_min_f32_e32 v168, 0, v151
	v_mul_f32_e64 v151, |v151|, s57
	v_exp_f32_e32 v151, v151
	s_nop 0
	v_add_f32_e32 v151, 1.0, v151
	v_log_f32_e32 v151, v151
	s_nop 0
	v_mul_f32_e32 v194, 0x3f317217, v151
	v_fma_f32 v194, v151, s52, -v194
	v_fmac_f32_e32 v194, 0x3377d1cf, v151
	v_fmac_f32_e32 v194, 0x3f317217, v151
	v_mov_b32_e32 v151, v194
	v_sub_f32_e32 v151, v168, v151
	v_min_f32_e32 v168, 0, v147
	v_mul_f32_e64 v147, |v147|, s57
	v_exp_f32_e32 v147, v147
	s_nop 0
	v_add_f32_e32 v147, 1.0, v147
	v_log_f32_e32 v147, v147
	s_nop 0
	v_mul_f32_e32 v194, 0x3f317217, v147
	v_fma_f32 v194, v147, s52, -v194
	v_fmac_f32_e32 v194, 0x3377d1cf, v147
	v_fmac_f32_e32 v194, 0x3f317217, v147
	v_mov_b32_e32 v147, v194
	v_sub_f32_e32 v168, v168, v147
	v_mul_f32_e32 v147, 0x3fb8aa3b, v151
	v_exp_f32_e32 v147, v147
	s_nop 0
	v_fma_f32 v147, v177, v147, v135
	v_cmp_gt_f32_e64 s[40:41], s97, v147
	s_nop 1
	v_cndmask_b32_e64 v194, 0, 32, s[40:41]
	v_ldexp_f32 v147, v147, v194
	v_log_f32_e32 v147, v147
	s_nop 0
	v_mul_f32_e32 v194, 0x3f317217, v147
	v_fma_f32 v194, v147, s52, -v194
	v_fmac_f32_e32 v194, 0x3377d1cf, v147
	v_fmac_f32_e32 v194, 0x3f317217, v147
	v_mov_b32_e32 v147, v194
	v_cndmask_b32_e64 v194, 0, v216, s[40:41]
	v_sub_f32_e32 v147, v147, v194
	v_cndmask_b32_e64 v147, v151, v147, s[8:9]
	v_mul_f32_e32 v151, 0x3fb8aa3b, v168
	v_exp_f32_e32 v151, v151
	s_nop 0
	v_fma_f32 v151, v167, v151, v131
	v_cmp_gt_f32_e64 s[40:41], s97, v151
	s_nop 1
	v_cndmask_b32_e64 v194, 0, 32, s[40:41]
	v_ldexp_f32 v151, v151, v194
	v_log_f32_e32 v151, v151
	s_nop 0
	v_mul_f32_e32 v194, 0x3f317217, v151
	v_fma_f32 v194, v151, s52, -v194
	v_fmac_f32_e32 v194, 0x3377d1cf, v151
	v_fmac_f32_e32 v194, 0x3f317217, v151
	v_mov_b32_e32 v151, v194
	v_cndmask_b32_e64 v194, 0, v216, s[40:41]
	v_sub_f32_e32 v151, v151, v194
	v_cndmask_b32_e32 v151, v168, v151, vcc
	global_store_dwordx4 v[170:171], v[144:147], off offset:512
	global_store_dwordx4 v[170:171], v[148:151], off offset:528
	s_nop 1
	v_add_u32_e32 v148, 0xb0, v166
	v_ashrrev_i32_e32 v149, 31, v148
	v_lshlrev_b64 v[144:145], 6, v[148:149]
	v_lshl_add_u64 v[144:145], v[160:161], 0, v[144:145]
	s_nop 0
	s_waitcnt lgkmcnt(0)
	s_nop 3
	v_lshlrev_b64 v[146:147], 11, v[148:149]
	s_nop 1
	v_lshl_add_u64 v[146:147], s[50:51], 0, v[146:147]
	v_lshl_add_u64 v[146:147], v[146:147], 0, v[192:193]
	s_waitcnt lgkmcnt(0)
	s_nop 1
	s_waitcnt lgkmcnt(0)
; __device__ __forceinline__ float silu_f(float x) { return x * __builtin_amdgcn_rcpf(1.f + __expf(-x)); }
; __device__ __forceinline__ v4u pack8(const f32x4 a, const f32x4 b) { v4u w; w.x = cvt_pk_bf16(a[0], a[1]); w.y = cvt_pk_bf16(a[2], a[3]); w.z = cvt_pk_bf16(b[0], b[1]); w.w = cvt_pk_bf16(b[2], b[3]); return w; }
;     __device__ __forceinline__ void operator()(const f32x4 (&acc)[2][2][4][2], const pg8::Unit& u, int wr, int wc, int fr, int fq) const {
;     ...
;         if (grp == 0) { WIN_LOOP( _Pragma("unroll") for (int i = 0; i < 4; ++i) { a[i] = silu_f(a[i]); b[i] = silu_f(b[i]); } *(v4u*)(QO + (size_t)row * DM + c) = pack8(a, b); ) }
;         else if (grp == 3) { WIN_LOOP( _Pragma("unroll") for (int i = 0; i < 4; ++i) { a[i] = silu_f(a[i]); b[i] = silu_f(b[i]); } *(v4u*)(GH + (size_t)row * 512 + c) = pack8(a, b); ) }
;         else if (grp == 1) {
;             f32x4 l0[2], l1[2];
; #pragma unroll
;             for (int bj = 0; bj < 2; ++bj) { l0[bj] = *(const f32x4*)(lb + cb + bj * 128); l1[bj] = *(const f32x4*)(lb + cb + bj * 128 + 4); }
;             WIN_LOOP( _Pragma("unroll") for (int i = 0; i < 4; ++i) { const float s0 = fminf(a[i], 0.f) - __logf(1.f + __expf(-fabsf(a[i]))), s1 = fminf(b[i], 0.f) - __logf(1.f + __expf(-fabsf(b[i]))); const float la = l0[bj][i], lbv = l1[bj][i];
;                     a[i] = la > 0.f ? __logf(la + (1.f - la) * __expf(s0)) : s0; b[i] = lbv > 0.f ? __logf(lbv + (1.f - lbv) * __expf(s1)) : s1; }
;                 *(f32x4*)(LF + (size_t)row * 512 + c) = a; *(f32x4*)(LF + (size_t)row * 512 + c + 4) = b; __builtin_amdgcn_sched_barrier(0); ) }
	s_nop 1
	v_mov_b32_e32 v144, v245
	s_nop 0
	v_pk_mul_f32 v[170:171], v[4:5], v[144:145] op_sel_hi:[1,0]
	v_pk_mul_f32 v[150:151], v[6:7], v[144:145] op_sel_hi:[1,0]
	v_pk_mul_f32 v[148:149], v[2:3], v[144:145] op_sel_hi:[1,0]
	v_pk_mul_f32 v[168:169], v[0:1], v[144:145] op_sel_hi:[1,0]
	v_min_f32_e32 v145, 0, v170
	v_mul_f32_e64 v170, |v170|, s57
	v_exp_f32_e32 v170, v170
	s_nop 0
	v_add_f32_e32 v170, 1.0, v170
	v_log_f32_e32 v170, v170
	s_nop 0
	v_mul_f32_e32 v194, 0x3f317217, v170
	v_fma_f32 v194, v170, s52, -v194
	v_fmac_f32_e32 v194, 0x3377d1cf, v170
	v_fmac_f32_e32 v194, 0x3f317217, v170
	v_mov_b32_e32 v170, v194
	v_sub_f32_e32 v145, v145, v170
	v_min_f32_e32 v170, 0, v168
	v_mul_f32_e64 v168, |v168|, s57
	v_exp_f32_e32 v168, v168
	s_nop 0
	v_add_f32_e32 v168, 1.0, v168
	v_log_f32_e32 v168, v168
	s_nop 0
	v_mul_f32_e32 v194, 0x3f317217, v168
	v_fma_f32 v194, v168, s52, -v194
	v_fmac_f32_e32 v194, 0x3377d1cf, v168
	v_fmac_f32_e32 v194, 0x3f317217, v168
	v_mov_b32_e32 v168, v194
	v_sub_f32_e32 v168, v170, v168
	v_mul_f32_e32 v170, 0x3fb8aa3b, v145
	v_exp_f32_e32 v170, v170
	s_nop 0
	v_fma_f32 v140, v190, v170, v140
	v_cmp_gt_f32_e64 s[40:41], s97, v140
	s_nop 1
	v_cndmask_b32_e64 v170, 0, 32, s[40:41]
	v_ldexp_f32 v140, v140, v170
	v_log_f32_e32 v140, v140
	s_nop 0
	v_mul_f32_e32 v170, 0x3f317217, v140
	v_fma_f32 v170, v140, s52, -v170
	v_fmac_f32_e32 v170, 0x3377d1cf, v140
	v_fmac_f32_e32 v170, 0x3f317217, v140
	v_mov_b32_e32 v140, v170
	v_cndmask_b32_e64 v170, 0, v216, s[40:41]
	v_sub_f32_e32 v140, v140, v170
	v_cndmask_b32_e64 v140, v145, v140, s[38:39]
	v_mul_f32_e32 v145, 0x3fb8aa3b, v168
	v_exp_f32_e32 v145, v145
	v_readlane_b32 s42, v255, 57
	v_readlane_b32 s43, v255, 58
	v_fma_f32 v136, v191, v145, v136
	v_cmp_gt_f32_e64 s[38:39], s97, v136
	s_nop 1
	v_cndmask_b32_e64 v145, 0, 32, s[38:39]
	v_ldexp_f32 v136, v136, v145
	v_log_f32_e32 v136, v136
	s_nop 0
	v_mul_f32_e32 v145, 0x3f317217, v136
	v_fma_f32 v145, v136, s52, -v145
	v_fmac_f32_e32 v145, 0x3377d1cf, v136
	v_fmac_f32_e32 v145, 0x3f317217, v136
	v_mov_b32_e32 v136, v145
	v_cndmask_b32_e64 v145, 0, v216, s[38:39]
	v_sub_f32_e32 v136, v136, v145
	v_cndmask_b32_e64 v136, v168, v136, s[36:37]
	v_mul_f32_e64 v168, |v171|, s57
	v_exp_f32_e32 v168, v168
	v_min_f32_e32 v145, 0, v171
	s_mov_b32 s40, s2
	v_add_f32_e32 v168, 1.0, v168
	v_log_f32_e32 v168, v168
	s_nop 0
	v_mul_f32_e32 v170, 0x3f317217, v168
	v_fma_f32 v170, v168, s52, -v170
	v_fmac_f32_e32 v170, 0x3377d1cf, v168
	v_fmac_f32_e32 v170, 0x3f317217, v168
	v_mov_b32_e32 v168, v170
	v_sub_f32_e32 v145, v145, v168
	v_min_f32_e32 v168, 0, v169
	v_mul_f32_e64 v169, |v169|, s57
	v_exp_f32_e32 v169, v169
	s_nop 0
	v_add_f32_e32 v169, 1.0, v169
	v_log_f32_e32 v169, v169
	s_nop 0
	v_mul_f32_e32 v170, 0x3f317217, v169
	v_fma_f32 v170, v169, s52, -v170
	v_fmac_f32_e32 v170, 0x3377d1cf, v169
	v_fmac_f32_e32 v170, 0x3f317217, v169
	v_mov_b32_e32 v169, v170
	v_sub_f32_e32 v168, v168, v169
	v_mul_f32_e32 v169, 0x3fb8aa3b, v145
	v_exp_f32_e32 v169, v169
	s_nop 0
	v_fma_f32 v141, v188, v169, v141
	v_cmp_gt_f32_e64 s[36:37], s97, v141
	s_nop 1
	v_cndmask_b32_e64 v169, 0, 32, s[36:37]
	v_ldexp_f32 v141, v141, v169
	v_log_f32_e32 v141, v141
	s_nop 0
	v_mul_f32_e32 v169, 0x3f317217, v141
	v_fma_f32 v169, v141, s52, -v169
	v_fmac_f32_e32 v169, 0x3377d1cf, v141
	v_fmac_f32_e32 v169, 0x3f317217, v141
	v_mov_b32_e32 v141, v169
	v_cndmask_b32_e64 v169, 0, v216, s[36:37]
	v_sub_f32_e32 v141, v141, v169
	v_cndmask_b32_e64 v141, v145, v141, s[34:35]
	v_mul_f32_e32 v145, 0x3fb8aa3b, v168
	v_exp_f32_e32 v145, v145
	v_readlane_b32 s38, v255, 53
	v_readlane_b32 s39, v255, 54
	v_fma_f32 v137, v189, v145, v137
	v_cmp_gt_f32_e64 s[34:35], s97, v137
	s_nop 1
	v_cndmask_b32_e64 v145, 0, 32, s[34:35]
	v_ldexp_f32 v137, v137, v145
	v_log_f32_e32 v137, v137
	s_nop 0
	v_mul_f32_e32 v145, 0x3f317217, v137
	v_fma_f32 v145, v137, s52, -v145
	v_fmac_f32_e32 v145, 0x3377d1cf, v137
	v_fmac_f32_e32 v145, 0x3f317217, v137
	v_mov_b32_e32 v137, v145
	v_cndmask_b32_e64 v145, 0, v216, s[34:35]
	v_sub_f32_e32 v137, v137, v145
	v_min_f32_e32 v145, 0, v150
	v_mul_f32_e64 v150, |v150|, s57
	v_exp_f32_e32 v150, v150
	v_cndmask_b32_e64 v137, v168, v137, s[30:31]
	v_readlane_b32 s36, v255, 51
	v_readlane_b32 s37, v255, 52
	v_add_f32_e32 v150, 1.0, v150
	v_log_f32_e32 v150, v150
	s_nop 0
	v_mul_f32_e32 v168, 0x3f317217, v150
	v_fma_f32 v168, v150, s52, -v168
	v_fmac_f32_e32 v168, 0x3377d1cf, v150
	v_fmac_f32_e32 v168, 0x3f317217, v150
	v_mov_b32_e32 v150, v168
	v_sub_f32_e32 v145, v145, v150
	v_min_f32_e32 v150, 0, v148
	v_mul_f32_e64 v148, |v148|, s57
	v_exp_f32_e32 v148, v148
	s_nop 0
	v_add_f32_e32 v148, 1.0, v148
	v_log_f32_e32 v148, v148
	s_nop 0
	v_mul_f32_e32 v168, 0x3f317217, v148
	v_fma_f32 v168, v148, s52, -v168
	v_fmac_f32_e32 v168, 0x3377d1cf, v148
	v_fmac_f32_e32 v168, 0x3f317217, v148
	v_mov_b32_e32 v148, v168
	v_sub_f32_e32 v148, v150, v148
	v_mul_f32_e32 v150, 0x3fb8aa3b, v145
	v_exp_f32_e32 v150, v150
	s_nop 0
	v_fma_f32 v142, v187, v150, v142
	v_cmp_gt_f32_e64 s[30:31], s97, v142
	s_nop 1
	v_cndmask_b32_e64 v150, 0, 32, s[30:31]
	v_ldexp_f32 v142, v142, v150
	v_log_f32_e32 v142, v142
	s_nop 0
	v_mul_f32_e32 v150, 0x3f317217, v142
	v_fma_f32 v150, v142, s52, -v150
	v_fmac_f32_e32 v150, 0x3377d1cf, v142
	v_fmac_f32_e32 v150, 0x3f317217, v142
	v_mov_b32_e32 v142, v150
	v_cndmask_b32_e64 v150, 0, v216, s[30:31]
	v_sub_f32_e32 v142, v142, v150
	v_cndmask_b32_e64 v142, v145, v142, s[28:29]
	v_mul_f32_e32 v145, 0x3fb8aa3b, v148
	v_exp_f32_e32 v145, v145
	v_readlane_b32 s34, v255, 49
	v_readlane_b32 s35, v255, 50
	v_fma_f32 v138, v186, v145, v138
	v_cmp_gt_f32_e64 s[28:29], s97, v138
; __device__ __forceinline__ float silu_f(float x) { return x * __builtin_amdgcn_rcpf(1.f + __expf(-x)); }
; __device__ __forceinline__ v4u pack8(const f32x4 a, const f32x4 b) { v4u w; w.x = cvt_pk_bf16(a[0], a[1]); w.y = cvt_pk_bf16(a[2], a[3]); w.z = cvt_pk_bf16(b[0], b[1]); w.w = cvt_pk_bf16(b[2], b[3]); return w; }
;     __device__ __forceinline__ void operator()(const f32x4 (&acc)[2][2][4][2], const pg8::Unit& u, int wr, int wc, int fr, int fq) const {
;     ...
;         if (grp == 0) { WIN_LOOP( _Pragma("unroll") for (int i = 0; i < 4; ++i) { a[i] = silu_f(a[i]); b[i] = silu_f(b[i]); } *(v4u*)(QO + (size_t)row * DM + c) = pack8(a, b); ) }
;         else if (grp == 3) { WIN_LOOP( _Pragma("unroll") for (int i = 0; i < 4; ++i) { a[i] = silu_f(a[i]); b[i] = silu_f(b[i]); } *(v4u*)(GH + (size_t)row * 512 + c) = pack8(a, b); ) }
;         else if (grp == 1) {
;             f32x4 l0[2], l1[2];
; #pragma unroll
;             for (int bj = 0; bj < 2; ++bj) { l0[bj] = *(const f32x4*)(lb + cb + bj * 128); l1[bj] = *(const f32x4*)(lb + cb + bj * 128 + 4); }
;             WIN_LOOP( _Pragma("unroll") for (int i = 0; i < 4; ++i) { const float s0 = fminf(a[i], 0.f) - __logf(1.f + __expf(-fabsf(a[i]))), s1 = fminf(b[i], 0.f) - __logf(1.f + __expf(-fabsf(b[i]))); const float la = l0[bj][i], lbv = l1[bj][i];
;                     a[i] = la > 0.f ? __logf(la + (1.f - la) * __expf(s0)) : s0; b[i] = lbv > 0.f ? __logf(lbv + (1.f - lbv) * __expf(s1)) : s1; }
;                 *(f32x4*)(LF + (size_t)row * 512 + c) = a; *(f32x4*)(LF + (size_t)row * 512 + c + 4) = b; __builtin_amdgcn_sched_barrier(0); ) }
	s_nop 1
	v_cndmask_b32_e64 v145, 0, 32, s[28:29]
	v_ldexp_f32 v138, v138, v145
	v_log_f32_e32 v138, v138
	s_nop 0
	v_mul_f32_e32 v145, 0x3f317217, v138
	v_fma_f32 v145, v138, s52, -v145
	v_fmac_f32_e32 v145, 0x3377d1cf, v138
	v_fmac_f32_e32 v145, 0x3f317217, v138
	v_mov_b32_e32 v138, v145
	v_cndmask_b32_e64 v145, 0, v216, s[28:29]
	v_sub_f32_e32 v138, v138, v145
	v_cndmask_b32_e64 v138, v148, v138, s[26:27]
	v_mul_f32_e64 v148, |v151|, s57
	v_exp_f32_e32 v148, v148
	v_min_f32_e32 v145, 0, v151
	v_readlane_b32 s30, v255, 47
	v_readlane_b32 s31, v255, 48
	v_add_f32_e32 v148, 1.0, v148
	v_log_f32_e32 v148, v148
	s_nop 0
	v_mul_f32_e32 v150, 0x3f317217, v148
	v_fma_f32 v150, v148, s52, -v150
	v_fmac_f32_e32 v150, 0x3377d1cf, v148
	v_fmac_f32_e32 v150, 0x3f317217, v148
	v_mov_b32_e32 v148, v150
	v_sub_f32_e32 v145, v145, v148
	v_min_f32_e32 v148, 0, v149
	v_mul_f32_e64 v149, |v149|, s57
	v_exp_f32_e32 v149, v149
	s_nop 0
	v_add_f32_e32 v149, 1.0, v149
	v_log_f32_e32 v149, v149
	s_nop 0
	v_mul_f32_e32 v150, 0x3f317217, v149
	v_fma_f32 v150, v149, s52, -v150
	v_fmac_f32_e32 v150, 0x3377d1cf, v149
	v_fmac_f32_e32 v150, 0x3f317217, v149
	v_mov_b32_e32 v149, v150
	v_sub_f32_e32 v148, v148, v149
	v_mul_f32_e32 v149, 0x3fb8aa3b, v145
	v_exp_f32_e32 v149, v149
	s_nop 0
	v_fmac_f32_e32 v143, v185, v149
	v_cmp_gt_f32_e64 s[26:27], s97, v143
	s_nop 1
	v_cndmask_b32_e64 v149, 0, 32, s[26:27]
	v_ldexp_f32 v143, v143, v149
	v_log_f32_e32 v143, v143
	s_nop 0
	v_mul_f32_e32 v149, 0x3f317217, v143
	v_fma_f32 v149, v143, s52, -v149
	v_fmac_f32_e32 v149, 0x3377d1cf, v143
	v_fmac_f32_e32 v149, 0x3f317217, v143
	v_cmp_lt_f32_e64 s[28:29], |v143|, s53
	s_nop 1
	v_cndmask_b32_e64 v143, v143, v149, s[28:29]
	v_cndmask_b32_e64 v149, 0, v216, s[26:27]
	v_sub_f32_e32 v143, v143, v149
	v_cndmask_b32_e64 v143, v145, v143, s[24:25]
	v_mul_f32_e32 v145, 0x3fb8aa3b, v148
	v_exp_f32_e32 v145, v145
	s_mov_b32 s29, s91
	s_mov_b32 s28, s95
	v_fmac_f32_e32 v139, v184, v145
	v_cmp_gt_f32_e64 s[24:25], s97, v139
	s_nop 1
	v_cndmask_b32_e64 v145, 0, 32, s[24:25]
	v_ldexp_f32 v139, v139, v145
	v_log_f32_e32 v139, v139
	s_nop 0
	v_mul_f32_e32 v145, 0x3f317217, v139
	v_fma_f32 v145, v139, s52, -v145
	v_fmac_f32_e32 v145, 0x3377d1cf, v139
	v_fmac_f32_e32 v145, 0x3f317217, v139
	v_cmp_lt_f32_e64 s[26:27], |v139|, s53
	s_nop 1
	v_cndmask_b32_e64 v139, v139, v145, s[26:27]
	v_cndmask_b32_e64 v145, 0, v216, s[24:25]
	v_readlane_b32 s27, v255, 56
	v_readlane_b32 s26, v255, 31
	v_sub_f32_e32 v139, v139, v145
	v_cndmask_b32_e64 v139, v148, v139, s[22:23]
	global_store_dwordx4 v[146:147], v[140:143], off
	global_store_dwordx4 v[146:147], v[136:139], off offset:16
	s_nop 0
	v_pk_mul_f32 v[142:143], v[68:69], v[144:145] op_sel_hi:[1,0]
	v_pk_mul_f32 v[138:139], v[70:71], v[144:145] op_sel_hi:[1,0]
	v_pk_mul_f32 v[136:137], v[66:67], v[144:145] op_sel_hi:[1,0]
	v_pk_mul_f32 v[140:141], v[64:65], v[144:145] op_sel_hi:[1,0]
	v_min_f32_e32 v144, 0, v142
	v_mul_f32_e64 v142, |v142|, s57
	v_exp_f32_e32 v142, v142
	s_nop 0
	v_add_f32_e32 v142, 1.0, v142
	v_log_f32_e32 v142, v142
	s_nop 0
	v_mul_f32_e32 v145, 0x3f317217, v142
	v_fma_f32 v145, v142, s52, -v145
	v_fmac_f32_e32 v145, 0x3377d1cf, v142
	v_fmac_f32_e32 v145, 0x3f317217, v142
	v_mov_b32_e32 v142, v145
	v_sub_f32_e32 v142, v144, v142
	v_min_f32_e32 v144, 0, v140
	v_mul_f32_e64 v140, |v140|, s57
	v_exp_f32_e32 v140, v140
	s_nop 0
	v_add_f32_e32 v140, 1.0, v140
	v_log_f32_e32 v140, v140
	s_nop 0
	v_mul_f32_e32 v145, 0x3f317217, v140
	v_fma_f32 v145, v140, s52, -v145
	v_fmac_f32_e32 v145, 0x3377d1cf, v140
	v_fmac_f32_e32 v145, 0x3f317217, v140
	v_mov_b32_e32 v140, v145
	v_sub_f32_e32 v140, v144, v140
	v_mul_f32_e32 v144, 0x3fb8aa3b, v142
	v_exp_f32_e32 v144, v144
	s_nop 0
	v_fma_f32 v132, v183, v144, v132
	v_cmp_gt_f32_e64 s[22:23], s97, v132
	s_nop 1
	v_cndmask_b32_e64 v144, 0, 32, s[22:23]
	v_ldexp_f32 v132, v132, v144
	v_log_f32_e32 v132, v132
	s_nop 0
	v_mul_f32_e32 v144, 0x3f317217, v132
	v_fma_f32 v144, v132, s52, -v144
	v_fmac_f32_e32 v144, 0x3377d1cf, v132
	v_fmac_f32_e32 v144, 0x3f317217, v132
	v_mov_b32_e32 v132, v144
	v_cndmask_b32_e64 v144, 0, v216, s[22:23]
	v_sub_f32_e32 v132, v132, v144
	v_cndmask_b32_e64 v132, v142, v132, s[20:21]
	v_mul_f32_e32 v142, 0x3fb8aa3b, v140
	v_exp_f32_e32 v142, v142
	s_nop 0
	v_fma_f32 v128, v182, v142, v128
	v_cmp_gt_f32_e64 s[20:21], s97, v128
	s_nop 1
	v_cndmask_b32_e64 v142, 0, 32, s[20:21]
	v_ldexp_f32 v128, v128, v142
	v_log_f32_e32 v128, v128
	s_nop 0
	v_mul_f32_e32 v142, 0x3f317217, v128
	v_fma_f32 v142, v128, s52, -v142
	v_fmac_f32_e32 v142, 0x3377d1cf, v128
	v_fmac_f32_e32 v142, 0x3f317217, v128
	v_mov_b32_e32 v128, v142
	v_cndmask_b32_e64 v142, 0, v216, s[20:21]
	v_sub_f32_e32 v128, v128, v142
	v_mul_f32_e64 v142, |v143|, s57
	v_exp_f32_e32 v142, v142
	v_cndmask_b32_e64 v128, v140, v128, s[18:19]
	v_min_f32_e32 v140, 0, v143
	v_readlane_b32 s23, v255, 55
	v_add_f32_e32 v142, 1.0, v142
	v_log_f32_e32 v142, v142
	s_nop 0
	v_mul_f32_e32 v143, 0x3f317217, v142
	v_fma_f32 v143, v142, s52, -v143
	v_fmac_f32_e32 v143, 0x3377d1cf, v142
	v_fmac_f32_e32 v143, 0x3f317217, v142
	v_mov_b32_e32 v142, v143
	v_sub_f32_e32 v140, v140, v142
	v_min_f32_e32 v142, 0, v141
	v_mul_f32_e64 v141, |v141|, s57
	v_exp_f32_e32 v141, v141
	s_nop 0
	v_add_f32_e32 v141, 1.0, v141
	v_log_f32_e32 v141, v141
	s_nop 0
	v_mul_f32_e32 v143, 0x3f317217, v141
	v_fma_f32 v143, v141, s52, -v143
	v_fmac_f32_e32 v143, 0x3377d1cf, v141
	v_fmac_f32_e32 v143, 0x3f317217, v141
	v_mov_b32_e32 v141, v143
	v_sub_f32_e32 v141, v142, v141
	v_mul_f32_e32 v142, 0x3fb8aa3b, v140
	v_exp_f32_e32 v142, v142
	s_nop 0
	v_fma_f32 v133, v181, v142, v133
; __device__ __forceinline__ float silu_f(float x) { return x * __builtin_amdgcn_rcpf(1.f + __expf(-x)); }
; __device__ __forceinline__ v4u pack8(const f32x4 a, const f32x4 b) { v4u w; w.x = cvt_pk_bf16(a[0], a[1]); w.y = cvt_pk_bf16(a[2], a[3]); w.z = cvt_pk_bf16(b[0], b[1]); w.w = cvt_pk_bf16(b[2], b[3]); return w; }
;     __device__ __forceinline__ void operator()(const f32x4 (&acc)[2][2][4][2], const pg8::Unit& u, int wr, int wc, int fr, int fq) const {
;     ...
;         if (grp == 0) { WIN_LOOP( _Pragma("unroll") for (int i = 0; i < 4; ++i) { a[i] = silu_f(a[i]); b[i] = silu_f(b[i]); } *(v4u*)(QO + (size_t)row * DM + c) = pack8(a, b); ) }
;         else if (grp == 3) { WIN_LOOP( _Pragma("unroll") for (int i = 0; i < 4; ++i) { a[i] = silu_f(a[i]); b[i] = silu_f(b[i]); } *(v4u*)(GH + (size_t)row * 512 + c) = pack8(a, b); ) }
;         else if (grp == 1) {
;             f32x4 l0[2], l1[2];
; #pragma unroll
;             for (int bj = 0; bj < 2; ++bj) { l0[bj] = *(const f32x4*)(lb + cb + bj * 128); l1[bj] = *(const f32x4*)(lb + cb + bj * 128 + 4); }
;             WIN_LOOP( _Pragma("unroll") for (int i = 0; i < 4; ++i) { const float s0 = fminf(a[i], 0.f) - __logf(1.f + __expf(-fabsf(a[i]))), s1 = fminf(b[i], 0.f) - __logf(1.f + __expf(-fabsf(b[i]))); const float la = l0[bj][i], lbv = l1[bj][i];
;                     a[i] = la > 0.f ? __logf(la + (1.f - la) * __expf(s0)) : s0; b[i] = lbv > 0.f ? __logf(lbv + (1.f - lbv) * __expf(s1)) : s1; }
;                 *(f32x4*)(LF + (size_t)row * 512 + c) = a; *(f32x4*)(LF + (size_t)row * 512 + c + 4) = b; __builtin_amdgcn_sched_barrier(0); ) }
	v_cmp_gt_f32_e64 s[18:19], s97, v133
	s_nop 1
	v_cndmask_b32_e64 v142, 0, 32, s[18:19]
	v_ldexp_f32 v133, v133, v142
	v_log_f32_e32 v133, v133
	s_nop 0
	v_mul_f32_e32 v142, 0x3f317217, v133
	v_fma_f32 v142, v133, s52, -v142
	v_fmac_f32_e32 v142, 0x3377d1cf, v133
	v_fmac_f32_e32 v142, 0x3f317217, v133
	v_mov_b32_e32 v133, v142
	v_cndmask_b32_e64 v142, 0, v216, s[18:19]
	v_sub_f32_e32 v133, v133, v142
	v_cndmask_b32_e64 v133, v140, v133, s[16:17]
	v_mul_f32_e32 v140, 0x3fb8aa3b, v141
	v_exp_f32_e32 v140, v140
	s_nop 0
	v_fma_f32 v129, v180, v140, v129
	v_cmp_gt_f32_e64 s[16:17], s97, v129
	s_nop 1
	v_cndmask_b32_e64 v140, 0, 32, s[16:17]
	v_ldexp_f32 v129, v129, v140
	v_log_f32_e32 v129, v129
	s_nop 0
	v_mul_f32_e32 v140, 0x3f317217, v129
	v_fma_f32 v140, v129, s52, -v140
	v_fmac_f32_e32 v140, 0x3377d1cf, v129
	v_fmac_f32_e32 v140, 0x3f317217, v129
	v_mov_b32_e32 v129, v140
	v_cndmask_b32_e64 v140, 0, v216, s[16:17]
	v_sub_f32_e32 v129, v129, v140
	v_min_f32_e32 v140, 0, v138
	v_mul_f32_e64 v138, |v138|, s57
	v_exp_f32_e32 v138, v138
	v_cndmask_b32_e64 v129, v141, v129, s[14:15]
	v_add_f32_e32 v138, 1.0, v138
	v_log_f32_e32 v138, v138
	s_nop 0
	v_mul_f32_e32 v141, 0x3f317217, v138
	v_fma_f32 v141, v138, s52, -v141
	v_fmac_f32_e32 v141, 0x3377d1cf, v138
	v_fmac_f32_e32 v141, 0x3f317217, v138
	v_mov_b32_e32 v138, v141
	v_sub_f32_e32 v138, v140, v138
	v_min_f32_e32 v140, 0, v136
	v_mul_f32_e64 v136, |v136|, s57
	v_exp_f32_e32 v136, v136
	s_nop 0
	v_add_f32_e32 v136, 1.0, v136
	v_log_f32_e32 v136, v136
	s_nop 0
	v_mul_f32_e32 v141, 0x3f317217, v136
	v_fma_f32 v141, v136, s52, -v141
	v_fmac_f32_e32 v141, 0x3377d1cf, v136
	v_fmac_f32_e32 v141, 0x3f317217, v136
	v_mov_b32_e32 v136, v141
	v_sub_f32_e32 v136, v140, v136
	v_mul_f32_e32 v140, 0x3fb8aa3b, v138
	v_exp_f32_e32 v140, v140
	s_nop 0
	v_fma_f32 v134, v179, v140, v134
	v_cmp_gt_f32_e64 s[14:15], s97, v134
	s_nop 1
	v_cndmask_b32_e64 v140, 0, 32, s[14:15]
	v_ldexp_f32 v134, v134, v140
	v_log_f32_e32 v134, v134
	s_nop 0
	v_mul_f32_e32 v140, 0x3f317217, v134
	v_fma_f32 v140, v134, s52, -v140
	v_fmac_f32_e32 v140, 0x3377d1cf, v134
	v_fmac_f32_e32 v140, 0x3f317217, v134
	v_mov_b32_e32 v134, v140
	v_cndmask_b32_e64 v140, 0, v216, s[14:15]
	v_sub_f32_e32 v134, v134, v140
	v_cndmask_b32_e64 v134, v138, v134, s[12:13]
	v_mul_f32_e32 v138, 0x3fb8aa3b, v136
	v_exp_f32_e32 v138, v138
	s_nop 0
	v_fma_f32 v130, v178, v138, v130
	v_cmp_gt_f32_e64 s[12:13], s97, v130
	s_nop 1
	v_cndmask_b32_e64 v138, 0, 32, s[12:13]
	v_ldexp_f32 v130, v130, v138
	v_log_f32_e32 v130, v130
	s_nop 0
	v_mul_f32_e32 v138, 0x3f317217, v130
	v_fma_f32 v138, v130, s52, -v138
	v_fmac_f32_e32 v138, 0x3377d1cf, v130
	v_fmac_f32_e32 v138, 0x3f317217, v130
	v_mov_b32_e32 v130, v138
	v_cndmask_b32_e64 v138, 0, v216, s[12:13]
	v_sub_f32_e32 v130, v130, v138
	v_mul_f32_e64 v138, |v139|, s57
	v_exp_f32_e32 v138, v138
	v_cndmask_b32_e64 v130, v136, v130, s[10:11]
	v_min_f32_e32 v136, 0, v139
	v_add_f32_e32 v138, 1.0, v138
	v_log_f32_e32 v138, v138
	s_nop 0
	v_mul_f32_e32 v139, 0x3f317217, v138
	v_fma_f32 v139, v138, s52, -v139
	v_fmac_f32_e32 v139, 0x3377d1cf, v138
	v_fmac_f32_e32 v139, 0x3f317217, v138
	v_mov_b32_e32 v138, v139
	v_sub_f32_e32 v136, v136, v138
	v_min_f32_e32 v138, 0, v137
	v_mul_f32_e64 v137, |v137|, s57
	v_exp_f32_e32 v137, v137
	s_nop 0
	v_add_f32_e32 v137, 1.0, v137
	v_log_f32_e32 v137, v137
	s_nop 0
	v_mul_f32_e32 v139, 0x3f317217, v137
	v_fma_f32 v139, v137, s52, -v139
	v_fmac_f32_e32 v139, 0x3377d1cf, v137
	v_fmac_f32_e32 v139, 0x3f317217, v137
	v_mov_b32_e32 v137, v139
	v_sub_f32_e32 v137, v138, v137
	v_mul_f32_e32 v138, 0x3fb8aa3b, v136
	v_exp_f32_e32 v138, v138
	s_nop 0
	v_fmac_f32_e32 v135, v177, v138
	v_cmp_gt_f32_e64 s[10:11], s97, v135
	s_nop 1
	v_cndmask_b32_e64 v138, 0, 32, s[10:11]
	v_ldexp_f32 v135, v135, v138
	v_log_f32_e32 v135, v135
	s_nop 0
	v_mul_f32_e32 v138, 0x3f317217, v135
	v_fma_f32 v138, v135, s52, -v138
	v_fmac_f32_e32 v138, 0x3377d1cf, v135
	v_fmac_f32_e32 v138, 0x3f317217, v135
	v_cmp_lt_f32_e64 s[12:13], |v135|, s53
	s_nop 1
	v_cndmask_b32_e64 v135, v135, v138, s[12:13]
	v_cndmask_b32_e64 v138, 0, v216, s[10:11]
	v_sub_f32_e32 v135, v135, v138
	v_cndmask_b32_e64 v135, v136, v135, s[8:9]
	v_mul_f32_e32 v136, 0x3fb8aa3b, v137
	v_exp_f32_e32 v136, v136
	s_nop 0
	v_fmac_f32_e32 v131, v167, v136
	v_cmp_gt_f32_e64 s[8:9], s97, v131
	s_nop 1
	v_cndmask_b32_e64 v136, 0, 32, s[8:9]
	v_ldexp_f32 v131, v131, v136
	v_log_f32_e32 v131, v131
	s_nop 0
	v_mul_f32_e32 v136, 0x3f317217, v131
	v_fma_f32 v136, v131, s52, -v136
	v_fmac_f32_e32 v136, 0x3377d1cf, v131
	v_fmac_f32_e32 v136, 0x3f317217, v131
	v_cmp_lt_f32_e64 s[10:11], |v131|, s53
	s_nop 1
	v_cndmask_b32_e64 v131, v131, v136, s[10:11]
	v_cndmask_b32_e64 v136, 0, v216, s[8:9]
	v_sub_f32_e32 v131, v131, v136
	v_cndmask_b32_e32 v131, v137, v131, vcc
	global_store_dwordx4 v[146:147], v[132:135], off offset:512
	global_store_dwordx4 v[146:147], v[128:131], off offset:528
	s_branch .LBB0_416
; __device__ __forceinline__ float silu_f(float x) { return x * __builtin_amdgcn_rcpf(1.f + __expf(-x)); }
; __device__ __forceinline__ v4u pack8(const f32x4 a, const f32x4 b) { v4u w; w.x = cvt_pk_bf16(a[0], a[1]); w.y = cvt_pk_bf16(a[2], a[3]); w.z = cvt_pk_bf16(b[0], b[1]); w.w = cvt_pk_bf16(b[2], b[3]); return w; }
;     __device__ __forceinline__ void operator()(const f32x4 (&acc)[2][2][4][2], const pg8::Unit& u, int wr, int wc, int fr, int fq) const {
;     ...
;         if (grp == 0) { WIN_LOOP( _Pragma("unroll") for (int i = 0; i < 4; ++i) { a[i] = silu_f(a[i]); b[i] = silu_f(b[i]); } *(v4u*)(QO + (size_t)row * DM + c) = pack8(a, b); ) }
;         else if (grp == 3) { WIN_LOOP( _Pragma("unroll") for (int i = 0; i < 4; ++i) { a[i] = silu_f(a[i]); b[i] = silu_f(b[i]); } *(v4u*)(GH + (size_t)row * 512 + c) = pack8(a, b); ) }
;         else if (grp == 1) {
;             f32x4 l0[2], l1[2];
; #pragma unroll
;             for (int bj = 0; bj < 2; ++bj) { l0[bj] = *(const f32x4*)(lb + cb + bj * 128); l1[bj] = *(const f32x4*)(lb + cb + bj * 128 + 4); }
;             WIN_LOOP( _Pragma("unroll") for (int i = 0; i < 4; ++i) { const float s0 = fminf(a[i], 0.f) - __logf(1.f + __expf(-fabsf(a[i]))), s1 = fminf(b[i], 0.f) - __logf(1.f + __expf(-fabsf(b[i]))); const float la = l0[bj][i], lbv = l1[bj][i];
;                     a[i] = la > 0.f ? __logf(la + (1.f - la) * __expf(s0)) : s0; b[i] = lbv > 0.f ? __logf(lbv + (1.f - lbv) * __expf(s1)) : s1; }
;                 *(f32x4*)(LF + (size_t)row * 512 + c) = a; *(f32x4*)(LF + (size_t)row * 512 + c + 4) = b; __builtin_amdgcn_sched_barrier(0); ) }
.Llf_fast:
	v_ashrrev_i32_e32 v167, 31, v166
	v_lshlrev_b64 v[128:129], 6, v[166:167]
	v_lshl_add_u64 v[128:129], v[160:161], 0, v[128:129]
	s_nop 0
	v_readlane_b32 s8, v255, 35
	v_lshlrev_b32_e32 v192, 2, v176
	v_readlane_b32 s9, v255, 36
	v_and_b32_e32 v133, 64, v215
	v_xor_b32_e32 v132, 16, v215
	v_lshl_add_u64 v[144:145], s[8:9], 0, v[192:193]
	flat_load_dwordx4 v[140:143], v[144:145]
	flat_load_dwordx4 v[136:139], v[144:145] offset:16
	v_add_u32_e32 v134, 64, v133
	v_cmp_lt_i32_e32 vcc, v132, v134
	v_lshlrev_b64 v[146:147], 11, v[166:167]
	v_readlane_b32 s50, v255, 45
	v_cndmask_b32_e32 v132, v215, v132, vcc
	v_lshlrev_b32_e32 v169, 2, v132
	v_readlane_b32 s51, v255, 46
	s_mov_b32 s95, s28
	s_mov_b32 s91, s29
	v_lshl_add_u64 v[170:171], s[50:51], 0, v[146:147]
	v_lshl_add_u64 v[170:171], v[170:171], 0, v[192:193]
	s_waitcnt vmcnt(0) lgkmcnt(0)
	s_nop 3
	v_xor_b32_e32 v130, 32, v215
	s_nop 1
	v_cmp_lt_i32_e32 vcc, v130, v134
	v_sub_f32_e32 v190, 1.0, v140
	v_sub_f32_e32 v191, 1.0, v136
	v_cndmask_b32_e32 v130, v215, v130, vcc
	v_lshlrev_b32_e32 v202, 2, v130
	s_waitcnt lgkmcnt(0)
	s_nop 1
	flat_load_dwordx4 v[132:135], v[144:145] offset:512
	flat_load_dwordx4 v[128:131], v[144:145] offset:528
	v_sub_f32_e32 v188, 1.0, v141
	v_cmp_lt_f32_e64 s[38:39], 0, v140
	v_cmp_lt_f32_e64 s[36:37], 0, v136
	s_waitcnt lgkmcnt(0)
	s_nop 1
	v_mov_b32_e32 v168, v250
	v_sub_f32_e32 v189, 1.0, v137
	v_cmp_lt_f32_e64 s[34:35], 0, v141
	v_cmp_lt_f32_e64 s[30:31], 0, v137
	v_pk_mul_f32 v[144:145], v[60:61], v[168:169] op_sel_hi:[1,0]
	v_pk_mul_f32 v[148:149], v[56:57], v[168:169] op_sel_hi:[1,0]
	v_min_f32_e32 v167, 0, v144
	v_mul_f32_e64 v144, |v144|, s57
	v_min_f32_e32 v177, 0, v148
	v_mul_f32_e64 v148, |v148|, s57
	v_exp_f32_e32 v144, v144
	v_exp_f32_e32 v148, v148
	v_min_f32_e32 v179, 0, v149
	v_mul_f32_e64 v149, |v149|, s57
	v_add_f32_e32 v144, 1.0, v144
	v_exp_f32_e32 v149, v149
	v_add_f32_e32 v148, 1.0, v148
	v_min_f32_e32 v178, 0, v145
	v_mul_f32_e64 v145, |v145|, s57
	v_exp_f32_e32 v145, v145
	v_log_f32_e32 v144, v144
	v_add_f32_e32 v149, 1.0, v149
	v_log_f32_e32 v148, v148
	v_add_f32_e32 v145, 1.0, v145
	v_mul_f32_e32 v183, 0x3f317217, v144
	v_mul_f32_e32 v184, 0x3f317217, v148
	v_fma_f32 v183, v144, s52, -v183
	v_fma_f32 v184, v148, s52, -v184
	v_fmac_f32_e32 v183, 0x3377d1cf, v144
	v_fmac_f32_e32 v184, 0x3377d1cf, v148
	v_fmac_f32_e32 v183, 0x3f317217, v144
	v_log_f32_e32 v145, v145
	v_fmac_f32_e32 v184, 0x3f317217, v148
	v_mov_b32_e32 v144, v183
	v_log_f32_e32 v149, v149
	v_mov_b32_e32 v148, v184
	v_sub_f32_e32 v144, v167, v144
	v_sub_f32_e32 v167, v177, v148
	v_mul_f32_e32 v148, 0x3fb8aa3b, v144
	v_mul_f32_e32 v185, 0x3f317217, v145
	v_mul_f32_e32 v177, 0x3fb8aa3b, v167
	v_exp_f32_e32 v148, v148
	v_mul_f32_e32 v186, 0x3f317217, v149
	v_fma_f32 v185, v145, s52, -v185
	v_exp_f32_e32 v177, v177
	v_fma_f32 v186, v149, s52, -v186
	v_fmac_f32_e32 v185, 0x3377d1cf, v145
	v_fmac_f32_e32 v186, 0x3377d1cf, v149
	v_fmac_f32_e32 v185, 0x3f317217, v145
	v_fmac_f32_e32 v186, 0x3f317217, v149
	v_fma_f32 v148, v190, v148, v140
	v_mov_b32_e32 v145, v185
	v_fma_f32 v177, v191, v177, v136
	v_mov_b32_e32 v149, v186
	v_log_f32_e32 v148, v148
	v_log_f32_e32 v177, v177
	v_sub_f32_e32 v145, v178, v145
	v_mul_f32_e32 v178, 0x3fb8aa3b, v145
	v_mul_f32_e32 v182, 0x3f317217, v148
	v_exp_f32_e32 v178, v178
	v_mul_f32_e32 v183, 0x3f317217, v177
	v_fma_f32 v182, v148, s52, -v182
	v_fma_f32 v183, v177, s52, -v183
	v_fmac_f32_e32 v182, 0x3377d1cf, v148
	v_fmac_f32_e32 v183, 0x3377d1cf, v177
	v_fmac_f32_e32 v182, 0x3f317217, v148
	v_fmac_f32_e32 v183, 0x3f317217, v177
	v_fma_f32 v178, v188, v178, v141
	v_mov_b32_e32 v148, v182
	v_mov_b32_e32 v177, v183
	v_cndmask_b32_e64 v148, v144, v148, s[38:39]
	v_cndmask_b32_e64 v144, v167, v177, s[36:37]
	v_mov_b32_e32 v167, v178
	v_log_f32_e32 v167, v167
	v_sub_f32_e32 v177, v179, v149
	v_mul_f32_e32 v178, 0x3fb8aa3b, v177
	v_exp_f32_e32 v178, v178
	v_mul_f32_e32 v149, 0x3f317217, v167
	v_fma_f32 v149, v167, s52, -v149
	v_fmac_f32_e32 v149, 0x3377d1cf, v167
	v_fmac_f32_e32 v149, 0x3f317217, v167
	v_fma_f32 v178, v189, v178, v137
	v_pk_mul_f32 v[150:151], v[62:63], v[168:169] op_sel_hi:[1,0]
	v_log_f32_e32 v178, v178
	v_mul_f32_e64 v167, |v150|, s57
	v_exp_f32_e32 v167, v167
	v_cndmask_b32_e64 v149, v145, v149, s[34:35]
	v_mul_f32_e32 v145, 0x3f317217, v178
	v_fma_f32 v145, v178, s52, -v145
	v_fmac_f32_e32 v145, 0x3377d1cf, v178
	v_fmac_f32_e32 v145, 0x3f317217, v178
	v_add_f32_e32 v167, 1.0, v167
	v_pk_mul_f32 v[146:147], v[58:59], v[168:169] op_sel_hi:[1,0]
	v_cndmask_b32_e64 v145, v177, v145, s[30:31]
	v_log_f32_e32 v167, v167
	v_mul_f32_e64 v178, |v146|, s57
	v_exp_f32_e32 v178, v178
	v_min_f32_e32 v150, 0, v150
	v_mul_f32_e32 v177, 0x3f317217, v167
	v_fma_f32 v177, v167, s52, -v177
	v_fmac_f32_e32 v177, 0x3377d1cf, v167
	v_fmac_f32_e32 v177, 0x3f317217, v167
	v_add_f32_e32 v178, 1.0, v178
	v_sub_f32_e32 v187, 1.0, v142
	v_mov_b32_e32 v167, v177
	v_sub_f32_e32 v150, v150, v167
	v_log_f32_e32 v178, v178
	v_mul_f32_e32 v177, 0x3fb8aa3b, v150
	v_exp_f32_e32 v177, v177
	v_min_f32_e32 v146, 0, v146
	v_mul_f32_e32 v167, 0x3f317217, v178
	v_fma_f32 v167, v178, s52, -v167
	v_fmac_f32_e32 v167, 0x3377d1cf, v178
	v_fmac_f32_e32 v167, 0x3f317217, v178
	v_fma_f32 v177, v187, v177, v142
	v_sub_f32_e32 v186, 1.0, v138
	v_mov_b32_e32 v167, v167
	v_cmp_lt_f32_e64 s[28:29], 0, v142
	v_cmp_lt_f32_e64 s[26:27], 0, v138
	v_log_f32_e32 v177, v177
	v_sub_f32_e32 v146, v146, v167
	v_mul_f32_e32 v178, 0x3fb8aa3b, v146
	v_exp_f32_e32 v178, v178
	v_mul_f32_e32 v167, 0x3f317217, v177
	v_fma_f32 v167, v177, s52, -v167
	v_fmac_f32_e32 v167, 0x3377d1cf, v177
; __device__ __forceinline__ float silu_f(float x) { return x * __builtin_amdgcn_rcpf(1.f + __expf(-x)); }
; __device__ __forceinline__ v4u pack8(const f32x4 a, const f32x4 b) { v4u w; w.x = cvt_pk_bf16(a[0], a[1]); w.y = cvt_pk_bf16(a[2], a[3]); w.z = cvt_pk_bf16(b[0], b[1]); w.w = cvt_pk_bf16(b[2], b[3]); return w; }
;     __device__ __forceinline__ void operator()(const f32x4 (&acc)[2][2][4][2], const pg8::Unit& u, int wr, int wc, int fr, int fq) const {
;     ...
;         if (grp == 0) { WIN_LOOP( _Pragma("unroll") for (int i = 0; i < 4; ++i) { a[i] = silu_f(a[i]); b[i] = silu_f(b[i]); } *(v4u*)(QO + (size_t)row * DM + c) = pack8(a, b); ) }
;         else if (grp == 3) { WIN_LOOP( _Pragma("unroll") for (int i = 0; i < 4; ++i) { a[i] = silu_f(a[i]); b[i] = silu_f(b[i]); } *(v4u*)(GH + (size_t)row * 512 + c) = pack8(a, b); ) }
;         else if (grp == 1) {
;             f32x4 l0[2], l1[2];
; #pragma unroll
;             for (int bj = 0; bj < 2; ++bj) { l0[bj] = *(const f32x4*)(lb + cb + bj * 128); l1[bj] = *(const f32x4*)(lb + cb + bj * 128 + 4); }
;             WIN_LOOP( _Pragma("unroll") for (int i = 0; i < 4; ++i) { const float s0 = fminf(a[i], 0.f) - __logf(1.f + __expf(-fabsf(a[i]))), s1 = fminf(b[i], 0.f) - __logf(1.f + __expf(-fabsf(b[i]))); const float la = l0[bj][i], lbv = l1[bj][i];
;                     a[i] = la > 0.f ? __logf(la + (1.f - la) * __expf(s0)) : s0; b[i] = lbv > 0.f ? __logf(lbv + (1.f - lbv) * __expf(s1)) : s1; }
;                 *(f32x4*)(LF + (size_t)row * 512 + c) = a; *(f32x4*)(LF + (size_t)row * 512 + c + 4) = b; __builtin_amdgcn_sched_barrier(0); ) }
	v_fmac_f32_e32 v167, 0x3f317217, v177
	v_fma_f32 v178, v186, v178, v138
	v_sub_f32_e32 v185, 1.0, v143
	v_log_f32_e32 v178, v178
	v_mul_f32_e64 v177, |v151|, s57
	v_exp_f32_e32 v177, v177
	v_cndmask_b32_e64 v150, v150, v167, s[28:29]
	v_mul_f32_e32 v167, 0x3f317217, v178
	v_fma_f32 v167, v178, s52, -v167
	v_fmac_f32_e32 v167, 0x3377d1cf, v178
	v_fmac_f32_e32 v167, 0x3f317217, v178
	v_add_f32_e32 v177, 1.0, v177
	v_min_f32_e32 v151, 0, v151
	v_cndmask_b32_e64 v146, v146, v167, s[26:27]
	v_log_f32_e32 v177, v177
	v_mul_f32_e64 v178, |v147|, s57
	v_exp_f32_e32 v178, v178
	v_min_f32_e32 v147, 0, v147
	v_mul_f32_e32 v167, 0x3f317217, v177
	v_fma_f32 v167, v177, s52, -v167
	v_fmac_f32_e32 v167, 0x3377d1cf, v177
	v_fmac_f32_e32 v167, 0x3f317217, v177
	v_add_f32_e32 v178, 1.0, v178
	v_sub_f32_e32 v184, 1.0, v139
	v_mov_b32_e32 v167, v167
	v_sub_f32_e32 v151, v151, v167
	v_log_f32_e32 v178, v178
	v_mul_f32_e32 v177, 0x3fb8aa3b, v151
	v_exp_f32_e32 v177, v177
	v_cmp_lt_f32_e64 s[24:25], 0, v143
	v_mul_f32_e32 v167, 0x3f317217, v178
	v_fma_f32 v167, v178, s52, -v167
	v_fmac_f32_e32 v167, 0x3377d1cf, v178
	v_fmac_f32_e32 v167, 0x3f317217, v178
	v_fma_f32 v177, v185, v177, v143
	v_cmp_lt_f32_e64 s[22:23], 0, v139
	v_mov_b32_e32 v167, v167
	v_log_f32_e32 v177, v177
	v_sub_f32_e32 v147, v147, v167
	v_mul_f32_e32 v178, 0x3fb8aa3b, v147
	v_exp_f32_e32 v178, v178
	v_mul_f32_e32 v167, 0x3f317217, v177
	v_fma_f32 v167, v177, s52, -v167
	v_fmac_f32_e32 v167, 0x3377d1cf, v177
	v_fmac_f32_e32 v167, 0x3f317217, v177
	v_fma_f32 v178, v184, v178, v139
	s_nop 0
	v_log_f32_e32 v178, v178
	v_cndmask_b32_e64 v151, v151, v167, s[24:25]
	v_mul_f32_e32 v167, 0x3f317217, v178
	v_fma_f32 v167, v178, s52, -v167
	v_fmac_f32_e32 v167, 0x3377d1cf, v178
	v_fmac_f32_e32 v167, 0x3f317217, v178
	v_cndmask_b32_e64 v147, v147, v167, s[22:23]
	global_store_dwordx4 v[170:171], v[148:151], off
	global_store_dwordx4 v[170:171], v[144:147], off offset:16
	s_nop 1
	v_pk_mul_f32 v[144:145], v[124:125], v[168:169] op_sel_hi:[1,0]
	v_pk_mul_f32 v[150:151], v[126:127], v[168:169] op_sel_hi:[1,0]
	v_mul_f32_e64 v146, |v144|, s57
	v_exp_f32_e32 v148, v146
	v_pk_mul_f32 v[146:147], v[122:123], v[168:169] op_sel_hi:[1,0]
	v_min_f32_e32 v144, 0, v144
	s_waitcnt vmcnt(0)
	v_sub_f32_e32 v183, 1.0, v132
	v_add_f32_e32 v148, 1.0, v148
	v_sub_f32_e32 v182, 1.0, v128
	v_cmp_lt_f32_e64 s[20:21], 0, v132
	v_log_f32_e32 v167, v148
	v_pk_mul_f32 v[148:149], v[120:121], v[168:169] op_sel_hi:[1,0]
	v_cmp_lt_f32_e64 s[18:19], 0, v128
	v_mul_f32_e64 v168, |v148|, s57
	v_exp_f32_e32 v168, v168
	v_mul_f32_e32 v177, 0x3f317217, v167
	v_fma_f32 v177, v167, s52, -v177
	v_fmac_f32_e32 v177, 0x3377d1cf, v167
	v_fmac_f32_e32 v177, 0x3f317217, v167
	v_add_f32_e32 v168, 1.0, v168
	v_min_f32_e32 v148, 0, v148
	v_mov_b32_e32 v167, v177
	v_sub_f32_e32 v144, v144, v167
	v_log_f32_e32 v168, v168
	v_mul_f32_e32 v177, 0x3fb8aa3b, v144
	v_exp_f32_e32 v177, v177
	v_sub_f32_e32 v181, 1.0, v133
	v_mul_f32_e32 v167, 0x3f317217, v168
	v_fma_f32 v167, v168, s52, -v167
	v_fmac_f32_e32 v167, 0x3377d1cf, v168
	v_fmac_f32_e32 v167, 0x3f317217, v168
	v_sub_f32_e32 v180, 1.0, v129
	v_cmp_lt_f32_e64 s[16:17], 0, v133
	v_mov_b32_e32 v167, v167
	v_fma_f32 v168, v183, v177, v132
	v_cmp_lt_f32_e64 s[14:15], 0, v129
	v_sub_f32_e32 v179, 1.0, v134
	v_log_f32_e32 v168, v168
	v_sub_f32_e32 v148, v148, v167
	v_mul_f32_e32 v177, 0x3fb8aa3b, v148
	v_exp_f32_e32 v177, v177
	v_mul_f32_e32 v167, 0x3f317217, v168
	v_fma_f32 v167, v168, s52, -v167
	v_fmac_f32_e32 v167, 0x3377d1cf, v168
	v_fmac_f32_e32 v167, 0x3f317217, v168
	v_fma_f32 v177, v182, v177, v128
	v_cmp_lt_f32_e64 s[12:13], 0, v134
	v_log_f32_e32 v177, v177
	v_mul_f32_e64 v168, |v145|, s57
	v_exp_f32_e32 v168, v168
	v_cndmask_b32_e64 v144, v144, v167, s[20:21]
	v_mul_f32_e32 v167, 0x3f317217, v177
	v_fma_f32 v167, v177, s52, -v167
	v_fmac_f32_e32 v167, 0x3377d1cf, v177
	v_fmac_f32_e32 v167, 0x3f317217, v177
	v_add_f32_e32 v168, 1.0, v168
	v_min_f32_e32 v145, 0, v145
	v_cndmask_b32_e64 v148, v148, v167, s[18:19]
	v_log_f32_e32 v168, v168
	v_mul_f32_e64 v177, |v149|, s57
	v_exp_f32_e32 v177, v177
	v_min_f32_e32 v149, 0, v149
	v_mul_f32_e32 v167, 0x3f317217, v168
	v_fma_f32 v167, v168, s52, -v167
	v_fmac_f32_e32 v167, 0x3377d1cf, v168
	v_fmac_f32_e32 v167, 0x3f317217, v168
	v_add_f32_e32 v177, 1.0, v177
	v_cmp_lt_f32_e64 s[10:11], 0, v130
	v_mov_b32_e32 v167, v167
	v_sub_f32_e32 v145, v145, v167
	v_log_f32_e32 v177, v177
	v_mul_f32_e32 v168, 0x3fb8aa3b, v145
	v_exp_f32_e32 v168, v168
	s_mov_b32 s2, s40
	v_mul_f32_e32 v167, 0x3f317217, v177
	v_fma_f32 v167, v177, s52, -v167
	v_fmac_f32_e32 v167, 0x3377d1cf, v177
	v_fmac_f32_e32 v167, 0x3f317217, v177
	v_fma_f32 v168, v181, v168, v133
	s_nop 0
	v_mov_b32_e32 v167, v167
	v_log_f32_e32 v168, v168
	v_sub_f32_e32 v149, v149, v167
	v_mul_f32_e32 v177, 0x3fb8aa3b, v149
	v_exp_f32_e32 v177, v177
	v_mul_f32_e32 v167, 0x3f317217, v168
	v_fma_f32 v167, v168, s52, -v167
	v_fmac_f32_e32 v167, 0x3377d1cf, v168
	v_fmac_f32_e32 v167, 0x3f317217, v168
	v_fma_f32 v177, v180, v177, v129
	s_nop 0
	v_log_f32_e32 v177, v177
	v_mul_f32_e64 v168, |v150|, s57
	v_exp_f32_e32 v168, v168
	v_cndmask_b32_e64 v145, v145, v167, s[16:17]
	v_mul_f32_e32 v167, 0x3f317217, v177
	v_fma_f32 v167, v177, s52, -v167
	v_fmac_f32_e32 v167, 0x3377d1cf, v177
	v_fmac_f32_e32 v167, 0x3f317217, v177
	v_add_f32_e32 v168, 1.0, v168
	v_min_f32_e32 v150, 0, v150
	v_cndmask_b32_e64 v149, v149, v167, s[14:15]
	v_log_f32_e32 v168, v168
	v_mul_f32_e64 v177, |v146|, s57
	v_exp_f32_e32 v177, v177
	v_min_f32_e32 v146, 0, v146
	v_mul_f32_e32 v167, 0x3f317217, v168
	v_fma_f32 v167, v168, s52, -v167
; __device__ __forceinline__ float silu_f(float x) { return x * __builtin_amdgcn_rcpf(1.f + __expf(-x)); }
; __device__ __forceinline__ v4u pack8(const f32x4 a, const f32x4 b) { v4u w; w.x = cvt_pk_bf16(a[0], a[1]); w.y = cvt_pk_bf16(a[2], a[3]); w.z = cvt_pk_bf16(b[0], b[1]); w.w = cvt_pk_bf16(b[2], b[3]); return w; }
;     __device__ __forceinline__ void operator()(const f32x4 (&acc)[2][2][4][2], const pg8::Unit& u, int wr, int wc, int fr, int fq) const {
;     ...
;         if (grp == 0) { WIN_LOOP( _Pragma("unroll") for (int i = 0; i < 4; ++i) { a[i] = silu_f(a[i]); b[i] = silu_f(b[i]); } *(v4u*)(QO + (size_t)row * DM + c) = pack8(a, b); ) }
;         else if (grp == 3) { WIN_LOOP( _Pragma("unroll") for (int i = 0; i < 4; ++i) { a[i] = silu_f(a[i]); b[i] = silu_f(b[i]); } *(v4u*)(GH + (size_t)row * 512 + c) = pack8(a, b); ) }
;         else if (grp == 1) {
;             f32x4 l0[2], l1[2];
; #pragma unroll
;             for (int bj = 0; bj < 2; ++bj) { l0[bj] = *(const f32x4*)(lb + cb + bj * 128); l1[bj] = *(const f32x4*)(lb + cb + bj * 128 + 4); }
;             WIN_LOOP( _Pragma("unroll") for (int i = 0; i < 4; ++i) { const float s0 = fminf(a[i], 0.f) - __logf(1.f + __expf(-fabsf(a[i]))), s1 = fminf(b[i], 0.f) - __logf(1.f + __expf(-fabsf(b[i]))); const float la = l0[bj][i], lbv = l1[bj][i];
;                     a[i] = la > 0.f ? __logf(la + (1.f - la) * __expf(s0)) : s0; b[i] = lbv > 0.f ? __logf(lbv + (1.f - lbv) * __expf(s1)) : s1; }
;                 *(f32x4*)(LF + (size_t)row * 512 + c) = a; *(f32x4*)(LF + (size_t)row * 512 + c + 4) = b; __builtin_amdgcn_sched_barrier(0); ) }
	v_fmac_f32_e32 v167, 0x3377d1cf, v168
	v_fmac_f32_e32 v167, 0x3f317217, v168
	v_add_f32_e32 v177, 1.0, v177
	s_nop 0
	v_mov_b32_e32 v167, v167
	v_sub_f32_e32 v150, v150, v167
	v_log_f32_e32 v177, v177
	v_mul_f32_e32 v168, 0x3fb8aa3b, v150
	v_exp_f32_e32 v168, v168
	v_sub_f32_e32 v178, 1.0, v130
	v_mul_f32_e32 v167, 0x3f317217, v177
	v_fma_f32 v167, v177, s52, -v167
	v_fmac_f32_e32 v167, 0x3377d1cf, v177
	v_fmac_f32_e32 v167, 0x3f317217, v177
	v_fma_f32 v168, v179, v168, v134
	s_nop 0
	v_mov_b32_e32 v167, v167
	v_log_f32_e32 v168, v168
	v_sub_f32_e32 v167, v146, v167
	v_mul_f32_e32 v177, 0x3fb8aa3b, v167
	v_exp_f32_e32 v177, v177
	v_mul_f32_e32 v146, 0x3f317217, v168
	v_fma_f32 v146, v168, s52, -v146
	v_fmac_f32_e32 v146, 0x3377d1cf, v168
	v_fmac_f32_e32 v146, 0x3f317217, v168
	v_fma_f32 v177, v178, v177, v130
	s_nop 0
	v_log_f32_e32 v177, v177
	v_mul_f32_e64 v168, |v151|, s57
	v_exp_f32_e32 v168, v168
	v_cndmask_b32_e64 v146, v150, v146, s[12:13]
	v_mul_f32_e32 v150, 0x3f317217, v177
	v_fma_f32 v150, v177, s52, -v150
	v_fmac_f32_e32 v150, 0x3377d1cf, v177
	v_fmac_f32_e32 v150, 0x3f317217, v177
	v_add_f32_e32 v168, 1.0, v168
	v_min_f32_e32 v151, 0, v151
	v_cndmask_b32_e64 v150, v167, v150, s[10:11]
	v_log_f32_e32 v168, v168
	v_mul_f32_e64 v177, |v147|, s57
	v_exp_f32_e32 v177, v177
	v_min_f32_e32 v147, 0, v147
	v_mul_f32_e32 v167, 0x3f317217, v168
	v_fma_f32 v167, v168, s52, -v167
	v_fmac_f32_e32 v167, 0x3377d1cf, v168
	v_fmac_f32_e32 v167, 0x3f317217, v168
	v_add_f32_e32 v177, 1.0, v177
	s_nop 0
	v_mov_b32_e32 v167, v167
	v_sub_f32_e32 v151, v151, v167
	v_log_f32_e32 v177, v177
	v_mul_f32_e32 v168, 0x3fb8aa3b, v151
	v_exp_f32_e32 v168, v168
	v_mul_f32_e32 v167, 0x3f317217, v177
	v_fma_f32 v167, v177, s52, -v167
	v_fmac_f32_e32 v167, 0x3377d1cf, v177
	v_fmac_f32_e32 v167, 0x3f317217, v177
	v_mov_b32_e32 v167, v167
	v_sub_f32_e32 v177, 1.0, v135
	v_fma_f32 v168, v177, v168, v135
	v_log_f32_e32 v168, v168
	v_sub_f32_e32 v194, v147, v167
	v_mul_f32_e32 v167, 0x3fb8aa3b, v194
	v_exp_f32_e32 v195, v167
	v_mul_f32_e32 v147, 0x3f317217, v168
	v_fma_f32 v147, v168, s52, -v147
	v_fmac_f32_e32 v147, 0x3377d1cf, v168
	v_sub_f32_e32 v167, 1.0, v131
	v_fmac_f32_e32 v147, 0x3f317217, v168
	v_fma_f32 v195, v167, v195, v131
	s_nop 0
	v_log_f32_e32 v195, v195
	v_cmp_lt_f32_e64 s[8:9], 0, v135
	v_cmp_lt_f32_e32 vcc, 0, v131
	s_nop 0
	v_cndmask_b32_e64 v147, v151, v147, s[8:9]
	v_mul_f32_e32 v151, 0x3f317217, v195
	v_fma_f32 v151, v195, s52, -v151
	v_fmac_f32_e32 v151, 0x3377d1cf, v195
	v_fmac_f32_e32 v151, 0x3f317217, v195
	v_cndmask_b32_e32 v151, v194, v151, vcc
	global_store_dwordx4 v[170:171], v[144:147], off offset:512
	global_store_dwordx4 v[170:171], v[148:151], off offset:528
	s_nop 1
	v_or_b32_e32 v148, 16, v166
	v_ashrrev_i32_e32 v149, 31, v148
	v_lshlrev_b64 v[144:145], 6, v[148:149]
	v_lshl_add_u64 v[144:145], v[160:161], 0, v[144:145]
	s_nop 0
	s_waitcnt lgkmcnt(0)
	s_nop 3
	s_nop 0
	s_nop 1
	s_waitcnt lgkmcnt(0)
	s_nop 1
	s_waitcnt lgkmcnt(0)
	s_nop 1
	v_mov_b32_e32 v168, v251
	v_lshlrev_b64 v[144:145], 11, v[148:149]
	v_lshl_add_u64 v[170:171], s[50:51], 0, v[144:145]
	v_lshl_add_u64 v[170:171], v[170:171], 0, v[192:193]
	v_pk_mul_f32 v[148:149], v[52:53], v[168:169] op_sel_hi:[1,0]
	v_pk_mul_f32 v[144:145], v[48:49], v[168:169] op_sel_hi:[1,0]
	v_min_f32_e32 v194, 0, v148
	v_mul_f32_e64 v148, |v148|, s57
	v_exp_f32_e32 v148, v148
	v_pk_mul_f32 v[150:151], v[54:55], v[168:169] op_sel_hi:[1,0]
	v_pk_mul_f32 v[146:147], v[50:51], v[168:169] op_sel_hi:[1,0]
	v_add_f32_e32 v148, 1.0, v148
	v_log_f32_e32 v148, v148
	s_nop 0
	v_mul_f32_e32 v195, 0x3f317217, v148
	v_fma_f32 v195, v148, s52, -v195
	v_fmac_f32_e32 v195, 0x3377d1cf, v148
	v_fmac_f32_e32 v195, 0x3f317217, v148
	v_mov_b32_e32 v148, v195
	v_sub_f32_e32 v148, v194, v148
	v_min_f32_e32 v194, 0, v144
	v_mul_f32_e64 v144, |v144|, s57
	v_exp_f32_e32 v144, v144
	s_nop 0
	v_add_f32_e32 v144, 1.0, v144
	v_log_f32_e32 v144, v144
	s_nop 0
	v_mul_f32_e32 v195, 0x3f317217, v144
	v_fma_f32 v195, v144, s52, -v195
	v_fmac_f32_e32 v195, 0x3377d1cf, v144
	v_fmac_f32_e32 v195, 0x3f317217, v144
	v_mov_b32_e32 v144, v195
	v_sub_f32_e32 v194, v194, v144
	v_mul_f32_e32 v144, 0x3fb8aa3b, v148
	v_exp_f32_e32 v144, v144
	s_nop 0
	v_fma_f32 v144, v190, v144, v140
	v_log_f32_e32 v144, v144
	s_nop 0
	v_mul_f32_e32 v195, 0x3f317217, v144
	v_fma_f32 v195, v144, s52, -v195
	v_fmac_f32_e32 v195, 0x3377d1cf, v144
	v_fmac_f32_e32 v195, 0x3f317217, v144
	v_mov_b32_e32 v144, v195
	v_cndmask_b32_e64 v144, v148, v144, s[38:39]
	v_mul_f32_e32 v148, 0x3fb8aa3b, v194
	v_exp_f32_e32 v148, v148
	s_nop 0
	v_fma_f32 v148, v191, v148, v136
	v_log_f32_e32 v148, v148
	s_nop 0
	v_mul_f32_e32 v195, 0x3f317217, v148
	v_fma_f32 v195, v148, s52, -v195
	v_fmac_f32_e32 v195, 0x3377d1cf, v148
	v_fmac_f32_e32 v195, 0x3f317217, v148
	v_mov_b32_e32 v148, v195
	v_cndmask_b32_e64 v148, v194, v148, s[36:37]
	v_min_f32_e32 v194, 0, v149
	v_mul_f32_e64 v149, |v149|, s57
	v_exp_f32_e32 v149, v149
	s_nop 0
	v_add_f32_e32 v149, 1.0, v149
	v_log_f32_e32 v149, v149
	s_nop 0
	v_mul_f32_e32 v195, 0x3f317217, v149
	v_fma_f32 v195, v149, s52, -v195
	v_fmac_f32_e32 v195, 0x3377d1cf, v149
	v_fmac_f32_e32 v195, 0x3f317217, v149
	v_mov_b32_e32 v149, v195
	v_sub_f32_e32 v149, v194, v149
	v_min_f32_e32 v194, 0, v145
	v_mul_f32_e64 v145, |v145|, s57
	v_exp_f32_e32 v145, v145
	s_nop 0
	v_add_f32_e32 v145, 1.0, v145
	v_log_f32_e32 v145, v145
	s_nop 0
	v_mul_f32_e32 v195, 0x3f317217, v145
	v_fma_f32 v195, v145, s52, -v195
	v_fmac_f32_e32 v195, 0x3377d1cf, v145
	v_fmac_f32_e32 v195, 0x3f317217, v145
	v_mov_b32_e32 v145, v195
	v_sub_f32_e32 v194, v194, v145
; __device__ __forceinline__ float silu_f(float x) { return x * __builtin_amdgcn_rcpf(1.f + __expf(-x)); }
; __device__ __forceinline__ v4u pack8(const f32x4 a, const f32x4 b) { v4u w; w.x = cvt_pk_bf16(a[0], a[1]); w.y = cvt_pk_bf16(a[2], a[3]); w.z = cvt_pk_bf16(b[0], b[1]); w.w = cvt_pk_bf16(b[2], b[3]); return w; }
;     __device__ __forceinline__ void operator()(const f32x4 (&acc)[2][2][4][2], const pg8::Unit& u, int wr, int wc, int fr, int fq) const {
;     ...
;         if (grp == 0) { WIN_LOOP( _Pragma("unroll") for (int i = 0; i < 4; ++i) { a[i] = silu_f(a[i]); b[i] = silu_f(b[i]); } *(v4u*)(QO + (size_t)row * DM + c) = pack8(a, b); ) }
;         else if (grp == 3) { WIN_LOOP( _Pragma("unroll") for (int i = 0; i < 4; ++i) { a[i] = silu_f(a[i]); b[i] = silu_f(b[i]); } *(v4u*)(GH + (size_t)row * 512 + c) = pack8(a, b); ) }
;         else if (grp == 1) {
;             f32x4 l0[2], l1[2];
; #pragma unroll
;             for (int bj = 0; bj < 2; ++bj) { l0[bj] = *(const f32x4*)(lb + cb + bj * 128); l1[bj] = *(const f32x4*)(lb + cb + bj * 128 + 4); }
;             WIN_LOOP( _Pragma("unroll") for (int i = 0; i < 4; ++i) { const float s0 = fminf(a[i], 0.f) - __logf(1.f + __expf(-fabsf(a[i]))), s1 = fminf(b[i], 0.f) - __logf(1.f + __expf(-fabsf(b[i]))); const float la = l0[bj][i], lbv = l1[bj][i];
;                     a[i] = la > 0.f ? __logf(la + (1.f - la) * __expf(s0)) : s0; b[i] = lbv > 0.f ? __logf(lbv + (1.f - lbv) * __expf(s1)) : s1; }
;                 *(f32x4*)(LF + (size_t)row * 512 + c) = a; *(f32x4*)(LF + (size_t)row * 512 + c + 4) = b; __builtin_amdgcn_sched_barrier(0); ) }
	v_mul_f32_e32 v145, 0x3fb8aa3b, v149
	v_exp_f32_e32 v145, v145
	s_nop 0
	v_fma_f32 v145, v188, v145, v141
	v_log_f32_e32 v145, v145
	s_nop 0
	v_mul_f32_e32 v195, 0x3f317217, v145
	v_fma_f32 v195, v145, s52, -v195
	v_fmac_f32_e32 v195, 0x3377d1cf, v145
	v_fmac_f32_e32 v195, 0x3f317217, v145
	v_mov_b32_e32 v145, v195
	v_cndmask_b32_e64 v145, v149, v145, s[34:35]
	v_mul_f32_e32 v149, 0x3fb8aa3b, v194
	v_exp_f32_e32 v149, v149
	s_nop 0
	v_fma_f32 v149, v189, v149, v137
	v_log_f32_e32 v149, v149
	s_nop 0
	v_mul_f32_e32 v195, 0x3f317217, v149
	v_fma_f32 v195, v149, s52, -v195
	v_fmac_f32_e32 v195, 0x3377d1cf, v149
	v_fmac_f32_e32 v195, 0x3f317217, v149
	v_mov_b32_e32 v149, v195
	v_cndmask_b32_e64 v149, v194, v149, s[30:31]
	v_min_f32_e32 v194, 0, v150
	v_mul_f32_e64 v150, |v150|, s57
	v_exp_f32_e32 v150, v150
	s_nop 0
	v_add_f32_e32 v150, 1.0, v150
	v_log_f32_e32 v150, v150
	s_nop 0
	v_mul_f32_e32 v195, 0x3f317217, v150
	v_fma_f32 v195, v150, s52, -v195
	v_fmac_f32_e32 v195, 0x3377d1cf, v150
	v_fmac_f32_e32 v195, 0x3f317217, v150
	v_mov_b32_e32 v150, v195
	v_sub_f32_e32 v150, v194, v150
	v_min_f32_e32 v194, 0, v146
	v_mul_f32_e64 v146, |v146|, s57
	v_exp_f32_e32 v146, v146
	s_nop 0
	v_add_f32_e32 v146, 1.0, v146
	v_log_f32_e32 v146, v146
	s_nop 0
	v_mul_f32_e32 v195, 0x3f317217, v146
	v_fma_f32 v195, v146, s52, -v195
	v_fmac_f32_e32 v195, 0x3377d1cf, v146
	v_fmac_f32_e32 v195, 0x3f317217, v146
	v_mov_b32_e32 v146, v195
	v_sub_f32_e32 v194, v194, v146
	v_mul_f32_e32 v146, 0x3fb8aa3b, v150
	v_exp_f32_e32 v146, v146
	s_nop 0
	v_fma_f32 v146, v187, v146, v142
	v_log_f32_e32 v146, v146
	s_nop 0
	v_mul_f32_e32 v195, 0x3f317217, v146
	v_fma_f32 v195, v146, s52, -v195
	v_fmac_f32_e32 v195, 0x3377d1cf, v146
	v_fmac_f32_e32 v195, 0x3f317217, v146
	v_mov_b32_e32 v146, v195
	v_cndmask_b32_e64 v146, v150, v146, s[28:29]
	v_mul_f32_e32 v150, 0x3fb8aa3b, v194
	v_exp_f32_e32 v150, v150
	s_nop 0
	v_fma_f32 v150, v186, v150, v138
	v_log_f32_e32 v150, v150
	s_nop 0
	v_mul_f32_e32 v195, 0x3f317217, v150
	v_fma_f32 v195, v150, s52, -v195
	v_fmac_f32_e32 v195, 0x3377d1cf, v150
	v_fmac_f32_e32 v195, 0x3f317217, v150
	v_mov_b32_e32 v150, v195
	v_cndmask_b32_e64 v150, v194, v150, s[26:27]
	v_min_f32_e32 v194, 0, v151
	v_mul_f32_e64 v151, |v151|, s57
	v_exp_f32_e32 v151, v151
	s_nop 0
	v_add_f32_e32 v151, 1.0, v151
	v_log_f32_e32 v151, v151
	s_nop 0
	v_mul_f32_e32 v195, 0x3f317217, v151
	v_fma_f32 v195, v151, s52, -v195
	v_fmac_f32_e32 v195, 0x3377d1cf, v151
	v_fmac_f32_e32 v195, 0x3f317217, v151
	v_mov_b32_e32 v151, v195
	v_sub_f32_e32 v151, v194, v151
	v_min_f32_e32 v194, 0, v147
	v_mul_f32_e64 v147, |v147|, s57
	v_exp_f32_e32 v147, v147
	s_nop 0
	v_add_f32_e32 v147, 1.0, v147
	v_log_f32_e32 v147, v147
	s_nop 0
	v_mul_f32_e32 v195, 0x3f317217, v147
	v_fma_f32 v195, v147, s52, -v195
	v_fmac_f32_e32 v195, 0x3377d1cf, v147
	v_fmac_f32_e32 v195, 0x3f317217, v147
	v_mov_b32_e32 v147, v195
	v_sub_f32_e32 v194, v194, v147
	v_mul_f32_e32 v147, 0x3fb8aa3b, v151
	v_exp_f32_e32 v147, v147
	s_nop 0
	v_fma_f32 v147, v185, v147, v143
	v_log_f32_e32 v147, v147
	s_nop 0
	v_mul_f32_e32 v195, 0x3f317217, v147
	v_fma_f32 v195, v147, s52, -v195
	v_fmac_f32_e32 v195, 0x3377d1cf, v147
	v_fmac_f32_e32 v195, 0x3f317217, v147
	v_mov_b32_e32 v147, v195
	v_cndmask_b32_e64 v147, v151, v147, s[24:25]
	v_mul_f32_e32 v151, 0x3fb8aa3b, v194
	v_exp_f32_e32 v151, v151
	s_nop 0
	v_fma_f32 v151, v184, v151, v139
	v_log_f32_e32 v151, v151
	s_nop 0
	v_mul_f32_e32 v195, 0x3f317217, v151
	v_fma_f32 v195, v151, s52, -v195
	v_fmac_f32_e32 v195, 0x3377d1cf, v151
	v_fmac_f32_e32 v195, 0x3f317217, v151
	v_mov_b32_e32 v151, v195
	v_cndmask_b32_e64 v151, v194, v151, s[22:23]
	global_store_dwordx4 v[170:171], v[144:147], off
	global_store_dwordx4 v[170:171], v[148:151], off offset:16
	s_nop 1
	v_pk_mul_f32 v[148:149], v[116:117], v[168:169] op_sel_hi:[1,0]
	v_pk_mul_f32 v[150:151], v[118:119], v[168:169] op_sel_hi:[1,0]
	v_pk_mul_f32 v[146:147], v[114:115], v[168:169] op_sel_hi:[1,0]
	v_pk_mul_f32 v[144:145], v[112:113], v[168:169] op_sel_hi:[1,0]
	v_min_f32_e32 v168, 0, v148
	v_mul_f32_e64 v148, |v148|, s57
	v_exp_f32_e32 v148, v148
	s_nop 0
	v_add_f32_e32 v148, 1.0, v148
	v_log_f32_e32 v148, v148
	s_nop 0
	v_mul_f32_e32 v194, 0x3f317217, v148
	v_fma_f32 v194, v148, s52, -v194
	v_fmac_f32_e32 v194, 0x3377d1cf, v148
	v_fmac_f32_e32 v194, 0x3f317217, v148
	v_mov_b32_e32 v148, v194
	v_sub_f32_e32 v148, v168, v148
	v_min_f32_e32 v168, 0, v144
	v_mul_f32_e64 v144, |v144|, s57
	v_exp_f32_e32 v144, v144
	s_nop 0
	v_add_f32_e32 v144, 1.0, v144
	v_log_f32_e32 v144, v144
	s_nop 0
	v_mul_f32_e32 v194, 0x3f317217, v144
	v_fma_f32 v194, v144, s52, -v194
	v_fmac_f32_e32 v194, 0x3377d1cf, v144
	v_fmac_f32_e32 v194, 0x3f317217, v144
	v_mov_b32_e32 v144, v194
	v_sub_f32_e32 v168, v168, v144
	v_mul_f32_e32 v144, 0x3fb8aa3b, v148
	v_exp_f32_e32 v144, v144
	s_nop 0
	v_fma_f32 v144, v183, v144, v132
	v_log_f32_e32 v144, v144
	s_nop 0
	v_mul_f32_e32 v194, 0x3f317217, v144
	v_fma_f32 v194, v144, s52, -v194
	v_fmac_f32_e32 v194, 0x3377d1cf, v144
	v_fmac_f32_e32 v194, 0x3f317217, v144
	v_mov_b32_e32 v144, v194
	v_cndmask_b32_e64 v144, v148, v144, s[20:21]
	v_mul_f32_e32 v148, 0x3fb8aa3b, v168
	v_exp_f32_e32 v148, v148
	s_nop 0
	v_fma_f32 v148, v182, v148, v128
	v_log_f32_e32 v148, v148
	s_nop 0
	v_mul_f32_e32 v194, 0x3f317217, v148
	v_fma_f32 v194, v148, s52, -v194
	v_fmac_f32_e32 v194, 0x3377d1cf, v148
	v_fmac_f32_e32 v194, 0x3f317217, v148
	v_mov_b32_e32 v148, v194
	v_cndmask_b32_e64 v148, v168, v148, s[18:19]
	v_min_f32_e32 v168, 0, v149
	v_mul_f32_e64 v149, |v149|, s57
	v_exp_f32_e32 v149, v149
	s_nop 0
	v_add_f32_e32 v149, 1.0, v149
; __device__ __forceinline__ float silu_f(float x) { return x * __builtin_amdgcn_rcpf(1.f + __expf(-x)); }
; __device__ __forceinline__ v4u pack8(const f32x4 a, const f32x4 b) { v4u w; w.x = cvt_pk_bf16(a[0], a[1]); w.y = cvt_pk_bf16(a[2], a[3]); w.z = cvt_pk_bf16(b[0], b[1]); w.w = cvt_pk_bf16(b[2], b[3]); return w; }
;     __device__ __forceinline__ void operator()(const f32x4 (&acc)[2][2][4][2], const pg8::Unit& u, int wr, int wc, int fr, int fq) const {
;     ...
;         if (grp == 0) { WIN_LOOP( _Pragma("unroll") for (int i = 0; i < 4; ++i) { a[i] = silu_f(a[i]); b[i] = silu_f(b[i]); } *(v4u*)(QO + (size_t)row * DM + c) = pack8(a, b); ) }
;         else if (grp == 3) { WIN_LOOP( _Pragma("unroll") for (int i = 0; i < 4; ++i) { a[i] = silu_f(a[i]); b[i] = silu_f(b[i]); } *(v4u*)(GH + (size_t)row * 512 + c) = pack8(a, b); ) }
;         else if (grp == 1) {
;             f32x4 l0[2], l1[2];
; #pragma unroll
;             for (int bj = 0; bj < 2; ++bj) { l0[bj] = *(const f32x4*)(lb + cb + bj * 128); l1[bj] = *(const f32x4*)(lb + cb + bj * 128 + 4); }
;             WIN_LOOP( _Pragma("unroll") for (int i = 0; i < 4; ++i) { const float s0 = fminf(a[i], 0.f) - __logf(1.f + __expf(-fabsf(a[i]))), s1 = fminf(b[i], 0.f) - __logf(1.f + __expf(-fabsf(b[i]))); const float la = l0[bj][i], lbv = l1[bj][i];
;                     a[i] = la > 0.f ? __logf(la + (1.f - la) * __expf(s0)) : s0; b[i] = lbv > 0.f ? __logf(lbv + (1.f - lbv) * __expf(s1)) : s1; }
;                 *(f32x4*)(LF + (size_t)row * 512 + c) = a; *(f32x4*)(LF + (size_t)row * 512 + c + 4) = b; __builtin_amdgcn_sched_barrier(0); ) }
	v_log_f32_e32 v149, v149
	s_nop 0
	v_mul_f32_e32 v194, 0x3f317217, v149
	v_fma_f32 v194, v149, s52, -v194
	v_fmac_f32_e32 v194, 0x3377d1cf, v149
	v_fmac_f32_e32 v194, 0x3f317217, v149
	v_mov_b32_e32 v149, v194
	v_sub_f32_e32 v149, v168, v149
	v_min_f32_e32 v168, 0, v145
	v_mul_f32_e64 v145, |v145|, s57
	v_exp_f32_e32 v145, v145
	s_nop 0
	v_add_f32_e32 v145, 1.0, v145
	v_log_f32_e32 v145, v145
	s_nop 0
	v_mul_f32_e32 v194, 0x3f317217, v145
	v_fma_f32 v194, v145, s52, -v194
	v_fmac_f32_e32 v194, 0x3377d1cf, v145
	v_fmac_f32_e32 v194, 0x3f317217, v145
	v_mov_b32_e32 v145, v194
	v_sub_f32_e32 v168, v168, v145
	v_mul_f32_e32 v145, 0x3fb8aa3b, v149
	v_exp_f32_e32 v145, v145
	s_nop 0
	v_fma_f32 v145, v181, v145, v133
	v_log_f32_e32 v145, v145
	s_nop 0
	v_mul_f32_e32 v194, 0x3f317217, v145
	v_fma_f32 v194, v145, s52, -v194
	v_fmac_f32_e32 v194, 0x3377d1cf, v145
	v_fmac_f32_e32 v194, 0x3f317217, v145
	v_mov_b32_e32 v145, v194
	v_cndmask_b32_e64 v145, v149, v145, s[16:17]
	v_mul_f32_e32 v149, 0x3fb8aa3b, v168
	v_exp_f32_e32 v149, v149
	s_nop 0
	v_fma_f32 v149, v180, v149, v129
	v_log_f32_e32 v149, v149
	s_nop 0
	v_mul_f32_e32 v194, 0x3f317217, v149
	v_fma_f32 v194, v149, s52, -v194
	v_fmac_f32_e32 v194, 0x3377d1cf, v149
	v_fmac_f32_e32 v194, 0x3f317217, v149
	v_mov_b32_e32 v149, v194
	v_cndmask_b32_e64 v149, v168, v149, s[14:15]
	v_min_f32_e32 v168, 0, v150
	v_mul_f32_e64 v150, |v150|, s57
	v_exp_f32_e32 v150, v150
	s_nop 0
	v_add_f32_e32 v150, 1.0, v150
	v_log_f32_e32 v150, v150
	s_nop 0
	v_mul_f32_e32 v194, 0x3f317217, v150
	v_fma_f32 v194, v150, s52, -v194
	v_fmac_f32_e32 v194, 0x3377d1cf, v150
	v_fmac_f32_e32 v194, 0x3f317217, v150
	v_mov_b32_e32 v150, v194
	v_sub_f32_e32 v150, v168, v150
	v_min_f32_e32 v168, 0, v146
	v_mul_f32_e64 v146, |v146|, s57
	v_exp_f32_e32 v146, v146
	s_nop 0
	v_add_f32_e32 v146, 1.0, v146
	v_log_f32_e32 v146, v146
	s_nop 0
	v_mul_f32_e32 v194, 0x3f317217, v146
	v_fma_f32 v194, v146, s52, -v194
	v_fmac_f32_e32 v194, 0x3377d1cf, v146
	v_fmac_f32_e32 v194, 0x3f317217, v146
	v_mov_b32_e32 v146, v194
	v_sub_f32_e32 v168, v168, v146
	v_mul_f32_e32 v146, 0x3fb8aa3b, v150
	v_exp_f32_e32 v146, v146
	s_nop 0
	v_fma_f32 v146, v179, v146, v134
	v_log_f32_e32 v146, v146
	s_nop 0
	v_mul_f32_e32 v194, 0x3f317217, v146
	v_fma_f32 v194, v146, s52, -v194
	v_fmac_f32_e32 v194, 0x3377d1cf, v146
	v_fmac_f32_e32 v194, 0x3f317217, v146
	v_mov_b32_e32 v146, v194
	v_cndmask_b32_e64 v146, v150, v146, s[12:13]
	v_mul_f32_e32 v150, 0x3fb8aa3b, v168
	v_exp_f32_e32 v150, v150
	s_nop 0
	v_fma_f32 v150, v178, v150, v130
	v_log_f32_e32 v150, v150
	s_nop 0
	v_mul_f32_e32 v194, 0x3f317217, v150
	v_fma_f32 v194, v150, s52, -v194
	v_fmac_f32_e32 v194, 0x3377d1cf, v150
	v_fmac_f32_e32 v194, 0x3f317217, v150
	v_mov_b32_e32 v150, v194
	v_cndmask_b32_e64 v150, v168, v150, s[10:11]
	v_min_f32_e32 v168, 0, v151
	v_mul_f32_e64 v151, |v151|, s57
	v_exp_f32_e32 v151, v151
	s_nop 0
	v_add_f32_e32 v151, 1.0, v151
	v_log_f32_e32 v151, v151
	s_nop 0
	v_mul_f32_e32 v194, 0x3f317217, v151
	v_fma_f32 v194, v151, s52, -v194
	v_fmac_f32_e32 v194, 0x3377d1cf, v151
	v_fmac_f32_e32 v194, 0x3f317217, v151
	v_mov_b32_e32 v151, v194
	v_sub_f32_e32 v151, v168, v151
	v_min_f32_e32 v168, 0, v147
	v_mul_f32_e64 v147, |v147|, s57
	v_exp_f32_e32 v147, v147
	s_nop 0
	v_add_f32_e32 v147, 1.0, v147
	v_log_f32_e32 v147, v147
	s_nop 0
	v_mul_f32_e32 v194, 0x3f317217, v147
	v_fma_f32 v194, v147, s52, -v194
	v_fmac_f32_e32 v194, 0x3377d1cf, v147
	v_fmac_f32_e32 v194, 0x3f317217, v147
	v_mov_b32_e32 v147, v194
	v_sub_f32_e32 v168, v168, v147
	v_mul_f32_e32 v147, 0x3fb8aa3b, v151
	v_exp_f32_e32 v147, v147
	s_nop 0
	v_fma_f32 v147, v177, v147, v135
	v_log_f32_e32 v147, v147
	s_nop 0
	v_mul_f32_e32 v194, 0x3f317217, v147
	v_fma_f32 v194, v147, s52, -v194
	v_fmac_f32_e32 v194, 0x3377d1cf, v147
	v_fmac_f32_e32 v194, 0x3f317217, v147
	v_mov_b32_e32 v147, v194
	v_cndmask_b32_e64 v147, v151, v147, s[8:9]
	v_mul_f32_e32 v151, 0x3fb8aa3b, v168
	v_exp_f32_e32 v151, v151
	s_nop 0
	v_fma_f32 v151, v167, v151, v131
	v_log_f32_e32 v151, v151
	s_nop 0
	v_mul_f32_e32 v194, 0x3f317217, v151
	v_fma_f32 v194, v151, s52, -v194
	v_fmac_f32_e32 v194, 0x3377d1cf, v151
	v_fmac_f32_e32 v194, 0x3f317217, v151
	v_mov_b32_e32 v151, v194
	v_cndmask_b32_e32 v151, v168, v151, vcc
	global_store_dwordx4 v[170:171], v[144:147], off offset:512
	global_store_dwordx4 v[170:171], v[148:151], off offset:528
	s_nop 1
	v_or_b32_e32 v148, 32, v166
	v_ashrrev_i32_e32 v149, 31, v148
	v_lshlrev_b64 v[144:145], 6, v[148:149]
	v_lshl_add_u64 v[144:145], v[160:161], 0, v[144:145]
	s_nop 0
	s_waitcnt lgkmcnt(0)
	s_nop 3
	s_nop 0
	s_nop 1
	s_waitcnt lgkmcnt(0)
	s_nop 1
	s_waitcnt lgkmcnt(0)
; __device__ __forceinline__ float silu_f(float x) { return x * __builtin_amdgcn_rcpf(1.f + __expf(-x)); }
; __device__ __forceinline__ v4u pack8(const f32x4 a, const f32x4 b) { v4u w; w.x = cvt_pk_bf16(a[0], a[1]); w.y = cvt_pk_bf16(a[2], a[3]); w.z = cvt_pk_bf16(b[0], b[1]); w.w = cvt_pk_bf16(b[2], b[3]); return w; }
;     __device__ __forceinline__ void operator()(const f32x4 (&acc)[2][2][4][2], const pg8::Unit& u, int wr, int wc, int fr, int fq) const {
;     ...
;         if (grp == 0) { WIN_LOOP( _Pragma("unroll") for (int i = 0; i < 4; ++i) { a[i] = silu_f(a[i]); b[i] = silu_f(b[i]); } *(v4u*)(QO + (size_t)row * DM + c) = pack8(a, b); ) }
;         else if (grp == 3) { WIN_LOOP( _Pragma("unroll") for (int i = 0; i < 4; ++i) { a[i] = silu_f(a[i]); b[i] = silu_f(b[i]); } *(v4u*)(GH + (size_t)row * 512 + c) = pack8(a, b); ) }
;         else if (grp == 1) {
;             f32x4 l0[2], l1[2];
; #pragma unroll
;             for (int bj = 0; bj < 2; ++bj) { l0[bj] = *(const f32x4*)(lb + cb + bj * 128); l1[bj] = *(const f32x4*)(lb + cb + bj * 128 + 4); }
;             WIN_LOOP( _Pragma("unroll") for (int i = 0; i < 4; ++i) { const float s0 = fminf(a[i], 0.f) - __logf(1.f + __expf(-fabsf(a[i]))), s1 = fminf(b[i], 0.f) - __logf(1.f + __expf(-fabsf(b[i]))); const float la = l0[bj][i], lbv = l1[bj][i];
;                     a[i] = la > 0.f ? __logf(la + (1.f - la) * __expf(s0)) : s0; b[i] = lbv > 0.f ? __logf(lbv + (1.f - lbv) * __expf(s1)) : s1; }
;                 *(f32x4*)(LF + (size_t)row * 512 + c) = a; *(f32x4*)(LF + (size_t)row * 512 + c + 4) = b; __builtin_amdgcn_sched_barrier(0); ) }
	s_nop 1
	v_mov_b32_e32 v168, v252
	v_lshlrev_b64 v[144:145], 11, v[148:149]
	v_lshl_add_u64 v[170:171], s[50:51], 0, v[144:145]
	v_lshl_add_u64 v[170:171], v[170:171], 0, v[192:193]
	v_pk_mul_f32 v[148:149], v[44:45], v[168:169] op_sel_hi:[1,0]
	v_pk_mul_f32 v[144:145], v[40:41], v[168:169] op_sel_hi:[1,0]
	v_min_f32_e32 v194, 0, v148
	v_mul_f32_e64 v148, |v148|, s57
	v_exp_f32_e32 v148, v148
	v_pk_mul_f32 v[150:151], v[46:47], v[168:169] op_sel_hi:[1,0]
	v_pk_mul_f32 v[146:147], v[42:43], v[168:169] op_sel_hi:[1,0]
	v_add_f32_e32 v148, 1.0, v148
	v_log_f32_e32 v148, v148
	s_nop 0
	v_mul_f32_e32 v195, 0x3f317217, v148
	v_fma_f32 v195, v148, s52, -v195
	v_fmac_f32_e32 v195, 0x3377d1cf, v148
	v_fmac_f32_e32 v195, 0x3f317217, v148
	v_mov_b32_e32 v148, v195
	v_sub_f32_e32 v148, v194, v148
	v_min_f32_e32 v194, 0, v144
	v_mul_f32_e64 v144, |v144|, s57
	v_exp_f32_e32 v144, v144
	s_nop 0
	v_add_f32_e32 v144, 1.0, v144
	v_log_f32_e32 v144, v144
	s_nop 0
	v_mul_f32_e32 v195, 0x3f317217, v144
	v_fma_f32 v195, v144, s52, -v195
	v_fmac_f32_e32 v195, 0x3377d1cf, v144
	v_fmac_f32_e32 v195, 0x3f317217, v144
	v_mov_b32_e32 v144, v195
	v_sub_f32_e32 v194, v194, v144
	v_mul_f32_e32 v144, 0x3fb8aa3b, v148
	v_exp_f32_e32 v144, v144
	s_nop 0
	v_fma_f32 v144, v190, v144, v140
	v_log_f32_e32 v144, v144
	s_nop 0
	v_mul_f32_e32 v195, 0x3f317217, v144
	v_fma_f32 v195, v144, s52, -v195
	v_fmac_f32_e32 v195, 0x3377d1cf, v144
	v_fmac_f32_e32 v195, 0x3f317217, v144
	v_mov_b32_e32 v144, v195
	v_cndmask_b32_e64 v144, v148, v144, s[38:39]
	v_mul_f32_e32 v148, 0x3fb8aa3b, v194
	v_exp_f32_e32 v148, v148
	s_nop 0
	v_fma_f32 v148, v191, v148, v136
	v_log_f32_e32 v148, v148
	s_nop 0
	v_mul_f32_e32 v195, 0x3f317217, v148
	v_fma_f32 v195, v148, s52, -v195
	v_fmac_f32_e32 v195, 0x3377d1cf, v148
	v_fmac_f32_e32 v195, 0x3f317217, v148
	v_mov_b32_e32 v148, v195
	v_cndmask_b32_e64 v148, v194, v148, s[36:37]
	v_min_f32_e32 v194, 0, v149
	v_mul_f32_e64 v149, |v149|, s57
	v_exp_f32_e32 v149, v149
	s_nop 0
	v_add_f32_e32 v149, 1.0, v149
	v_log_f32_e32 v149, v149
	s_nop 0
	v_mul_f32_e32 v195, 0x3f317217, v149
	v_fma_f32 v195, v149, s52, -v195
	v_fmac_f32_e32 v195, 0x3377d1cf, v149
	v_fmac_f32_e32 v195, 0x3f317217, v149
	v_mov_b32_e32 v149, v195
	v_sub_f32_e32 v149, v194, v149
	v_min_f32_e32 v194, 0, v145
	v_mul_f32_e64 v145, |v145|, s57
	v_exp_f32_e32 v145, v145
	s_nop 0
	v_add_f32_e32 v145, 1.0, v145
	v_log_f32_e32 v145, v145
	s_nop 0
	v_mul_f32_e32 v195, 0x3f317217, v145
	v_fma_f32 v195, v145, s52, -v195
	v_fmac_f32_e32 v195, 0x3377d1cf, v145
	v_fmac_f32_e32 v195, 0x3f317217, v145
	v_mov_b32_e32 v145, v195
	v_sub_f32_e32 v194, v194, v145
	v_mul_f32_e32 v145, 0x3fb8aa3b, v149
	v_exp_f32_e32 v145, v145
	s_nop 0
	v_fma_f32 v145, v188, v145, v141
	v_log_f32_e32 v145, v145
	s_nop 0
	v_mul_f32_e32 v195, 0x3f317217, v145
	v_fma_f32 v195, v145, s52, -v195
	v_fmac_f32_e32 v195, 0x3377d1cf, v145
	v_fmac_f32_e32 v195, 0x3f317217, v145
	v_mov_b32_e32 v145, v195
	v_cndmask_b32_e64 v145, v149, v145, s[34:35]
	v_mul_f32_e32 v149, 0x3fb8aa3b, v194
	v_exp_f32_e32 v149, v149
	s_nop 0
	v_fma_f32 v149, v189, v149, v137
	v_log_f32_e32 v149, v149
	s_nop 0
	v_mul_f32_e32 v195, 0x3f317217, v149
	v_fma_f32 v195, v149, s52, -v195
	v_fmac_f32_e32 v195, 0x3377d1cf, v149
	v_fmac_f32_e32 v195, 0x3f317217, v149
	v_mov_b32_e32 v149, v195
	v_cndmask_b32_e64 v149, v194, v149, s[30:31]
	v_min_f32_e32 v194, 0, v150
	v_mul_f32_e64 v150, |v150|, s57
	v_exp_f32_e32 v150, v150
	s_nop 0
	v_add_f32_e32 v150, 1.0, v150
	v_log_f32_e32 v150, v150
	s_nop 0
	v_mul_f32_e32 v195, 0x3f317217, v150
	v_fma_f32 v195, v150, s52, -v195
	v_fmac_f32_e32 v195, 0x3377d1cf, v150
	v_fmac_f32_e32 v195, 0x3f317217, v150
	v_mov_b32_e32 v150, v195
	v_sub_f32_e32 v150, v194, v150
	v_min_f32_e32 v194, 0, v146
	v_mul_f32_e64 v146, |v146|, s57
	v_exp_f32_e32 v146, v146
	s_nop 0
	v_add_f32_e32 v146, 1.0, v146
	v_log_f32_e32 v146, v146
	s_nop 0
	v_mul_f32_e32 v195, 0x3f317217, v146
	v_fma_f32 v195, v146, s52, -v195
	v_fmac_f32_e32 v195, 0x3377d1cf, v146
	v_fmac_f32_e32 v195, 0x3f317217, v146
	v_mov_b32_e32 v146, v195
	v_sub_f32_e32 v194, v194, v146
	v_mul_f32_e32 v146, 0x3fb8aa3b, v150
	v_exp_f32_e32 v146, v146
	s_nop 0
	v_fma_f32 v146, v187, v146, v142
	v_log_f32_e32 v146, v146
	s_nop 0
	v_mul_f32_e32 v195, 0x3f317217, v146
	v_fma_f32 v195, v146, s52, -v195
	v_fmac_f32_e32 v195, 0x3377d1cf, v146
	v_fmac_f32_e32 v195, 0x3f317217, v146
	v_mov_b32_e32 v146, v195
	v_cndmask_b32_e64 v146, v150, v146, s[28:29]
	v_mul_f32_e32 v150, 0x3fb8aa3b, v194
	v_exp_f32_e32 v150, v150
	s_nop 0
	v_fma_f32 v150, v186, v150, v138
	v_log_f32_e32 v150, v150
	s_nop 0
	v_mul_f32_e32 v195, 0x3f317217, v150
	v_fma_f32 v195, v150, s52, -v195
	v_fmac_f32_e32 v195, 0x3377d1cf, v150
	v_fmac_f32_e32 v195, 0x3f317217, v150
	v_mov_b32_e32 v150, v195
	v_cndmask_b32_e64 v150, v194, v150, s[26:27]
	v_min_f32_e32 v194, 0, v151
	v_mul_f32_e64 v151, |v151|, s57
	v_exp_f32_e32 v151, v151
	s_nop 0
	v_add_f32_e32 v151, 1.0, v151
	v_log_f32_e32 v151, v151
	s_nop 0
	v_mul_f32_e32 v195, 0x3f317217, v151
	v_fma_f32 v195, v151, s52, -v195
	v_fmac_f32_e32 v195, 0x3377d1cf, v151
	v_fmac_f32_e32 v195, 0x3f317217, v151
	v_mov_b32_e32 v151, v195
	v_sub_f32_e32 v151, v194, v151
	v_min_f32_e32 v194, 0, v147
	v_mul_f32_e64 v147, |v147|, s57
	v_exp_f32_e32 v147, v147
	s_nop 0
	v_add_f32_e32 v147, 1.0, v147
	v_log_f32_e32 v147, v147
	s_nop 0
	v_mul_f32_e32 v195, 0x3f317217, v147
	v_fma_f32 v195, v147, s52, -v195
	v_fmac_f32_e32 v195, 0x3377d1cf, v147
	v_fmac_f32_e32 v195, 0x3f317217, v147
	v_mov_b32_e32 v147, v195
	v_sub_f32_e32 v194, v194, v147
	v_mul_f32_e32 v147, 0x3fb8aa3b, v151
	v_exp_f32_e32 v147, v147
; __device__ __forceinline__ float silu_f(float x) { return x * __builtin_amdgcn_rcpf(1.f + __expf(-x)); }
; __device__ __forceinline__ v4u pack8(const f32x4 a, const f32x4 b) { v4u w; w.x = cvt_pk_bf16(a[0], a[1]); w.y = cvt_pk_bf16(a[2], a[3]); w.z = cvt_pk_bf16(b[0], b[1]); w.w = cvt_pk_bf16(b[2], b[3]); return w; }
;     __device__ __forceinline__ void operator()(const f32x4 (&acc)[2][2][4][2], const pg8::Unit& u, int wr, int wc, int fr, int fq) const {
;     ...
;         if (grp == 0) { WIN_LOOP( _Pragma("unroll") for (int i = 0; i < 4; ++i) { a[i] = silu_f(a[i]); b[i] = silu_f(b[i]); } *(v4u*)(QO + (size_t)row * DM + c) = pack8(a, b); ) }
;         else if (grp == 3) { WIN_LOOP( _Pragma("unroll") for (int i = 0; i < 4; ++i) { a[i] = silu_f(a[i]); b[i] = silu_f(b[i]); } *(v4u*)(GH + (size_t)row * 512 + c) = pack8(a, b); ) }
;         else if (grp == 1) {
;             f32x4 l0[2], l1[2];
; #pragma unroll
;             for (int bj = 0; bj < 2; ++bj) { l0[bj] = *(const f32x4*)(lb + cb + bj * 128); l1[bj] = *(const f32x4*)(lb + cb + bj * 128 + 4); }
;             WIN_LOOP( _Pragma("unroll") for (int i = 0; i < 4; ++i) { const float s0 = fminf(a[i], 0.f) - __logf(1.f + __expf(-fabsf(a[i]))), s1 = fminf(b[i], 0.f) - __logf(1.f + __expf(-fabsf(b[i]))); const float la = l0[bj][i], lbv = l1[bj][i];
;                     a[i] = la > 0.f ? __logf(la + (1.f - la) * __expf(s0)) : s0; b[i] = lbv > 0.f ? __logf(lbv + (1.f - lbv) * __expf(s1)) : s1; }
;                 *(f32x4*)(LF + (size_t)row * 512 + c) = a; *(f32x4*)(LF + (size_t)row * 512 + c + 4) = b; __builtin_amdgcn_sched_barrier(0); ) }
	s_nop 0
	v_fma_f32 v147, v185, v147, v143
	v_log_f32_e32 v147, v147
	s_nop 0
	v_mul_f32_e32 v195, 0x3f317217, v147
	v_fma_f32 v195, v147, s52, -v195
	v_fmac_f32_e32 v195, 0x3377d1cf, v147
	v_fmac_f32_e32 v195, 0x3f317217, v147
	v_mov_b32_e32 v147, v195
	v_cndmask_b32_e64 v147, v151, v147, s[24:25]
	v_mul_f32_e32 v151, 0x3fb8aa3b, v194
	v_exp_f32_e32 v151, v151
	s_nop 0
	v_fma_f32 v151, v184, v151, v139
	v_log_f32_e32 v151, v151
	s_nop 0
	v_mul_f32_e32 v195, 0x3f317217, v151
	v_fma_f32 v195, v151, s52, -v195
	v_fmac_f32_e32 v195, 0x3377d1cf, v151
	v_fmac_f32_e32 v195, 0x3f317217, v151
	v_mov_b32_e32 v151, v195
	v_cndmask_b32_e64 v151, v194, v151, s[22:23]
	global_store_dwordx4 v[170:171], v[144:147], off
	global_store_dwordx4 v[170:171], v[148:151], off offset:16
	s_nop 1
	v_pk_mul_f32 v[148:149], v[108:109], v[168:169] op_sel_hi:[1,0]
	v_pk_mul_f32 v[150:151], v[110:111], v[168:169] op_sel_hi:[1,0]
	v_pk_mul_f32 v[146:147], v[106:107], v[168:169] op_sel_hi:[1,0]
	v_pk_mul_f32 v[144:145], v[104:105], v[168:169] op_sel_hi:[1,0]
	v_min_f32_e32 v168, 0, v148
	v_mul_f32_e64 v148, |v148|, s57
	v_exp_f32_e32 v148, v148
	s_nop 0
	v_add_f32_e32 v148, 1.0, v148
	v_log_f32_e32 v148, v148
	s_nop 0
	v_mul_f32_e32 v194, 0x3f317217, v148
	v_fma_f32 v194, v148, s52, -v194
	v_fmac_f32_e32 v194, 0x3377d1cf, v148
	v_fmac_f32_e32 v194, 0x3f317217, v148
	v_mov_b32_e32 v148, v194
	v_sub_f32_e32 v148, v168, v148
	v_min_f32_e32 v168, 0, v144
	v_mul_f32_e64 v144, |v144|, s57
	v_exp_f32_e32 v144, v144
	s_nop 0
	v_add_f32_e32 v144, 1.0, v144
	v_log_f32_e32 v144, v144
	s_nop 0
	v_mul_f32_e32 v194, 0x3f317217, v144
	v_fma_f32 v194, v144, s52, -v194
	v_fmac_f32_e32 v194, 0x3377d1cf, v144
	v_fmac_f32_e32 v194, 0x3f317217, v144
	v_mov_b32_e32 v144, v194
	v_sub_f32_e32 v168, v168, v144
	v_mul_f32_e32 v144, 0x3fb8aa3b, v148
	v_exp_f32_e32 v144, v144
	s_nop 0
	v_fma_f32 v144, v183, v144, v132
	v_log_f32_e32 v144, v144
	s_nop 0
	v_mul_f32_e32 v194, 0x3f317217, v144
	v_fma_f32 v194, v144, s52, -v194
	v_fmac_f32_e32 v194, 0x3377d1cf, v144
	v_fmac_f32_e32 v194, 0x3f317217, v144
	v_mov_b32_e32 v144, v194
	v_cndmask_b32_e64 v144, v148, v144, s[20:21]
	v_mul_f32_e32 v148, 0x3fb8aa3b, v168
	v_exp_f32_e32 v148, v148
	s_nop 0
	v_fma_f32 v148, v182, v148, v128
	v_log_f32_e32 v148, v148
	s_nop 0
	v_mul_f32_e32 v194, 0x3f317217, v148
	v_fma_f32 v194, v148, s52, -v194
	v_fmac_f32_e32 v194, 0x3377d1cf, v148
	v_fmac_f32_e32 v194, 0x3f317217, v148
	v_mov_b32_e32 v148, v194
	v_cndmask_b32_e64 v148, v168, v148, s[18:19]
	v_min_f32_e32 v168, 0, v149
	v_mul_f32_e64 v149, |v149|, s57
	v_exp_f32_e32 v149, v149
	s_nop 0
	v_add_f32_e32 v149, 1.0, v149
	v_log_f32_e32 v149, v149
	s_nop 0
	v_mul_f32_e32 v194, 0x3f317217, v149
	v_fma_f32 v194, v149, s52, -v194
	v_fmac_f32_e32 v194, 0x3377d1cf, v149
	v_fmac_f32_e32 v194, 0x3f317217, v149
	v_mov_b32_e32 v149, v194
	v_sub_f32_e32 v149, v168, v149
	v_min_f32_e32 v168, 0, v145
	v_mul_f32_e64 v145, |v145|, s57
	v_exp_f32_e32 v145, v145
	s_nop 0
	v_add_f32_e32 v145, 1.0, v145
	v_log_f32_e32 v145, v145
	s_nop 0
	v_mul_f32_e32 v194, 0x3f317217, v145
	v_fma_f32 v194, v145, s52, -v194
	v_fmac_f32_e32 v194, 0x3377d1cf, v145
	v_fmac_f32_e32 v194, 0x3f317217, v145
	v_mov_b32_e32 v145, v194
	v_sub_f32_e32 v168, v168, v145
	v_mul_f32_e32 v145, 0x3fb8aa3b, v149
	v_exp_f32_e32 v145, v145
	s_nop 0
	v_fma_f32 v145, v181, v145, v133
	v_log_f32_e32 v145, v145
	s_nop 0
	v_mul_f32_e32 v194, 0x3f317217, v145
	v_fma_f32 v194, v145, s52, -v194
	v_fmac_f32_e32 v194, 0x3377d1cf, v145
	v_fmac_f32_e32 v194, 0x3f317217, v145
	v_mov_b32_e32 v145, v194
	v_cndmask_b32_e64 v145, v149, v145, s[16:17]
	v_mul_f32_e32 v149, 0x3fb8aa3b, v168
	v_exp_f32_e32 v149, v149
	s_nop 0
	v_fma_f32 v149, v180, v149, v129
	v_log_f32_e32 v149, v149
	s_nop 0
	v_mul_f32_e32 v194, 0x3f317217, v149
	v_fma_f32 v194, v149, s52, -v194
	v_fmac_f32_e32 v194, 0x3377d1cf, v149
	v_fmac_f32_e32 v194, 0x3f317217, v149
	v_mov_b32_e32 v149, v194
	v_cndmask_b32_e64 v149, v168, v149, s[14:15]
	v_min_f32_e32 v168, 0, v150
	v_mul_f32_e64 v150, |v150|, s57
	v_exp_f32_e32 v150, v150
	s_nop 0
	v_add_f32_e32 v150, 1.0, v150
	v_log_f32_e32 v150, v150
	s_nop 0
	v_mul_f32_e32 v194, 0x3f317217, v150
	v_fma_f32 v194, v150, s52, -v194
	v_fmac_f32_e32 v194, 0x3377d1cf, v150
	v_fmac_f32_e32 v194, 0x3f317217, v150
	v_mov_b32_e32 v150, v194
	v_sub_f32_e32 v150, v168, v150
	v_min_f32_e32 v168, 0, v146
	v_mul_f32_e64 v146, |v146|, s57
	v_exp_f32_e32 v146, v146
	s_nop 0
	v_add_f32_e32 v146, 1.0, v146
	v_log_f32_e32 v146, v146
	s_nop 0
	v_mul_f32_e32 v194, 0x3f317217, v146
	v_fma_f32 v194, v146, s52, -v194
	v_fmac_f32_e32 v194, 0x3377d1cf, v146
	v_fmac_f32_e32 v194, 0x3f317217, v146
	v_mov_b32_e32 v146, v194
	v_sub_f32_e32 v168, v168, v146
	v_mul_f32_e32 v146, 0x3fb8aa3b, v150
	v_exp_f32_e32 v146, v146
	s_nop 0
	v_fma_f32 v146, v179, v146, v134
	v_log_f32_e32 v146, v146
	s_nop 0
	v_mul_f32_e32 v194, 0x3f317217, v146
	v_fma_f32 v194, v146, s52, -v194
	v_fmac_f32_e32 v194, 0x3377d1cf, v146
	v_fmac_f32_e32 v194, 0x3f317217, v146
	v_mov_b32_e32 v146, v194
	v_cndmask_b32_e64 v146, v150, v146, s[12:13]
	v_mul_f32_e32 v150, 0x3fb8aa3b, v168
	v_exp_f32_e32 v150, v150
	s_nop 0
	v_fma_f32 v150, v178, v150, v130
	v_log_f32_e32 v150, v150
	s_nop 0
	v_mul_f32_e32 v194, 0x3f317217, v150
	v_fma_f32 v194, v150, s52, -v194
	v_fmac_f32_e32 v194, 0x3377d1cf, v150
	v_fmac_f32_e32 v194, 0x3f317217, v150
	v_mov_b32_e32 v150, v194
	v_cndmask_b32_e64 v150, v168, v150, s[10:11]
	v_min_f32_e32 v168, 0, v151
	v_mul_f32_e64 v151, |v151|, s57
	v_exp_f32_e32 v151, v151
	s_nop 0
	v_add_f32_e32 v151, 1.0, v151
	v_log_f32_e32 v151, v151
	s_nop 0
	v_mul_f32_e32 v194, 0x3f317217, v151
; __device__ __forceinline__ float silu_f(float x) { return x * __builtin_amdgcn_rcpf(1.f + __expf(-x)); }
; __device__ __forceinline__ v4u pack8(const f32x4 a, const f32x4 b) { v4u w; w.x = cvt_pk_bf16(a[0], a[1]); w.y = cvt_pk_bf16(a[2], a[3]); w.z = cvt_pk_bf16(b[0], b[1]); w.w = cvt_pk_bf16(b[2], b[3]); return w; }
;     __device__ __forceinline__ void operator()(const f32x4 (&acc)[2][2][4][2], const pg8::Unit& u, int wr, int wc, int fr, int fq) const {
;     ...
;         if (grp == 0) { WIN_LOOP( _Pragma("unroll") for (int i = 0; i < 4; ++i) { a[i] = silu_f(a[i]); b[i] = silu_f(b[i]); } *(v4u*)(QO + (size_t)row * DM + c) = pack8(a, b); ) }
;         else if (grp == 3) { WIN_LOOP( _Pragma("unroll") for (int i = 0; i < 4; ++i) { a[i] = silu_f(a[i]); b[i] = silu_f(b[i]); } *(v4u*)(GH + (size_t)row * 512 + c) = pack8(a, b); ) }
;         else if (grp == 1) {
;             f32x4 l0[2], l1[2];
; #pragma unroll
;             for (int bj = 0; bj < 2; ++bj) { l0[bj] = *(const f32x4*)(lb + cb + bj * 128); l1[bj] = *(const f32x4*)(lb + cb + bj * 128 + 4); }
;             WIN_LOOP( _Pragma("unroll") for (int i = 0; i < 4; ++i) { const float s0 = fminf(a[i], 0.f) - __logf(1.f + __expf(-fabsf(a[i]))), s1 = fminf(b[i], 0.f) - __logf(1.f + __expf(-fabsf(b[i]))); const float la = l0[bj][i], lbv = l1[bj][i];
;                     a[i] = la > 0.f ? __logf(la + (1.f - la) * __expf(s0)) : s0; b[i] = lbv > 0.f ? __logf(lbv + (1.f - lbv) * __expf(s1)) : s1; }
;                 *(f32x4*)(LF + (size_t)row * 512 + c) = a; *(f32x4*)(LF + (size_t)row * 512 + c + 4) = b; __builtin_amdgcn_sched_barrier(0); ) }
	v_fma_f32 v194, v151, s52, -v194
	v_fmac_f32_e32 v194, 0x3377d1cf, v151
	v_fmac_f32_e32 v194, 0x3f317217, v151
	v_mov_b32_e32 v151, v194
	v_sub_f32_e32 v151, v168, v151
	v_min_f32_e32 v168, 0, v147
	v_mul_f32_e64 v147, |v147|, s57
	v_exp_f32_e32 v147, v147
	s_nop 0
	v_add_f32_e32 v147, 1.0, v147
	v_log_f32_e32 v147, v147
	s_nop 0
	v_mul_f32_e32 v194, 0x3f317217, v147
	v_fma_f32 v194, v147, s52, -v194
	v_fmac_f32_e32 v194, 0x3377d1cf, v147
	v_fmac_f32_e32 v194, 0x3f317217, v147
	v_mov_b32_e32 v147, v194
	v_sub_f32_e32 v168, v168, v147
	v_mul_f32_e32 v147, 0x3fb8aa3b, v151
	v_exp_f32_e32 v147, v147
	s_nop 0
	v_fma_f32 v147, v177, v147, v135
	v_log_f32_e32 v147, v147
	s_nop 0
	v_mul_f32_e32 v194, 0x3f317217, v147
	v_fma_f32 v194, v147, s52, -v194
	v_fmac_f32_e32 v194, 0x3377d1cf, v147
	v_fmac_f32_e32 v194, 0x3f317217, v147
	v_mov_b32_e32 v147, v194
	v_cndmask_b32_e64 v147, v151, v147, s[8:9]
	v_mul_f32_e32 v151, 0x3fb8aa3b, v168
	v_exp_f32_e32 v151, v151
	s_nop 0
	v_fma_f32 v151, v167, v151, v131
	v_log_f32_e32 v151, v151
	s_nop 0
	v_mul_f32_e32 v194, 0x3f317217, v151
	v_fma_f32 v194, v151, s52, -v194
	v_fmac_f32_e32 v194, 0x3377d1cf, v151
	v_fmac_f32_e32 v194, 0x3f317217, v151
	v_mov_b32_e32 v151, v194
	v_cndmask_b32_e32 v151, v168, v151, vcc
	global_store_dwordx4 v[170:171], v[144:147], off offset:512
	global_store_dwordx4 v[170:171], v[148:151], off offset:528
	s_nop 1
	v_or_b32_e32 v148, 48, v166
	v_ashrrev_i32_e32 v149, 31, v148
	v_lshlrev_b64 v[144:145], 6, v[148:149]
	v_lshl_add_u64 v[144:145], v[160:161], 0, v[144:145]
	s_nop 0
	s_waitcnt lgkmcnt(0)
	s_nop 3
	s_nop 0
	s_nop 1
	s_waitcnt lgkmcnt(0)
	s_nop 1
	s_waitcnt lgkmcnt(0)
	s_nop 1
	v_mov_b32_e32 v168, v253
	v_lshlrev_b64 v[144:145], 11, v[148:149]
	v_lshl_add_u64 v[170:171], s[50:51], 0, v[144:145]
	v_lshl_add_u64 v[170:171], v[170:171], 0, v[192:193]
	v_pk_mul_f32 v[148:149], v[36:37], v[168:169] op_sel_hi:[1,0]
	v_pk_mul_f32 v[144:145], v[32:33], v[168:169] op_sel_hi:[1,0]
	v_min_f32_e32 v194, 0, v148
	v_mul_f32_e64 v148, |v148|, s57
	v_exp_f32_e32 v148, v148
	v_pk_mul_f32 v[150:151], v[38:39], v[168:169] op_sel_hi:[1,0]
	v_pk_mul_f32 v[146:147], v[34:35], v[168:169] op_sel_hi:[1,0]
	v_add_f32_e32 v148, 1.0, v148
	v_log_f32_e32 v148, v148
	s_nop 0
	v_mul_f32_e32 v195, 0x3f317217, v148
	v_fma_f32 v195, v148, s52, -v195
	v_fmac_f32_e32 v195, 0x3377d1cf, v148
	v_fmac_f32_e32 v195, 0x3f317217, v148
	v_mov_b32_e32 v148, v195
	v_sub_f32_e32 v148, v194, v148
	v_min_f32_e32 v194, 0, v144
	v_mul_f32_e64 v144, |v144|, s57
	v_exp_f32_e32 v144, v144
	s_nop 0
	v_add_f32_e32 v144, 1.0, v144
	v_log_f32_e32 v144, v144
	s_nop 0
	v_mul_f32_e32 v195, 0x3f317217, v144
	v_fma_f32 v195, v144, s52, -v195
	v_fmac_f32_e32 v195, 0x3377d1cf, v144
	v_fmac_f32_e32 v195, 0x3f317217, v144
	v_mov_b32_e32 v144, v195
	v_sub_f32_e32 v194, v194, v144
	v_mul_f32_e32 v144, 0x3fb8aa3b, v148
	v_exp_f32_e32 v144, v144
	s_nop 0
	v_fma_f32 v144, v190, v144, v140
	v_log_f32_e32 v144, v144
	s_nop 0
	v_mul_f32_e32 v195, 0x3f317217, v144
	v_fma_f32 v195, v144, s52, -v195
	v_fmac_f32_e32 v195, 0x3377d1cf, v144
	v_fmac_f32_e32 v195, 0x3f317217, v144
	v_mov_b32_e32 v144, v195
	v_cndmask_b32_e64 v144, v148, v144, s[38:39]
	v_mul_f32_e32 v148, 0x3fb8aa3b, v194
	v_exp_f32_e32 v148, v148
	s_nop 0
	v_fma_f32 v148, v191, v148, v136
	v_log_f32_e32 v148, v148
	s_nop 0
	v_mul_f32_e32 v195, 0x3f317217, v148
	v_fma_f32 v195, v148, s52, -v195
	v_fmac_f32_e32 v195, 0x3377d1cf, v148
	v_fmac_f32_e32 v195, 0x3f317217, v148
	v_mov_b32_e32 v148, v195
	v_cndmask_b32_e64 v148, v194, v148, s[36:37]
	v_min_f32_e32 v194, 0, v149
	v_mul_f32_e64 v149, |v149|, s57
	v_exp_f32_e32 v149, v149
	s_nop 0
	v_add_f32_e32 v149, 1.0, v149
	v_log_f32_e32 v149, v149
	s_nop 0
	v_mul_f32_e32 v195, 0x3f317217, v149
	v_fma_f32 v195, v149, s52, -v195
	v_fmac_f32_e32 v195, 0x3377d1cf, v149
	v_fmac_f32_e32 v195, 0x3f317217, v149
	v_mov_b32_e32 v149, v195
	v_sub_f32_e32 v149, v194, v149
	v_min_f32_e32 v194, 0, v145
	v_mul_f32_e64 v145, |v145|, s57
	v_exp_f32_e32 v145, v145
	s_nop 0
	v_add_f32_e32 v145, 1.0, v145
	v_log_f32_e32 v145, v145
	s_nop 0
	v_mul_f32_e32 v195, 0x3f317217, v145
	v_fma_f32 v195, v145, s52, -v195
	v_fmac_f32_e32 v195, 0x3377d1cf, v145
	v_fmac_f32_e32 v195, 0x3f317217, v145
	v_mov_b32_e32 v145, v195
	v_sub_f32_e32 v194, v194, v145
	v_mul_f32_e32 v145, 0x3fb8aa3b, v149
	v_exp_f32_e32 v145, v145
	s_nop 0
	v_fma_f32 v145, v188, v145, v141
	v_log_f32_e32 v145, v145
	s_nop 0
	v_mul_f32_e32 v195, 0x3f317217, v145
	v_fma_f32 v195, v145, s52, -v195
	v_fmac_f32_e32 v195, 0x3377d1cf, v145
	v_fmac_f32_e32 v195, 0x3f317217, v145
	v_mov_b32_e32 v145, v195
	v_cndmask_b32_e64 v145, v149, v145, s[34:35]
	v_mul_f32_e32 v149, 0x3fb8aa3b, v194
	v_exp_f32_e32 v149, v149
	s_nop 0
	v_fma_f32 v149, v189, v149, v137
	v_log_f32_e32 v149, v149
	s_nop 0
	v_mul_f32_e32 v195, 0x3f317217, v149
	v_fma_f32 v195, v149, s52, -v195
	v_fmac_f32_e32 v195, 0x3377d1cf, v149
	v_fmac_f32_e32 v195, 0x3f317217, v149
	v_mov_b32_e32 v149, v195
	v_cndmask_b32_e64 v149, v194, v149, s[30:31]
	v_min_f32_e32 v194, 0, v150
	v_mul_f32_e64 v150, |v150|, s57
	v_exp_f32_e32 v150, v150
	s_nop 0
	v_add_f32_e32 v150, 1.0, v150
	v_log_f32_e32 v150, v150
	s_nop 0
	v_mul_f32_e32 v195, 0x3f317217, v150
	v_fma_f32 v195, v150, s52, -v195
	v_fmac_f32_e32 v195, 0x3377d1cf, v150
	v_fmac_f32_e32 v195, 0x3f317217, v150
	v_mov_b32_e32 v150, v195
	v_sub_f32_e32 v150, v194, v150
	v_min_f32_e32 v194, 0, v146
	v_mul_f32_e64 v146, |v146|, s57
	v_exp_f32_e32 v146, v146
	s_nop 0
	v_add_f32_e32 v146, 1.0, v146
	v_log_f32_e32 v146, v146
	s_nop 0
	v_mul_f32_e32 v195, 0x3f317217, v146
	v_fma_f32 v195, v146, s52, -v195
; __device__ __forceinline__ float silu_f(float x) { return x * __builtin_amdgcn_rcpf(1.f + __expf(-x)); }
; __device__ __forceinline__ v4u pack8(const f32x4 a, const f32x4 b) { v4u w; w.x = cvt_pk_bf16(a[0], a[1]); w.y = cvt_pk_bf16(a[2], a[3]); w.z = cvt_pk_bf16(b[0], b[1]); w.w = cvt_pk_bf16(b[2], b[3]); return w; }
;     __device__ __forceinline__ void operator()(const f32x4 (&acc)[2][2][4][2], const pg8::Unit& u, int wr, int wc, int fr, int fq) const {
;     ...
;         if (grp == 0) { WIN_LOOP( _Pragma("unroll") for (int i = 0; i < 4; ++i) { a[i] = silu_f(a[i]); b[i] = silu_f(b[i]); } *(v4u*)(QO + (size_t)row * DM + c) = pack8(a, b); ) }
;         else if (grp == 3) { WIN_LOOP( _Pragma("unroll") for (int i = 0; i < 4; ++i) { a[i] = silu_f(a[i]); b[i] = silu_f(b[i]); } *(v4u*)(GH + (size_t)row * 512 + c) = pack8(a, b); ) }
;         else if (grp == 1) {
;             f32x4 l0[2], l1[2];
; #pragma unroll
;             for (int bj = 0; bj < 2; ++bj) { l0[bj] = *(const f32x4*)(lb + cb + bj * 128); l1[bj] = *(const f32x4*)(lb + cb + bj * 128 + 4); }
;             WIN_LOOP( _Pragma("unroll") for (int i = 0; i < 4; ++i) { const float s0 = fminf(a[i], 0.f) - __logf(1.f + __expf(-fabsf(a[i]))), s1 = fminf(b[i], 0.f) - __logf(1.f + __expf(-fabsf(b[i]))); const float la = l0[bj][i], lbv = l1[bj][i];
;                     a[i] = la > 0.f ? __logf(la + (1.f - la) * __expf(s0)) : s0; b[i] = lbv > 0.f ? __logf(lbv + (1.f - lbv) * __expf(s1)) : s1; }
;                 *(f32x4*)(LF + (size_t)row * 512 + c) = a; *(f32x4*)(LF + (size_t)row * 512 + c + 4) = b; __builtin_amdgcn_sched_barrier(0); ) }
	v_fmac_f32_e32 v195, 0x3377d1cf, v146
	v_fmac_f32_e32 v195, 0x3f317217, v146
	v_mov_b32_e32 v146, v195
	v_sub_f32_e32 v194, v194, v146
	v_mul_f32_e32 v146, 0x3fb8aa3b, v150
	v_exp_f32_e32 v146, v146
	s_nop 0
	v_fma_f32 v146, v187, v146, v142
	v_log_f32_e32 v146, v146
	s_nop 0
	v_mul_f32_e32 v195, 0x3f317217, v146
	v_fma_f32 v195, v146, s52, -v195
	v_fmac_f32_e32 v195, 0x3377d1cf, v146
	v_fmac_f32_e32 v195, 0x3f317217, v146
	v_mov_b32_e32 v146, v195
	v_cndmask_b32_e64 v146, v150, v146, s[28:29]
	v_mul_f32_e32 v150, 0x3fb8aa3b, v194
	v_exp_f32_e32 v150, v150
	s_nop 0
	v_fma_f32 v150, v186, v150, v138
	v_log_f32_e32 v150, v150
	s_nop 0
	v_mul_f32_e32 v195, 0x3f317217, v150
	v_fma_f32 v195, v150, s52, -v195
	v_fmac_f32_e32 v195, 0x3377d1cf, v150
	v_fmac_f32_e32 v195, 0x3f317217, v150
	v_mov_b32_e32 v150, v195
	v_cndmask_b32_e64 v150, v194, v150, s[26:27]
	v_min_f32_e32 v194, 0, v151
	v_mul_f32_e64 v151, |v151|, s57
	v_exp_f32_e32 v151, v151
	s_nop 0
	v_add_f32_e32 v151, 1.0, v151
	v_log_f32_e32 v151, v151
	s_nop 0
	v_mul_f32_e32 v195, 0x3f317217, v151
	v_fma_f32 v195, v151, s52, -v195
	v_fmac_f32_e32 v195, 0x3377d1cf, v151
	v_fmac_f32_e32 v195, 0x3f317217, v151
	v_mov_b32_e32 v151, v195
	v_sub_f32_e32 v151, v194, v151
	v_min_f32_e32 v194, 0, v147
	v_mul_f32_e64 v147, |v147|, s57
	v_exp_f32_e32 v147, v147
	s_nop 0
	v_add_f32_e32 v147, 1.0, v147
	v_log_f32_e32 v147, v147
	s_nop 0
	v_mul_f32_e32 v195, 0x3f317217, v147
	v_fma_f32 v195, v147, s52, -v195
	v_fmac_f32_e32 v195, 0x3377d1cf, v147
	v_fmac_f32_e32 v195, 0x3f317217, v147
	v_mov_b32_e32 v147, v195
	v_sub_f32_e32 v194, v194, v147
	v_mul_f32_e32 v147, 0x3fb8aa3b, v151
	v_exp_f32_e32 v147, v147
	s_nop 0
	v_fma_f32 v147, v185, v147, v143
	v_log_f32_e32 v147, v147
	s_nop 0
	v_mul_f32_e32 v195, 0x3f317217, v147
	v_fma_f32 v195, v147, s52, -v195
	v_fmac_f32_e32 v195, 0x3377d1cf, v147
	v_fmac_f32_e32 v195, 0x3f317217, v147
	v_mov_b32_e32 v147, v195
	v_cndmask_b32_e64 v147, v151, v147, s[24:25]
	v_mul_f32_e32 v151, 0x3fb8aa3b, v194
	v_exp_f32_e32 v151, v151
	s_nop 0
	v_fma_f32 v151, v184, v151, v139
	v_log_f32_e32 v151, v151
	s_nop 0
	v_mul_f32_e32 v195, 0x3f317217, v151
	v_fma_f32 v195, v151, s52, -v195
	v_fmac_f32_e32 v195, 0x3377d1cf, v151
	v_fmac_f32_e32 v195, 0x3f317217, v151
	v_mov_b32_e32 v151, v195
	v_cndmask_b32_e64 v151, v194, v151, s[22:23]
	global_store_dwordx4 v[170:171], v[144:147], off
	global_store_dwordx4 v[170:171], v[148:151], off offset:16
	s_nop 1
	v_pk_mul_f32 v[148:149], v[100:101], v[168:169] op_sel_hi:[1,0]
	v_pk_mul_f32 v[150:151], v[102:103], v[168:169] op_sel_hi:[1,0]
	v_pk_mul_f32 v[146:147], v[98:99], v[168:169] op_sel_hi:[1,0]
	v_pk_mul_f32 v[144:145], v[96:97], v[168:169] op_sel_hi:[1,0]
	v_min_f32_e32 v168, 0, v148
	v_mul_f32_e64 v148, |v148|, s57
	v_exp_f32_e32 v148, v148
	s_nop 0
	v_add_f32_e32 v148, 1.0, v148
	v_log_f32_e32 v148, v148
	s_nop 0
	v_mul_f32_e32 v194, 0x3f317217, v148
	v_fma_f32 v194, v148, s52, -v194
	v_fmac_f32_e32 v194, 0x3377d1cf, v148
	v_fmac_f32_e32 v194, 0x3f317217, v148
	v_mov_b32_e32 v148, v194
	v_sub_f32_e32 v148, v168, v148
	v_min_f32_e32 v168, 0, v144
	v_mul_f32_e64 v144, |v144|, s57
	v_exp_f32_e32 v144, v144
	s_nop 0
	v_add_f32_e32 v144, 1.0, v144
	v_log_f32_e32 v144, v144
	s_nop 0
	v_mul_f32_e32 v194, 0x3f317217, v144
	v_fma_f32 v194, v144, s52, -v194
	v_fmac_f32_e32 v194, 0x3377d1cf, v144
	v_fmac_f32_e32 v194, 0x3f317217, v144
	v_mov_b32_e32 v144, v194
	v_sub_f32_e32 v168, v168, v144
	v_mul_f32_e32 v144, 0x3fb8aa3b, v148
	v_exp_f32_e32 v144, v144
	s_nop 0
	v_fma_f32 v144, v183, v144, v132
	v_log_f32_e32 v144, v144
	s_nop 0
	v_mul_f32_e32 v194, 0x3f317217, v144
	v_fma_f32 v194, v144, s52, -v194
	v_fmac_f32_e32 v194, 0x3377d1cf, v144
	v_fmac_f32_e32 v194, 0x3f317217, v144
	v_mov_b32_e32 v144, v194
	v_cndmask_b32_e64 v144, v148, v144, s[20:21]
	v_mul_f32_e32 v148, 0x3fb8aa3b, v168
	v_exp_f32_e32 v148, v148
	s_nop 0
	v_fma_f32 v148, v182, v148, v128
	v_log_f32_e32 v148, v148
	s_nop 0
	v_mul_f32_e32 v194, 0x3f317217, v148
	v_fma_f32 v194, v148, s52, -v194
	v_fmac_f32_e32 v194, 0x3377d1cf, v148
	v_fmac_f32_e32 v194, 0x3f317217, v148
	v_mov_b32_e32 v148, v194
	v_cndmask_b32_e64 v148, v168, v148, s[18:19]
	v_min_f32_e32 v168, 0, v149
	v_mul_f32_e64 v149, |v149|, s57
	v_exp_f32_e32 v149, v149
	s_nop 0
	v_add_f32_e32 v149, 1.0, v149
	v_log_f32_e32 v149, v149
	s_nop 0
	v_mul_f32_e32 v194, 0x3f317217, v149
	v_fma_f32 v194, v149, s52, -v194
	v_fmac_f32_e32 v194, 0x3377d1cf, v149
	v_fmac_f32_e32 v194, 0x3f317217, v149
	v_mov_b32_e32 v149, v194
	v_sub_f32_e32 v149, v168, v149
	v_min_f32_e32 v168, 0, v145
	v_mul_f32_e64 v145, |v145|, s57
	v_exp_f32_e32 v145, v145
	s_nop 0
	v_add_f32_e32 v145, 1.0, v145
	v_log_f32_e32 v145, v145
	s_nop 0
	v_mul_f32_e32 v194, 0x3f317217, v145
	v_fma_f32 v194, v145, s52, -v194
	v_fmac_f32_e32 v194, 0x3377d1cf, v145
	v_fmac_f32_e32 v194, 0x3f317217, v145
	v_mov_b32_e32 v145, v194
	v_sub_f32_e32 v168, v168, v145
	v_mul_f32_e32 v145, 0x3fb8aa3b, v149
	v_exp_f32_e32 v145, v145
	s_nop 0
	v_fma_f32 v145, v181, v145, v133
	v_log_f32_e32 v145, v145
	s_nop 0
	v_mul_f32_e32 v194, 0x3f317217, v145
	v_fma_f32 v194, v145, s52, -v194
	v_fmac_f32_e32 v194, 0x3377d1cf, v145
	v_fmac_f32_e32 v194, 0x3f317217, v145
	v_mov_b32_e32 v145, v194
	v_cndmask_b32_e64 v145, v149, v145, s[16:17]
	v_mul_f32_e32 v149, 0x3fb8aa3b, v168
	v_exp_f32_e32 v149, v149
	s_nop 0
	v_fma_f32 v149, v180, v149, v129
	v_log_f32_e32 v149, v149
	s_nop 0
	v_mul_f32_e32 v194, 0x3f317217, v149
	v_fma_f32 v194, v149, s52, -v194
	v_fmac_f32_e32 v194, 0x3377d1cf, v149
	v_fmac_f32_e32 v194, 0x3f317217, v149
	v_mov_b32_e32 v149, v194
	v_cndmask_b32_e64 v149, v168, v149, s[14:15]
; __device__ __forceinline__ float silu_f(float x) { return x * __builtin_amdgcn_rcpf(1.f + __expf(-x)); }
; __device__ __forceinline__ v4u pack8(const f32x4 a, const f32x4 b) { v4u w; w.x = cvt_pk_bf16(a[0], a[1]); w.y = cvt_pk_bf16(a[2], a[3]); w.z = cvt_pk_bf16(b[0], b[1]); w.w = cvt_pk_bf16(b[2], b[3]); return w; }
;     __device__ __forceinline__ void operator()(const f32x4 (&acc)[2][2][4][2], const pg8::Unit& u, int wr, int wc, int fr, int fq) const {
;     ...
;         if (grp == 0) { WIN_LOOP( _Pragma("unroll") for (int i = 0; i < 4; ++i) { a[i] = silu_f(a[i]); b[i] = silu_f(b[i]); } *(v4u*)(QO + (size_t)row * DM + c) = pack8(a, b); ) }
;         else if (grp == 3) { WIN_LOOP( _Pragma("unroll") for (int i = 0; i < 4; ++i) { a[i] = silu_f(a[i]); b[i] = silu_f(b[i]); } *(v4u*)(GH + (size_t)row * 512 + c) = pack8(a, b); ) }
;         else if (grp == 1) {
;             f32x4 l0[2], l1[2];
; #pragma unroll
;             for (int bj = 0; bj < 2; ++bj) { l0[bj] = *(const f32x4*)(lb + cb + bj * 128); l1[bj] = *(const f32x4*)(lb + cb + bj * 128 + 4); }
;             WIN_LOOP( _Pragma("unroll") for (int i = 0; i < 4; ++i) { const float s0 = fminf(a[i], 0.f) - __logf(1.f + __expf(-fabsf(a[i]))), s1 = fminf(b[i], 0.f) - __logf(1.f + __expf(-fabsf(b[i]))); const float la = l0[bj][i], lbv = l1[bj][i];
;                     a[i] = la > 0.f ? __logf(la + (1.f - la) * __expf(s0)) : s0; b[i] = lbv > 0.f ? __logf(lbv + (1.f - lbv) * __expf(s1)) : s1; }
;                 *(f32x4*)(LF + (size_t)row * 512 + c) = a; *(f32x4*)(LF + (size_t)row * 512 + c + 4) = b; __builtin_amdgcn_sched_barrier(0); ) }
	v_min_f32_e32 v168, 0, v150
	v_mul_f32_e64 v150, |v150|, s57
	v_exp_f32_e32 v150, v150
	s_nop 0
	v_add_f32_e32 v150, 1.0, v150
	v_log_f32_e32 v150, v150
	s_nop 0
	v_mul_f32_e32 v194, 0x3f317217, v150
	v_fma_f32 v194, v150, s52, -v194
	v_fmac_f32_e32 v194, 0x3377d1cf, v150
	v_fmac_f32_e32 v194, 0x3f317217, v150
	v_mov_b32_e32 v150, v194
	v_sub_f32_e32 v150, v168, v150
	v_min_f32_e32 v168, 0, v146
	v_mul_f32_e64 v146, |v146|, s57
	v_exp_f32_e32 v146, v146
	s_nop 0
	v_add_f32_e32 v146, 1.0, v146
	v_log_f32_e32 v146, v146
	s_nop 0
	v_mul_f32_e32 v194, 0x3f317217, v146
	v_fma_f32 v194, v146, s52, -v194
	v_fmac_f32_e32 v194, 0x3377d1cf, v146
	v_fmac_f32_e32 v194, 0x3f317217, v146
	v_mov_b32_e32 v146, v194
	v_sub_f32_e32 v168, v168, v146
	v_mul_f32_e32 v146, 0x3fb8aa3b, v150
	v_exp_f32_e32 v146, v146
	s_nop 0
	v_fma_f32 v146, v179, v146, v134
	v_log_f32_e32 v146, v146
	s_nop 0
	v_mul_f32_e32 v194, 0x3f317217, v146
	v_fma_f32 v194, v146, s52, -v194
	v_fmac_f32_e32 v194, 0x3377d1cf, v146
	v_fmac_f32_e32 v194, 0x3f317217, v146
	v_mov_b32_e32 v146, v194
	v_cndmask_b32_e64 v146, v150, v146, s[12:13]
	v_mul_f32_e32 v150, 0x3fb8aa3b, v168
	v_exp_f32_e32 v150, v150
	s_nop 0
	v_fma_f32 v150, v178, v150, v130
	v_log_f32_e32 v150, v150
	s_nop 0
	v_mul_f32_e32 v194, 0x3f317217, v150
	v_fma_f32 v194, v150, s52, -v194
	v_fmac_f32_e32 v194, 0x3377d1cf, v150
	v_fmac_f32_e32 v194, 0x3f317217, v150
	v_mov_b32_e32 v150, v194
	v_cndmask_b32_e64 v150, v168, v150, s[10:11]
	v_min_f32_e32 v168, 0, v151
	v_mul_f32_e64 v151, |v151|, s57
	v_exp_f32_e32 v151, v151
	s_nop 0
	v_add_f32_e32 v151, 1.0, v151
	v_log_f32_e32 v151, v151
	s_nop 0
	v_mul_f32_e32 v194, 0x3f317217, v151
	v_fma_f32 v194, v151, s52, -v194
	v_fmac_f32_e32 v194, 0x3377d1cf, v151
	v_fmac_f32_e32 v194, 0x3f317217, v151
	v_mov_b32_e32 v151, v194
	v_sub_f32_e32 v151, v168, v151
	v_min_f32_e32 v168, 0, v147
	v_mul_f32_e64 v147, |v147|, s57
	v_exp_f32_e32 v147, v147
	s_nop 0
	v_add_f32_e32 v147, 1.0, v147
	v_log_f32_e32 v147, v147
	s_nop 0
	v_mul_f32_e32 v194, 0x3f317217, v147
	v_fma_f32 v194, v147, s52, -v194
	v_fmac_f32_e32 v194, 0x3377d1cf, v147
	v_fmac_f32_e32 v194, 0x3f317217, v147
	v_mov_b32_e32 v147, v194
	v_sub_f32_e32 v168, v168, v147
	v_mul_f32_e32 v147, 0x3fb8aa3b, v151
	v_exp_f32_e32 v147, v147
	s_nop 0
	v_fma_f32 v147, v177, v147, v135
	v_log_f32_e32 v147, v147
	s_nop 0
	v_mul_f32_e32 v194, 0x3f317217, v147
	v_fma_f32 v194, v147, s52, -v194
	v_fmac_f32_e32 v194, 0x3377d1cf, v147
	v_fmac_f32_e32 v194, 0x3f317217, v147
	v_mov_b32_e32 v147, v194
	v_cndmask_b32_e64 v147, v151, v147, s[8:9]
	v_mul_f32_e32 v151, 0x3fb8aa3b, v168
	v_exp_f32_e32 v151, v151
	s_nop 0
	v_fma_f32 v151, v167, v151, v131
	v_log_f32_e32 v151, v151
	s_nop 0
	v_mul_f32_e32 v194, 0x3f317217, v151
	v_fma_f32 v194, v151, s52, -v194
	v_fmac_f32_e32 v194, 0x3377d1cf, v151
	v_fmac_f32_e32 v194, 0x3f317217, v151
	v_mov_b32_e32 v151, v194
	v_cndmask_b32_e32 v151, v168, v151, vcc
	global_store_dwordx4 v[170:171], v[144:147], off offset:512
	global_store_dwordx4 v[170:171], v[148:151], off offset:528
	s_nop 1
	v_add_u32_e32 v148, 0x80, v166
	v_ashrrev_i32_e32 v149, 31, v148
	v_lshlrev_b64 v[144:145], 6, v[148:149]
	v_lshl_add_u64 v[144:145], v[160:161], 0, v[144:145]
	s_nop 0
	s_waitcnt lgkmcnt(0)
	s_nop 3
	s_nop 0
	s_nop 1
	s_waitcnt lgkmcnt(0)
	s_nop 1
	s_waitcnt lgkmcnt(0)
	s_nop 1
	v_mov_b32_e32 v168, v254
	v_lshlrev_b64 v[144:145], 11, v[148:149]
	v_lshl_add_u64 v[170:171], s[50:51], 0, v[144:145]
	v_lshl_add_u64 v[170:171], v[170:171], 0, v[192:193]
	v_pk_mul_f32 v[148:149], v[28:29], v[168:169] op_sel_hi:[1,0]
	v_pk_mul_f32 v[144:145], v[24:25], v[168:169] op_sel_hi:[1,0]
	v_min_f32_e32 v194, 0, v148
	v_mul_f32_e64 v148, |v148|, s57
	v_exp_f32_e32 v148, v148
	v_pk_mul_f32 v[150:151], v[30:31], v[168:169] op_sel_hi:[1,0]
	v_pk_mul_f32 v[146:147], v[26:27], v[168:169] op_sel_hi:[1,0]
	v_add_f32_e32 v148, 1.0, v148
	v_log_f32_e32 v148, v148
	s_nop 0
	v_mul_f32_e32 v195, 0x3f317217, v148
	v_fma_f32 v195, v148, s52, -v195
	v_fmac_f32_e32 v195, 0x3377d1cf, v148
	v_fmac_f32_e32 v195, 0x3f317217, v148
	v_mov_b32_e32 v148, v195
	v_sub_f32_e32 v148, v194, v148
	v_min_f32_e32 v194, 0, v144
	v_mul_f32_e64 v144, |v144|, s57
	v_exp_f32_e32 v144, v144
	s_nop 0
	v_add_f32_e32 v144, 1.0, v144
	v_log_f32_e32 v144, v144
	s_nop 0
	v_mul_f32_e32 v195, 0x3f317217, v144
	v_fma_f32 v195, v144, s52, -v195
	v_fmac_f32_e32 v195, 0x3377d1cf, v144
	v_fmac_f32_e32 v195, 0x3f317217, v144
	v_mov_b32_e32 v144, v195
	v_sub_f32_e32 v194, v194, v144
	v_mul_f32_e32 v144, 0x3fb8aa3b, v148
	v_exp_f32_e32 v144, v144
	s_nop 0
	v_fma_f32 v144, v190, v144, v140
	v_log_f32_e32 v144, v144
	s_nop 0
	v_mul_f32_e32 v195, 0x3f317217, v144
	v_fma_f32 v195, v144, s52, -v195
	v_fmac_f32_e32 v195, 0x3377d1cf, v144
	v_fmac_f32_e32 v195, 0x3f317217, v144
	v_mov_b32_e32 v144, v195
	v_cndmask_b32_e64 v144, v148, v144, s[38:39]
	v_mul_f32_e32 v148, 0x3fb8aa3b, v194
	v_exp_f32_e32 v148, v148
	s_nop 0
	v_fma_f32 v148, v191, v148, v136
	v_log_f32_e32 v148, v148
	s_nop 0
	v_mul_f32_e32 v195, 0x3f317217, v148
	v_fma_f32 v195, v148, s52, -v195
	v_fmac_f32_e32 v195, 0x3377d1cf, v148
	v_fmac_f32_e32 v195, 0x3f317217, v148
	v_mov_b32_e32 v148, v195
	v_cndmask_b32_e64 v148, v194, v148, s[36:37]
	v_min_f32_e32 v194, 0, v149
	v_mul_f32_e64 v149, |v149|, s57
	v_exp_f32_e32 v149, v149
	s_nop 0
	v_add_f32_e32 v149, 1.0, v149
	v_log_f32_e32 v149, v149
	s_nop 0
	v_mul_f32_e32 v195, 0x3f317217, v149
	v_fma_f32 v195, v149, s52, -v195
	v_fmac_f32_e32 v195, 0x3377d1cf, v149
	v_fmac_f32_e32 v195, 0x3f317217, v149
	v_mov_b32_e32 v149, v195
	v_sub_f32_e32 v149, v194, v149
	v_min_f32_e32 v194, 0, v145
; __device__ __forceinline__ float silu_f(float x) { return x * __builtin_amdgcn_rcpf(1.f + __expf(-x)); }
; __device__ __forceinline__ v4u pack8(const f32x4 a, const f32x4 b) { v4u w; w.x = cvt_pk_bf16(a[0], a[1]); w.y = cvt_pk_bf16(a[2], a[3]); w.z = cvt_pk_bf16(b[0], b[1]); w.w = cvt_pk_bf16(b[2], b[3]); return w; }
;     __device__ __forceinline__ void operator()(const f32x4 (&acc)[2][2][4][2], const pg8::Unit& u, int wr, int wc, int fr, int fq) const {
;     ...
;         if (grp == 0) { WIN_LOOP( _Pragma("unroll") for (int i = 0; i < 4; ++i) { a[i] = silu_f(a[i]); b[i] = silu_f(b[i]); } *(v4u*)(QO + (size_t)row * DM + c) = pack8(a, b); ) }
;         else if (grp == 3) { WIN_LOOP( _Pragma("unroll") for (int i = 0; i < 4; ++i) { a[i] = silu_f(a[i]); b[i] = silu_f(b[i]); } *(v4u*)(GH + (size_t)row * 512 + c) = pack8(a, b); ) }
;         else if (grp == 1) {
;             f32x4 l0[2], l1[2];
; #pragma unroll
;             for (int bj = 0; bj < 2; ++bj) { l0[bj] = *(const f32x4*)(lb + cb + bj * 128); l1[bj] = *(const f32x4*)(lb + cb + bj * 128 + 4); }
;             WIN_LOOP( _Pragma("unroll") for (int i = 0; i < 4; ++i) { const float s0 = fminf(a[i], 0.f) - __logf(1.f + __expf(-fabsf(a[i]))), s1 = fminf(b[i], 0.f) - __logf(1.f + __expf(-fabsf(b[i]))); const float la = l0[bj][i], lbv = l1[bj][i];
;                     a[i] = la > 0.f ? __logf(la + (1.f - la) * __expf(s0)) : s0; b[i] = lbv > 0.f ? __logf(lbv + (1.f - lbv) * __expf(s1)) : s1; }
;                 *(f32x4*)(LF + (size_t)row * 512 + c) = a; *(f32x4*)(LF + (size_t)row * 512 + c + 4) = b; __builtin_amdgcn_sched_barrier(0); ) }
	v_mul_f32_e64 v145, |v145|, s57
	v_exp_f32_e32 v145, v145
	s_nop 0
	v_add_f32_e32 v145, 1.0, v145
	v_log_f32_e32 v145, v145
	s_nop 0
	v_mul_f32_e32 v195, 0x3f317217, v145
	v_fma_f32 v195, v145, s52, -v195
	v_fmac_f32_e32 v195, 0x3377d1cf, v145
	v_fmac_f32_e32 v195, 0x3f317217, v145
	v_mov_b32_e32 v145, v195
	v_sub_f32_e32 v194, v194, v145
	v_mul_f32_e32 v145, 0x3fb8aa3b, v149
	v_exp_f32_e32 v145, v145
	s_nop 0
	v_fma_f32 v145, v188, v145, v141
	v_log_f32_e32 v145, v145
	s_nop 0
	v_mul_f32_e32 v195, 0x3f317217, v145
	v_fma_f32 v195, v145, s52, -v195
	v_fmac_f32_e32 v195, 0x3377d1cf, v145
	v_fmac_f32_e32 v195, 0x3f317217, v145
	v_mov_b32_e32 v145, v195
	v_cndmask_b32_e64 v145, v149, v145, s[34:35]
	v_mul_f32_e32 v149, 0x3fb8aa3b, v194
	v_exp_f32_e32 v149, v149
	s_nop 0
	v_fma_f32 v149, v189, v149, v137
	v_log_f32_e32 v149, v149
	s_nop 0
	v_mul_f32_e32 v195, 0x3f317217, v149
	v_fma_f32 v195, v149, s52, -v195
	v_fmac_f32_e32 v195, 0x3377d1cf, v149
	v_fmac_f32_e32 v195, 0x3f317217, v149
	v_mov_b32_e32 v149, v195
	v_cndmask_b32_e64 v149, v194, v149, s[30:31]
	v_min_f32_e32 v194, 0, v150
	v_mul_f32_e64 v150, |v150|, s57
	v_exp_f32_e32 v150, v150
	s_nop 0
	v_add_f32_e32 v150, 1.0, v150
	v_log_f32_e32 v150, v150
	s_nop 0
	v_mul_f32_e32 v195, 0x3f317217, v150
	v_fma_f32 v195, v150, s52, -v195
	v_fmac_f32_e32 v195, 0x3377d1cf, v150
	v_fmac_f32_e32 v195, 0x3f317217, v150
	v_mov_b32_e32 v150, v195
	v_sub_f32_e32 v150, v194, v150
	v_min_f32_e32 v194, 0, v146
	v_mul_f32_e64 v146, |v146|, s57
	v_exp_f32_e32 v146, v146
	s_nop 0
	v_add_f32_e32 v146, 1.0, v146
	v_log_f32_e32 v146, v146
	s_nop 0
	v_mul_f32_e32 v195, 0x3f317217, v146
	v_fma_f32 v195, v146, s52, -v195
	v_fmac_f32_e32 v195, 0x3377d1cf, v146
	v_fmac_f32_e32 v195, 0x3f317217, v146
	v_mov_b32_e32 v146, v195
	v_sub_f32_e32 v194, v194, v146
	v_mul_f32_e32 v146, 0x3fb8aa3b, v150
	v_exp_f32_e32 v146, v146
	s_nop 0
	v_fma_f32 v146, v187, v146, v142
	v_log_f32_e32 v146, v146
	s_nop 0
	v_mul_f32_e32 v195, 0x3f317217, v146
	v_fma_f32 v195, v146, s52, -v195
	v_fmac_f32_e32 v195, 0x3377d1cf, v146
	v_fmac_f32_e32 v195, 0x3f317217, v146
	v_mov_b32_e32 v146, v195
	v_cndmask_b32_e64 v146, v150, v146, s[28:29]
	v_mul_f32_e32 v150, 0x3fb8aa3b, v194
	v_exp_f32_e32 v150, v150
	s_nop 0
	v_fma_f32 v150, v186, v150, v138
	v_log_f32_e32 v150, v150
	s_nop 0
	v_mul_f32_e32 v195, 0x3f317217, v150
	v_fma_f32 v195, v150, s52, -v195
	v_fmac_f32_e32 v195, 0x3377d1cf, v150
	v_fmac_f32_e32 v195, 0x3f317217, v150
	v_mov_b32_e32 v150, v195
	v_cndmask_b32_e64 v150, v194, v150, s[26:27]
	v_min_f32_e32 v194, 0, v151
	v_mul_f32_e64 v151, |v151|, s57
	v_exp_f32_e32 v151, v151
	s_nop 0
	v_add_f32_e32 v151, 1.0, v151
	v_log_f32_e32 v151, v151
	s_nop 0
	v_mul_f32_e32 v195, 0x3f317217, v151
	v_fma_f32 v195, v151, s52, -v195
	v_fmac_f32_e32 v195, 0x3377d1cf, v151
	v_fmac_f32_e32 v195, 0x3f317217, v151
	v_mov_b32_e32 v151, v195
	v_sub_f32_e32 v151, v194, v151
	v_min_f32_e32 v194, 0, v147
	v_mul_f32_e64 v147, |v147|, s57
	v_exp_f32_e32 v147, v147
	s_nop 0
	v_add_f32_e32 v147, 1.0, v147
	v_log_f32_e32 v147, v147
	s_nop 0
	v_mul_f32_e32 v195, 0x3f317217, v147
	v_fma_f32 v195, v147, s52, -v195
	v_fmac_f32_e32 v195, 0x3377d1cf, v147
	v_fmac_f32_e32 v195, 0x3f317217, v147
	v_mov_b32_e32 v147, v195
	v_sub_f32_e32 v194, v194, v147
	v_mul_f32_e32 v147, 0x3fb8aa3b, v151
	v_exp_f32_e32 v147, v147
	s_nop 0
	v_fma_f32 v147, v185, v147, v143
	v_log_f32_e32 v147, v147
	s_nop 0
	v_mul_f32_e32 v195, 0x3f317217, v147
	v_fma_f32 v195, v147, s52, -v195
	v_fmac_f32_e32 v195, 0x3377d1cf, v147
	v_fmac_f32_e32 v195, 0x3f317217, v147
	v_mov_b32_e32 v147, v195
	v_cndmask_b32_e64 v147, v151, v147, s[24:25]
	v_mul_f32_e32 v151, 0x3fb8aa3b, v194
	v_exp_f32_e32 v151, v151
	s_nop 0
	v_fma_f32 v151, v184, v151, v139
	v_log_f32_e32 v151, v151
	s_nop 0
	v_mul_f32_e32 v195, 0x3f317217, v151
	v_fma_f32 v195, v151, s52, -v195
	v_fmac_f32_e32 v195, 0x3377d1cf, v151
	v_fmac_f32_e32 v195, 0x3f317217, v151
	v_mov_b32_e32 v151, v195
	v_cndmask_b32_e64 v151, v194, v151, s[22:23]
	global_store_dwordx4 v[170:171], v[144:147], off
	global_store_dwordx4 v[170:171], v[148:151], off offset:16
	s_nop 1
	v_pk_mul_f32 v[148:149], v[92:93], v[168:169] op_sel_hi:[1,0]
	v_pk_mul_f32 v[150:151], v[94:95], v[168:169] op_sel_hi:[1,0]
	v_pk_mul_f32 v[146:147], v[90:91], v[168:169] op_sel_hi:[1,0]
	v_pk_mul_f32 v[144:145], v[88:89], v[168:169] op_sel_hi:[1,0]
	v_min_f32_e32 v168, 0, v148
	v_mul_f32_e64 v148, |v148|, s57
	v_exp_f32_e32 v148, v148
	s_nop 0
	v_add_f32_e32 v148, 1.0, v148
	v_log_f32_e32 v148, v148
	s_nop 0
	v_mul_f32_e32 v194, 0x3f317217, v148
	v_fma_f32 v194, v148, s52, -v194
	v_fmac_f32_e32 v194, 0x3377d1cf, v148
	v_fmac_f32_e32 v194, 0x3f317217, v148
	v_mov_b32_e32 v148, v194
	v_sub_f32_e32 v148, v168, v148
	v_min_f32_e32 v168, 0, v144
	v_mul_f32_e64 v144, |v144|, s57
	v_exp_f32_e32 v144, v144
	s_nop 0
	v_add_f32_e32 v144, 1.0, v144
	v_log_f32_e32 v144, v144
	s_nop 0
	v_mul_f32_e32 v194, 0x3f317217, v144
	v_fma_f32 v194, v144, s52, -v194
	v_fmac_f32_e32 v194, 0x3377d1cf, v144
	v_fmac_f32_e32 v194, 0x3f317217, v144
	v_mov_b32_e32 v144, v194
	v_sub_f32_e32 v168, v168, v144
	v_mul_f32_e32 v144, 0x3fb8aa3b, v148
	v_exp_f32_e32 v144, v144
	s_nop 0
	v_fma_f32 v144, v183, v144, v132
	v_log_f32_e32 v144, v144
	s_nop 0
	v_mul_f32_e32 v194, 0x3f317217, v144
	v_fma_f32 v194, v144, s52, -v194
	v_fmac_f32_e32 v194, 0x3377d1cf, v144
	v_fmac_f32_e32 v194, 0x3f317217, v144
	v_mov_b32_e32 v144, v194
	v_cndmask_b32_e64 v144, v148, v144, s[20:21]
	v_mul_f32_e32 v148, 0x3fb8aa3b, v168
	v_exp_f32_e32 v148, v148
	s_nop 0
	v_fma_f32 v148, v182, v148, v128
	v_log_f32_e32 v148, v148
	s_nop 0
; __device__ __forceinline__ float silu_f(float x) { return x * __builtin_amdgcn_rcpf(1.f + __expf(-x)); }
; __device__ __forceinline__ v4u pack8(const f32x4 a, const f32x4 b) { v4u w; w.x = cvt_pk_bf16(a[0], a[1]); w.y = cvt_pk_bf16(a[2], a[3]); w.z = cvt_pk_bf16(b[0], b[1]); w.w = cvt_pk_bf16(b[2], b[3]); return w; }
;     __device__ __forceinline__ void operator()(const f32x4 (&acc)[2][2][4][2], const pg8::Unit& u, int wr, int wc, int fr, int fq) const {
;     ...
;         if (grp == 0) { WIN_LOOP( _Pragma("unroll") for (int i = 0; i < 4; ++i) { a[i] = silu_f(a[i]); b[i] = silu_f(b[i]); } *(v4u*)(QO + (size_t)row * DM + c) = pack8(a, b); ) }
;         else if (grp == 3) { WIN_LOOP( _Pragma("unroll") for (int i = 0; i < 4; ++i) { a[i] = silu_f(a[i]); b[i] = silu_f(b[i]); } *(v4u*)(GH + (size_t)row * 512 + c) = pack8(a, b); ) }
;         else if (grp == 1) {
;             f32x4 l0[2], l1[2];
; #pragma unroll
;             for (int bj = 0; bj < 2; ++bj) { l0[bj] = *(const f32x4*)(lb + cb + bj * 128); l1[bj] = *(const f32x4*)(lb + cb + bj * 128 + 4); }
;             WIN_LOOP( _Pragma("unroll") for (int i = 0; i < 4; ++i) { const float s0 = fminf(a[i], 0.f) - __logf(1.f + __expf(-fabsf(a[i]))), s1 = fminf(b[i], 0.f) - __logf(1.f + __expf(-fabsf(b[i]))); const float la = l0[bj][i], lbv = l1[bj][i];
;                     a[i] = la > 0.f ? __logf(la + (1.f - la) * __expf(s0)) : s0; b[i] = lbv > 0.f ? __logf(lbv + (1.f - lbv) * __expf(s1)) : s1; }
;                 *(f32x4*)(LF + (size_t)row * 512 + c) = a; *(f32x4*)(LF + (size_t)row * 512 + c + 4) = b; __builtin_amdgcn_sched_barrier(0); ) }
	v_mul_f32_e32 v194, 0x3f317217, v148
	v_fma_f32 v194, v148, s52, -v194
	v_fmac_f32_e32 v194, 0x3377d1cf, v148
	v_fmac_f32_e32 v194, 0x3f317217, v148
	v_mov_b32_e32 v148, v194
	v_cndmask_b32_e64 v148, v168, v148, s[18:19]
	v_min_f32_e32 v168, 0, v149
	v_mul_f32_e64 v149, |v149|, s57
	v_exp_f32_e32 v149, v149
	s_nop 0
	v_add_f32_e32 v149, 1.0, v149
	v_log_f32_e32 v149, v149
	s_nop 0
	v_mul_f32_e32 v194, 0x3f317217, v149
	v_fma_f32 v194, v149, s52, -v194
	v_fmac_f32_e32 v194, 0x3377d1cf, v149
	v_fmac_f32_e32 v194, 0x3f317217, v149
	v_mov_b32_e32 v149, v194
	v_sub_f32_e32 v149, v168, v149
	v_min_f32_e32 v168, 0, v145
	v_mul_f32_e64 v145, |v145|, s57
	v_exp_f32_e32 v145, v145
	s_nop 0
	v_add_f32_e32 v145, 1.0, v145
	v_log_f32_e32 v145, v145
	s_nop 0
	v_mul_f32_e32 v194, 0x3f317217, v145
	v_fma_f32 v194, v145, s52, -v194
	v_fmac_f32_e32 v194, 0x3377d1cf, v145
	v_fmac_f32_e32 v194, 0x3f317217, v145
	v_mov_b32_e32 v145, v194
	v_sub_f32_e32 v168, v168, v145
	v_mul_f32_e32 v145, 0x3fb8aa3b, v149
	v_exp_f32_e32 v145, v145
	s_nop 0
	v_fma_f32 v145, v181, v145, v133
	v_log_f32_e32 v145, v145
	s_nop 0
	v_mul_f32_e32 v194, 0x3f317217, v145
	v_fma_f32 v194, v145, s52, -v194
	v_fmac_f32_e32 v194, 0x3377d1cf, v145
	v_fmac_f32_e32 v194, 0x3f317217, v145
	v_mov_b32_e32 v145, v194
	v_cndmask_b32_e64 v145, v149, v145, s[16:17]
	v_mul_f32_e32 v149, 0x3fb8aa3b, v168
	v_exp_f32_e32 v149, v149
	s_nop 0
	v_fma_f32 v149, v180, v149, v129
	v_log_f32_e32 v149, v149
	s_nop 0
	v_mul_f32_e32 v194, 0x3f317217, v149
	v_fma_f32 v194, v149, s52, -v194
	v_fmac_f32_e32 v194, 0x3377d1cf, v149
	v_fmac_f32_e32 v194, 0x3f317217, v149
	v_mov_b32_e32 v149, v194
	v_cndmask_b32_e64 v149, v168, v149, s[14:15]
	v_min_f32_e32 v168, 0, v150
	v_mul_f32_e64 v150, |v150|, s57
	v_exp_f32_e32 v150, v150
	s_nop 0
	v_add_f32_e32 v150, 1.0, v150
	v_log_f32_e32 v150, v150
	s_nop 0
	v_mul_f32_e32 v194, 0x3f317217, v150
	v_fma_f32 v194, v150, s52, -v194
	v_fmac_f32_e32 v194, 0x3377d1cf, v150
	v_fmac_f32_e32 v194, 0x3f317217, v150
	v_mov_b32_e32 v150, v194
	v_sub_f32_e32 v150, v168, v150
	v_min_f32_e32 v168, 0, v146
	v_mul_f32_e64 v146, |v146|, s57
	v_exp_f32_e32 v146, v146
	s_nop 0
	v_add_f32_e32 v146, 1.0, v146
	v_log_f32_e32 v146, v146
	s_nop 0
	v_mul_f32_e32 v194, 0x3f317217, v146
	v_fma_f32 v194, v146, s52, -v194
	v_fmac_f32_e32 v194, 0x3377d1cf, v146
	v_fmac_f32_e32 v194, 0x3f317217, v146
	v_mov_b32_e32 v146, v194
	v_sub_f32_e32 v168, v168, v146
	v_mul_f32_e32 v146, 0x3fb8aa3b, v150
	v_exp_f32_e32 v146, v146
	s_nop 0
	v_fma_f32 v146, v179, v146, v134
	v_log_f32_e32 v146, v146
	s_nop 0
	v_mul_f32_e32 v194, 0x3f317217, v146
	v_fma_f32 v194, v146, s52, -v194
	v_fmac_f32_e32 v194, 0x3377d1cf, v146
	v_fmac_f32_e32 v194, 0x3f317217, v146
	v_mov_b32_e32 v146, v194
	v_cndmask_b32_e64 v146, v150, v146, s[12:13]
	v_mul_f32_e32 v150, 0x3fb8aa3b, v168
	v_exp_f32_e32 v150, v150
	s_nop 0
	v_fma_f32 v150, v178, v150, v130
	v_log_f32_e32 v150, v150
	s_nop 0
	v_mul_f32_e32 v194, 0x3f317217, v150
	v_fma_f32 v194, v150, s52, -v194
	v_fmac_f32_e32 v194, 0x3377d1cf, v150
	v_fmac_f32_e32 v194, 0x3f317217, v150
	v_mov_b32_e32 v150, v194
	v_cndmask_b32_e64 v150, v168, v150, s[10:11]
	v_min_f32_e32 v168, 0, v151
	v_mul_f32_e64 v151, |v151|, s57
	v_exp_f32_e32 v151, v151
	s_nop 0
	v_add_f32_e32 v151, 1.0, v151
	v_log_f32_e32 v151, v151
	s_nop 0
	v_mul_f32_e32 v194, 0x3f317217, v151
	v_fma_f32 v194, v151, s52, -v194
	v_fmac_f32_e32 v194, 0x3377d1cf, v151
	v_fmac_f32_e32 v194, 0x3f317217, v151
	v_mov_b32_e32 v151, v194
	v_sub_f32_e32 v151, v168, v151
	v_min_f32_e32 v168, 0, v147
	v_mul_f32_e64 v147, |v147|, s57
	v_exp_f32_e32 v147, v147
	s_nop 0
	v_add_f32_e32 v147, 1.0, v147
	v_log_f32_e32 v147, v147
	s_nop 0
	v_mul_f32_e32 v194, 0x3f317217, v147
	v_fma_f32 v194, v147, s52, -v194
	v_fmac_f32_e32 v194, 0x3377d1cf, v147
	v_fmac_f32_e32 v194, 0x3f317217, v147
	v_mov_b32_e32 v147, v194
	v_sub_f32_e32 v168, v168, v147
	v_mul_f32_e32 v147, 0x3fb8aa3b, v151
	v_exp_f32_e32 v147, v147
	s_nop 0
	v_fma_f32 v147, v177, v147, v135
	v_log_f32_e32 v147, v147
	s_nop 0
	v_mul_f32_e32 v194, 0x3f317217, v147
	v_fma_f32 v194, v147, s52, -v194
	v_fmac_f32_e32 v194, 0x3377d1cf, v147
	v_fmac_f32_e32 v194, 0x3f317217, v147
	v_mov_b32_e32 v147, v194
	v_cndmask_b32_e64 v147, v151, v147, s[8:9]
	v_mul_f32_e32 v151, 0x3fb8aa3b, v168
	v_exp_f32_e32 v151, v151
	s_nop 0
	v_fma_f32 v151, v167, v151, v131
	v_log_f32_e32 v151, v151
	s_nop 0
	v_mul_f32_e32 v194, 0x3f317217, v151
	v_fma_f32 v194, v151, s52, -v194
	v_fmac_f32_e32 v194, 0x3377d1cf, v151
	v_fmac_f32_e32 v194, 0x3f317217, v151
	v_mov_b32_e32 v151, v194
	v_cndmask_b32_e32 v151, v168, v151, vcc
	global_store_dwordx4 v[170:171], v[144:147], off offset:512
	global_store_dwordx4 v[170:171], v[148:151], off offset:528
	s_nop 1
	v_add_u32_e32 v148, 0x90, v166
	v_ashrrev_i32_e32 v149, 31, v148
	v_lshlrev_b64 v[144:145], 6, v[148:149]
	v_lshl_add_u64 v[144:145], v[160:161], 0, v[144:145]
	s_nop 0
	s_waitcnt lgkmcnt(0)
	s_nop 3
	s_nop 0
	s_nop 1
	s_waitcnt lgkmcnt(0)
	s_nop 1
	s_waitcnt lgkmcnt(0)
; __device__ __forceinline__ float silu_f(float x) { return x * __builtin_amdgcn_rcpf(1.f + __expf(-x)); }
; __device__ __forceinline__ v4u pack8(const f32x4 a, const f32x4 b) { v4u w; w.x = cvt_pk_bf16(a[0], a[1]); w.y = cvt_pk_bf16(a[2], a[3]); w.z = cvt_pk_bf16(b[0], b[1]); w.w = cvt_pk_bf16(b[2], b[3]); return w; }
;     __device__ __forceinline__ void operator()(const f32x4 (&acc)[2][2][4][2], const pg8::Unit& u, int wr, int wc, int fr, int fq) const {
;     ...
;         if (grp == 0) { WIN_LOOP( _Pragma("unroll") for (int i = 0; i < 4; ++i) { a[i] = silu_f(a[i]); b[i] = silu_f(b[i]); } *(v4u*)(QO + (size_t)row * DM + c) = pack8(a, b); ) }
;         else if (grp == 3) { WIN_LOOP( _Pragma("unroll") for (int i = 0; i < 4; ++i) { a[i] = silu_f(a[i]); b[i] = silu_f(b[i]); } *(v4u*)(GH + (size_t)row * 512 + c) = pack8(a, b); ) }
;         else if (grp == 1) {
;             f32x4 l0[2], l1[2];
; #pragma unroll
;             for (int bj = 0; bj < 2; ++bj) { l0[bj] = *(const f32x4*)(lb + cb + bj * 128); l1[bj] = *(const f32x4*)(lb + cb + bj * 128 + 4); }
;             WIN_LOOP( _Pragma("unroll") for (int i = 0; i < 4; ++i) { const float s0 = fminf(a[i], 0.f) - __logf(1.f + __expf(-fabsf(a[i]))), s1 = fminf(b[i], 0.f) - __logf(1.f + __expf(-fabsf(b[i]))); const float la = l0[bj][i], lbv = l1[bj][i];
;                     a[i] = la > 0.f ? __logf(la + (1.f - la) * __expf(s0)) : s0; b[i] = lbv > 0.f ? __logf(lbv + (1.f - lbv) * __expf(s1)) : s1; }
;                 *(f32x4*)(LF + (size_t)row * 512 + c) = a; *(f32x4*)(LF + (size_t)row * 512 + c + 4) = b; __builtin_amdgcn_sched_barrier(0); ) }
	s_nop 1
	v_mov_b32_e32 v168, v240
	v_lshlrev_b64 v[144:145], 11, v[148:149]
	v_lshl_add_u64 v[170:171], s[50:51], 0, v[144:145]
	v_lshl_add_u64 v[170:171], v[170:171], 0, v[192:193]
	v_pk_mul_f32 v[148:149], v[20:21], v[168:169] op_sel_hi:[1,0]
	v_pk_mul_f32 v[144:145], v[16:17], v[168:169] op_sel_hi:[1,0]
	v_min_f32_e32 v194, 0, v148
	v_mul_f32_e64 v148, |v148|, s57
	v_exp_f32_e32 v148, v148
	v_pk_mul_f32 v[150:151], v[22:23], v[168:169] op_sel_hi:[1,0]
	v_pk_mul_f32 v[146:147], v[18:19], v[168:169] op_sel_hi:[1,0]
	v_add_f32_e32 v148, 1.0, v148
	v_log_f32_e32 v148, v148
	s_nop 0
	v_mul_f32_e32 v195, 0x3f317217, v148
	v_fma_f32 v195, v148, s52, -v195
	v_fmac_f32_e32 v195, 0x3377d1cf, v148
	v_fmac_f32_e32 v195, 0x3f317217, v148
	v_mov_b32_e32 v148, v195
	v_sub_f32_e32 v148, v194, v148
	v_min_f32_e32 v194, 0, v144
	v_mul_f32_e64 v144, |v144|, s57
	v_exp_f32_e32 v144, v144
	s_nop 0
	v_add_f32_e32 v144, 1.0, v144
	v_log_f32_e32 v144, v144
	s_nop 0
	v_mul_f32_e32 v195, 0x3f317217, v144
	v_fma_f32 v195, v144, s52, -v195
	v_fmac_f32_e32 v195, 0x3377d1cf, v144
	v_fmac_f32_e32 v195, 0x3f317217, v144
	v_mov_b32_e32 v144, v195
	v_sub_f32_e32 v194, v194, v144
	v_mul_f32_e32 v144, 0x3fb8aa3b, v148
	v_exp_f32_e32 v144, v144
	s_nop 0
	v_fma_f32 v144, v190, v144, v140
	v_log_f32_e32 v144, v144
	s_nop 0
	v_mul_f32_e32 v195, 0x3f317217, v144
	v_fma_f32 v195, v144, s52, -v195
	v_fmac_f32_e32 v195, 0x3377d1cf, v144
	v_fmac_f32_e32 v195, 0x3f317217, v144
	v_mov_b32_e32 v144, v195
	v_cndmask_b32_e64 v144, v148, v144, s[38:39]
	v_mul_f32_e32 v148, 0x3fb8aa3b, v194
	v_exp_f32_e32 v148, v148
	s_nop 0
	v_fma_f32 v148, v191, v148, v136
	v_log_f32_e32 v148, v148
	s_nop 0
	v_mul_f32_e32 v195, 0x3f317217, v148
	v_fma_f32 v195, v148, s52, -v195
	v_fmac_f32_e32 v195, 0x3377d1cf, v148
	v_fmac_f32_e32 v195, 0x3f317217, v148
	v_mov_b32_e32 v148, v195
	v_cndmask_b32_e64 v148, v194, v148, s[36:37]
	v_min_f32_e32 v194, 0, v149
	v_mul_f32_e64 v149, |v149|, s57
	v_exp_f32_e32 v149, v149
	s_nop 0
	v_add_f32_e32 v149, 1.0, v149
	v_log_f32_e32 v149, v149
	s_nop 0
	v_mul_f32_e32 v195, 0x3f317217, v149
	v_fma_f32 v195, v149, s52, -v195
	v_fmac_f32_e32 v195, 0x3377d1cf, v149
	v_fmac_f32_e32 v195, 0x3f317217, v149
	v_mov_b32_e32 v149, v195
	v_sub_f32_e32 v149, v194, v149
	v_min_f32_e32 v194, 0, v145
	v_mul_f32_e64 v145, |v145|, s57
	v_exp_f32_e32 v145, v145
	s_nop 0
	v_add_f32_e32 v145, 1.0, v145
	v_log_f32_e32 v145, v145
	s_nop 0
	v_mul_f32_e32 v195, 0x3f317217, v145
	v_fma_f32 v195, v145, s52, -v195
	v_fmac_f32_e32 v195, 0x3377d1cf, v145
	v_fmac_f32_e32 v195, 0x3f317217, v145
	v_mov_b32_e32 v145, v195
	v_sub_f32_e32 v194, v194, v145
	v_mul_f32_e32 v145, 0x3fb8aa3b, v149
	v_exp_f32_e32 v145, v145
	s_nop 0
	v_fma_f32 v145, v188, v145, v141
	v_log_f32_e32 v145, v145
	s_nop 0
	v_mul_f32_e32 v195, 0x3f317217, v145
	v_fma_f32 v195, v145, s52, -v195
	v_fmac_f32_e32 v195, 0x3377d1cf, v145
	v_fmac_f32_e32 v195, 0x3f317217, v145
	v_mov_b32_e32 v145, v195
	v_cndmask_b32_e64 v145, v149, v145, s[34:35]
	v_mul_f32_e32 v149, 0x3fb8aa3b, v194
	v_exp_f32_e32 v149, v149
	s_nop 0
	v_fma_f32 v149, v189, v149, v137
	v_log_f32_e32 v149, v149
	s_nop 0
	v_mul_f32_e32 v195, 0x3f317217, v149
	v_fma_f32 v195, v149, s52, -v195
	v_fmac_f32_e32 v195, 0x3377d1cf, v149
	v_fmac_f32_e32 v195, 0x3f317217, v149
	v_mov_b32_e32 v149, v195
	v_cndmask_b32_e64 v149, v194, v149, s[30:31]
	v_min_f32_e32 v194, 0, v150
	v_mul_f32_e64 v150, |v150|, s57
	v_exp_f32_e32 v150, v150
	s_nop 0
	v_add_f32_e32 v150, 1.0, v150
	v_log_f32_e32 v150, v150
	s_nop 0
	v_mul_f32_e32 v195, 0x3f317217, v150
	v_fma_f32 v195, v150, s52, -v195
	v_fmac_f32_e32 v195, 0x3377d1cf, v150
	v_fmac_f32_e32 v195, 0x3f317217, v150
	v_mov_b32_e32 v150, v195
	v_sub_f32_e32 v150, v194, v150
	v_min_f32_e32 v194, 0, v146
	v_mul_f32_e64 v146, |v146|, s57
	v_exp_f32_e32 v146, v146
	s_nop 0
	v_add_f32_e32 v146, 1.0, v146
	v_log_f32_e32 v146, v146
	s_nop 0
	v_mul_f32_e32 v195, 0x3f317217, v146
	v_fma_f32 v195, v146, s52, -v195
	v_fmac_f32_e32 v195, 0x3377d1cf, v146
	v_fmac_f32_e32 v195, 0x3f317217, v146
	v_mov_b32_e32 v146, v195
	v_sub_f32_e32 v194, v194, v146
	v_mul_f32_e32 v146, 0x3fb8aa3b, v150
	v_exp_f32_e32 v146, v146
	s_nop 0
	v_fma_f32 v146, v187, v146, v142
	v_log_f32_e32 v146, v146
	s_nop 0
	v_mul_f32_e32 v195, 0x3f317217, v146
	v_fma_f32 v195, v146, s52, -v195
	v_fmac_f32_e32 v195, 0x3377d1cf, v146
	v_fmac_f32_e32 v195, 0x3f317217, v146
	v_mov_b32_e32 v146, v195
	v_cndmask_b32_e64 v146, v150, v146, s[28:29]
	v_mul_f32_e32 v150, 0x3fb8aa3b, v194
	v_exp_f32_e32 v150, v150
	s_nop 0
	v_fma_f32 v150, v186, v150, v138
	v_log_f32_e32 v150, v150
	s_nop 0
	v_mul_f32_e32 v195, 0x3f317217, v150
	v_fma_f32 v195, v150, s52, -v195
	v_fmac_f32_e32 v195, 0x3377d1cf, v150
	v_fmac_f32_e32 v195, 0x3f317217, v150
	v_mov_b32_e32 v150, v195
	v_cndmask_b32_e64 v150, v194, v150, s[26:27]
	v_min_f32_e32 v194, 0, v151
	v_mul_f32_e64 v151, |v151|, s57
	v_exp_f32_e32 v151, v151
	s_nop 0
	v_add_f32_e32 v151, 1.0, v151
	v_log_f32_e32 v151, v151
	s_nop 0
	v_mul_f32_e32 v195, 0x3f317217, v151
	v_fma_f32 v195, v151, s52, -v195
	v_fmac_f32_e32 v195, 0x3377d1cf, v151
	v_fmac_f32_e32 v195, 0x3f317217, v151
	v_mov_b32_e32 v151, v195
	v_sub_f32_e32 v151, v194, v151
	v_min_f32_e32 v194, 0, v147
	v_mul_f32_e64 v147, |v147|, s57
	v_exp_f32_e32 v147, v147
	s_nop 0
	v_add_f32_e32 v147, 1.0, v147
	v_log_f32_e32 v147, v147
	s_nop 0
	v_mul_f32_e32 v195, 0x3f317217, v147
	v_fma_f32 v195, v147, s52, -v195
	v_fmac_f32_e32 v195, 0x3377d1cf, v147
	v_fmac_f32_e32 v195, 0x3f317217, v147
	v_mov_b32_e32 v147, v195
	v_sub_f32_e32 v194, v194, v147
	v_mul_f32_e32 v147, 0x3fb8aa3b, v151
	v_exp_f32_e32 v147, v147
; __device__ __forceinline__ float silu_f(float x) { return x * __builtin_amdgcn_rcpf(1.f + __expf(-x)); }
; __device__ __forceinline__ v4u pack8(const f32x4 a, const f32x4 b) { v4u w; w.x = cvt_pk_bf16(a[0], a[1]); w.y = cvt_pk_bf16(a[2], a[3]); w.z = cvt_pk_bf16(b[0], b[1]); w.w = cvt_pk_bf16(b[2], b[3]); return w; }
;     __device__ __forceinline__ void operator()(const f32x4 (&acc)[2][2][4][2], const pg8::Unit& u, int wr, int wc, int fr, int fq) const {
;     ...
;         if (grp == 0) { WIN_LOOP( _Pragma("unroll") for (int i = 0; i < 4; ++i) { a[i] = silu_f(a[i]); b[i] = silu_f(b[i]); } *(v4u*)(QO + (size_t)row * DM + c) = pack8(a, b); ) }
;         else if (grp == 3) { WIN_LOOP( _Pragma("unroll") for (int i = 0; i < 4; ++i) { a[i] = silu_f(a[i]); b[i] = silu_f(b[i]); } *(v4u*)(GH + (size_t)row * 512 + c) = pack8(a, b); ) }
;         else if (grp == 1) {
;             f32x4 l0[2], l1[2];
; #pragma unroll
;             for (int bj = 0; bj < 2; ++bj) { l0[bj] = *(const f32x4*)(lb + cb + bj * 128); l1[bj] = *(const f32x4*)(lb + cb + bj * 128 + 4); }
;             WIN_LOOP( _Pragma("unroll") for (int i = 0; i < 4; ++i) { const float s0 = fminf(a[i], 0.f) - __logf(1.f + __expf(-fabsf(a[i]))), s1 = fminf(b[i], 0.f) - __logf(1.f + __expf(-fabsf(b[i]))); const float la = l0[bj][i], lbv = l1[bj][i];
;                     a[i] = la > 0.f ? __logf(la + (1.f - la) * __expf(s0)) : s0; b[i] = lbv > 0.f ? __logf(lbv + (1.f - lbv) * __expf(s1)) : s1; }
;                 *(f32x4*)(LF + (size_t)row * 512 + c) = a; *(f32x4*)(LF + (size_t)row * 512 + c + 4) = b; __builtin_amdgcn_sched_barrier(0); ) }
	s_nop 0
	v_fma_f32 v147, v185, v147, v143
	v_log_f32_e32 v147, v147
	s_nop 0
	v_mul_f32_e32 v195, 0x3f317217, v147
	v_fma_f32 v195, v147, s52, -v195
	v_fmac_f32_e32 v195, 0x3377d1cf, v147
	v_fmac_f32_e32 v195, 0x3f317217, v147
	v_mov_b32_e32 v147, v195
	v_cndmask_b32_e64 v147, v151, v147, s[24:25]
	v_mul_f32_e32 v151, 0x3fb8aa3b, v194
	v_exp_f32_e32 v151, v151
	s_nop 0
	v_fma_f32 v151, v184, v151, v139
	v_log_f32_e32 v151, v151
	s_nop 0
	v_mul_f32_e32 v195, 0x3f317217, v151
	v_fma_f32 v195, v151, s52, -v195
	v_fmac_f32_e32 v195, 0x3377d1cf, v151
	v_fmac_f32_e32 v195, 0x3f317217, v151
	v_mov_b32_e32 v151, v195
	v_cndmask_b32_e64 v151, v194, v151, s[22:23]
	global_store_dwordx4 v[170:171], v[144:147], off
	global_store_dwordx4 v[170:171], v[148:151], off offset:16
	s_nop 1
	v_pk_mul_f32 v[148:149], v[84:85], v[168:169] op_sel_hi:[1,0]
	v_pk_mul_f32 v[150:151], v[86:87], v[168:169] op_sel_hi:[1,0]
	v_pk_mul_f32 v[146:147], v[82:83], v[168:169] op_sel_hi:[1,0]
	v_pk_mul_f32 v[144:145], v[80:81], v[168:169] op_sel_hi:[1,0]
	v_min_f32_e32 v168, 0, v148
	v_mul_f32_e64 v148, |v148|, s57
	v_exp_f32_e32 v148, v148
	s_nop 0
	v_add_f32_e32 v148, 1.0, v148
	v_log_f32_e32 v148, v148
	s_nop 0
	v_mul_f32_e32 v194, 0x3f317217, v148
	v_fma_f32 v194, v148, s52, -v194
	v_fmac_f32_e32 v194, 0x3377d1cf, v148
	v_fmac_f32_e32 v194, 0x3f317217, v148
	v_mov_b32_e32 v148, v194
	v_sub_f32_e32 v148, v168, v148
	v_min_f32_e32 v168, 0, v144
	v_mul_f32_e64 v144, |v144|, s57
	v_exp_f32_e32 v144, v144
	s_nop 0
	v_add_f32_e32 v144, 1.0, v144
	v_log_f32_e32 v144, v144
	s_nop 0
	v_mul_f32_e32 v194, 0x3f317217, v144
	v_fma_f32 v194, v144, s52, -v194
	v_fmac_f32_e32 v194, 0x3377d1cf, v144
	v_fmac_f32_e32 v194, 0x3f317217, v144
	v_mov_b32_e32 v144, v194
	v_sub_f32_e32 v168, v168, v144
	v_mul_f32_e32 v144, 0x3fb8aa3b, v148
	v_exp_f32_e32 v144, v144
	s_nop 0
	v_fma_f32 v144, v183, v144, v132
	v_log_f32_e32 v144, v144
	s_nop 0
	v_mul_f32_e32 v194, 0x3f317217, v144
	v_fma_f32 v194, v144, s52, -v194
	v_fmac_f32_e32 v194, 0x3377d1cf, v144
	v_fmac_f32_e32 v194, 0x3f317217, v144
	v_mov_b32_e32 v144, v194
	v_cndmask_b32_e64 v144, v148, v144, s[20:21]
	v_mul_f32_e32 v148, 0x3fb8aa3b, v168
	v_exp_f32_e32 v148, v148
	s_nop 0
	v_fma_f32 v148, v182, v148, v128
	v_log_f32_e32 v148, v148
	s_nop 0
	v_mul_f32_e32 v194, 0x3f317217, v148
	v_fma_f32 v194, v148, s52, -v194
	v_fmac_f32_e32 v194, 0x3377d1cf, v148
	v_fmac_f32_e32 v194, 0x3f317217, v148
	v_mov_b32_e32 v148, v194
	v_cndmask_b32_e64 v148, v168, v148, s[18:19]
	v_min_f32_e32 v168, 0, v149
	v_mul_f32_e64 v149, |v149|, s57
	v_exp_f32_e32 v149, v149
	s_nop 0
	v_add_f32_e32 v149, 1.0, v149
	v_log_f32_e32 v149, v149
	s_nop 0
	v_mul_f32_e32 v194, 0x3f317217, v149
	v_fma_f32 v194, v149, s52, -v194
	v_fmac_f32_e32 v194, 0x3377d1cf, v149
	v_fmac_f32_e32 v194, 0x3f317217, v149
	v_mov_b32_e32 v149, v194
	v_sub_f32_e32 v149, v168, v149
	v_min_f32_e32 v168, 0, v145
	v_mul_f32_e64 v145, |v145|, s57
	v_exp_f32_e32 v145, v145
	s_nop 0
	v_add_f32_e32 v145, 1.0, v145
	v_log_f32_e32 v145, v145
	s_nop 0
	v_mul_f32_e32 v194, 0x3f317217, v145
	v_fma_f32 v194, v145, s52, -v194
	v_fmac_f32_e32 v194, 0x3377d1cf, v145
	v_fmac_f32_e32 v194, 0x3f317217, v145
	v_mov_b32_e32 v145, v194
	v_sub_f32_e32 v168, v168, v145
	v_mul_f32_e32 v145, 0x3fb8aa3b, v149
	v_exp_f32_e32 v145, v145
	s_nop 0
	v_fma_f32 v145, v181, v145, v133
	v_log_f32_e32 v145, v145
	s_nop 0
	v_mul_f32_e32 v194, 0x3f317217, v145
	v_fma_f32 v194, v145, s52, -v194
	v_fmac_f32_e32 v194, 0x3377d1cf, v145
	v_fmac_f32_e32 v194, 0x3f317217, v145
	v_mov_b32_e32 v145, v194
	v_cndmask_b32_e64 v145, v149, v145, s[16:17]
	v_mul_f32_e32 v149, 0x3fb8aa3b, v168
	v_exp_f32_e32 v149, v149
	s_nop 0
	v_fma_f32 v149, v180, v149, v129
	v_log_f32_e32 v149, v149
	s_nop 0
	v_mul_f32_e32 v194, 0x3f317217, v149
	v_fma_f32 v194, v149, s52, -v194
	v_fmac_f32_e32 v194, 0x3377d1cf, v149
	v_fmac_f32_e32 v194, 0x3f317217, v149
	v_mov_b32_e32 v149, v194
	v_cndmask_b32_e64 v149, v168, v149, s[14:15]
	v_min_f32_e32 v168, 0, v150
	v_mul_f32_e64 v150, |v150|, s57
	v_exp_f32_e32 v150, v150
	s_nop 0
	v_add_f32_e32 v150, 1.0, v150
	v_log_f32_e32 v150, v150
	s_nop 0
	v_mul_f32_e32 v194, 0x3f317217, v150
	v_fma_f32 v194, v150, s52, -v194
	v_fmac_f32_e32 v194, 0x3377d1cf, v150
	v_fmac_f32_e32 v194, 0x3f317217, v150
	v_mov_b32_e32 v150, v194
	v_sub_f32_e32 v150, v168, v150
	v_min_f32_e32 v168, 0, v146
	v_mul_f32_e64 v146, |v146|, s57
	v_exp_f32_e32 v146, v146
	s_nop 0
	v_add_f32_e32 v146, 1.0, v146
	v_log_f32_e32 v146, v146
	s_nop 0
	v_mul_f32_e32 v194, 0x3f317217, v146
	v_fma_f32 v194, v146, s52, -v194
	v_fmac_f32_e32 v194, 0x3377d1cf, v146
	v_fmac_f32_e32 v194, 0x3f317217, v146
	v_mov_b32_e32 v146, v194
	v_sub_f32_e32 v168, v168, v146
	v_mul_f32_e32 v146, 0x3fb8aa3b, v150
	v_exp_f32_e32 v146, v146
	s_nop 0
	v_fma_f32 v146, v179, v146, v134
	v_log_f32_e32 v146, v146
	s_nop 0
	v_mul_f32_e32 v194, 0x3f317217, v146
	v_fma_f32 v194, v146, s52, -v194
	v_fmac_f32_e32 v194, 0x3377d1cf, v146
	v_fmac_f32_e32 v194, 0x3f317217, v146
	v_mov_b32_e32 v146, v194
	v_cndmask_b32_e64 v146, v150, v146, s[12:13]
	v_mul_f32_e32 v150, 0x3fb8aa3b, v168
	v_exp_f32_e32 v150, v150
	s_nop 0
	v_fma_f32 v150, v178, v150, v130
	v_log_f32_e32 v150, v150
	s_nop 0
	v_mul_f32_e32 v194, 0x3f317217, v150
	v_fma_f32 v194, v150, s52, -v194
	v_fmac_f32_e32 v194, 0x3377d1cf, v150
	v_fmac_f32_e32 v194, 0x3f317217, v150
	v_mov_b32_e32 v150, v194
	v_cndmask_b32_e64 v150, v168, v150, s[10:11]
	v_min_f32_e32 v168, 0, v151
	v_mul_f32_e64 v151, |v151|, s57
	v_exp_f32_e32 v151, v151
	s_nop 0
	v_add_f32_e32 v151, 1.0, v151
	v_log_f32_e32 v151, v151
	s_nop 0
	v_mul_f32_e32 v194, 0x3f317217, v151
; __device__ __forceinline__ float silu_f(float x) { return x * __builtin_amdgcn_rcpf(1.f + __expf(-x)); }
; __device__ __forceinline__ v4u pack8(const f32x4 a, const f32x4 b) { v4u w; w.x = cvt_pk_bf16(a[0], a[1]); w.y = cvt_pk_bf16(a[2], a[3]); w.z = cvt_pk_bf16(b[0], b[1]); w.w = cvt_pk_bf16(b[2], b[3]); return w; }
;     __device__ __forceinline__ void operator()(const f32x4 (&acc)[2][2][4][2], const pg8::Unit& u, int wr, int wc, int fr, int fq) const {
;     ...
;         if (grp == 0) { WIN_LOOP( _Pragma("unroll") for (int i = 0; i < 4; ++i) { a[i] = silu_f(a[i]); b[i] = silu_f(b[i]); } *(v4u*)(QO + (size_t)row * DM + c) = pack8(a, b); ) }
;         else if (grp == 3) { WIN_LOOP( _Pragma("unroll") for (int i = 0; i < 4; ++i) { a[i] = silu_f(a[i]); b[i] = silu_f(b[i]); } *(v4u*)(GH + (size_t)row * 512 + c) = pack8(a, b); ) }
;         else if (grp == 1) {
;             f32x4 l0[2], l1[2];
; #pragma unroll
;             for (int bj = 0; bj < 2; ++bj) { l0[bj] = *(const f32x4*)(lb + cb + bj * 128); l1[bj] = *(const f32x4*)(lb + cb + bj * 128 + 4); }
;             WIN_LOOP( _Pragma("unroll") for (int i = 0; i < 4; ++i) { const float s0 = fminf(a[i], 0.f) - __logf(1.f + __expf(-fabsf(a[i]))), s1 = fminf(b[i], 0.f) - __logf(1.f + __expf(-fabsf(b[i]))); const float la = l0[bj][i], lbv = l1[bj][i];
;                     a[i] = la > 0.f ? __logf(la + (1.f - la) * __expf(s0)) : s0; b[i] = lbv > 0.f ? __logf(lbv + (1.f - lbv) * __expf(s1)) : s1; }
;                 *(f32x4*)(LF + (size_t)row * 512 + c) = a; *(f32x4*)(LF + (size_t)row * 512 + c + 4) = b; __builtin_amdgcn_sched_barrier(0); ) }
	v_fma_f32 v194, v151, s52, -v194
	v_fmac_f32_e32 v194, 0x3377d1cf, v151
	v_fmac_f32_e32 v194, 0x3f317217, v151
	v_mov_b32_e32 v151, v194
	v_sub_f32_e32 v151, v168, v151
	v_min_f32_e32 v168, 0, v147
	v_mul_f32_e64 v147, |v147|, s57
	v_exp_f32_e32 v147, v147
	s_nop 0
	v_add_f32_e32 v147, 1.0, v147
	v_log_f32_e32 v147, v147
	s_nop 0
	v_mul_f32_e32 v194, 0x3f317217, v147
	v_fma_f32 v194, v147, s52, -v194
	v_fmac_f32_e32 v194, 0x3377d1cf, v147
	v_fmac_f32_e32 v194, 0x3f317217, v147
	v_mov_b32_e32 v147, v194
	v_sub_f32_e32 v168, v168, v147
	v_mul_f32_e32 v147, 0x3fb8aa3b, v151
	v_exp_f32_e32 v147, v147
	s_nop 0
	v_fma_f32 v147, v177, v147, v135
	v_log_f32_e32 v147, v147
	s_nop 0
	v_mul_f32_e32 v194, 0x3f317217, v147
	v_fma_f32 v194, v147, s52, -v194
	v_fmac_f32_e32 v194, 0x3377d1cf, v147
	v_fmac_f32_e32 v194, 0x3f317217, v147
	v_mov_b32_e32 v147, v194
	v_cndmask_b32_e64 v147, v151, v147, s[8:9]
	v_mul_f32_e32 v151, 0x3fb8aa3b, v168
	v_exp_f32_e32 v151, v151
	s_nop 0
	v_fma_f32 v151, v167, v151, v131
	v_log_f32_e32 v151, v151
	s_nop 0
	v_mul_f32_e32 v194, 0x3f317217, v151
	v_fma_f32 v194, v151, s52, -v194
	v_fmac_f32_e32 v194, 0x3377d1cf, v151
	v_fmac_f32_e32 v194, 0x3f317217, v151
	v_mov_b32_e32 v151, v194
	v_cndmask_b32_e32 v151, v168, v151, vcc
	global_store_dwordx4 v[170:171], v[144:147], off offset:512
	global_store_dwordx4 v[170:171], v[148:151], off offset:528
	s_nop 1
	v_add_u32_e32 v148, 0xa0, v166
	v_ashrrev_i32_e32 v149, 31, v148
	v_lshlrev_b64 v[144:145], 6, v[148:149]
	v_lshl_add_u64 v[144:145], v[160:161], 0, v[144:145]
	s_nop 0
	s_waitcnt lgkmcnt(0)
	s_nop 3
	s_nop 0
	s_nop 1
	s_waitcnt lgkmcnt(0)
	s_nop 1
	s_waitcnt lgkmcnt(0)
	s_nop 1
	v_mov_b32_e32 v168, v241
	v_lshlrev_b64 v[144:145], 11, v[148:149]
	v_lshl_add_u64 v[170:171], s[50:51], 0, v[144:145]
	v_lshl_add_u64 v[170:171], v[170:171], 0, v[192:193]
	v_pk_mul_f32 v[148:149], v[12:13], v[168:169] op_sel_hi:[1,0]
	v_pk_mul_f32 v[144:145], v[8:9], v[168:169] op_sel_hi:[1,0]
	v_min_f32_e32 v194, 0, v148
	v_mul_f32_e64 v148, |v148|, s57
	v_exp_f32_e32 v148, v148
	v_pk_mul_f32 v[150:151], v[14:15], v[168:169] op_sel_hi:[1,0]
	v_pk_mul_f32 v[146:147], v[10:11], v[168:169] op_sel_hi:[1,0]
	v_add_f32_e32 v148, 1.0, v148
	v_log_f32_e32 v148, v148
	s_nop 0
	v_mul_f32_e32 v195, 0x3f317217, v148
	v_fma_f32 v195, v148, s52, -v195
	v_fmac_f32_e32 v195, 0x3377d1cf, v148
	v_fmac_f32_e32 v195, 0x3f317217, v148
	v_mov_b32_e32 v148, v195
	v_sub_f32_e32 v148, v194, v148
	v_min_f32_e32 v194, 0, v144
	v_mul_f32_e64 v144, |v144|, s57
	v_exp_f32_e32 v144, v144
	s_nop 0
	v_add_f32_e32 v144, 1.0, v144
	v_log_f32_e32 v144, v144
	s_nop 0
	v_mul_f32_e32 v195, 0x3f317217, v144
	v_fma_f32 v195, v144, s52, -v195
	v_fmac_f32_e32 v195, 0x3377d1cf, v144
	v_fmac_f32_e32 v195, 0x3f317217, v144
	v_mov_b32_e32 v144, v195
	v_sub_f32_e32 v194, v194, v144
	v_mul_f32_e32 v144, 0x3fb8aa3b, v148
	v_exp_f32_e32 v144, v144
	s_nop 0
	v_fma_f32 v144, v190, v144, v140
	v_log_f32_e32 v144, v144
	s_nop 0
	v_mul_f32_e32 v195, 0x3f317217, v144
	v_fma_f32 v195, v144, s52, -v195
	v_fmac_f32_e32 v195, 0x3377d1cf, v144
	v_fmac_f32_e32 v195, 0x3f317217, v144
	v_mov_b32_e32 v144, v195
	v_cndmask_b32_e64 v144, v148, v144, s[38:39]
	v_mul_f32_e32 v148, 0x3fb8aa3b, v194
	v_exp_f32_e32 v148, v148
	s_nop 0
	v_fma_f32 v148, v191, v148, v136
	v_log_f32_e32 v148, v148
	s_nop 0
	v_mul_f32_e32 v195, 0x3f317217, v148
	v_fma_f32 v195, v148, s52, -v195
	v_fmac_f32_e32 v195, 0x3377d1cf, v148
	v_fmac_f32_e32 v195, 0x3f317217, v148
	v_mov_b32_e32 v148, v195
	v_cndmask_b32_e64 v148, v194, v148, s[36:37]
	v_min_f32_e32 v194, 0, v149
	v_mul_f32_e64 v149, |v149|, s57
	v_exp_f32_e32 v149, v149
	s_nop 0
	v_add_f32_e32 v149, 1.0, v149
	v_log_f32_e32 v149, v149
	s_nop 0
	v_mul_f32_e32 v195, 0x3f317217, v149
	v_fma_f32 v195, v149, s52, -v195
	v_fmac_f32_e32 v195, 0x3377d1cf, v149
	v_fmac_f32_e32 v195, 0x3f317217, v149
	v_mov_b32_e32 v149, v195
	v_sub_f32_e32 v149, v194, v149
	v_min_f32_e32 v194, 0, v145
	v_mul_f32_e64 v145, |v145|, s57
	v_exp_f32_e32 v145, v145
	s_nop 0
	v_add_f32_e32 v145, 1.0, v145
	v_log_f32_e32 v145, v145
	s_nop 0
	v_mul_f32_e32 v195, 0x3f317217, v145
	v_fma_f32 v195, v145, s52, -v195
	v_fmac_f32_e32 v195, 0x3377d1cf, v145
	v_fmac_f32_e32 v195, 0x3f317217, v145
	v_mov_b32_e32 v145, v195
	v_sub_f32_e32 v194, v194, v145
	v_mul_f32_e32 v145, 0x3fb8aa3b, v149
	v_exp_f32_e32 v145, v145
	s_nop 0
	v_fma_f32 v145, v188, v145, v141
	v_log_f32_e32 v145, v145
	s_nop 0
	v_mul_f32_e32 v195, 0x3f317217, v145
	v_fma_f32 v195, v145, s52, -v195
	v_fmac_f32_e32 v195, 0x3377d1cf, v145
	v_fmac_f32_e32 v195, 0x3f317217, v145
	v_mov_b32_e32 v145, v195
	v_cndmask_b32_e64 v145, v149, v145, s[34:35]
	v_mul_f32_e32 v149, 0x3fb8aa3b, v194
	v_exp_f32_e32 v149, v149
	s_nop 0
	v_fma_f32 v149, v189, v149, v137
	v_log_f32_e32 v149, v149
	s_nop 0
	v_mul_f32_e32 v195, 0x3f317217, v149
	v_fma_f32 v195, v149, s52, -v195
	v_fmac_f32_e32 v195, 0x3377d1cf, v149
	v_fmac_f32_e32 v195, 0x3f317217, v149
	v_mov_b32_e32 v149, v195
	v_cndmask_b32_e64 v149, v194, v149, s[30:31]
	v_min_f32_e32 v194, 0, v150
	v_mul_f32_e64 v150, |v150|, s57
	v_exp_f32_e32 v150, v150
	s_nop 0
	v_add_f32_e32 v150, 1.0, v150
	v_log_f32_e32 v150, v150
	s_nop 0
	v_mul_f32_e32 v195, 0x3f317217, v150
	v_fma_f32 v195, v150, s52, -v195
	v_fmac_f32_e32 v195, 0x3377d1cf, v150
	v_fmac_f32_e32 v195, 0x3f317217, v150
	v_mov_b32_e32 v150, v195
	v_sub_f32_e32 v150, v194, v150
	v_min_f32_e32 v194, 0, v146
	v_mul_f32_e64 v146, |v146|, s57
	v_exp_f32_e32 v146, v146
	s_nop 0
	v_add_f32_e32 v146, 1.0, v146
	v_log_f32_e32 v146, v146
	s_nop 0
	v_mul_f32_e32 v195, 0x3f317217, v146
	v_fma_f32 v195, v146, s52, -v195
; __device__ __forceinline__ float silu_f(float x) { return x * __builtin_amdgcn_rcpf(1.f + __expf(-x)); }
; __device__ __forceinline__ v4u pack8(const f32x4 a, const f32x4 b) { v4u w; w.x = cvt_pk_bf16(a[0], a[1]); w.y = cvt_pk_bf16(a[2], a[3]); w.z = cvt_pk_bf16(b[0], b[1]); w.w = cvt_pk_bf16(b[2], b[3]); return w; }
;     __device__ __forceinline__ void operator()(const f32x4 (&acc)[2][2][4][2], const pg8::Unit& u, int wr, int wc, int fr, int fq) const {
;     ...
;         if (grp == 0) { WIN_LOOP( _Pragma("unroll") for (int i = 0; i < 4; ++i) { a[i] = silu_f(a[i]); b[i] = silu_f(b[i]); } *(v4u*)(QO + (size_t)row * DM + c) = pack8(a, b); ) }
;         else if (grp == 3) { WIN_LOOP( _Pragma("unroll") for (int i = 0; i < 4; ++i) { a[i] = silu_f(a[i]); b[i] = silu_f(b[i]); } *(v4u*)(GH + (size_t)row * 512 + c) = pack8(a, b); ) }
;         else if (grp == 1) {
;             f32x4 l0[2], l1[2];
; #pragma unroll
;             for (int bj = 0; bj < 2; ++bj) { l0[bj] = *(const f32x4*)(lb + cb + bj * 128); l1[bj] = *(const f32x4*)(lb + cb + bj * 128 + 4); }
;             WIN_LOOP( _Pragma("unroll") for (int i = 0; i < 4; ++i) { const float s0 = fminf(a[i], 0.f) - __logf(1.f + __expf(-fabsf(a[i]))), s1 = fminf(b[i], 0.f) - __logf(1.f + __expf(-fabsf(b[i]))); const float la = l0[bj][i], lbv = l1[bj][i];
;                     a[i] = la > 0.f ? __logf(la + (1.f - la) * __expf(s0)) : s0; b[i] = lbv > 0.f ? __logf(lbv + (1.f - lbv) * __expf(s1)) : s1; }
;                 *(f32x4*)(LF + (size_t)row * 512 + c) = a; *(f32x4*)(LF + (size_t)row * 512 + c + 4) = b; __builtin_amdgcn_sched_barrier(0); ) }
	v_fmac_f32_e32 v195, 0x3377d1cf, v146
	v_fmac_f32_e32 v195, 0x3f317217, v146
	v_mov_b32_e32 v146, v195
	v_sub_f32_e32 v194, v194, v146
	v_mul_f32_e32 v146, 0x3fb8aa3b, v150
	v_exp_f32_e32 v146, v146
	s_nop 0
	v_fma_f32 v146, v187, v146, v142
	v_log_f32_e32 v146, v146
	s_nop 0
	v_mul_f32_e32 v195, 0x3f317217, v146
	v_fma_f32 v195, v146, s52, -v195
	v_fmac_f32_e32 v195, 0x3377d1cf, v146
	v_fmac_f32_e32 v195, 0x3f317217, v146
	v_mov_b32_e32 v146, v195
	v_cndmask_b32_e64 v146, v150, v146, s[28:29]
	v_mul_f32_e32 v150, 0x3fb8aa3b, v194
	v_exp_f32_e32 v150, v150
	s_nop 0
	v_fma_f32 v150, v186, v150, v138
	v_log_f32_e32 v150, v150
	s_nop 0
	v_mul_f32_e32 v195, 0x3f317217, v150
	v_fma_f32 v195, v150, s52, -v195
	v_fmac_f32_e32 v195, 0x3377d1cf, v150
	v_fmac_f32_e32 v195, 0x3f317217, v150
	v_mov_b32_e32 v150, v195
	v_cndmask_b32_e64 v150, v194, v150, s[26:27]
	v_min_f32_e32 v194, 0, v151
	v_mul_f32_e64 v151, |v151|, s57
	v_exp_f32_e32 v151, v151
	s_nop 0
	v_add_f32_e32 v151, 1.0, v151
	v_log_f32_e32 v151, v151
	s_nop 0
	v_mul_f32_e32 v195, 0x3f317217, v151
	v_fma_f32 v195, v151, s52, -v195
	v_fmac_f32_e32 v195, 0x3377d1cf, v151
	v_fmac_f32_e32 v195, 0x3f317217, v151
	v_mov_b32_e32 v151, v195
	v_sub_f32_e32 v151, v194, v151
	v_min_f32_e32 v194, 0, v147
	v_mul_f32_e64 v147, |v147|, s57
	v_exp_f32_e32 v147, v147
	s_nop 0
	v_add_f32_e32 v147, 1.0, v147
	v_log_f32_e32 v147, v147
	s_nop 0
	v_mul_f32_e32 v195, 0x3f317217, v147
	v_fma_f32 v195, v147, s52, -v195
	v_fmac_f32_e32 v195, 0x3377d1cf, v147
	v_fmac_f32_e32 v195, 0x3f317217, v147
	v_mov_b32_e32 v147, v195
	v_sub_f32_e32 v194, v194, v147
	v_mul_f32_e32 v147, 0x3fb8aa3b, v151
	v_exp_f32_e32 v147, v147
	s_nop 0
	v_fma_f32 v147, v185, v147, v143
	v_log_f32_e32 v147, v147
	s_nop 0
	v_mul_f32_e32 v195, 0x3f317217, v147
	v_fma_f32 v195, v147, s52, -v195
	v_fmac_f32_e32 v195, 0x3377d1cf, v147
	v_fmac_f32_e32 v195, 0x3f317217, v147
	v_mov_b32_e32 v147, v195
	v_cndmask_b32_e64 v147, v151, v147, s[24:25]
	v_mul_f32_e32 v151, 0x3fb8aa3b, v194
	v_exp_f32_e32 v151, v151
	s_nop 0
	v_fma_f32 v151, v184, v151, v139
	v_log_f32_e32 v151, v151
	s_nop 0
	v_mul_f32_e32 v195, 0x3f317217, v151
	v_fma_f32 v195, v151, s52, -v195
	v_fmac_f32_e32 v195, 0x3377d1cf, v151
	v_fmac_f32_e32 v195, 0x3f317217, v151
	v_mov_b32_e32 v151, v195
	v_cndmask_b32_e64 v151, v194, v151, s[22:23]
	global_store_dwordx4 v[170:171], v[144:147], off
	global_store_dwordx4 v[170:171], v[148:151], off offset:16
	s_nop 1
	v_pk_mul_f32 v[148:149], v[76:77], v[168:169] op_sel_hi:[1,0]
	v_pk_mul_f32 v[150:151], v[78:79], v[168:169] op_sel_hi:[1,0]
	v_pk_mul_f32 v[146:147], v[74:75], v[168:169] op_sel_hi:[1,0]
	v_pk_mul_f32 v[144:145], v[72:73], v[168:169] op_sel_hi:[1,0]
	v_min_f32_e32 v168, 0, v148
	v_mul_f32_e64 v148, |v148|, s57
	v_exp_f32_e32 v148, v148
	s_nop 0
	v_add_f32_e32 v148, 1.0, v148
	v_log_f32_e32 v148, v148
	s_nop 0
	v_mul_f32_e32 v194, 0x3f317217, v148
	v_fma_f32 v194, v148, s52, -v194
	v_fmac_f32_e32 v194, 0x3377d1cf, v148
	v_fmac_f32_e32 v194, 0x3f317217, v148
	v_mov_b32_e32 v148, v194
	v_sub_f32_e32 v148, v168, v148
	v_min_f32_e32 v168, 0, v144
	v_mul_f32_e64 v144, |v144|, s57
	v_exp_f32_e32 v144, v144
	s_nop 0
	v_add_f32_e32 v144, 1.0, v144
	v_log_f32_e32 v144, v144
	s_nop 0
	v_mul_f32_e32 v194, 0x3f317217, v144
	v_fma_f32 v194, v144, s52, -v194
	v_fmac_f32_e32 v194, 0x3377d1cf, v144
	v_fmac_f32_e32 v194, 0x3f317217, v144
	v_mov_b32_e32 v144, v194
	v_sub_f32_e32 v168, v168, v144
	v_mul_f32_e32 v144, 0x3fb8aa3b, v148
	v_exp_f32_e32 v144, v144
	s_nop 0
	v_fma_f32 v144, v183, v144, v132
	v_log_f32_e32 v144, v144
	s_nop 0
	v_mul_f32_e32 v194, 0x3f317217, v144
	v_fma_f32 v194, v144, s52, -v194
	v_fmac_f32_e32 v194, 0x3377d1cf, v144
	v_fmac_f32_e32 v194, 0x3f317217, v144
	v_mov_b32_e32 v144, v194
	v_cndmask_b32_e64 v144, v148, v144, s[20:21]
	v_mul_f32_e32 v148, 0x3fb8aa3b, v168
	v_exp_f32_e32 v148, v148
	s_nop 0
	v_fma_f32 v148, v182, v148, v128
	v_log_f32_e32 v148, v148
	s_nop 0
	v_mul_f32_e32 v194, 0x3f317217, v148
	v_fma_f32 v194, v148, s52, -v194
	v_fmac_f32_e32 v194, 0x3377d1cf, v148
	v_fmac_f32_e32 v194, 0x3f317217, v148
	v_mov_b32_e32 v148, v194
	v_cndmask_b32_e64 v148, v168, v148, s[18:19]
	v_min_f32_e32 v168, 0, v149
	v_mul_f32_e64 v149, |v149|, s57
	v_exp_f32_e32 v149, v149
	s_nop 0
	v_add_f32_e32 v149, 1.0, v149
	v_log_f32_e32 v149, v149
	s_nop 0
	v_mul_f32_e32 v194, 0x3f317217, v149
	v_fma_f32 v194, v149, s52, -v194
	v_fmac_f32_e32 v194, 0x3377d1cf, v149
	v_fmac_f32_e32 v194, 0x3f317217, v149
	v_mov_b32_e32 v149, v194
	v_sub_f32_e32 v149, v168, v149
	v_min_f32_e32 v168, 0, v145
	v_mul_f32_e64 v145, |v145|, s57
	v_exp_f32_e32 v145, v145
	s_nop 0
	v_add_f32_e32 v145, 1.0, v145
	v_log_f32_e32 v145, v145
	s_nop 0
	v_mul_f32_e32 v194, 0x3f317217, v145
	v_fma_f32 v194, v145, s52, -v194
	v_fmac_f32_e32 v194, 0x3377d1cf, v145
	v_fmac_f32_e32 v194, 0x3f317217, v145
	v_mov_b32_e32 v145, v194
	v_sub_f32_e32 v168, v168, v145
	v_mul_f32_e32 v145, 0x3fb8aa3b, v149
	v_exp_f32_e32 v145, v145
	s_nop 0
	v_fma_f32 v145, v181, v145, v133
	v_log_f32_e32 v145, v145
	s_nop 0
	v_mul_f32_e32 v194, 0x3f317217, v145
	v_fma_f32 v194, v145, s52, -v194
	v_fmac_f32_e32 v194, 0x3377d1cf, v145
	v_fmac_f32_e32 v194, 0x3f317217, v145
	v_mov_b32_e32 v145, v194
	v_cndmask_b32_e64 v145, v149, v145, s[16:17]
	v_mul_f32_e32 v149, 0x3fb8aa3b, v168
	v_exp_f32_e32 v149, v149
	s_nop 0
	v_fma_f32 v149, v180, v149, v129
	v_log_f32_e32 v149, v149
	s_nop 0
	v_mul_f32_e32 v194, 0x3f317217, v149
	v_fma_f32 v194, v149, s52, -v194
	v_fmac_f32_e32 v194, 0x3377d1cf, v149
	v_fmac_f32_e32 v194, 0x3f317217, v149
	v_mov_b32_e32 v149, v194
	v_cndmask_b32_e64 v149, v168, v149, s[14:15]
; __device__ __forceinline__ float silu_f(float x) { return x * __builtin_amdgcn_rcpf(1.f + __expf(-x)); }
; __device__ __forceinline__ v4u pack8(const f32x4 a, const f32x4 b) { v4u w; w.x = cvt_pk_bf16(a[0], a[1]); w.y = cvt_pk_bf16(a[2], a[3]); w.z = cvt_pk_bf16(b[0], b[1]); w.w = cvt_pk_bf16(b[2], b[3]); return w; }
;     __device__ __forceinline__ void operator()(const f32x4 (&acc)[2][2][4][2], const pg8::Unit& u, int wr, int wc, int fr, int fq) const {
;     ...
;         if (grp == 0) { WIN_LOOP( _Pragma("unroll") for (int i = 0; i < 4; ++i) { a[i] = silu_f(a[i]); b[i] = silu_f(b[i]); } *(v4u*)(QO + (size_t)row * DM + c) = pack8(a, b); ) }
;         else if (grp == 3) { WIN_LOOP( _Pragma("unroll") for (int i = 0; i < 4; ++i) { a[i] = silu_f(a[i]); b[i] = silu_f(b[i]); } *(v4u*)(GH + (size_t)row * 512 + c) = pack8(a, b); ) }
;         else if (grp == 1) {
;             f32x4 l0[2], l1[2];
; #pragma unroll
;             for (int bj = 0; bj < 2; ++bj) { l0[bj] = *(const f32x4*)(lb + cb + bj * 128); l1[bj] = *(const f32x4*)(lb + cb + bj * 128 + 4); }
;             WIN_LOOP( _Pragma("unroll") for (int i = 0; i < 4; ++i) { const float s0 = fminf(a[i], 0.f) - __logf(1.f + __expf(-fabsf(a[i]))), s1 = fminf(b[i], 0.f) - __logf(1.f + __expf(-fabsf(b[i]))); const float la = l0[bj][i], lbv = l1[bj][i];
;                     a[i] = la > 0.f ? __logf(la + (1.f - la) * __expf(s0)) : s0; b[i] = lbv > 0.f ? __logf(lbv + (1.f - lbv) * __expf(s1)) : s1; }
;                 *(f32x4*)(LF + (size_t)row * 512 + c) = a; *(f32x4*)(LF + (size_t)row * 512 + c + 4) = b; __builtin_amdgcn_sched_barrier(0); ) }
	v_min_f32_e32 v168, 0, v150
	v_mul_f32_e64 v150, |v150|, s57
	v_exp_f32_e32 v150, v150
	s_nop 0
	v_add_f32_e32 v150, 1.0, v150
	v_log_f32_e32 v150, v150
	s_nop 0
	v_mul_f32_e32 v194, 0x3f317217, v150
	v_fma_f32 v194, v150, s52, -v194
	v_fmac_f32_e32 v194, 0x3377d1cf, v150
	v_fmac_f32_e32 v194, 0x3f317217, v150
	v_mov_b32_e32 v150, v194
	v_sub_f32_e32 v150, v168, v150
	v_min_f32_e32 v168, 0, v146
	v_mul_f32_e64 v146, |v146|, s57
	v_exp_f32_e32 v146, v146
	s_nop 0
	v_add_f32_e32 v146, 1.0, v146
	v_log_f32_e32 v146, v146
	s_nop 0
	v_mul_f32_e32 v194, 0x3f317217, v146
	v_fma_f32 v194, v146, s52, -v194
	v_fmac_f32_e32 v194, 0x3377d1cf, v146
	v_fmac_f32_e32 v194, 0x3f317217, v146
	v_mov_b32_e32 v146, v194
	v_sub_f32_e32 v168, v168, v146
	v_mul_f32_e32 v146, 0x3fb8aa3b, v150
	v_exp_f32_e32 v146, v146
	s_nop 0
	v_fma_f32 v146, v179, v146, v134
	v_log_f32_e32 v146, v146
	s_nop 0
	v_mul_f32_e32 v194, 0x3f317217, v146
	v_fma_f32 v194, v146, s52, -v194
	v_fmac_f32_e32 v194, 0x3377d1cf, v146
	v_fmac_f32_e32 v194, 0x3f317217, v146
	v_mov_b32_e32 v146, v194
	v_cndmask_b32_e64 v146, v150, v146, s[12:13]
	v_mul_f32_e32 v150, 0x3fb8aa3b, v168
	v_exp_f32_e32 v150, v150
	s_nop 0
	v_fma_f32 v150, v178, v150, v130
	v_log_f32_e32 v150, v150
	s_nop 0
	v_mul_f32_e32 v194, 0x3f317217, v150
	v_fma_f32 v194, v150, s52, -v194
	v_fmac_f32_e32 v194, 0x3377d1cf, v150
	v_fmac_f32_e32 v194, 0x3f317217, v150
	v_mov_b32_e32 v150, v194
	v_cndmask_b32_e64 v150, v168, v150, s[10:11]
	v_min_f32_e32 v168, 0, v151
	v_mul_f32_e64 v151, |v151|, s57
	v_exp_f32_e32 v151, v151
	s_nop 0
	v_add_f32_e32 v151, 1.0, v151
	v_log_f32_e32 v151, v151
	s_nop 0
	v_mul_f32_e32 v194, 0x3f317217, v151
	v_fma_f32 v194, v151, s52, -v194
	v_fmac_f32_e32 v194, 0x3377d1cf, v151
	v_fmac_f32_e32 v194, 0x3f317217, v151
	v_mov_b32_e32 v151, v194
	v_sub_f32_e32 v151, v168, v151
	v_min_f32_e32 v168, 0, v147
	v_mul_f32_e64 v147, |v147|, s57
	v_exp_f32_e32 v147, v147
	s_nop 0
	v_add_f32_e32 v147, 1.0, v147
	v_log_f32_e32 v147, v147
	s_nop 0
	v_mul_f32_e32 v194, 0x3f317217, v147
	v_fma_f32 v194, v147, s52, -v194
	v_fmac_f32_e32 v194, 0x3377d1cf, v147
	v_fmac_f32_e32 v194, 0x3f317217, v147
	v_mov_b32_e32 v147, v194
	v_sub_f32_e32 v168, v168, v147
	v_mul_f32_e32 v147, 0x3fb8aa3b, v151
	v_exp_f32_e32 v147, v147
	s_nop 0
	v_fma_f32 v147, v177, v147, v135
	v_log_f32_e32 v147, v147
	s_nop 0
	v_mul_f32_e32 v194, 0x3f317217, v147
	v_fma_f32 v194, v147, s52, -v194
	v_fmac_f32_e32 v194, 0x3377d1cf, v147
	v_fmac_f32_e32 v194, 0x3f317217, v147
	v_mov_b32_e32 v147, v194
	v_cndmask_b32_e64 v147, v151, v147, s[8:9]
	v_mul_f32_e32 v151, 0x3fb8aa3b, v168
	v_exp_f32_e32 v151, v151
	s_nop 0
	v_fma_f32 v151, v167, v151, v131
	v_log_f32_e32 v151, v151
	s_nop 0
	v_mul_f32_e32 v194, 0x3f317217, v151
	v_fma_f32 v194, v151, s52, -v194
	v_fmac_f32_e32 v194, 0x3377d1cf, v151
	v_fmac_f32_e32 v194, 0x3f317217, v151
	v_mov_b32_e32 v151, v194
	v_cndmask_b32_e32 v151, v168, v151, vcc
	global_store_dwordx4 v[170:171], v[144:147], off offset:512
	global_store_dwordx4 v[170:171], v[148:151], off offset:528
	s_nop 1
	v_add_u32_e32 v148, 0xb0, v166
	v_ashrrev_i32_e32 v149, 31, v148
	v_lshlrev_b64 v[144:145], 6, v[148:149]
	v_lshl_add_u64 v[144:145], v[160:161], 0, v[144:145]
	s_nop 0
	s_waitcnt lgkmcnt(0)
	s_nop 3
	v_lshlrev_b64 v[146:147], 11, v[148:149]
	s_nop 1
	v_lshl_add_u64 v[146:147], s[50:51], 0, v[146:147]
	v_lshl_add_u64 v[146:147], v[146:147], 0, v[192:193]
	s_waitcnt lgkmcnt(0)
	s_nop 1
	s_waitcnt lgkmcnt(0)
	s_nop 1
	v_mov_b32_e32 v144, v245
	s_nop 0
	v_pk_mul_f32 v[170:171], v[4:5], v[144:145] op_sel_hi:[1,0]
	v_pk_mul_f32 v[150:151], v[6:7], v[144:145] op_sel_hi:[1,0]
	v_pk_mul_f32 v[148:149], v[2:3], v[144:145] op_sel_hi:[1,0]
	v_pk_mul_f32 v[168:169], v[0:1], v[144:145] op_sel_hi:[1,0]
	v_min_f32_e32 v145, 0, v170
	v_mul_f32_e64 v170, |v170|, s57
	v_exp_f32_e32 v170, v170
	s_nop 0
	v_add_f32_e32 v170, 1.0, v170
	v_log_f32_e32 v170, v170
	s_nop 0
	v_mul_f32_e32 v194, 0x3f317217, v170
	v_fma_f32 v194, v170, s52, -v194
	v_fmac_f32_e32 v194, 0x3377d1cf, v170
	v_fmac_f32_e32 v194, 0x3f317217, v170
	v_mov_b32_e32 v170, v194
	v_sub_f32_e32 v145, v145, v170
	v_min_f32_e32 v170, 0, v168
	v_mul_f32_e64 v168, |v168|, s57
	v_exp_f32_e32 v168, v168
	s_nop 0
	v_add_f32_e32 v168, 1.0, v168
	v_log_f32_e32 v168, v168
	s_nop 0
	v_mul_f32_e32 v194, 0x3f317217, v168
	v_fma_f32 v194, v168, s52, -v194
	v_fmac_f32_e32 v194, 0x3377d1cf, v168
	v_fmac_f32_e32 v194, 0x3f317217, v168
	v_mov_b32_e32 v168, v194
	v_sub_f32_e32 v168, v170, v168
	v_mul_f32_e32 v170, 0x3fb8aa3b, v145
	v_exp_f32_e32 v170, v170
	s_nop 0
	v_fma_f32 v140, v190, v170, v140
	v_log_f32_e32 v140, v140
	s_nop 0
	v_mul_f32_e32 v170, 0x3f317217, v140
	v_fma_f32 v170, v140, s52, -v170
	v_fmac_f32_e32 v170, 0x3377d1cf, v140
	v_fmac_f32_e32 v170, 0x3f317217, v140
	v_mov_b32_e32 v140, v170
	v_cndmask_b32_e64 v140, v145, v140, s[38:39]
	v_mul_f32_e32 v145, 0x3fb8aa3b, v168
	v_exp_f32_e32 v145, v145
	v_readlane_b32 s42, v255, 57
	v_readlane_b32 s43, v255, 58
	v_fma_f32 v136, v191, v145, v136
	v_log_f32_e32 v136, v136
	s_nop 0
	v_mul_f32_e32 v145, 0x3f317217, v136
	v_fma_f32 v145, v136, s52, -v145
	v_fmac_f32_e32 v145, 0x3377d1cf, v136
	v_fmac_f32_e32 v145, 0x3f317217, v136
	v_mov_b32_e32 v136, v145
	v_cndmask_b32_e64 v136, v168, v136, s[36:37]
	v_mul_f32_e64 v168, |v171|, s57
	v_exp_f32_e32 v168, v168
	v_min_f32_e32 v145, 0, v171
	s_mov_b32 s40, s2
	v_add_f32_e32 v168, 1.0, v168
	v_log_f32_e32 v168, v168
	s_nop 0
	v_mul_f32_e32 v170, 0x3f317217, v168
	v_fma_f32 v170, v168, s52, -v170
	v_fmac_f32_e32 v170, 0x3377d1cf, v168
	v_fmac_f32_e32 v170, 0x3f317217, v168
	v_mov_b32_e32 v168, v170
; __device__ __forceinline__ float silu_f(float x) { return x * __builtin_amdgcn_rcpf(1.f + __expf(-x)); }
; __device__ __forceinline__ v4u pack8(const f32x4 a, const f32x4 b) { v4u w; w.x = cvt_pk_bf16(a[0], a[1]); w.y = cvt_pk_bf16(a[2], a[3]); w.z = cvt_pk_bf16(b[0], b[1]); w.w = cvt_pk_bf16(b[2], b[3]); return w; }
;     __device__ __forceinline__ void operator()(const f32x4 (&acc)[2][2][4][2], const pg8::Unit& u, int wr, int wc, int fr, int fq) const {
;     ...
;         if (grp == 0) { WIN_LOOP( _Pragma("unroll") for (int i = 0; i < 4; ++i) { a[i] = silu_f(a[i]); b[i] = silu_f(b[i]); } *(v4u*)(QO + (size_t)row * DM + c) = pack8(a, b); ) }
;         else if (grp == 3) { WIN_LOOP( _Pragma("unroll") for (int i = 0; i < 4; ++i) { a[i] = silu_f(a[i]); b[i] = silu_f(b[i]); } *(v4u*)(GH + (size_t)row * 512 + c) = pack8(a, b); ) }
;         else if (grp == 1) {
;             f32x4 l0[2], l1[2];
; #pragma unroll
;             for (int bj = 0; bj < 2; ++bj) { l0[bj] = *(const f32x4*)(lb + cb + bj * 128); l1[bj] = *(const f32x4*)(lb + cb + bj * 128 + 4); }
;             WIN_LOOP( _Pragma("unroll") for (int i = 0; i < 4; ++i) { const float s0 = fminf(a[i], 0.f) - __logf(1.f + __expf(-fabsf(a[i]))), s1 = fminf(b[i], 0.f) - __logf(1.f + __expf(-fabsf(b[i]))); const float la = l0[bj][i], lbv = l1[bj][i];
;                     a[i] = la > 0.f ? __logf(la + (1.f - la) * __expf(s0)) : s0; b[i] = lbv > 0.f ? __logf(lbv + (1.f - lbv) * __expf(s1)) : s1; }
;                 *(f32x4*)(LF + (size_t)row * 512 + c) = a; *(f32x4*)(LF + (size_t)row * 512 + c + 4) = b; __builtin_amdgcn_sched_barrier(0); ) }
	v_sub_f32_e32 v145, v145, v168
	v_min_f32_e32 v168, 0, v169
	v_mul_f32_e64 v169, |v169|, s57
	v_exp_f32_e32 v169, v169
	s_nop 0
	v_add_f32_e32 v169, 1.0, v169
	v_log_f32_e32 v169, v169
	s_nop 0
	v_mul_f32_e32 v170, 0x3f317217, v169
	v_fma_f32 v170, v169, s52, -v170
	v_fmac_f32_e32 v170, 0x3377d1cf, v169
	v_fmac_f32_e32 v170, 0x3f317217, v169
	v_mov_b32_e32 v169, v170
	v_sub_f32_e32 v168, v168, v169
	v_mul_f32_e32 v169, 0x3fb8aa3b, v145
	v_exp_f32_e32 v169, v169
	s_nop 0
	v_fma_f32 v141, v188, v169, v141
	v_log_f32_e32 v141, v141
	s_nop 0
	v_mul_f32_e32 v169, 0x3f317217, v141
	v_fma_f32 v169, v141, s52, -v169
	v_fmac_f32_e32 v169, 0x3377d1cf, v141
	v_fmac_f32_e32 v169, 0x3f317217, v141
	v_mov_b32_e32 v141, v169
	v_cndmask_b32_e64 v141, v145, v141, s[34:35]
	v_mul_f32_e32 v145, 0x3fb8aa3b, v168
	v_exp_f32_e32 v145, v145
	v_readlane_b32 s38, v255, 53
	v_readlane_b32 s39, v255, 54
	v_fma_f32 v137, v189, v145, v137
	v_log_f32_e32 v137, v137
	s_nop 0
	v_mul_f32_e32 v145, 0x3f317217, v137
	v_fma_f32 v145, v137, s52, -v145
	v_fmac_f32_e32 v145, 0x3377d1cf, v137
	v_fmac_f32_e32 v145, 0x3f317217, v137
	v_mov_b32_e32 v137, v145
	v_min_f32_e32 v145, 0, v150
	v_mul_f32_e64 v150, |v150|, s57
	v_exp_f32_e32 v150, v150
	v_cndmask_b32_e64 v137, v168, v137, s[30:31]
	v_readlane_b32 s36, v255, 51
	v_readlane_b32 s37, v255, 52
	v_add_f32_e32 v150, 1.0, v150
	v_log_f32_e32 v150, v150
	s_nop 0
	v_mul_f32_e32 v168, 0x3f317217, v150
	v_fma_f32 v168, v150, s52, -v168
	v_fmac_f32_e32 v168, 0x3377d1cf, v150
	v_fmac_f32_e32 v168, 0x3f317217, v150
	v_mov_b32_e32 v150, v168
	v_sub_f32_e32 v145, v145, v150
	v_min_f32_e32 v150, 0, v148
	v_mul_f32_e64 v148, |v148|, s57
	v_exp_f32_e32 v148, v148
	s_nop 0
	v_add_f32_e32 v148, 1.0, v148
	v_log_f32_e32 v148, v148
	s_nop 0
	v_mul_f32_e32 v168, 0x3f317217, v148
	v_fma_f32 v168, v148, s52, -v168
	v_fmac_f32_e32 v168, 0x3377d1cf, v148
	v_fmac_f32_e32 v168, 0x3f317217, v148
	v_mov_b32_e32 v148, v168
	v_sub_f32_e32 v148, v150, v148
	v_mul_f32_e32 v150, 0x3fb8aa3b, v145
	v_exp_f32_e32 v150, v150
	s_nop 0
	v_fma_f32 v142, v187, v150, v142
	v_log_f32_e32 v142, v142
	s_nop 0
	v_mul_f32_e32 v150, 0x3f317217, v142
	v_fma_f32 v150, v142, s52, -v150
	v_fmac_f32_e32 v150, 0x3377d1cf, v142
	v_fmac_f32_e32 v150, 0x3f317217, v142
	v_mov_b32_e32 v142, v150
	v_cndmask_b32_e64 v142, v145, v142, s[28:29]
	v_mul_f32_e32 v145, 0x3fb8aa3b, v148
	v_exp_f32_e32 v145, v145
	v_readlane_b32 s34, v255, 49
	v_readlane_b32 s35, v255, 50
	v_fma_f32 v138, v186, v145, v138
	v_log_f32_e32 v138, v138
	s_nop 0
	v_mul_f32_e32 v145, 0x3f317217, v138
	v_fma_f32 v145, v138, s52, -v145
	v_fmac_f32_e32 v145, 0x3377d1cf, v138
	v_fmac_f32_e32 v145, 0x3f317217, v138
	v_mov_b32_e32 v138, v145
	v_cndmask_b32_e64 v138, v148, v138, s[26:27]
	v_mul_f32_e64 v148, |v151|, s57
	v_exp_f32_e32 v148, v148
	v_min_f32_e32 v145, 0, v151
	v_readlane_b32 s30, v255, 47
	v_readlane_b32 s31, v255, 48
	v_add_f32_e32 v148, 1.0, v148
	v_log_f32_e32 v148, v148
	s_nop 0
	v_mul_f32_e32 v150, 0x3f317217, v148
	v_fma_f32 v150, v148, s52, -v150
	v_fmac_f32_e32 v150, 0x3377d1cf, v148
	v_fmac_f32_e32 v150, 0x3f317217, v148
	v_mov_b32_e32 v148, v150
	v_sub_f32_e32 v145, v145, v148
	v_min_f32_e32 v148, 0, v149
	v_mul_f32_e64 v149, |v149|, s57
	v_exp_f32_e32 v149, v149
	s_nop 0
	v_add_f32_e32 v149, 1.0, v149
	v_log_f32_e32 v149, v149
	s_nop 0
	v_mul_f32_e32 v150, 0x3f317217, v149
	v_fma_f32 v150, v149, s52, -v150
	v_fmac_f32_e32 v150, 0x3377d1cf, v149
	v_fmac_f32_e32 v150, 0x3f317217, v149
	v_mov_b32_e32 v149, v150
	v_sub_f32_e32 v148, v148, v149
	v_mul_f32_e32 v149, 0x3fb8aa3b, v145
	v_exp_f32_e32 v149, v149
	s_nop 0
	v_fmac_f32_e32 v143, v185, v149
	v_cmp_gt_f32_e64 s[26:27], s97, v143
	s_nop 1
	v_cndmask_b32_e64 v149, 0, 32, s[26:27]
	v_ldexp_f32 v143, v143, v149
	v_log_f32_e32 v143, v143
	s_nop 0
	v_mul_f32_e32 v149, 0x3f317217, v143
	v_fma_f32 v149, v143, s52, -v149
	v_fmac_f32_e32 v149, 0x3377d1cf, v143
	v_fmac_f32_e32 v149, 0x3f317217, v143
	v_cmp_lt_f32_e64 s[28:29], |v143|, s53
	s_nop 1
	v_cndmask_b32_e64 v143, v143, v149, s[28:29]
	v_cndmask_b32_e64 v149, 0, v216, s[26:27]
	v_sub_f32_e32 v143, v143, v149
	v_cndmask_b32_e64 v143, v145, v143, s[24:25]
	v_mul_f32_e32 v145, 0x3fb8aa3b, v148
	v_exp_f32_e32 v145, v145
	s_mov_b32 s29, s91
	s_mov_b32 s28, s95
	v_fmac_f32_e32 v139, v184, v145
	v_cmp_gt_f32_e64 s[24:25], s97, v139
	s_nop 1
	v_cndmask_b32_e64 v145, 0, 32, s[24:25]
	v_ldexp_f32 v139, v139, v145
	v_log_f32_e32 v139, v139
	s_nop 0
	v_mul_f32_e32 v145, 0x3f317217, v139
	v_fma_f32 v145, v139, s52, -v145
	v_fmac_f32_e32 v145, 0x3377d1cf, v139
	v_fmac_f32_e32 v145, 0x3f317217, v139
	v_cmp_lt_f32_e64 s[26:27], |v139|, s53
	s_nop 1
	v_cndmask_b32_e64 v139, v139, v145, s[26:27]
	v_cndmask_b32_e64 v145, 0, v216, s[24:25]
	v_readlane_b32 s27, v255, 56
	v_readlane_b32 s26, v255, 31
	v_sub_f32_e32 v139, v139, v145
	v_cndmask_b32_e64 v139, v148, v139, s[22:23]
	global_store_dwordx4 v[146:147], v[140:143], off
	global_store_dwordx4 v[146:147], v[136:139], off offset:16
	s_nop 0
	v_pk_mul_f32 v[142:143], v[68:69], v[144:145] op_sel_hi:[1,0]
	v_pk_mul_f32 v[138:139], v[70:71], v[144:145] op_sel_hi:[1,0]
	v_pk_mul_f32 v[136:137], v[66:67], v[144:145] op_sel_hi:[1,0]
	v_pk_mul_f32 v[140:141], v[64:65], v[144:145] op_sel_hi:[1,0]
	v_min_f32_e32 v144, 0, v142
	v_mul_f32_e64 v142, |v142|, s57
	v_exp_f32_e32 v142, v142
	s_nop 0
	v_add_f32_e32 v142, 1.0, v142
	v_log_f32_e32 v142, v142
	s_nop 0
	v_mul_f32_e32 v145, 0x3f317217, v142
	v_fma_f32 v145, v142, s52, -v145
	v_fmac_f32_e32 v145, 0x3377d1cf, v142
	v_fmac_f32_e32 v145, 0x3f317217, v142
	v_mov_b32_e32 v142, v145
	v_sub_f32_e32 v142, v144, v142
; __device__ __forceinline__ float silu_f(float x) { return x * __builtin_amdgcn_rcpf(1.f + __expf(-x)); }
; __device__ __forceinline__ v4u pack8(const f32x4 a, const f32x4 b) { v4u w; w.x = cvt_pk_bf16(a[0], a[1]); w.y = cvt_pk_bf16(a[2], a[3]); w.z = cvt_pk_bf16(b[0], b[1]); w.w = cvt_pk_bf16(b[2], b[3]); return w; }
;     __device__ __forceinline__ void operator()(const f32x4 (&acc)[2][2][4][2], const pg8::Unit& u, int wr, int wc, int fr, int fq) const {
;     ...
;         if (grp == 0) { WIN_LOOP( _Pragma("unroll") for (int i = 0; i < 4; ++i) { a[i] = silu_f(a[i]); b[i] = silu_f(b[i]); } *(v4u*)(QO + (size_t)row * DM + c) = pack8(a, b); ) }
;         else if (grp == 3) { WIN_LOOP( _Pragma("unroll") for (int i = 0; i < 4; ++i) { a[i] = silu_f(a[i]); b[i] = silu_f(b[i]); } *(v4u*)(GH + (size_t)row * 512 + c) = pack8(a, b); ) }
;         else if (grp == 1) {
;             f32x4 l0[2], l1[2];
; #pragma unroll
;             for (int bj = 0; bj < 2; ++bj) { l0[bj] = *(const f32x4*)(lb + cb + bj * 128); l1[bj] = *(const f32x4*)(lb + cb + bj * 128 + 4); }
;             WIN_LOOP( _Pragma("unroll") for (int i = 0; i < 4; ++i) { const float s0 = fminf(a[i], 0.f) - __logf(1.f + __expf(-fabsf(a[i]))), s1 = fminf(b[i], 0.f) - __logf(1.f + __expf(-fabsf(b[i]))); const float la = l0[bj][i], lbv = l1[bj][i];
;                     a[i] = la > 0.f ? __logf(la + (1.f - la) * __expf(s0)) : s0; b[i] = lbv > 0.f ? __logf(lbv + (1.f - lbv) * __expf(s1)) : s1; }
;                 *(f32x4*)(LF + (size_t)row * 512 + c) = a; *(f32x4*)(LF + (size_t)row * 512 + c + 4) = b; __builtin_amdgcn_sched_barrier(0); ) }
	v_min_f32_e32 v144, 0, v140
	v_mul_f32_e64 v140, |v140|, s57
	v_exp_f32_e32 v140, v140
	s_nop 0
	v_add_f32_e32 v140, 1.0, v140
	v_log_f32_e32 v140, v140
	s_nop 0
	v_mul_f32_e32 v145, 0x3f317217, v140
	v_fma_f32 v145, v140, s52, -v145
	v_fmac_f32_e32 v145, 0x3377d1cf, v140
	v_fmac_f32_e32 v145, 0x3f317217, v140
	v_mov_b32_e32 v140, v145
	v_sub_f32_e32 v140, v144, v140
	v_mul_f32_e32 v144, 0x3fb8aa3b, v142
	v_exp_f32_e32 v144, v144
	s_nop 0
	v_fma_f32 v132, v183, v144, v132
	v_log_f32_e32 v132, v132
	s_nop 0
	v_mul_f32_e32 v144, 0x3f317217, v132
	v_fma_f32 v144, v132, s52, -v144
	v_fmac_f32_e32 v144, 0x3377d1cf, v132
	v_fmac_f32_e32 v144, 0x3f317217, v132
	v_mov_b32_e32 v132, v144
	v_cndmask_b32_e64 v132, v142, v132, s[20:21]
	v_mul_f32_e32 v142, 0x3fb8aa3b, v140
	v_exp_f32_e32 v142, v142
	s_nop 0
	v_fma_f32 v128, v182, v142, v128
	v_log_f32_e32 v128, v128
	s_nop 0
	v_mul_f32_e32 v142, 0x3f317217, v128
	v_fma_f32 v142, v128, s52, -v142
	v_fmac_f32_e32 v142, 0x3377d1cf, v128
	v_fmac_f32_e32 v142, 0x3f317217, v128
	v_mov_b32_e32 v128, v142
	v_mul_f32_e64 v142, |v143|, s57
	v_exp_f32_e32 v142, v142
	v_cndmask_b32_e64 v128, v140, v128, s[18:19]
	v_min_f32_e32 v140, 0, v143
	v_readlane_b32 s23, v255, 55
	v_add_f32_e32 v142, 1.0, v142
	v_log_f32_e32 v142, v142
	s_nop 0
	v_mul_f32_e32 v143, 0x3f317217, v142
	v_fma_f32 v143, v142, s52, -v143
	v_fmac_f32_e32 v143, 0x3377d1cf, v142
	v_fmac_f32_e32 v143, 0x3f317217, v142
	v_mov_b32_e32 v142, v143
	v_sub_f32_e32 v140, v140, v142
	v_min_f32_e32 v142, 0, v141
	v_mul_f32_e64 v141, |v141|, s57
	v_exp_f32_e32 v141, v141
	s_nop 0
	v_add_f32_e32 v141, 1.0, v141
	v_log_f32_e32 v141, v141
	s_nop 0
	v_mul_f32_e32 v143, 0x3f317217, v141
	v_fma_f32 v143, v141, s52, -v143
	v_fmac_f32_e32 v143, 0x3377d1cf, v141
	v_fmac_f32_e32 v143, 0x3f317217, v141
	v_mov_b32_e32 v141, v143
	v_sub_f32_e32 v141, v142, v141
	v_mul_f32_e32 v142, 0x3fb8aa3b, v140
	v_exp_f32_e32 v142, v142
	s_nop 0
	v_fma_f32 v133, v181, v142, v133
	v_log_f32_e32 v133, v133
	s_nop 0
	v_mul_f32_e32 v142, 0x3f317217, v133
	v_fma_f32 v142, v133, s52, -v142
	v_fmac_f32_e32 v142, 0x3377d1cf, v133
	v_fmac_f32_e32 v142, 0x3f317217, v133
	v_mov_b32_e32 v133, v142
	v_cndmask_b32_e64 v133, v140, v133, s[16:17]
	v_mul_f32_e32 v140, 0x3fb8aa3b, v141
	v_exp_f32_e32 v140, v140
	s_nop 0
	v_fma_f32 v129, v180, v140, v129
	v_log_f32_e32 v129, v129
	s_nop 0
	v_mul_f32_e32 v140, 0x3f317217, v129
	v_fma_f32 v140, v129, s52, -v140
	v_fmac_f32_e32 v140, 0x3377d1cf, v129
	v_fmac_f32_e32 v140, 0x3f317217, v129
	v_mov_b32_e32 v129, v140
	v_min_f32_e32 v140, 0, v138
	v_mul_f32_e64 v138, |v138|, s57
	v_exp_f32_e32 v138, v138
	v_cndmask_b32_e64 v129, v141, v129, s[14:15]
	v_add_f32_e32 v138, 1.0, v138
	v_log_f32_e32 v138, v138
	s_nop 0
	v_mul_f32_e32 v141, 0x3f317217, v138
	v_fma_f32 v141, v138, s52, -v141
	v_fmac_f32_e32 v141, 0x3377d1cf, v138
	v_fmac_f32_e32 v141, 0x3f317217, v138
	v_mov_b32_e32 v138, v141
	v_sub_f32_e32 v138, v140, v138
	v_min_f32_e32 v140, 0, v136
	v_mul_f32_e64 v136, |v136|, s57
	v_exp_f32_e32 v136, v136
	s_nop 0
	v_add_f32_e32 v136, 1.0, v136
	v_log_f32_e32 v136, v136
	s_nop 0
	v_mul_f32_e32 v141, 0x3f317217, v136
	v_fma_f32 v141, v136, s52, -v141
	v_fmac_f32_e32 v141, 0x3377d1cf, v136
	v_fmac_f32_e32 v141, 0x3f317217, v136
	v_mov_b32_e32 v136, v141
	v_sub_f32_e32 v136, v140, v136
	v_mul_f32_e32 v140, 0x3fb8aa3b, v138
	v_exp_f32_e32 v140, v140
	s_nop 0
	v_fma_f32 v134, v179, v140, v134
	v_log_f32_e32 v134, v134
	s_nop 0
	v_mul_f32_e32 v140, 0x3f317217, v134
	v_fma_f32 v140, v134, s52, -v140
	v_fmac_f32_e32 v140, 0x3377d1cf, v134
	v_fmac_f32_e32 v140, 0x3f317217, v134
	v_mov_b32_e32 v134, v140
	v_cndmask_b32_e64 v134, v138, v134, s[12:13]
	v_mul_f32_e32 v138, 0x3fb8aa3b, v136
	v_exp_f32_e32 v138, v138
	s_nop 0
	v_fma_f32 v130, v178, v138, v130
	v_log_f32_e32 v130, v130
	s_nop 0
	v_mul_f32_e32 v138, 0x3f317217, v130
	v_fma_f32 v138, v130, s52, -v138
	v_fmac_f32_e32 v138, 0x3377d1cf, v130
	v_fmac_f32_e32 v138, 0x3f317217, v130
	v_mov_b32_e32 v130, v138
	v_mul_f32_e64 v138, |v139|, s57
	v_exp_f32_e32 v138, v138
	v_cndmask_b32_e64 v130, v136, v130, s[10:11]
	v_min_f32_e32 v136, 0, v139
	v_add_f32_e32 v138, 1.0, v138
	v_log_f32_e32 v138, v138
	s_nop 0
	v_mul_f32_e32 v139, 0x3f317217, v138
	v_fma_f32 v139, v138, s52, -v139
	v_fmac_f32_e32 v139, 0x3377d1cf, v138
	v_fmac_f32_e32 v139, 0x3f317217, v138
	v_mov_b32_e32 v138, v139
	v_sub_f32_e32 v136, v136, v138
	v_min_f32_e32 v138, 0, v137
	v_mul_f32_e64 v137, |v137|, s57
	v_exp_f32_e32 v137, v137
	s_nop 0
	v_add_f32_e32 v137, 1.0, v137
	v_log_f32_e32 v137, v137
	s_nop 0
	v_mul_f32_e32 v139, 0x3f317217, v137
	v_fma_f32 v139, v137, s52, -v139
	v_fmac_f32_e32 v139, 0x3377d1cf, v137
	v_fmac_f32_e32 v139, 0x3f317217, v137
	v_mov_b32_e32 v137, v139
	v_sub_f32_e32 v137, v138, v137
	v_mul_f32_e32 v138, 0x3fb8aa3b, v136
	v_exp_f32_e32 v138, v138
	s_nop 0
	v_fmac_f32_e32 v135, v177, v138
	v_cmp_gt_f32_e64 s[10:11], s97, v135
	s_nop 1
	v_cndmask_b32_e64 v138, 0, 32, s[10:11]
	v_ldexp_f32 v135, v135, v138
	v_log_f32_e32 v135, v135
	s_nop 0
	v_mul_f32_e32 v138, 0x3f317217, v135
	v_fma_f32 v138, v135, s52, -v138
	v_fmac_f32_e32 v138, 0x3377d1cf, v135
	v_fmac_f32_e32 v138, 0x3f317217, v135
	v_cmp_lt_f32_e64 s[12:13], |v135|, s53
	s_nop 1
	v_cndmask_b32_e64 v135, v135, v138, s[12:13]
	v_cndmask_b32_e64 v138, 0, v216, s[10:11]
	v_sub_f32_e32 v135, v135, v138
	v_cndmask_b32_e64 v135, v136, v135, s[8:9]
	v_mul_f32_e32 v136, 0x3fb8aa3b, v137
	v_exp_f32_e32 v136, v136
	s_nop 0
	v_fmac_f32_e32 v131, v167, v136
	v_cmp_gt_f32_e64 s[8:9], s97, v131
	s_nop 1
	v_cndmask_b32_e64 v136, 0, 32, s[8:9]
	v_ldexp_f32 v131, v131, v136
	v_log_f32_e32 v131, v131
	s_nop 0
	v_mul_f32_e32 v136, 0x3f317217, v131
	v_fma_f32 v136, v131, s52, -v136
	v_fmac_f32_e32 v136, 0x3377d1cf, v131
	v_fmac_f32_e32 v136, 0x3f317217, v131
	v_cmp_lt_f32_e64 s[10:11], |v131|, s53
	s_nop 1
	v_cndmask_b32_e64 v131, v131, v136, s[10:11]
	v_cndmask_b32_e64 v136, 0, v216, s[8:9]
	v_sub_f32_e32 v131, v131, v136
	v_cndmask_b32_e32 v131, v137, v131, vcc
	global_store_dwordx4 v[146:147], v[132:135], off offset:512
	global_store_dwordx4 v[146:147], v[128:131], off offset:528

; __device__ __forceinline__ unsigned cvt_pk_bf16(float lo, float hi) { const f32x2cv v = {lo, hi}; const bf16x2cv b = __builtin_convertvector(v, bf16x2cv); return __builtin_bit_cast(unsigned, b); }
; __device__ __forceinline__ float bflo(unsigned w) { return __uint_as_float(w << 16); }
; __device__ __forceinline__ float bfhi(unsigned w) { return __uint_as_float(w & 0xffff0000u); }
; __device__ __forceinline__ void hgrn_pass2(Frame& F) {
;     ...
;     for (int item = F.vcu * 256 + F.tid; item < 8 * 128 * 64; item += F.G * 256) {
;         const int bh = item >> 13, rem = item & 8191;
;         unsigned* up = (unsigned*)((bf16*)F.out + (size_t)bh * 128 * 16384) + rem; const float2* dp = (const float2*)((const float*)(F.ws + WS_HD) + (size_t)bh * 128 * 128) + (rem & 63);
;         float s0 = 0.f, s1 = 0.f;
; #pragma unroll 32
;         for (int c = 0; c < 128; ++c) { const unsigned u = up[(size_t)c * 8192]; const float2 d = dp[c * 64];
;             up[(size_t)c * 8192] = cvt_pk_bf16(s0, s1);
;             s0 = d.x * s0 + bflo(u); s1 = d.y * s1 + bfhi(u); }
.LBB0_621:
	v_ashrrev_i32_e32 v2, 13, v10
	v_and_b32_e32 v3, 0x1fff, v11
	v_lshlrev_b32_e32 v4, 22, v2
	v_lshl_or_b32 v6, v3, 2, v4
	v_lshlrev_b32_e32 v4, 16, v2
	v_add_u32_e32 v12, v4, v192
	v_add_u32_e32 v12, 0x3900000, v12
	v_mov_b32_e32 v14, v6
	v_mov_b32_e32 v8, 0
	v_mov_b32_e32 v9, 0
	global_load_dword v32, v6, s[8:9]
	global_load_dwordx2 v[80:81], v12, s[10:11]
	v_add_u32_e32 v6, 0x8000, v6
	v_add_u32_e32 v12, 0x200, v12
	global_load_dword v33, v6, s[8:9]
	global_load_dwordx2 v[82:83], v12, s[10:11]
	v_add_u32_e32 v6, 0x8000, v6
	v_add_u32_e32 v12, 0x200, v12
	global_load_dword v34, v6, s[8:9]
	global_load_dwordx2 v[84:85], v12, s[10:11]
	v_add_u32_e32 v6, 0x8000, v6
	v_add_u32_e32 v12, 0x200, v12
	global_load_dword v35, v6, s[8:9]
	global_load_dwordx2 v[86:87], v12, s[10:11]
	v_add_u32_e32 v6, 0x8000, v6
	v_add_u32_e32 v12, 0x200, v12
	global_load_dword v36, v6, s[8:9]
	global_load_dwordx2 v[88:89], v12, s[10:11]
	v_add_u32_e32 v6, 0x8000, v6
	v_add_u32_e32 v12, 0x200, v12
	global_load_dword v37, v6, s[8:9]
	global_load_dwordx2 v[90:91], v12, s[10:11]
	v_add_u32_e32 v6, 0x8000, v6
	v_add_u32_e32 v12, 0x200, v12
	global_load_dword v38, v6, s[8:9]
	global_load_dwordx2 v[92:93], v12, s[10:11]
	v_add_u32_e32 v6, 0x8000, v6
	v_add_u32_e32 v12, 0x200, v12
	global_load_dword v39, v6, s[8:9]
	global_load_dwordx2 v[94:95], v12, s[10:11]
	v_add_u32_e32 v6, 0x8000, v6
	v_add_u32_e32 v12, 0x200, v12
	global_load_dword v40, v6, s[8:9]
	global_load_dwordx2 v[96:97], v12, s[10:11]
	v_add_u32_e32 v6, 0x8000, v6
	v_add_u32_e32 v12, 0x200, v12
	global_load_dword v41, v6, s[8:9]
	global_load_dwordx2 v[98:99], v12, s[10:11]
	v_add_u32_e32 v6, 0x8000, v6
	v_add_u32_e32 v12, 0x200, v12
	global_load_dword v42, v6, s[8:9]
	global_load_dwordx2 v[100:101], v12, s[10:11]
	v_add_u32_e32 v6, 0x8000, v6
	v_add_u32_e32 v12, 0x200, v12
	global_load_dword v43, v6, s[8:9]
	global_load_dwordx2 v[102:103], v12, s[10:11]
	v_add_u32_e32 v6, 0x8000, v6
	v_add_u32_e32 v12, 0x200, v12
	global_load_dword v44, v6, s[8:9]
	global_load_dwordx2 v[104:105], v12, s[10:11]
	v_add_u32_e32 v6, 0x8000, v6
	v_add_u32_e32 v12, 0x200, v12
	global_load_dword v45, v6, s[8:9]
	global_load_dwordx2 v[106:107], v12, s[10:11]
	v_add_u32_e32 v6, 0x8000, v6
	v_add_u32_e32 v12, 0x200, v12
	global_load_dword v46, v6, s[8:9]
	global_load_dwordx2 v[108:109], v12, s[10:11]
	v_add_u32_e32 v6, 0x8000, v6
	v_add_u32_e32 v12, 0x200, v12
	global_load_dword v47, v6, s[8:9]
	global_load_dwordx2 v[110:111], v12, s[10:11]
	v_add_u32_e32 v6, 0x8000, v6
	v_add_u32_e32 v12, 0x200, v12
	global_load_dword v48, v6, s[8:9]
	global_load_dwordx2 v[112:113], v12, s[10:11]
	v_add_u32_e32 v6, 0x8000, v6
	v_add_u32_e32 v12, 0x200, v12
	global_load_dword v49, v6, s[8:9]
	global_load_dwordx2 v[114:115], v12, s[10:11]
	v_add_u32_e32 v6, 0x8000, v6
	v_add_u32_e32 v12, 0x200, v12
	global_load_dword v50, v6, s[8:9]
	global_load_dwordx2 v[116:117], v12, s[10:11]
	v_add_u32_e32 v6, 0x8000, v6
	v_add_u32_e32 v12, 0x200, v12
	global_load_dword v51, v6, s[8:9]
	global_load_dwordx2 v[118:119], v12, s[10:11]
	v_add_u32_e32 v6, 0x8000, v6
	v_add_u32_e32 v12, 0x200, v12
	global_load_dword v52, v6, s[8:9]
	global_load_dwordx2 v[120:121], v12, s[10:11]
	v_add_u32_e32 v6, 0x8000, v6
	v_add_u32_e32 v12, 0x200, v12
	global_load_dword v53, v6, s[8:9]
	global_load_dwordx2 v[122:123], v12, s[10:11]
	v_add_u32_e32 v6, 0x8000, v6
	v_add_u32_e32 v12, 0x200, v12
	global_load_dword v54, v6, s[8:9]
	global_load_dwordx2 v[124:125], v12, s[10:11]
	v_add_u32_e32 v6, 0x8000, v6
	v_add_u32_e32 v12, 0x200, v12
	global_load_dword v55, v6, s[8:9]
	global_load_dwordx2 v[126:127], v12, s[10:11]
	v_add_u32_e32 v6, 0x8000, v6
	v_add_u32_e32 v12, 0x200, v12
	global_load_dword v56, v6, s[8:9]
	global_load_dwordx2 v[128:129], v12, s[10:11]
	v_add_u32_e32 v6, 0x8000, v6
	v_add_u32_e32 v12, 0x200, v12
	global_load_dword v57, v6, s[8:9]
	global_load_dwordx2 v[130:131], v12, s[10:11]
	v_add_u32_e32 v6, 0x8000, v6
	v_add_u32_e32 v12, 0x200, v12
	global_load_dword v58, v6, s[8:9]
	global_load_dwordx2 v[132:133], v12, s[10:11]
	v_add_u32_e32 v6, 0x8000, v6
	v_add_u32_e32 v12, 0x200, v12
	global_load_dword v59, v6, s[8:9]
	global_load_dwordx2 v[134:135], v12, s[10:11]
	v_add_u32_e32 v6, 0x8000, v6
	v_add_u32_e32 v12, 0x200, v12
	global_load_dword v60, v6, s[8:9]
	global_load_dwordx2 v[136:137], v12, s[10:11]
	v_add_u32_e32 v6, 0x8000, v6
	v_add_u32_e32 v12, 0x200, v12
	global_load_dword v61, v6, s[8:9]
	global_load_dwordx2 v[138:139], v12, s[10:11]
	v_add_u32_e32 v6, 0x8000, v6
	v_add_u32_e32 v12, 0x200, v12
	global_load_dword v62, v6, s[8:9]
	global_load_dwordx2 v[140:141], v12, s[10:11]
	v_add_u32_e32 v6, 0x8000, v6
	v_add_u32_e32 v12, 0x200, v12
	global_load_dword v63, v6, s[8:9]
	global_load_dwordx2 v[142:143], v12, s[10:11]
	v_add_u32_e32 v6, 0x8000, v6
	v_add_u32_e32 v12, 0x200, v12
	s_waitcnt vmcnt(32)
; __device__ __forceinline__ unsigned cvt_pk_bf16(float lo, float hi) { const f32x2cv v = {lo, hi}; const bf16x2cv b = __builtin_convertvector(v, bf16x2cv); return __builtin_bit_cast(unsigned, b); }
; __device__ __forceinline__ float bflo(unsigned w) { return __uint_as_float(w << 16); }
; __device__ __forceinline__ float bfhi(unsigned w) { return __uint_as_float(w & 0xffff0000u); }
; __device__ __forceinline__ void hgrn_pass2(Frame& F) {
;     ...
;         float s0 = 0.f, s1 = 0.f;
; #pragma unroll 32
;         for (int c = 0; c < 128; ++c) { const unsigned u = up[(size_t)c * 8192]; const float2 d = dp[c * 64];
;             up[(size_t)c * 8192] = cvt_pk_bf16(s0, s1);
;             s0 = d.x * s0 + bflo(u); s1 = d.y * s1 + bfhi(u); }
	v_cvt_pk_bf16_f32 v16, v8, v9
	global_store_dword v14, v16, s[8:9]
	v_lshlrev_b32_e32 v18, 16, v32
	v_and_b32_e32 v19, 0xffff0000, v32
	v_pk_fma_f32 v[8:9], v[8:9], v[80:81], v[18:19]
	v_add_u32_e32 v14, 0x8000, v14
	v_cvt_pk_bf16_f32 v16, v8, v9
	global_store_dword v14, v16, s[8:9]
	v_lshlrev_b32_e32 v18, 16, v33
	v_and_b32_e32 v19, 0xffff0000, v33
	v_pk_fma_f32 v[8:9], v[8:9], v[82:83], v[18:19]
	v_add_u32_e32 v14, 0x8000, v14
	v_cvt_pk_bf16_f32 v16, v8, v9
	global_store_dword v14, v16, s[8:9]
	v_lshlrev_b32_e32 v18, 16, v34
	v_and_b32_e32 v19, 0xffff0000, v34
	v_pk_fma_f32 v[8:9], v[8:9], v[84:85], v[18:19]
	v_add_u32_e32 v14, 0x8000, v14
	v_cvt_pk_bf16_f32 v16, v8, v9
	global_store_dword v14, v16, s[8:9]
	v_lshlrev_b32_e32 v18, 16, v35
	v_and_b32_e32 v19, 0xffff0000, v35
	v_pk_fma_f32 v[8:9], v[8:9], v[86:87], v[18:19]
	v_add_u32_e32 v14, 0x8000, v14
	v_cvt_pk_bf16_f32 v16, v8, v9
	global_store_dword v14, v16, s[8:9]
	v_lshlrev_b32_e32 v18, 16, v36
	v_and_b32_e32 v19, 0xffff0000, v36
	v_pk_fma_f32 v[8:9], v[8:9], v[88:89], v[18:19]
	v_add_u32_e32 v14, 0x8000, v14
	v_cvt_pk_bf16_f32 v16, v8, v9
	global_store_dword v14, v16, s[8:9]
	v_lshlrev_b32_e32 v18, 16, v37
	v_and_b32_e32 v19, 0xffff0000, v37
	v_pk_fma_f32 v[8:9], v[8:9], v[90:91], v[18:19]
	v_add_u32_e32 v14, 0x8000, v14
	v_cvt_pk_bf16_f32 v16, v8, v9
	global_store_dword v14, v16, s[8:9]
	v_lshlrev_b32_e32 v18, 16, v38
	v_and_b32_e32 v19, 0xffff0000, v38
	v_pk_fma_f32 v[8:9], v[8:9], v[92:93], v[18:19]
	v_add_u32_e32 v14, 0x8000, v14
	v_cvt_pk_bf16_f32 v16, v8, v9
	global_store_dword v14, v16, s[8:9]
	v_lshlrev_b32_e32 v18, 16, v39
	v_and_b32_e32 v19, 0xffff0000, v39
	v_pk_fma_f32 v[8:9], v[8:9], v[94:95], v[18:19]
	v_add_u32_e32 v14, 0x8000, v14
	v_cvt_pk_bf16_f32 v16, v8, v9
	global_store_dword v14, v16, s[8:9]
	v_lshlrev_b32_e32 v18, 16, v40
	v_and_b32_e32 v19, 0xffff0000, v40
	v_pk_fma_f32 v[8:9], v[8:9], v[96:97], v[18:19]
	v_add_u32_e32 v14, 0x8000, v14
	v_cvt_pk_bf16_f32 v16, v8, v9
	global_store_dword v14, v16, s[8:9]
	v_lshlrev_b32_e32 v18, 16, v41
	v_and_b32_e32 v19, 0xffff0000, v41
	v_pk_fma_f32 v[8:9], v[8:9], v[98:99], v[18:19]
	v_add_u32_e32 v14, 0x8000, v14
	v_cvt_pk_bf16_f32 v16, v8, v9
	global_store_dword v14, v16, s[8:9]
	v_lshlrev_b32_e32 v18, 16, v42
	v_and_b32_e32 v19, 0xffff0000, v42
	v_pk_fma_f32 v[8:9], v[8:9], v[100:101], v[18:19]
	v_add_u32_e32 v14, 0x8000, v14
	v_cvt_pk_bf16_f32 v16, v8, v9
	global_store_dword v14, v16, s[8:9]
	v_lshlrev_b32_e32 v18, 16, v43
	v_and_b32_e32 v19, 0xffff0000, v43
	v_pk_fma_f32 v[8:9], v[8:9], v[102:103], v[18:19]
	v_add_u32_e32 v14, 0x8000, v14
	v_cvt_pk_bf16_f32 v16, v8, v9
	global_store_dword v14, v16, s[8:9]
	v_lshlrev_b32_e32 v18, 16, v44
	v_and_b32_e32 v19, 0xffff0000, v44
	v_pk_fma_f32 v[8:9], v[8:9], v[104:105], v[18:19]
	v_add_u32_e32 v14, 0x8000, v14
	v_cvt_pk_bf16_f32 v16, v8, v9
	global_store_dword v14, v16, s[8:9]
	v_lshlrev_b32_e32 v18, 16, v45
	v_and_b32_e32 v19, 0xffff0000, v45
	v_pk_fma_f32 v[8:9], v[8:9], v[106:107], v[18:19]
	v_add_u32_e32 v14, 0x8000, v14
	v_cvt_pk_bf16_f32 v16, v8, v9
	global_store_dword v14, v16, s[8:9]
	v_lshlrev_b32_e32 v18, 16, v46
	v_and_b32_e32 v19, 0xffff0000, v46
	v_pk_fma_f32 v[8:9], v[8:9], v[108:109], v[18:19]
	v_add_u32_e32 v14, 0x8000, v14
	v_cvt_pk_bf16_f32 v16, v8, v9
	global_store_dword v14, v16, s[8:9]
	v_lshlrev_b32_e32 v18, 16, v47
	v_and_b32_e32 v19, 0xffff0000, v47
	v_pk_fma_f32 v[8:9], v[8:9], v[110:111], v[18:19]
	v_add_u32_e32 v14, 0x8000, v14
	global_load_dword v64, v6, s[8:9]
	global_load_dwordx2 v[144:145], v12, s[10:11]
	v_add_u32_e32 v6, 0x8000, v6
	v_add_u32_e32 v12, 0x200, v12
	global_load_dword v65, v6, s[8:9]
	global_load_dwordx2 v[146:147], v12, s[10:11]
	v_add_u32_e32 v6, 0x8000, v6
	v_add_u32_e32 v12, 0x200, v12
	global_load_dword v66, v6, s[8:9]
	global_load_dwordx2 v[148:149], v12, s[10:11]
	v_add_u32_e32 v6, 0x8000, v6
	v_add_u32_e32 v12, 0x200, v12
	global_load_dword v67, v6, s[8:9]
	global_load_dwordx2 v[150:151], v12, s[10:11]
	v_add_u32_e32 v6, 0x8000, v6
	v_add_u32_e32 v12, 0x200, v12
	global_load_dword v68, v6, s[8:9]
	global_load_dwordx2 v[152:153], v12, s[10:11]
	v_add_u32_e32 v6, 0x8000, v6
	v_add_u32_e32 v12, 0x200, v12
	global_load_dword v69, v6, s[8:9]
	global_load_dwordx2 v[154:155], v12, s[10:11]
	v_add_u32_e32 v6, 0x8000, v6
	v_add_u32_e32 v12, 0x200, v12
	global_load_dword v70, v6, s[8:9]
	global_load_dwordx2 v[156:157], v12, s[10:11]
	v_add_u32_e32 v6, 0x8000, v6
	v_add_u32_e32 v12, 0x200, v12
	global_load_dword v71, v6, s[8:9]
	global_load_dwordx2 v[158:159], v12, s[10:11]
	v_add_u32_e32 v6, 0x8000, v6
	v_add_u32_e32 v12, 0x200, v12
	global_load_dword v72, v6, s[8:9]
	global_load_dwordx2 v[160:161], v12, s[10:11]
	v_add_u32_e32 v6, 0x8000, v6
	v_add_u32_e32 v12, 0x200, v12
	global_load_dword v73, v6, s[8:9]
	global_load_dwordx2 v[162:163], v12, s[10:11]
	v_add_u32_e32 v6, 0x8000, v6
	v_add_u32_e32 v12, 0x200, v12
	global_load_dword v74, v6, s[8:9]
	global_load_dwordx2 v[164:165], v12, s[10:11]
	v_add_u32_e32 v6, 0x8000, v6
	v_add_u32_e32 v12, 0x200, v12
	global_load_dword v75, v6, s[8:9]
	global_load_dwordx2 v[166:167], v12, s[10:11]
	v_add_u32_e32 v6, 0x8000, v6
	v_add_u32_e32 v12, 0x200, v12
	global_load_dword v76, v6, s[8:9]
	global_load_dwordx2 v[168:169], v12, s[10:11]
	v_add_u32_e32 v6, 0x8000, v6
	v_add_u32_e32 v12, 0x200, v12
	global_load_dword v77, v6, s[8:9]
	global_load_dwordx2 v[170:171], v12, s[10:11]
	v_add_u32_e32 v6, 0x8000, v6
	v_add_u32_e32 v12, 0x200, v12
	global_load_dword v78, v6, s[8:9]
	global_load_dwordx2 v[172:173], v12, s[10:11]
	v_add_u32_e32 v6, 0x8000, v6
	v_add_u32_e32 v12, 0x200, v12
	global_load_dword v79, v6, s[8:9]
	global_load_dwordx2 v[174:175], v12, s[10:11]
	v_add_u32_e32 v6, 0x8000, v6
	v_add_u32_e32 v12, 0x200, v12
	s_waitcnt vmcnt(48)
; __device__ __forceinline__ unsigned cvt_pk_bf16(float lo, float hi) { const f32x2cv v = {lo, hi}; const bf16x2cv b = __builtin_convertvector(v, bf16x2cv); return __builtin_bit_cast(unsigned, b); }
; __device__ __forceinline__ float bflo(unsigned w) { return __uint_as_float(w << 16); }
; __device__ __forceinline__ float bfhi(unsigned w) { return __uint_as_float(w & 0xffff0000u); }
; __device__ __forceinline__ void hgrn_pass2(Frame& F) {
;     ...
;         float s0 = 0.f, s1 = 0.f;
; #pragma unroll 32
;         for (int c = 0; c < 128; ++c) { const unsigned u = up[(size_t)c * 8192]; const float2 d = dp[c * 64];
;             up[(size_t)c * 8192] = cvt_pk_bf16(s0, s1);
;             s0 = d.x * s0 + bflo(u); s1 = d.y * s1 + bfhi(u); }
	v_cvt_pk_bf16_f32 v16, v8, v9
	global_store_dword v14, v16, s[8:9]
	v_lshlrev_b32_e32 v18, 16, v48
	v_and_b32_e32 v19, 0xffff0000, v48
	v_pk_fma_f32 v[8:9], v[8:9], v[112:113], v[18:19]
	v_add_u32_e32 v14, 0x8000, v14
	v_cvt_pk_bf16_f32 v16, v8, v9
	global_store_dword v14, v16, s[8:9]
	v_lshlrev_b32_e32 v18, 16, v49
	v_and_b32_e32 v19, 0xffff0000, v49
	v_pk_fma_f32 v[8:9], v[8:9], v[114:115], v[18:19]
	v_add_u32_e32 v14, 0x8000, v14
	v_cvt_pk_bf16_f32 v16, v8, v9
	global_store_dword v14, v16, s[8:9]
	v_lshlrev_b32_e32 v18, 16, v50
	v_and_b32_e32 v19, 0xffff0000, v50
	v_pk_fma_f32 v[8:9], v[8:9], v[116:117], v[18:19]
	v_add_u32_e32 v14, 0x8000, v14
	v_cvt_pk_bf16_f32 v16, v8, v9
	global_store_dword v14, v16, s[8:9]
	v_lshlrev_b32_e32 v18, 16, v51
	v_and_b32_e32 v19, 0xffff0000, v51
	v_pk_fma_f32 v[8:9], v[8:9], v[118:119], v[18:19]
	v_add_u32_e32 v14, 0x8000, v14
	v_cvt_pk_bf16_f32 v16, v8, v9
	global_store_dword v14, v16, s[8:9]
	v_lshlrev_b32_e32 v18, 16, v52
	v_and_b32_e32 v19, 0xffff0000, v52
	v_pk_fma_f32 v[8:9], v[8:9], v[120:121], v[18:19]
	v_add_u32_e32 v14, 0x8000, v14
	v_cvt_pk_bf16_f32 v16, v8, v9
	global_store_dword v14, v16, s[8:9]
	v_lshlrev_b32_e32 v18, 16, v53
	v_and_b32_e32 v19, 0xffff0000, v53
	v_pk_fma_f32 v[8:9], v[8:9], v[122:123], v[18:19]
	v_add_u32_e32 v14, 0x8000, v14
	v_cvt_pk_bf16_f32 v16, v8, v9
	global_store_dword v14, v16, s[8:9]
	v_lshlrev_b32_e32 v18, 16, v54
	v_and_b32_e32 v19, 0xffff0000, v54
	v_pk_fma_f32 v[8:9], v[8:9], v[124:125], v[18:19]
	v_add_u32_e32 v14, 0x8000, v14
	v_cvt_pk_bf16_f32 v16, v8, v9
	global_store_dword v14, v16, s[8:9]
	v_lshlrev_b32_e32 v18, 16, v55
	v_and_b32_e32 v19, 0xffff0000, v55
	v_pk_fma_f32 v[8:9], v[8:9], v[126:127], v[18:19]
	v_add_u32_e32 v14, 0x8000, v14
	v_cvt_pk_bf16_f32 v16, v8, v9
	global_store_dword v14, v16, s[8:9]
	v_lshlrev_b32_e32 v18, 16, v56
	v_and_b32_e32 v19, 0xffff0000, v56
	v_pk_fma_f32 v[8:9], v[8:9], v[128:129], v[18:19]
	v_add_u32_e32 v14, 0x8000, v14
	v_cvt_pk_bf16_f32 v16, v8, v9
	global_store_dword v14, v16, s[8:9]
	v_lshlrev_b32_e32 v18, 16, v57
	v_and_b32_e32 v19, 0xffff0000, v57
	v_pk_fma_f32 v[8:9], v[8:9], v[130:131], v[18:19]
	v_add_u32_e32 v14, 0x8000, v14
	v_cvt_pk_bf16_f32 v16, v8, v9
	global_store_dword v14, v16, s[8:9]
	v_lshlrev_b32_e32 v18, 16, v58
	v_and_b32_e32 v19, 0xffff0000, v58
	v_pk_fma_f32 v[8:9], v[8:9], v[132:133], v[18:19]
	v_add_u32_e32 v14, 0x8000, v14
	v_cvt_pk_bf16_f32 v16, v8, v9
	global_store_dword v14, v16, s[8:9]
	v_lshlrev_b32_e32 v18, 16, v59
	v_and_b32_e32 v19, 0xffff0000, v59
	v_pk_fma_f32 v[8:9], v[8:9], v[134:135], v[18:19]
	v_add_u32_e32 v14, 0x8000, v14
	v_cvt_pk_bf16_f32 v16, v8, v9
	global_store_dword v14, v16, s[8:9]
	v_lshlrev_b32_e32 v18, 16, v60
	v_and_b32_e32 v19, 0xffff0000, v60
	v_pk_fma_f32 v[8:9], v[8:9], v[136:137], v[18:19]
	v_add_u32_e32 v14, 0x8000, v14
	v_cvt_pk_bf16_f32 v16, v8, v9
	global_store_dword v14, v16, s[8:9]
	v_lshlrev_b32_e32 v18, 16, v61
	v_and_b32_e32 v19, 0xffff0000, v61
	v_pk_fma_f32 v[8:9], v[8:9], v[138:139], v[18:19]
	v_add_u32_e32 v14, 0x8000, v14
	v_cvt_pk_bf16_f32 v16, v8, v9
	global_store_dword v14, v16, s[8:9]
	v_lshlrev_b32_e32 v18, 16, v62
	v_and_b32_e32 v19, 0xffff0000, v62
	v_pk_fma_f32 v[8:9], v[8:9], v[140:141], v[18:19]
	v_add_u32_e32 v14, 0x8000, v14
	v_cvt_pk_bf16_f32 v16, v8, v9
	global_store_dword v14, v16, s[8:9]
	v_lshlrev_b32_e32 v18, 16, v63
	v_and_b32_e32 v19, 0xffff0000, v63
	v_pk_fma_f32 v[8:9], v[8:9], v[142:143], v[18:19]
	v_add_u32_e32 v14, 0x8000, v14
	global_load_dword v32, v6, s[8:9]
	global_load_dwordx2 v[80:81], v12, s[10:11]
	v_add_u32_e32 v6, 0x8000, v6
	v_add_u32_e32 v12, 0x200, v12
	global_load_dword v33, v6, s[8:9]
	global_load_dwordx2 v[82:83], v12, s[10:11]
	v_add_u32_e32 v6, 0x8000, v6
	v_add_u32_e32 v12, 0x200, v12
	global_load_dword v34, v6, s[8:9]
	global_load_dwordx2 v[84:85], v12, s[10:11]
	v_add_u32_e32 v6, 0x8000, v6
	v_add_u32_e32 v12, 0x200, v12
	global_load_dword v35, v6, s[8:9]
	global_load_dwordx2 v[86:87], v12, s[10:11]
	v_add_u32_e32 v6, 0x8000, v6
	v_add_u32_e32 v12, 0x200, v12
	global_load_dword v36, v6, s[8:9]
	global_load_dwordx2 v[88:89], v12, s[10:11]
	v_add_u32_e32 v6, 0x8000, v6
	v_add_u32_e32 v12, 0x200, v12
	global_load_dword v37, v6, s[8:9]
	global_load_dwordx2 v[90:91], v12, s[10:11]
	v_add_u32_e32 v6, 0x8000, v6
	v_add_u32_e32 v12, 0x200, v12
	global_load_dword v38, v6, s[8:9]
	global_load_dwordx2 v[92:93], v12, s[10:11]
	v_add_u32_e32 v6, 0x8000, v6
	v_add_u32_e32 v12, 0x200, v12
	global_load_dword v39, v6, s[8:9]
	global_load_dwordx2 v[94:95], v12, s[10:11]
	v_add_u32_e32 v6, 0x8000, v6
	v_add_u32_e32 v12, 0x200, v12
	global_load_dword v40, v6, s[8:9]
	global_load_dwordx2 v[96:97], v12, s[10:11]
	v_add_u32_e32 v6, 0x8000, v6
	v_add_u32_e32 v12, 0x200, v12
	global_load_dword v41, v6, s[8:9]
	global_load_dwordx2 v[98:99], v12, s[10:11]
	v_add_u32_e32 v6, 0x8000, v6
	v_add_u32_e32 v12, 0x200, v12
	global_load_dword v42, v6, s[8:9]
	global_load_dwordx2 v[100:101], v12, s[10:11]
	v_add_u32_e32 v6, 0x8000, v6
	v_add_u32_e32 v12, 0x200, v12
	global_load_dword v43, v6, s[8:9]
	global_load_dwordx2 v[102:103], v12, s[10:11]
	v_add_u32_e32 v6, 0x8000, v6
	v_add_u32_e32 v12, 0x200, v12
	global_load_dword v44, v6, s[8:9]
	global_load_dwordx2 v[104:105], v12, s[10:11]
	v_add_u32_e32 v6, 0x8000, v6
	v_add_u32_e32 v12, 0x200, v12
	global_load_dword v45, v6, s[8:9]
	global_load_dwordx2 v[106:107], v12, s[10:11]
	v_add_u32_e32 v6, 0x8000, v6
	v_add_u32_e32 v12, 0x200, v12
	global_load_dword v46, v6, s[8:9]
	global_load_dwordx2 v[108:109], v12, s[10:11]
	v_add_u32_e32 v6, 0x8000, v6
	v_add_u32_e32 v12, 0x200, v12
	global_load_dword v47, v6, s[8:9]
	global_load_dwordx2 v[110:111], v12, s[10:11]
	v_add_u32_e32 v6, 0x8000, v6
	v_add_u32_e32 v12, 0x200, v12
	s_waitcnt vmcnt(48)
; __device__ __forceinline__ unsigned cvt_pk_bf16(float lo, float hi) { const f32x2cv v = {lo, hi}; const bf16x2cv b = __builtin_convertvector(v, bf16x2cv); return __builtin_bit_cast(unsigned, b); }
; __device__ __forceinline__ float bflo(unsigned w) { return __uint_as_float(w << 16); }
; __device__ __forceinline__ float bfhi(unsigned w) { return __uint_as_float(w & 0xffff0000u); }
; __device__ __forceinline__ void hgrn_pass2(Frame& F) {
;     ...
;         float s0 = 0.f, s1 = 0.f;
; #pragma unroll 32
;         for (int c = 0; c < 128; ++c) { const unsigned u = up[(size_t)c * 8192]; const float2 d = dp[c * 64];
;             up[(size_t)c * 8192] = cvt_pk_bf16(s0, s1);
;             s0 = d.x * s0 + bflo(u); s1 = d.y * s1 + bfhi(u); }
	v_cvt_pk_bf16_f32 v16, v8, v9
	global_store_dword v14, v16, s[8:9]
	v_lshlrev_b32_e32 v18, 16, v64
	v_and_b32_e32 v19, 0xffff0000, v64
	v_pk_fma_f32 v[8:9], v[8:9], v[144:145], v[18:19]
	v_add_u32_e32 v14, 0x8000, v14
	v_cvt_pk_bf16_f32 v16, v8, v9
	global_store_dword v14, v16, s[8:9]
	v_lshlrev_b32_e32 v18, 16, v65
	v_and_b32_e32 v19, 0xffff0000, v65
	v_pk_fma_f32 v[8:9], v[8:9], v[146:147], v[18:19]
	v_add_u32_e32 v14, 0x8000, v14
	v_cvt_pk_bf16_f32 v16, v8, v9
	global_store_dword v14, v16, s[8:9]
	v_lshlrev_b32_e32 v18, 16, v66
	v_and_b32_e32 v19, 0xffff0000, v66
	v_pk_fma_f32 v[8:9], v[8:9], v[148:149], v[18:19]
	v_add_u32_e32 v14, 0x8000, v14
	v_cvt_pk_bf16_f32 v16, v8, v9
	global_store_dword v14, v16, s[8:9]
	v_lshlrev_b32_e32 v18, 16, v67
	v_and_b32_e32 v19, 0xffff0000, v67
	v_pk_fma_f32 v[8:9], v[8:9], v[150:151], v[18:19]
	v_add_u32_e32 v14, 0x8000, v14
	v_cvt_pk_bf16_f32 v16, v8, v9
	global_store_dword v14, v16, s[8:9]
	v_lshlrev_b32_e32 v18, 16, v68
	v_and_b32_e32 v19, 0xffff0000, v68
	v_pk_fma_f32 v[8:9], v[8:9], v[152:153], v[18:19]
	v_add_u32_e32 v14, 0x8000, v14
	v_cvt_pk_bf16_f32 v16, v8, v9
	global_store_dword v14, v16, s[8:9]
	v_lshlrev_b32_e32 v18, 16, v69
	v_and_b32_e32 v19, 0xffff0000, v69
	v_pk_fma_f32 v[8:9], v[8:9], v[154:155], v[18:19]
	v_add_u32_e32 v14, 0x8000, v14
	v_cvt_pk_bf16_f32 v16, v8, v9
	global_store_dword v14, v16, s[8:9]
	v_lshlrev_b32_e32 v18, 16, v70
	v_and_b32_e32 v19, 0xffff0000, v70
	v_pk_fma_f32 v[8:9], v[8:9], v[156:157], v[18:19]
	v_add_u32_e32 v14, 0x8000, v14
	v_cvt_pk_bf16_f32 v16, v8, v9
	global_store_dword v14, v16, s[8:9]
	v_lshlrev_b32_e32 v18, 16, v71
	v_and_b32_e32 v19, 0xffff0000, v71
	v_pk_fma_f32 v[8:9], v[8:9], v[158:159], v[18:19]
	v_add_u32_e32 v14, 0x8000, v14
	v_cvt_pk_bf16_f32 v16, v8, v9
	global_store_dword v14, v16, s[8:9]
	v_lshlrev_b32_e32 v18, 16, v72
	v_and_b32_e32 v19, 0xffff0000, v72
	v_pk_fma_f32 v[8:9], v[8:9], v[160:161], v[18:19]
	v_add_u32_e32 v14, 0x8000, v14
	v_cvt_pk_bf16_f32 v16, v8, v9
	global_store_dword v14, v16, s[8:9]
	v_lshlrev_b32_e32 v18, 16, v73
	v_and_b32_e32 v19, 0xffff0000, v73
	v_pk_fma_f32 v[8:9], v[8:9], v[162:163], v[18:19]
	v_add_u32_e32 v14, 0x8000, v14
	v_cvt_pk_bf16_f32 v16, v8, v9
	global_store_dword v14, v16, s[8:9]
	v_lshlrev_b32_e32 v18, 16, v74
	v_and_b32_e32 v19, 0xffff0000, v74
	v_pk_fma_f32 v[8:9], v[8:9], v[164:165], v[18:19]
	v_add_u32_e32 v14, 0x8000, v14
	v_cvt_pk_bf16_f32 v16, v8, v9
	global_store_dword v14, v16, s[8:9]
	v_lshlrev_b32_e32 v18, 16, v75
	v_and_b32_e32 v19, 0xffff0000, v75
	v_pk_fma_f32 v[8:9], v[8:9], v[166:167], v[18:19]
	v_add_u32_e32 v14, 0x8000, v14
	v_cvt_pk_bf16_f32 v16, v8, v9
	global_store_dword v14, v16, s[8:9]
	v_lshlrev_b32_e32 v18, 16, v76
	v_and_b32_e32 v19, 0xffff0000, v76
	v_pk_fma_f32 v[8:9], v[8:9], v[168:169], v[18:19]
	v_add_u32_e32 v14, 0x8000, v14
	v_cvt_pk_bf16_f32 v16, v8, v9
	global_store_dword v14, v16, s[8:9]
	v_lshlrev_b32_e32 v18, 16, v77
	v_and_b32_e32 v19, 0xffff0000, v77
	v_pk_fma_f32 v[8:9], v[8:9], v[170:171], v[18:19]
	v_add_u32_e32 v14, 0x8000, v14
	v_cvt_pk_bf16_f32 v16, v8, v9
	global_store_dword v14, v16, s[8:9]
	v_lshlrev_b32_e32 v18, 16, v78
	v_and_b32_e32 v19, 0xffff0000, v78
	v_pk_fma_f32 v[8:9], v[8:9], v[172:173], v[18:19]
	v_add_u32_e32 v14, 0x8000, v14
	v_cvt_pk_bf16_f32 v16, v8, v9
	global_store_dword v14, v16, s[8:9]
	v_lshlrev_b32_e32 v18, 16, v79
	v_and_b32_e32 v19, 0xffff0000, v79
	v_pk_fma_f32 v[8:9], v[8:9], v[174:175], v[18:19]
	v_add_u32_e32 v14, 0x8000, v14
	global_load_dword v48, v6, s[8:9]
	global_load_dwordx2 v[112:113], v12, s[10:11]
	v_add_u32_e32 v6, 0x8000, v6
	v_add_u32_e32 v12, 0x200, v12
	global_load_dword v49, v6, s[8:9]
	global_load_dwordx2 v[114:115], v12, s[10:11]
	v_add_u32_e32 v6, 0x8000, v6
	v_add_u32_e32 v12, 0x200, v12
	global_load_dword v50, v6, s[8:9]
	global_load_dwordx2 v[116:117], v12, s[10:11]
	v_add_u32_e32 v6, 0x8000, v6
	v_add_u32_e32 v12, 0x200, v12
	global_load_dword v51, v6, s[8:9]
	global_load_dwordx2 v[118:119], v12, s[10:11]
	v_add_u32_e32 v6, 0x8000, v6
	v_add_u32_e32 v12, 0x200, v12
	global_load_dword v52, v6, s[8:9]
	global_load_dwordx2 v[120:121], v12, s[10:11]
	v_add_u32_e32 v6, 0x8000, v6
	v_add_u32_e32 v12, 0x200, v12
	global_load_dword v53, v6, s[8:9]
	global_load_dwordx2 v[122:123], v12, s[10:11]
	v_add_u32_e32 v6, 0x8000, v6
	v_add_u32_e32 v12, 0x200, v12
	global_load_dword v54, v6, s[8:9]
	global_load_dwordx2 v[124:125], v12, s[10:11]
	v_add_u32_e32 v6, 0x8000, v6
	v_add_u32_e32 v12, 0x200, v12
	global_load_dword v55, v6, s[8:9]
	global_load_dwordx2 v[126:127], v12, s[10:11]
	v_add_u32_e32 v6, 0x8000, v6
	v_add_u32_e32 v12, 0x200, v12
	global_load_dword v56, v6, s[8:9]
	global_load_dwordx2 v[128:129], v12, s[10:11]
	v_add_u32_e32 v6, 0x8000, v6
	v_add_u32_e32 v12, 0x200, v12
	global_load_dword v57, v6, s[8:9]
	global_load_dwordx2 v[130:131], v12, s[10:11]
	v_add_u32_e32 v6, 0x8000, v6
	v_add_u32_e32 v12, 0x200, v12
	global_load_dword v58, v6, s[8:9]
	global_load_dwordx2 v[132:133], v12, s[10:11]
	v_add_u32_e32 v6, 0x8000, v6
	v_add_u32_e32 v12, 0x200, v12
	global_load_dword v59, v6, s[8:9]
	global_load_dwordx2 v[134:135], v12, s[10:11]
	v_add_u32_e32 v6, 0x8000, v6
	v_add_u32_e32 v12, 0x200, v12
	global_load_dword v60, v6, s[8:9]
	global_load_dwordx2 v[136:137], v12, s[10:11]
	v_add_u32_e32 v6, 0x8000, v6
	v_add_u32_e32 v12, 0x200, v12
	global_load_dword v61, v6, s[8:9]
	global_load_dwordx2 v[138:139], v12, s[10:11]
	v_add_u32_e32 v6, 0x8000, v6
	v_add_u32_e32 v12, 0x200, v12
	global_load_dword v62, v6, s[8:9]
	global_load_dwordx2 v[140:141], v12, s[10:11]
	v_add_u32_e32 v6, 0x8000, v6
	v_add_u32_e32 v12, 0x200, v12
	global_load_dword v63, v6, s[8:9]
	global_load_dwordx2 v[142:143], v12, s[10:11]
	v_add_u32_e32 v6, 0x8000, v6
	v_add_u32_e32 v12, 0x200, v12
	s_waitcnt vmcnt(48)
; __device__ __forceinline__ unsigned cvt_pk_bf16(float lo, float hi) { const f32x2cv v = {lo, hi}; const bf16x2cv b = __builtin_convertvector(v, bf16x2cv); return __builtin_bit_cast(unsigned, b); }
; __device__ __forceinline__ float bflo(unsigned w) { return __uint_as_float(w << 16); }
; __device__ __forceinline__ float bfhi(unsigned w) { return __uint_as_float(w & 0xffff0000u); }
; __device__ __forceinline__ void hgrn_pass2(Frame& F) {
;     ...
;         float s0 = 0.f, s1 = 0.f;
; #pragma unroll 32
;         for (int c = 0; c < 128; ++c) { const unsigned u = up[(size_t)c * 8192]; const float2 d = dp[c * 64];
;             up[(size_t)c * 8192] = cvt_pk_bf16(s0, s1);
;             s0 = d.x * s0 + bflo(u); s1 = d.y * s1 + bfhi(u); }
	v_cvt_pk_bf16_f32 v16, v8, v9
	global_store_dword v14, v16, s[8:9]
	v_lshlrev_b32_e32 v18, 16, v32
	v_and_b32_e32 v19, 0xffff0000, v32
	v_pk_fma_f32 v[8:9], v[8:9], v[80:81], v[18:19]
	v_add_u32_e32 v14, 0x8000, v14
	v_cvt_pk_bf16_f32 v16, v8, v9
	global_store_dword v14, v16, s[8:9]
	v_lshlrev_b32_e32 v18, 16, v33
	v_and_b32_e32 v19, 0xffff0000, v33
	v_pk_fma_f32 v[8:9], v[8:9], v[82:83], v[18:19]
	v_add_u32_e32 v14, 0x8000, v14
	v_cvt_pk_bf16_f32 v16, v8, v9
	global_store_dword v14, v16, s[8:9]
	v_lshlrev_b32_e32 v18, 16, v34
	v_and_b32_e32 v19, 0xffff0000, v34
	v_pk_fma_f32 v[8:9], v[8:9], v[84:85], v[18:19]
	v_add_u32_e32 v14, 0x8000, v14
	v_cvt_pk_bf16_f32 v16, v8, v9
	global_store_dword v14, v16, s[8:9]
	v_lshlrev_b32_e32 v18, 16, v35
	v_and_b32_e32 v19, 0xffff0000, v35
	v_pk_fma_f32 v[8:9], v[8:9], v[86:87], v[18:19]
	v_add_u32_e32 v14, 0x8000, v14
	v_cvt_pk_bf16_f32 v16, v8, v9
	global_store_dword v14, v16, s[8:9]
	v_lshlrev_b32_e32 v18, 16, v36
	v_and_b32_e32 v19, 0xffff0000, v36
	v_pk_fma_f32 v[8:9], v[8:9], v[88:89], v[18:19]
	v_add_u32_e32 v14, 0x8000, v14
	v_cvt_pk_bf16_f32 v16, v8, v9
	global_store_dword v14, v16, s[8:9]
	v_lshlrev_b32_e32 v18, 16, v37
	v_and_b32_e32 v19, 0xffff0000, v37
	v_pk_fma_f32 v[8:9], v[8:9], v[90:91], v[18:19]
	v_add_u32_e32 v14, 0x8000, v14
	v_cvt_pk_bf16_f32 v16, v8, v9
	global_store_dword v14, v16, s[8:9]
	v_lshlrev_b32_e32 v18, 16, v38
	v_and_b32_e32 v19, 0xffff0000, v38
	v_pk_fma_f32 v[8:9], v[8:9], v[92:93], v[18:19]
	v_add_u32_e32 v14, 0x8000, v14
	v_cvt_pk_bf16_f32 v16, v8, v9
	global_store_dword v14, v16, s[8:9]
	v_lshlrev_b32_e32 v18, 16, v39
	v_and_b32_e32 v19, 0xffff0000, v39
	v_pk_fma_f32 v[8:9], v[8:9], v[94:95], v[18:19]
	v_add_u32_e32 v14, 0x8000, v14
	v_cvt_pk_bf16_f32 v16, v8, v9
	global_store_dword v14, v16, s[8:9]
	v_lshlrev_b32_e32 v18, 16, v40
	v_and_b32_e32 v19, 0xffff0000, v40
	v_pk_fma_f32 v[8:9], v[8:9], v[96:97], v[18:19]
	v_add_u32_e32 v14, 0x8000, v14
	v_cvt_pk_bf16_f32 v16, v8, v9
	global_store_dword v14, v16, s[8:9]
	v_lshlrev_b32_e32 v18, 16, v41
	v_and_b32_e32 v19, 0xffff0000, v41
	v_pk_fma_f32 v[8:9], v[8:9], v[98:99], v[18:19]
	v_add_u32_e32 v14, 0x8000, v14
	v_cvt_pk_bf16_f32 v16, v8, v9
	global_store_dword v14, v16, s[8:9]
	v_lshlrev_b32_e32 v18, 16, v42
	v_and_b32_e32 v19, 0xffff0000, v42
	v_pk_fma_f32 v[8:9], v[8:9], v[100:101], v[18:19]
	v_add_u32_e32 v14, 0x8000, v14
	v_cvt_pk_bf16_f32 v16, v8, v9
	global_store_dword v14, v16, s[8:9]
	v_lshlrev_b32_e32 v18, 16, v43
	v_and_b32_e32 v19, 0xffff0000, v43
	v_pk_fma_f32 v[8:9], v[8:9], v[102:103], v[18:19]
	v_add_u32_e32 v14, 0x8000, v14
	v_cvt_pk_bf16_f32 v16, v8, v9
	global_store_dword v14, v16, s[8:9]
	v_lshlrev_b32_e32 v18, 16, v44
	v_and_b32_e32 v19, 0xffff0000, v44
	v_pk_fma_f32 v[8:9], v[8:9], v[104:105], v[18:19]
	v_add_u32_e32 v14, 0x8000, v14
	v_cvt_pk_bf16_f32 v16, v8, v9
	global_store_dword v14, v16, s[8:9]
	v_lshlrev_b32_e32 v18, 16, v45
	v_and_b32_e32 v19, 0xffff0000, v45
	v_pk_fma_f32 v[8:9], v[8:9], v[106:107], v[18:19]
	v_add_u32_e32 v14, 0x8000, v14
	v_cvt_pk_bf16_f32 v16, v8, v9
	global_store_dword v14, v16, s[8:9]
	v_lshlrev_b32_e32 v18, 16, v46
	v_and_b32_e32 v19, 0xffff0000, v46
	v_pk_fma_f32 v[8:9], v[8:9], v[108:109], v[18:19]
	v_add_u32_e32 v14, 0x8000, v14
	v_cvt_pk_bf16_f32 v16, v8, v9
	global_store_dword v14, v16, s[8:9]
	v_lshlrev_b32_e32 v18, 16, v47
	v_and_b32_e32 v19, 0xffff0000, v47
	v_pk_fma_f32 v[8:9], v[8:9], v[110:111], v[18:19]
	v_add_u32_e32 v14, 0x8000, v14
	global_load_dword v64, v6, s[8:9]
	global_load_dwordx2 v[144:145], v12, s[10:11]
	v_add_u32_e32 v6, 0x8000, v6
	v_add_u32_e32 v12, 0x200, v12
	global_load_dword v65, v6, s[8:9]
	global_load_dwordx2 v[146:147], v12, s[10:11]
	v_add_u32_e32 v6, 0x8000, v6
	v_add_u32_e32 v12, 0x200, v12
	global_load_dword v66, v6, s[8:9]
	global_load_dwordx2 v[148:149], v12, s[10:11]
	v_add_u32_e32 v6, 0x8000, v6
	v_add_u32_e32 v12, 0x200, v12
	global_load_dword v67, v6, s[8:9]
	global_load_dwordx2 v[150:151], v12, s[10:11]
	v_add_u32_e32 v6, 0x8000, v6
	v_add_u32_e32 v12, 0x200, v12
	global_load_dword v68, v6, s[8:9]
	global_load_dwordx2 v[152:153], v12, s[10:11]
	v_add_u32_e32 v6, 0x8000, v6
	v_add_u32_e32 v12, 0x200, v12
	global_load_dword v69, v6, s[8:9]
	global_load_dwordx2 v[154:155], v12, s[10:11]
	v_add_u32_e32 v6, 0x8000, v6
	v_add_u32_e32 v12, 0x200, v12
	global_load_dword v70, v6, s[8:9]
	global_load_dwordx2 v[156:157], v12, s[10:11]
	v_add_u32_e32 v6, 0x8000, v6
	v_add_u32_e32 v12, 0x200, v12
	global_load_dword v71, v6, s[8:9]
	global_load_dwordx2 v[158:159], v12, s[10:11]
	v_add_u32_e32 v6, 0x8000, v6
	v_add_u32_e32 v12, 0x200, v12
	global_load_dword v72, v6, s[8:9]
	global_load_dwordx2 v[160:161], v12, s[10:11]
	v_add_u32_e32 v6, 0x8000, v6
	v_add_u32_e32 v12, 0x200, v12
	global_load_dword v73, v6, s[8:9]
	global_load_dwordx2 v[162:163], v12, s[10:11]
	v_add_u32_e32 v6, 0x8000, v6
	v_add_u32_e32 v12, 0x200, v12
	global_load_dword v74, v6, s[8:9]
	global_load_dwordx2 v[164:165], v12, s[10:11]
	v_add_u32_e32 v6, 0x8000, v6
	v_add_u32_e32 v12, 0x200, v12
	global_load_dword v75, v6, s[8:9]
	global_load_dwordx2 v[166:167], v12, s[10:11]
	v_add_u32_e32 v6, 0x8000, v6
	v_add_u32_e32 v12, 0x200, v12
	global_load_dword v76, v6, s[8:9]
	global_load_dwordx2 v[168:169], v12, s[10:11]
	v_add_u32_e32 v6, 0x8000, v6
	v_add_u32_e32 v12, 0x200, v12
	global_load_dword v77, v6, s[8:9]
	global_load_dwordx2 v[170:171], v12, s[10:11]
	v_add_u32_e32 v6, 0x8000, v6
	v_add_u32_e32 v12, 0x200, v12
	global_load_dword v78, v6, s[8:9]
	global_load_dwordx2 v[172:173], v12, s[10:11]
	v_add_u32_e32 v6, 0x8000, v6
	v_add_u32_e32 v12, 0x200, v12
	global_load_dword v79, v6, s[8:9]
	global_load_dwordx2 v[174:175], v12, s[10:11]
	v_add_u32_e32 v6, 0x8000, v6
	v_add_u32_e32 v12, 0x200, v12
	s_waitcnt vmcnt(48)
; __device__ __forceinline__ unsigned cvt_pk_bf16(float lo, float hi) { const f32x2cv v = {lo, hi}; const bf16x2cv b = __builtin_convertvector(v, bf16x2cv); return __builtin_bit_cast(unsigned, b); }
; __device__ __forceinline__ float bflo(unsigned w) { return __uint_as_float(w << 16); }
; __device__ __forceinline__ float bfhi(unsigned w) { return __uint_as_float(w & 0xffff0000u); }
; __device__ __forceinline__ void hgrn_pass2(Frame& F) {
;     ...
;         float s0 = 0.f, s1 = 0.f;
; #pragma unroll 32
;         for (int c = 0; c < 128; ++c) { const unsigned u = up[(size_t)c * 8192]; const float2 d = dp[c * 64];
;             up[(size_t)c * 8192] = cvt_pk_bf16(s0, s1);
;             s0 = d.x * s0 + bflo(u); s1 = d.y * s1 + bfhi(u); }
	v_cvt_pk_bf16_f32 v16, v8, v9
	global_store_dword v14, v16, s[8:9]
	v_lshlrev_b32_e32 v18, 16, v48
	v_and_b32_e32 v19, 0xffff0000, v48
	v_pk_fma_f32 v[8:9], v[8:9], v[112:113], v[18:19]
	v_add_u32_e32 v14, 0x8000, v14
	v_cvt_pk_bf16_f32 v16, v8, v9
	global_store_dword v14, v16, s[8:9]
	v_lshlrev_b32_e32 v18, 16, v49
	v_and_b32_e32 v19, 0xffff0000, v49
	v_pk_fma_f32 v[8:9], v[8:9], v[114:115], v[18:19]
	v_add_u32_e32 v14, 0x8000, v14
	v_cvt_pk_bf16_f32 v16, v8, v9
	global_store_dword v14, v16, s[8:9]
	v_lshlrev_b32_e32 v18, 16, v50
	v_and_b32_e32 v19, 0xffff0000, v50
	v_pk_fma_f32 v[8:9], v[8:9], v[116:117], v[18:19]
	v_add_u32_e32 v14, 0x8000, v14
	v_cvt_pk_bf16_f32 v16, v8, v9
	global_store_dword v14, v16, s[8:9]
	v_lshlrev_b32_e32 v18, 16, v51
	v_and_b32_e32 v19, 0xffff0000, v51
	v_pk_fma_f32 v[8:9], v[8:9], v[118:119], v[18:19]
	v_add_u32_e32 v14, 0x8000, v14
	v_cvt_pk_bf16_f32 v16, v8, v9
	global_store_dword v14, v16, s[8:9]
	v_lshlrev_b32_e32 v18, 16, v52
	v_and_b32_e32 v19, 0xffff0000, v52
	v_pk_fma_f32 v[8:9], v[8:9], v[120:121], v[18:19]
	v_add_u32_e32 v14, 0x8000, v14
	v_cvt_pk_bf16_f32 v16, v8, v9
	global_store_dword v14, v16, s[8:9]
	v_lshlrev_b32_e32 v18, 16, v53
	v_and_b32_e32 v19, 0xffff0000, v53
	v_pk_fma_f32 v[8:9], v[8:9], v[122:123], v[18:19]
	v_add_u32_e32 v14, 0x8000, v14
	v_cvt_pk_bf16_f32 v16, v8, v9
	global_store_dword v14, v16, s[8:9]
	v_lshlrev_b32_e32 v18, 16, v54
	v_and_b32_e32 v19, 0xffff0000, v54
	v_pk_fma_f32 v[8:9], v[8:9], v[124:125], v[18:19]
	v_add_u32_e32 v14, 0x8000, v14
	v_cvt_pk_bf16_f32 v16, v8, v9
	global_store_dword v14, v16, s[8:9]
	v_lshlrev_b32_e32 v18, 16, v55
	v_and_b32_e32 v19, 0xffff0000, v55
	v_pk_fma_f32 v[8:9], v[8:9], v[126:127], v[18:19]
	v_add_u32_e32 v14, 0x8000, v14
	v_cvt_pk_bf16_f32 v16, v8, v9
	global_store_dword v14, v16, s[8:9]
	v_lshlrev_b32_e32 v18, 16, v56
	v_and_b32_e32 v19, 0xffff0000, v56
	v_pk_fma_f32 v[8:9], v[8:9], v[128:129], v[18:19]
	v_add_u32_e32 v14, 0x8000, v14
	v_cvt_pk_bf16_f32 v16, v8, v9
	global_store_dword v14, v16, s[8:9]
	v_lshlrev_b32_e32 v18, 16, v57
	v_and_b32_e32 v19, 0xffff0000, v57
	v_pk_fma_f32 v[8:9], v[8:9], v[130:131], v[18:19]
	v_add_u32_e32 v14, 0x8000, v14
	v_cvt_pk_bf16_f32 v16, v8, v9
	global_store_dword v14, v16, s[8:9]
	v_lshlrev_b32_e32 v18, 16, v58
	v_and_b32_e32 v19, 0xffff0000, v58
	v_pk_fma_f32 v[8:9], v[8:9], v[132:133], v[18:19]
	v_add_u32_e32 v14, 0x8000, v14
	v_cvt_pk_bf16_f32 v16, v8, v9
	global_store_dword v14, v16, s[8:9]
	v_lshlrev_b32_e32 v18, 16, v59
	v_and_b32_e32 v19, 0xffff0000, v59
	v_pk_fma_f32 v[8:9], v[8:9], v[134:135], v[18:19]
	v_add_u32_e32 v14, 0x8000, v14
	v_cvt_pk_bf16_f32 v16, v8, v9
	global_store_dword v14, v16, s[8:9]
	v_lshlrev_b32_e32 v18, 16, v60
	v_and_b32_e32 v19, 0xffff0000, v60
	v_pk_fma_f32 v[8:9], v[8:9], v[136:137], v[18:19]
	v_add_u32_e32 v14, 0x8000, v14
	v_cvt_pk_bf16_f32 v16, v8, v9
	global_store_dword v14, v16, s[8:9]
	v_lshlrev_b32_e32 v18, 16, v61
	v_and_b32_e32 v19, 0xffff0000, v61
	v_pk_fma_f32 v[8:9], v[8:9], v[138:139], v[18:19]
	v_add_u32_e32 v14, 0x8000, v14
	v_cvt_pk_bf16_f32 v16, v8, v9
	global_store_dword v14, v16, s[8:9]
	v_lshlrev_b32_e32 v18, 16, v62
	v_and_b32_e32 v19, 0xffff0000, v62
	v_pk_fma_f32 v[8:9], v[8:9], v[140:141], v[18:19]
	v_add_u32_e32 v14, 0x8000, v14
	v_cvt_pk_bf16_f32 v16, v8, v9
	global_store_dword v14, v16, s[8:9]
	v_lshlrev_b32_e32 v18, 16, v63
	v_and_b32_e32 v19, 0xffff0000, v63
	v_pk_fma_f32 v[8:9], v[8:9], v[142:143], v[18:19]
	v_add_u32_e32 v14, 0x8000, v14
	global_load_dword v32, v6, s[8:9]
	global_load_dwordx2 v[80:81], v12, s[10:11]
	v_add_u32_e32 v6, 0x8000, v6
	v_add_u32_e32 v12, 0x200, v12
	global_load_dword v33, v6, s[8:9]
	global_load_dwordx2 v[82:83], v12, s[10:11]
	v_add_u32_e32 v6, 0x8000, v6
	v_add_u32_e32 v12, 0x200, v12
	global_load_dword v34, v6, s[8:9]
	global_load_dwordx2 v[84:85], v12, s[10:11]
	v_add_u32_e32 v6, 0x8000, v6
	v_add_u32_e32 v12, 0x200, v12
	global_load_dword v35, v6, s[8:9]
	global_load_dwordx2 v[86:87], v12, s[10:11]
	v_add_u32_e32 v6, 0x8000, v6
	v_add_u32_e32 v12, 0x200, v12
	global_load_dword v36, v6, s[8:9]
	global_load_dwordx2 v[88:89], v12, s[10:11]
	v_add_u32_e32 v6, 0x8000, v6
	v_add_u32_e32 v12, 0x200, v12
	global_load_dword v37, v6, s[8:9]
	global_load_dwordx2 v[90:91], v12, s[10:11]
	v_add_u32_e32 v6, 0x8000, v6
	v_add_u32_e32 v12, 0x200, v12
	global_load_dword v38, v6, s[8:9]
	global_load_dwordx2 v[92:93], v12, s[10:11]
	v_add_u32_e32 v6, 0x8000, v6
	v_add_u32_e32 v12, 0x200, v12
	global_load_dword v39, v6, s[8:9]
	global_load_dwordx2 v[94:95], v12, s[10:11]
	v_add_u32_e32 v6, 0x8000, v6
	v_add_u32_e32 v12, 0x200, v12
	global_load_dword v40, v6, s[8:9]
	global_load_dwordx2 v[96:97], v12, s[10:11]
	v_add_u32_e32 v6, 0x8000, v6
	v_add_u32_e32 v12, 0x200, v12
	global_load_dword v41, v6, s[8:9]
	global_load_dwordx2 v[98:99], v12, s[10:11]
	v_add_u32_e32 v6, 0x8000, v6
	v_add_u32_e32 v12, 0x200, v12
	global_load_dword v42, v6, s[8:9]
	global_load_dwordx2 v[100:101], v12, s[10:11]
	v_add_u32_e32 v6, 0x8000, v6
	v_add_u32_e32 v12, 0x200, v12
	global_load_dword v43, v6, s[8:9]
	global_load_dwordx2 v[102:103], v12, s[10:11]
	v_add_u32_e32 v6, 0x8000, v6
	v_add_u32_e32 v12, 0x200, v12
	global_load_dword v44, v6, s[8:9]
	global_load_dwordx2 v[104:105], v12, s[10:11]
	v_add_u32_e32 v6, 0x8000, v6
	v_add_u32_e32 v12, 0x200, v12
	global_load_dword v45, v6, s[8:9]
	global_load_dwordx2 v[106:107], v12, s[10:11]
	v_add_u32_e32 v6, 0x8000, v6
	v_add_u32_e32 v12, 0x200, v12
	global_load_dword v46, v6, s[8:9]
	global_load_dwordx2 v[108:109], v12, s[10:11]
	v_add_u32_e32 v6, 0x8000, v6
	v_add_u32_e32 v12, 0x200, v12
	global_load_dword v47, v6, s[8:9]
	global_load_dwordx2 v[110:111], v12, s[10:11]
	v_add_u32_e32 v6, 0x8000, v6
	v_add_u32_e32 v12, 0x200, v12
	s_waitcnt vmcnt(48)
; __device__ __forceinline__ unsigned cvt_pk_bf16(float lo, float hi) { const f32x2cv v = {lo, hi}; const bf16x2cv b = __builtin_convertvector(v, bf16x2cv); return __builtin_bit_cast(unsigned, b); }
; __device__ __forceinline__ float bflo(unsigned w) { return __uint_as_float(w << 16); }
; __device__ __forceinline__ float bfhi(unsigned w) { return __uint_as_float(w & 0xffff0000u); }
; __device__ __forceinline__ void hgrn_pass2(Frame& F) {
;     ...
;         float s0 = 0.f, s1 = 0.f;
; #pragma unroll 32
;         for (int c = 0; c < 128; ++c) { const unsigned u = up[(size_t)c * 8192]; const float2 d = dp[c * 64];
;             up[(size_t)c * 8192] = cvt_pk_bf16(s0, s1);
;             s0 = d.x * s0 + bflo(u); s1 = d.y * s1 + bfhi(u); }
	v_cvt_pk_bf16_f32 v16, v8, v9
	global_store_dword v14, v16, s[8:9]
	v_lshlrev_b32_e32 v18, 16, v64
	v_and_b32_e32 v19, 0xffff0000, v64
	v_pk_fma_f32 v[8:9], v[8:9], v[144:145], v[18:19]
	v_add_u32_e32 v14, 0x8000, v14
	v_cvt_pk_bf16_f32 v16, v8, v9
	global_store_dword v14, v16, s[8:9]
	v_lshlrev_b32_e32 v18, 16, v65
	v_and_b32_e32 v19, 0xffff0000, v65
	v_pk_fma_f32 v[8:9], v[8:9], v[146:147], v[18:19]
	v_add_u32_e32 v14, 0x8000, v14
	v_cvt_pk_bf16_f32 v16, v8, v9
	global_store_dword v14, v16, s[8:9]
	v_lshlrev_b32_e32 v18, 16, v66
	v_and_b32_e32 v19, 0xffff0000, v66
	v_pk_fma_f32 v[8:9], v[8:9], v[148:149], v[18:19]
	v_add_u32_e32 v14, 0x8000, v14
	v_cvt_pk_bf16_f32 v16, v8, v9
	global_store_dword v14, v16, s[8:9]
	v_lshlrev_b32_e32 v18, 16, v67
	v_and_b32_e32 v19, 0xffff0000, v67
	v_pk_fma_f32 v[8:9], v[8:9], v[150:151], v[18:19]
	v_add_u32_e32 v14, 0x8000, v14
	v_cvt_pk_bf16_f32 v16, v8, v9
	global_store_dword v14, v16, s[8:9]
	v_lshlrev_b32_e32 v18, 16, v68
	v_and_b32_e32 v19, 0xffff0000, v68
	v_pk_fma_f32 v[8:9], v[8:9], v[152:153], v[18:19]
	v_add_u32_e32 v14, 0x8000, v14
	v_cvt_pk_bf16_f32 v16, v8, v9
	global_store_dword v14, v16, s[8:9]
	v_lshlrev_b32_e32 v18, 16, v69
	v_and_b32_e32 v19, 0xffff0000, v69
	v_pk_fma_f32 v[8:9], v[8:9], v[154:155], v[18:19]
	v_add_u32_e32 v14, 0x8000, v14
	v_cvt_pk_bf16_f32 v16, v8, v9
	global_store_dword v14, v16, s[8:9]
	v_lshlrev_b32_e32 v18, 16, v70
	v_and_b32_e32 v19, 0xffff0000, v70
	v_pk_fma_f32 v[8:9], v[8:9], v[156:157], v[18:19]
	v_add_u32_e32 v14, 0x8000, v14
	v_cvt_pk_bf16_f32 v16, v8, v9
	global_store_dword v14, v16, s[8:9]
	v_lshlrev_b32_e32 v18, 16, v71
	v_and_b32_e32 v19, 0xffff0000, v71
	v_pk_fma_f32 v[8:9], v[8:9], v[158:159], v[18:19]
	v_add_u32_e32 v14, 0x8000, v14
	v_cvt_pk_bf16_f32 v16, v8, v9
	global_store_dword v14, v16, s[8:9]
	v_lshlrev_b32_e32 v18, 16, v72
	v_and_b32_e32 v19, 0xffff0000, v72
	v_pk_fma_f32 v[8:9], v[8:9], v[160:161], v[18:19]
	v_add_u32_e32 v14, 0x8000, v14
	v_cvt_pk_bf16_f32 v16, v8, v9
	global_store_dword v14, v16, s[8:9]
	v_lshlrev_b32_e32 v18, 16, v73
	v_and_b32_e32 v19, 0xffff0000, v73
	v_pk_fma_f32 v[8:9], v[8:9], v[162:163], v[18:19]
	v_add_u32_e32 v14, 0x8000, v14
	v_cvt_pk_bf16_f32 v16, v8, v9
	global_store_dword v14, v16, s[8:9]
	v_lshlrev_b32_e32 v18, 16, v74
	v_and_b32_e32 v19, 0xffff0000, v74
	v_pk_fma_f32 v[8:9], v[8:9], v[164:165], v[18:19]
	v_add_u32_e32 v14, 0x8000, v14
	v_cvt_pk_bf16_f32 v16, v8, v9
	global_store_dword v14, v16, s[8:9]
	v_lshlrev_b32_e32 v18, 16, v75
	v_and_b32_e32 v19, 0xffff0000, v75
	v_pk_fma_f32 v[8:9], v[8:9], v[166:167], v[18:19]
	v_add_u32_e32 v14, 0x8000, v14
	v_cvt_pk_bf16_f32 v16, v8, v9
	global_store_dword v14, v16, s[8:9]
	v_lshlrev_b32_e32 v18, 16, v76
	v_and_b32_e32 v19, 0xffff0000, v76
	v_pk_fma_f32 v[8:9], v[8:9], v[168:169], v[18:19]
	v_add_u32_e32 v14, 0x8000, v14
	v_cvt_pk_bf16_f32 v16, v8, v9
	global_store_dword v14, v16, s[8:9]
	v_lshlrev_b32_e32 v18, 16, v77
	v_and_b32_e32 v19, 0xffff0000, v77
	v_pk_fma_f32 v[8:9], v[8:9], v[170:171], v[18:19]
	v_add_u32_e32 v14, 0x8000, v14
	v_cvt_pk_bf16_f32 v16, v8, v9
	global_store_dword v14, v16, s[8:9]
	v_lshlrev_b32_e32 v18, 16, v78
	v_and_b32_e32 v19, 0xffff0000, v78
	v_pk_fma_f32 v[8:9], v[8:9], v[172:173], v[18:19]
	v_add_u32_e32 v14, 0x8000, v14
	v_cvt_pk_bf16_f32 v16, v8, v9
	global_store_dword v14, v16, s[8:9]
	v_lshlrev_b32_e32 v18, 16, v79
	v_and_b32_e32 v19, 0xffff0000, v79
	v_pk_fma_f32 v[8:9], v[8:9], v[174:175], v[18:19]
	v_add_u32_e32 v14, 0x8000, v14
	global_load_dword v48, v6, s[8:9]
	global_load_dwordx2 v[112:113], v12, s[10:11]
	v_add_u32_e32 v6, 0x8000, v6
	v_add_u32_e32 v12, 0x200, v12
	global_load_dword v49, v6, s[8:9]
	global_load_dwordx2 v[114:115], v12, s[10:11]
	v_add_u32_e32 v6, 0x8000, v6
	v_add_u32_e32 v12, 0x200, v12
	global_load_dword v50, v6, s[8:9]
	global_load_dwordx2 v[116:117], v12, s[10:11]
	v_add_u32_e32 v6, 0x8000, v6
	v_add_u32_e32 v12, 0x200, v12
	global_load_dword v51, v6, s[8:9]
	global_load_dwordx2 v[118:119], v12, s[10:11]
	v_add_u32_e32 v6, 0x8000, v6
	v_add_u32_e32 v12, 0x200, v12
	global_load_dword v52, v6, s[8:9]
	global_load_dwordx2 v[120:121], v12, s[10:11]
	v_add_u32_e32 v6, 0x8000, v6
	v_add_u32_e32 v12, 0x200, v12
	global_load_dword v53, v6, s[8:9]
	global_load_dwordx2 v[122:123], v12, s[10:11]
	v_add_u32_e32 v6, 0x8000, v6
	v_add_u32_e32 v12, 0x200, v12
	global_load_dword v54, v6, s[8:9]
	global_load_dwordx2 v[124:125], v12, s[10:11]
	v_add_u32_e32 v6, 0x8000, v6
	v_add_u32_e32 v12, 0x200, v12
	global_load_dword v55, v6, s[8:9]
	global_load_dwordx2 v[126:127], v12, s[10:11]
	v_add_u32_e32 v6, 0x8000, v6
	v_add_u32_e32 v12, 0x200, v12
	global_load_dword v56, v6, s[8:9]
	global_load_dwordx2 v[128:129], v12, s[10:11]
	v_add_u32_e32 v6, 0x8000, v6
	v_add_u32_e32 v12, 0x200, v12
	global_load_dword v57, v6, s[8:9]
	global_load_dwordx2 v[130:131], v12, s[10:11]
	v_add_u32_e32 v6, 0x8000, v6
	v_add_u32_e32 v12, 0x200, v12
	global_load_dword v58, v6, s[8:9]
	global_load_dwordx2 v[132:133], v12, s[10:11]
	v_add_u32_e32 v6, 0x8000, v6
	v_add_u32_e32 v12, 0x200, v12
	global_load_dword v59, v6, s[8:9]
	global_load_dwordx2 v[134:135], v12, s[10:11]
	v_add_u32_e32 v6, 0x8000, v6
	v_add_u32_e32 v12, 0x200, v12
	global_load_dword v60, v6, s[8:9]
	global_load_dwordx2 v[136:137], v12, s[10:11]
	v_add_u32_e32 v6, 0x8000, v6
	v_add_u32_e32 v12, 0x200, v12
	global_load_dword v61, v6, s[8:9]
	global_load_dwordx2 v[138:139], v12, s[10:11]
	v_add_u32_e32 v6, 0x8000, v6
	v_add_u32_e32 v12, 0x200, v12
	global_load_dword v62, v6, s[8:9]
	global_load_dwordx2 v[140:141], v12, s[10:11]
	v_add_u32_e32 v6, 0x8000, v6
	v_add_u32_e32 v12, 0x200, v12
	global_load_dword v63, v6, s[8:9]
	global_load_dwordx2 v[142:143], v12, s[10:11]
	v_add_u32_e32 v6, 0x8000, v6
	v_add_u32_e32 v12, 0x200, v12
	s_waitcnt vmcnt(48)
; __device__ __forceinline__ unsigned cvt_pk_bf16(float lo, float hi) { const f32x2cv v = {lo, hi}; const bf16x2cv b = __builtin_convertvector(v, bf16x2cv); return __builtin_bit_cast(unsigned, b); }
; __device__ __forceinline__ float bflo(unsigned w) { return __uint_as_float(w << 16); }
; __device__ __forceinline__ float bfhi(unsigned w) { return __uint_as_float(w & 0xffff0000u); }
; __device__ __forceinline__ void hgrn_pass2(Frame& F) {
;     ...
;         float s0 = 0.f, s1 = 0.f;
; #pragma unroll 32
;         for (int c = 0; c < 128; ++c) { const unsigned u = up[(size_t)c * 8192]; const float2 d = dp[c * 64];
;             up[(size_t)c * 8192] = cvt_pk_bf16(s0, s1);
;             s0 = d.x * s0 + bflo(u); s1 = d.y * s1 + bfhi(u); }
	v_cvt_pk_bf16_f32 v16, v8, v9
	global_store_dword v14, v16, s[8:9]
	v_lshlrev_b32_e32 v18, 16, v32
	v_and_b32_e32 v19, 0xffff0000, v32
	v_pk_fma_f32 v[8:9], v[8:9], v[80:81], v[18:19]
	v_add_u32_e32 v14, 0x8000, v14
	v_cvt_pk_bf16_f32 v16, v8, v9
	global_store_dword v14, v16, s[8:9]
	v_lshlrev_b32_e32 v18, 16, v33
	v_and_b32_e32 v19, 0xffff0000, v33
	v_pk_fma_f32 v[8:9], v[8:9], v[82:83], v[18:19]
	v_add_u32_e32 v14, 0x8000, v14
	v_cvt_pk_bf16_f32 v16, v8, v9
	global_store_dword v14, v16, s[8:9]
	v_lshlrev_b32_e32 v18, 16, v34
	v_and_b32_e32 v19, 0xffff0000, v34
	v_pk_fma_f32 v[8:9], v[8:9], v[84:85], v[18:19]
	v_add_u32_e32 v14, 0x8000, v14
	v_cvt_pk_bf16_f32 v16, v8, v9
	global_store_dword v14, v16, s[8:9]
	v_lshlrev_b32_e32 v18, 16, v35
	v_and_b32_e32 v19, 0xffff0000, v35
	v_pk_fma_f32 v[8:9], v[8:9], v[86:87], v[18:19]
	v_add_u32_e32 v14, 0x8000, v14
	v_cvt_pk_bf16_f32 v16, v8, v9
	global_store_dword v14, v16, s[8:9]
	v_lshlrev_b32_e32 v18, 16, v36
	v_and_b32_e32 v19, 0xffff0000, v36
	v_pk_fma_f32 v[8:9], v[8:9], v[88:89], v[18:19]
	v_add_u32_e32 v14, 0x8000, v14
	v_cvt_pk_bf16_f32 v16, v8, v9
	global_store_dword v14, v16, s[8:9]
	v_lshlrev_b32_e32 v18, 16, v37
	v_and_b32_e32 v19, 0xffff0000, v37
	v_pk_fma_f32 v[8:9], v[8:9], v[90:91], v[18:19]
	v_add_u32_e32 v14, 0x8000, v14
	v_cvt_pk_bf16_f32 v16, v8, v9
	global_store_dword v14, v16, s[8:9]
	v_lshlrev_b32_e32 v18, 16, v38
	v_and_b32_e32 v19, 0xffff0000, v38
	v_pk_fma_f32 v[8:9], v[8:9], v[92:93], v[18:19]
	v_add_u32_e32 v14, 0x8000, v14
	v_cvt_pk_bf16_f32 v16, v8, v9
	global_store_dword v14, v16, s[8:9]
	v_lshlrev_b32_e32 v18, 16, v39
	v_and_b32_e32 v19, 0xffff0000, v39
	v_pk_fma_f32 v[8:9], v[8:9], v[94:95], v[18:19]
	v_add_u32_e32 v14, 0x8000, v14
	v_cvt_pk_bf16_f32 v16, v8, v9
	global_store_dword v14, v16, s[8:9]
	v_lshlrev_b32_e32 v18, 16, v40
	v_and_b32_e32 v19, 0xffff0000, v40
	v_pk_fma_f32 v[8:9], v[8:9], v[96:97], v[18:19]
	v_add_u32_e32 v14, 0x8000, v14
	v_cvt_pk_bf16_f32 v16, v8, v9
	global_store_dword v14, v16, s[8:9]
	v_lshlrev_b32_e32 v18, 16, v41
	v_and_b32_e32 v19, 0xffff0000, v41
	v_pk_fma_f32 v[8:9], v[8:9], v[98:99], v[18:19]
	v_add_u32_e32 v14, 0x8000, v14
	v_cvt_pk_bf16_f32 v16, v8, v9
	global_store_dword v14, v16, s[8:9]
	v_lshlrev_b32_e32 v18, 16, v42
	v_and_b32_e32 v19, 0xffff0000, v42
	v_pk_fma_f32 v[8:9], v[8:9], v[100:101], v[18:19]
	v_add_u32_e32 v14, 0x8000, v14
	v_cvt_pk_bf16_f32 v16, v8, v9
	global_store_dword v14, v16, s[8:9]
	v_lshlrev_b32_e32 v18, 16, v43
	v_and_b32_e32 v19, 0xffff0000, v43
	v_pk_fma_f32 v[8:9], v[8:9], v[102:103], v[18:19]
	v_add_u32_e32 v14, 0x8000, v14
	v_cvt_pk_bf16_f32 v16, v8, v9
	global_store_dword v14, v16, s[8:9]
	v_lshlrev_b32_e32 v18, 16, v44
	v_and_b32_e32 v19, 0xffff0000, v44
	v_pk_fma_f32 v[8:9], v[8:9], v[104:105], v[18:19]
	v_add_u32_e32 v14, 0x8000, v14
	v_cvt_pk_bf16_f32 v16, v8, v9
	global_store_dword v14, v16, s[8:9]
	v_lshlrev_b32_e32 v18, 16, v45
	v_and_b32_e32 v19, 0xffff0000, v45
	v_pk_fma_f32 v[8:9], v[8:9], v[106:107], v[18:19]
	v_add_u32_e32 v14, 0x8000, v14
	v_cvt_pk_bf16_f32 v16, v8, v9
	global_store_dword v14, v16, s[8:9]
	v_lshlrev_b32_e32 v18, 16, v46
	v_and_b32_e32 v19, 0xffff0000, v46
	v_pk_fma_f32 v[8:9], v[8:9], v[108:109], v[18:19]
	v_add_u32_e32 v14, 0x8000, v14
	v_cvt_pk_bf16_f32 v16, v8, v9
	global_store_dword v14, v16, s[8:9]
	v_lshlrev_b32_e32 v18, 16, v47
	v_and_b32_e32 v19, 0xffff0000, v47
	v_pk_fma_f32 v[8:9], v[8:9], v[110:111], v[18:19]
	v_add_u32_e32 v14, 0x8000, v14
	s_waitcnt vmcnt(16)
; __device__ __forceinline__ unsigned cvt_pk_bf16(float lo, float hi) { const f32x2cv v = {lo, hi}; const bf16x2cv b = __builtin_convertvector(v, bf16x2cv); return __builtin_bit_cast(unsigned, b); }
; __device__ __forceinline__ float bflo(unsigned w) { return __uint_as_float(w << 16); }
; __device__ __forceinline__ float bfhi(unsigned w) { return __uint_as_float(w & 0xffff0000u); }
; __device__ __forceinline__ void hgrn_pass2(Frame& F) {
;     ...
;         unsigned* up = (unsigned*)((bf16*)F.out + (size_t)bh * 128 * 16384) + rem; const float2* dp = (const float2*)((const float*)(F.ws + WS_HD) + (size_t)bh * 128 * 128) + (rem & 63);
;         float s0 = 0.f, s1 = 0.f;
; #pragma unroll 32
;         for (int c = 0; c < 128; ++c) { const unsigned u = up[(size_t)c * 8192]; const float2 d = dp[c * 64];
;             up[(size_t)c * 8192] = cvt_pk_bf16(s0, s1);
;             s0 = d.x * s0 + bflo(u); s1 = d.y * s1 + bfhi(u); }
	v_cvt_pk_bf16_f32 v16, v8, v9
	global_store_dword v14, v16, s[8:9]
	v_lshlrev_b32_e32 v18, 16, v48
	v_and_b32_e32 v19, 0xffff0000, v48
	v_pk_fma_f32 v[8:9], v[8:9], v[112:113], v[18:19]
	v_add_u32_e32 v14, 0x8000, v14
	v_cvt_pk_bf16_f32 v16, v8, v9
	global_store_dword v14, v16, s[8:9]
	v_lshlrev_b32_e32 v18, 16, v49
	v_and_b32_e32 v19, 0xffff0000, v49
	v_pk_fma_f32 v[8:9], v[8:9], v[114:115], v[18:19]
	v_add_u32_e32 v14, 0x8000, v14
	v_cvt_pk_bf16_f32 v16, v8, v9
	global_store_dword v14, v16, s[8:9]
	v_lshlrev_b32_e32 v18, 16, v50
	v_and_b32_e32 v19, 0xffff0000, v50
	v_pk_fma_f32 v[8:9], v[8:9], v[116:117], v[18:19]
	v_add_u32_e32 v14, 0x8000, v14
	v_cvt_pk_bf16_f32 v16, v8, v9
	global_store_dword v14, v16, s[8:9]
	v_lshlrev_b32_e32 v18, 16, v51
	v_and_b32_e32 v19, 0xffff0000, v51
	v_pk_fma_f32 v[8:9], v[8:9], v[118:119], v[18:19]
	v_add_u32_e32 v14, 0x8000, v14
	v_cvt_pk_bf16_f32 v16, v8, v9
	global_store_dword v14, v16, s[8:9]
	v_lshlrev_b32_e32 v18, 16, v52
	v_and_b32_e32 v19, 0xffff0000, v52
	v_pk_fma_f32 v[8:9], v[8:9], v[120:121], v[18:19]
	v_add_u32_e32 v14, 0x8000, v14
	v_cvt_pk_bf16_f32 v16, v8, v9
	global_store_dword v14, v16, s[8:9]
	v_lshlrev_b32_e32 v18, 16, v53
	v_and_b32_e32 v19, 0xffff0000, v53
	v_pk_fma_f32 v[8:9], v[8:9], v[122:123], v[18:19]
	v_add_u32_e32 v14, 0x8000, v14
	v_cvt_pk_bf16_f32 v16, v8, v9
	global_store_dword v14, v16, s[8:9]
	v_lshlrev_b32_e32 v18, 16, v54
	v_and_b32_e32 v19, 0xffff0000, v54
	v_pk_fma_f32 v[8:9], v[8:9], v[124:125], v[18:19]
	v_add_u32_e32 v14, 0x8000, v14
	v_cvt_pk_bf16_f32 v16, v8, v9
	global_store_dword v14, v16, s[8:9]
	v_lshlrev_b32_e32 v18, 16, v55
	v_and_b32_e32 v19, 0xffff0000, v55
	v_pk_fma_f32 v[8:9], v[8:9], v[126:127], v[18:19]
	v_add_u32_e32 v14, 0x8000, v14
	v_cvt_pk_bf16_f32 v16, v8, v9
	global_store_dword v14, v16, s[8:9]
	v_lshlrev_b32_e32 v18, 16, v56
	v_and_b32_e32 v19, 0xffff0000, v56
	v_pk_fma_f32 v[8:9], v[8:9], v[128:129], v[18:19]
	v_add_u32_e32 v14, 0x8000, v14
	v_cvt_pk_bf16_f32 v16, v8, v9
	global_store_dword v14, v16, s[8:9]
	v_lshlrev_b32_e32 v18, 16, v57
	v_and_b32_e32 v19, 0xffff0000, v57
	v_pk_fma_f32 v[8:9], v[8:9], v[130:131], v[18:19]
	v_add_u32_e32 v14, 0x8000, v14
	v_cvt_pk_bf16_f32 v16, v8, v9
	global_store_dword v14, v16, s[8:9]
	v_lshlrev_b32_e32 v18, 16, v58
	v_and_b32_e32 v19, 0xffff0000, v58
	v_pk_fma_f32 v[8:9], v[8:9], v[132:133], v[18:19]
	v_add_u32_e32 v14, 0x8000, v14
	v_cvt_pk_bf16_f32 v16, v8, v9
	global_store_dword v14, v16, s[8:9]
	v_lshlrev_b32_e32 v18, 16, v59
	v_and_b32_e32 v19, 0xffff0000, v59
	v_pk_fma_f32 v[8:9], v[8:9], v[134:135], v[18:19]
	v_add_u32_e32 v14, 0x8000, v14
	v_cvt_pk_bf16_f32 v16, v8, v9
	global_store_dword v14, v16, s[8:9]
	v_lshlrev_b32_e32 v18, 16, v60
	v_and_b32_e32 v19, 0xffff0000, v60
	v_pk_fma_f32 v[8:9], v[8:9], v[136:137], v[18:19]
	v_add_u32_e32 v14, 0x8000, v14
	v_cvt_pk_bf16_f32 v16, v8, v9
	global_store_dword v14, v16, s[8:9]
	v_lshlrev_b32_e32 v18, 16, v61
	v_and_b32_e32 v19, 0xffff0000, v61
	v_pk_fma_f32 v[8:9], v[8:9], v[138:139], v[18:19]
	v_add_u32_e32 v14, 0x8000, v14
	v_cvt_pk_bf16_f32 v16, v8, v9
	global_store_dword v14, v16, s[8:9]
	v_lshlrev_b32_e32 v18, 16, v62
	v_and_b32_e32 v19, 0xffff0000, v62
	v_pk_fma_f32 v[8:9], v[8:9], v[140:141], v[18:19]
	v_add_u32_e32 v14, 0x8000, v14
	v_cvt_pk_bf16_f32 v16, v8, v9
	global_store_dword v14, v16, s[8:9]
	v_lshlrev_b32_e32 v18, 16, v63
	v_and_b32_e32 v19, 0xffff0000, v63
	v_pk_fma_f32 v[8:9], v[8:9], v[142:143], v[18:19]
	v_add_u32_e32 v14, 0x8000, v14
	v_add_u32_e32 v10, s1, v10
	s_mov_b32 s0, 0xffff
	v_cmp_lt_i32_e32 vcc, s0, v10
	s_or_b64 s[6:7], vcc, s[6:7]
	v_add_u16_e32 v11, s1, v11
	s_andn2_b64 exec, exec, s[6:7]
	s_cbranch_execnz .LBB0_621
